# removed 139 XNACK-rule s_nop 0 between back-to-back global_load_dwordx4 (process runs xnack-), mainly in GEMM K-loop load blocks
# speedup vs baseline: 1.0033x; 1.0033x over previous
; __device__ __forceinline__ void conv_tile(const float* __restrict__ W, int K, int N, int Npad, bf16_t* __restrict__ dst, int mode,
;                           int kt, int nt, char* smem) {
;   float* T = (float*)smem;
;   const int tid = threadIdx.x;
;   const int k0 = kt * 64, n0 = nt * 64;
;   __syncthreads();
;   {
;     const int r = tid >> 4, c4 = (tid & 15) * 4;
; #pragma unroll
;     for (int i = 0; i < 4; ++i) {
;       const int k = r + 16 * i, n = n0 + c4;
;       float4 v = make_float4(0.f, 0.f, 0.f, 0.f);
;       if (n < N) v = *(const float4*)(W + (size_t)(k0 + k) * N + n);
;       T[k * 65 + c4 + 0] = v.x;
;       T[k * 65 + c4 + 1] = v.y;
;       T[k * 65 + c4 + 2] = v.z;
;       T[k * 65 + c4 + 3] = v.w;
;     }
;   }
;   __syncthreads();
;   {
;     const int n = tid >> 2, ks = (tid & 3) * 16;
;     const int gn = n0 + n;
;     if (gn < Npad) {
;       const int drow = mode == 0 ? gn : ((gn >> 5) * 64 + (gn & 31) + (mode == 2 ? 32 : 0));
;       uint32_t w[8];
; #pragma unroll
;       for (int q = 0; q < 8; ++q) w[q] = pack2(T[(ks + 2 * q) * 65 + n], T[(ks + 2 * q + 1) * 65 + n]);
;       uint4* d = (uint4*)(dst + (size_t)drow * K + k0 + ks);
;       d[0] = make_uint4(w[0], w[1], w[2], w[3]);
;       d[1] = make_uint4(w[4], w[5], w[6], w[7]);
;     }
;   }
; }
; __device__ __forceinline__ void phase_conv(const Params& P, int layer, char* smem, int part, int rank, int nrank) {
;     ...
;   for (int t = t_lo + rank; t < total; t += nrank) {
;     if (t < t_in) {
;       conv_tile(w_in, 1024, n_in, np_in, (bf16_t*)(ws + OFF_WIN), 0, t / nt_in, t % nt_in, smem);
;     } else if (t < t_in + 256) {
;       const int q = t - t_in;
;       conv_tile(w_out, 1024, 1024, 1024, (bf16_t*)(ws + OFF_WOUT), 0, q >> 4, q & 15, smem);
;     } else if (t < t_in + 256 + 704) {
;       const int q = t - t_in - 256;
;       conv_tile(P.w_gate + (size_t)layer * 1024 * DFF, 1024, DFF, DFF, (bf16_t*)(ws + OFF_WGU), 1, q / 44, q % 44, smem);
;     } else if (t < t_in + 256 + 1408) {
;       const int q = t - t_in - 256 - 704;
;       conv_tile(P.w_up + (size_t)layer * 1024 * DFF, 1024, DFF, DFF, (bf16_t*)(ws + OFF_WGU), 2, q / 44, q % 44, smem);
;     } else {
;       const int q = t - t_in - 256 - 1408;
;       conv_tile(P.w_down + (size_t)layer * DFF * 1024, DFF, 1024, 1024, (bf16_t*)(ws + OFF_WDN), 0, q >> 4, q & 15, smem);
.LBB0_8:
	s_cmpk_gt_i32 s21, 0x23f
	s_cbranch_scc0 .LBB0_15
	s_cmpk_gt_u32 s21, 0x33f
	s_cbranch_scc0 .LBB0_16
	s_cmpk_gt_u32 s21, 0x5ff
	s_cbranch_scc0 .LBB0_17
	s_cmpk_gt_u32 s21, 0x8bf
	s_cbranch_scc0 .LBB0_18
	s_add_i32 s2, s14, 0x7ffff700
	s_and_b32 s2, s2, 0x7fffffc0
	s_load_dwordx16 s[36:51], s[0:1], 0x40
	s_add_i32 s4, s2, 0xffffe600
	s_and_b32 s2, s12, 0x3c0
	v_or_b32_e32 v2, s2, v26
	v_lshlrev_b32_e32 v18, 2, v2
	v_or_b32_e32 v2, s4, v1
	v_add_u32_e32 v4, s4, v27
	v_ashrrev_i32_e32 v3, 31, v2
	v_ashrrev_i32_e32 v5, 31, v4
	s_waitcnt lgkmcnt(0)
	v_lshl_add_u64 v[14:15], s[40:41], 0, v[18:19]
	v_lshlrev_b64 v[2:3], 12, v[2:3]
	v_lshlrev_b64 v[4:5], 12, v[4:5]
	v_lshl_add_u64 v[2:3], v[14:15], 0, v[2:3]
	v_lshl_add_u64 v[6:7], v[14:15], 0, v[4:5]
	s_barrier
	global_load_dwordx4 v[2:5], v[2:3], off
	global_load_dwordx4 v[6:9], v[6:7], off
	v_add_u32_e32 v10, s4, v28
	v_ashrrev_i32_e32 v11, 31, v10
	v_lshlrev_b64 v[10:11], 12, v[10:11]
	v_add_u32_e32 v16, s4, v29
	v_lshl_add_u64 v[10:11], v[14:15], 0, v[10:11]
	v_ashrrev_i32_e32 v17, 31, v16
	global_load_dwordx4 v[10:13], v[10:11], off
	v_lshlrev_b64 v[16:17], 12, v[16:17]
	v_lshl_add_u64 v[14:15], v[14:15], 0, v[16:17]
	global_load_dwordx4 v[14:17], v[14:15], off
	v_add_u32_e32 v18, s2, v30
	s_mov_b64 s[8:9], 0
	v_cmp_gt_u32_e32 vcc, s16, v18
	s_mov_b64 s[6:7], 0
	s_waitcnt vmcnt(3)
	ds_write2_b32 v35, v2, v3 offset1:1
	ds_write2_b32 v35, v4, v5 offset0:2 offset1:3
	s_waitcnt vmcnt(2)
	ds_write2_b32 v36, v6, v7 offset1:1
	ds_write2_b32 v37, v8, v9 offset1:1
	s_waitcnt vmcnt(1)
	ds_write2_b32 v38, v10, v11 offset1:1
	ds_write2_b32 v39, v12, v13 offset1:1
	s_waitcnt vmcnt(0)
	ds_write2_b32 v40, v14, v15 offset1:1
	ds_write2_b32 v41, v16, v17 offset1:1
	s_waitcnt lgkmcnt(0)
	s_barrier
	s_and_saveexec_b64 s[2:3], vcc
	s_xor_b64 s[10:11], exec, s[2:3]
	s_cbranch_execz .LBB0_14
	ds_read2_b32 v[8:9], v31 offset1:130
	ds_read2_b32 v[2:3], v32 offset0:65 offset1:195
	ds_read2_b32 v[12:13], v42 offset0:4 offset1:134
	ds_read2_b32 v[4:5], v43 offset0:69 offset1:199
	ds_read2_b32 v[16:17], v44 offset0:8 offset1:138
	ds_read2_b32 v[10:11], v45 offset0:73 offset1:203
	s_waitcnt lgkmcnt(5)
	v_mov_b32_e32 v6, v8
	s_waitcnt lgkmcnt(4)
	v_mov_b32_e32 v7, v2
	v_mov_b32_e32 v2, v9
	s_waitcnt lgkmcnt(3)
	v_mov_b32_e32 v8, v12
	s_waitcnt lgkmcnt(2)
	v_mov_b32_e32 v9, v4
	v_mov_b32_e32 v4, v13
	ds_read2_b32 v[22:23], v46 offset0:12 offset1:142
	ds_read2_b32 v[12:13], v47 offset0:77 offset1:207
	v_mul_u32_u24_e32 v18, 0xb00, v18
	v_lshlrev_b32_e32 v18, 1, v18
	s_mov_b64 s[6:7], exec
	s_waitcnt lgkmcnt(3)
	v_mov_b32_e32 v14, v16
	s_waitcnt lgkmcnt(2)
	v_mov_b32_e32 v15, v10
	v_mov_b32_e32 v10, v17
	s_waitcnt lgkmcnt(1)
	v_mov_b32_e32 v16, v22
	s_waitcnt lgkmcnt(0)
	v_mov_b32_e32 v17, v12
	v_mov_b32_e32 v12, v23
	v_lshl_add_u64 v[22:23], s[96:97], 0, v[18:19]

; __device__ __forceinline__ void conv_tile(const float* __restrict__ W, int K, int N, int Npad, bf16_t* __restrict__ dst, int mode,
;                           int kt, int nt, char* smem) {
;   float* T = (float*)smem;
;   const int tid = threadIdx.x;
;   const int k0 = kt * 64, n0 = nt * 64;
;   __syncthreads();
;   {
;     const int r = tid >> 4, c4 = (tid & 15) * 4;
; #pragma unroll
;     for (int i = 0; i < 4; ++i) {
;       const int k = r + 16 * i, n = n0 + c4;
;       float4 v = make_float4(0.f, 0.f, 0.f, 0.f);
;       if (n < N) v = *(const float4*)(W + (size_t)(k0 + k) * N + n);
;       T[k * 65 + c4 + 0] = v.x;
;       T[k * 65 + c4 + 1] = v.y;
;       T[k * 65 + c4 + 2] = v.z;
;       T[k * 65 + c4 + 3] = v.w;
;     }
;   }
;   __syncthreads();
;   {
;     const int n = tid >> 2, ks = (tid & 3) * 16;
;     const int gn = n0 + n;
;     if (gn < Npad) {
;       const int drow = mode == 0 ? gn : ((gn >> 5) * 64 + (gn & 31) + (mode == 2 ? 32 : 0));
;       uint32_t w[8];
; #pragma unroll
;       for (int q = 0; q < 8; ++q) w[q] = pack2(T[(ks + 2 * q) * 65 + n], T[(ks + 2 * q + 1) * 65 + n]);
;       uint4* d = (uint4*)(dst + (size_t)drow * K + k0 + ks);
;       d[0] = make_uint4(w[0], w[1], w[2], w[3]);
;       d[1] = make_uint4(w[4], w[5], w[6], w[7]);
;     }
;   }
; }
; __device__ __forceinline__ void phase_conv(const Params& P, int layer, char* smem, int part, int rank, int nrank) {
;     ...
;     } else if (t < t_in + 256 + 1408) {
;       const int q = t - t_in - 256 - 704;
;       conv_tile(P.w_up + (size_t)layer * 1024 * DFF, 1024, DFF, DFF, (bf16_t*)(ws + OFF_WGU), 2, q / 44, q % 44, smem);
.LBB0_19:
	s_add_i32 s2, s21, 0xfa00
	s_and_b32 s3, s2, 0xffff
	s_mul_i32 s3, s3, 0xba2f
	s_lshr_b32 s3, s3, 21
	s_mul_i32 s4, s3, 44
	s_sub_i32 s2, s2, s4
	s_load_dwordx16 s[36:51], s[0:1], 0x40
	s_lshl_b32 s2, s2, 6
	s_and_b32 s2, s2, 0xffc0
	s_lshl_b32 s4, s3, 6
	v_or_b32_e32 v2, s2, v26
	v_lshlrev_b32_e32 v18, 2, v2
	v_or_b32_e32 v2, s4, v1
	s_waitcnt lgkmcnt(0)
	v_lshl_add_u64 v[14:15], s[38:39], 0, v[18:19]
	v_mul_u32_u24_e32 v18, 0x2c00, v2
	v_add_u32_e32 v4, s4, v27
	v_lshl_add_u64 v[2:3], v[14:15], 0, v[18:19]
	v_mul_u32_u24_e32 v18, 0x2c00, v4
	v_lshl_add_u64 v[6:7], v[14:15], 0, v[18:19]
	s_barrier
	global_load_dwordx4 v[2:5], v[2:3], off
	global_load_dwordx4 v[6:9], v[6:7], off
	v_add_u32_e32 v10, s4, v28
	v_mul_u32_u24_e32 v18, 0x2c00, v10
	v_lshl_add_u64 v[10:11], v[14:15], 0, v[18:19]
	v_add_u32_e32 v12, s4, v29
	v_mul_u32_u24_e32 v18, 0x2c00, v12
	global_load_dwordx4 v[10:13], v[10:11], off
	v_lshl_add_u64 v[14:15], v[14:15], 0, v[18:19]
	global_load_dwordx4 v[14:17], v[14:15], off
	v_add_u32_e32 v18, s2, v30
	v_cmp_gt_u32_e32 vcc, s17, v18
	s_waitcnt vmcnt(3)
	ds_write2_b32 v35, v2, v3 offset1:1
	ds_write2_b32 v35, v4, v5 offset0:2 offset1:3
	s_waitcnt vmcnt(2)
	ds_write2_b32 v36, v6, v7 offset1:1
	ds_write2_b32 v37, v8, v9 offset1:1
	s_waitcnt vmcnt(1)
	ds_write2_b32 v38, v10, v11 offset1:1
	ds_write2_b32 v39, v12, v13 offset1:1
	s_waitcnt vmcnt(0)
	ds_write2_b32 v40, v14, v15 offset1:1
	ds_write2_b32 v41, v16, v17 offset1:1
	s_waitcnt lgkmcnt(0)
	s_barrier
	s_and_saveexec_b64 s[2:3], vcc
	s_xor_b64 s[8:9], exec, s[2:3]
	s_cbranch_execz .LBB0_21
	v_lshlrev_b32_e32 v4, 1, v18
	ds_read2_b32 v[8:9], v31 offset1:130
	ds_read2_b32 v[2:3], v32 offset0:65 offset1:195
	v_and_or_b32 v18, v4, s18, v34
	ds_read2_b32 v[12:13], v42 offset0:4 offset1:134
	ds_read2_b32 v[4:5], v43 offset0:69 offset1:199
	ds_read2_b32 v[16:17], v44 offset0:8 offset1:138
	ds_read2_b32 v[10:11], v45 offset0:73 offset1:203
	s_waitcnt lgkmcnt(5)
	v_mov_b32_e32 v6, v8
	s_waitcnt lgkmcnt(4)
	v_mov_b32_e32 v7, v2
	v_mov_b32_e32 v2, v9
	s_waitcnt lgkmcnt(3)
	v_mov_b32_e32 v8, v12
	s_waitcnt lgkmcnt(2)
	v_mov_b32_e32 v9, v4
	v_mov_b32_e32 v4, v13
	ds_read2_b32 v[22:23], v46 offset0:12 offset1:142
	ds_read2_b32 v[12:13], v47 offset0:77 offset1:207
	v_readlane_b32 s2, v211, 36
	v_lshlrev_b32_e32 v18, 11, v18
	v_readlane_b32 s3, v211, 37
	s_waitcnt lgkmcnt(3)
	v_mov_b32_e32 v14, v16
	s_waitcnt lgkmcnt(2)
	v_mov_b32_e32 v15, v10
	v_mov_b32_e32 v10, v17
	s_waitcnt lgkmcnt(1)
	v_mov_b32_e32 v16, v22
	s_waitcnt lgkmcnt(0)
	v_mov_b32_e32 v17, v12
	v_mov_b32_e32 v12, v23
	v_lshl_add_u64 v[22:23], s[2:3], 0, v[18:19]
	s_or_b64 s[6:7], s[6:7], exec

; __device__ __forceinline__ void conv_tile(const float* __restrict__ W, int K, int N, int Npad, bf16_t* __restrict__ dst, int mode,
;                           int kt, int nt, char* smem) {
;   float* T = (float*)smem;
;   const int tid = threadIdx.x;
;   const int k0 = kt * 64, n0 = nt * 64;
;   __syncthreads();
;   {
;     const int r = tid >> 4, c4 = (tid & 15) * 4;
; #pragma unroll
;     for (int i = 0; i < 4; ++i) {
;       const int k = r + 16 * i, n = n0 + c4;
;       float4 v = make_float4(0.f, 0.f, 0.f, 0.f);
;       if (n < N) v = *(const float4*)(W + (size_t)(k0 + k) * N + n);
;       T[k * 65 + c4 + 0] = v.x;
;       T[k * 65 + c4 + 1] = v.y;
;       T[k * 65 + c4 + 2] = v.z;
;       T[k * 65 + c4 + 3] = v.w;
;     }
;   }
;   __syncthreads();
;   {
;     const int n = tid >> 2, ks = (tid & 3) * 16;
;     const int gn = n0 + n;
;     if (gn < Npad) {
;       const int drow = mode == 0 ? gn : ((gn >> 5) * 64 + (gn & 31) + (mode == 2 ? 32 : 0));
;       uint32_t w[8];
; #pragma unroll
;       for (int q = 0; q < 8; ++q) w[q] = pack2(T[(ks + 2 * q) * 65 + n], T[(ks + 2 * q + 1) * 65 + n]);
;       uint4* d = (uint4*)(dst + (size_t)drow * K + k0 + ks);
;       d[0] = make_uint4(w[0], w[1], w[2], w[3]);
;       d[1] = make_uint4(w[4], w[5], w[6], w[7]);
;     }
;   }
; }
; __device__ __forceinline__ void phase_conv(const Params& P, int layer, char* smem, int part, int rank, int nrank) {
;     ...
;     } else if (t < t_in + 256 + 704) {
;       const int q = t - t_in - 256;
;       conv_tile(P.w_gate + (size_t)layer * 1024 * DFF, 1024, DFF, DFF, (bf16_t*)(ws + OFF_WGU), 1, q / 44, q % 44, smem);
.LBB0_23:
	s_add_i32 s2, s21, 0xfcc0
	s_and_b32 s3, s2, 0xffff
	s_mul_i32 s3, s3, 0xba2f
	s_lshr_b32 s3, s3, 21
	s_mul_i32 s4, s3, 44
	s_sub_i32 s2, s2, s4
	s_load_dwordx16 s[36:51], s[0:1], 0x40
	s_lshl_b32 s2, s2, 6
	s_and_b32 s2, s2, 0xffc0
	s_lshl_b32 s4, s3, 6
	v_or_b32_e32 v2, s2, v26
	v_lshlrev_b32_e32 v18, 2, v2
	v_or_b32_e32 v2, s4, v1
	s_waitcnt lgkmcnt(0)
	v_lshl_add_u64 v[14:15], s[36:37], 0, v[18:19]
	v_mul_u32_u24_e32 v18, 0x2c00, v2
	v_add_u32_e32 v4, s4, v27
	v_lshl_add_u64 v[2:3], v[14:15], 0, v[18:19]
	v_mul_u32_u24_e32 v18, 0x2c00, v4
	v_lshl_add_u64 v[6:7], v[14:15], 0, v[18:19]
	s_barrier
	global_load_dwordx4 v[2:5], v[2:3], off
	global_load_dwordx4 v[6:9], v[6:7], off
	v_add_u32_e32 v10, s4, v28
	v_mul_u32_u24_e32 v18, 0x2c00, v10
	v_lshl_add_u64 v[10:11], v[14:15], 0, v[18:19]
	v_add_u32_e32 v12, s4, v29
	v_mul_u32_u24_e32 v18, 0x2c00, v12
	global_load_dwordx4 v[10:13], v[10:11], off
	v_lshl_add_u64 v[14:15], v[14:15], 0, v[18:19]
	global_load_dwordx4 v[14:17], v[14:15], off
	v_add_u32_e32 v18, s2, v30
	v_cmp_gt_u32_e32 vcc, s17, v18
	s_waitcnt vmcnt(3)
	ds_write2_b32 v35, v2, v3 offset1:1
	ds_write2_b32 v35, v4, v5 offset0:2 offset1:3
	s_waitcnt vmcnt(2)
	ds_write2_b32 v36, v6, v7 offset1:1
	ds_write2_b32 v37, v8, v9 offset1:1
	s_waitcnt vmcnt(1)
	ds_write2_b32 v38, v10, v11 offset1:1
	ds_write2_b32 v39, v12, v13 offset1:1
	s_waitcnt vmcnt(0)
	ds_write2_b32 v40, v14, v15 offset1:1
	ds_write2_b32 v41, v16, v17 offset1:1
	s_waitcnt lgkmcnt(0)
	s_barrier
	s_and_saveexec_b64 s[2:3], vcc
	s_xor_b64 s[8:9], exec, s[2:3]
	s_cbranch_execz .LBB0_25
	v_lshlrev_b32_e32 v4, 1, v18
	ds_read2_b32 v[8:9], v31 offset1:130
	ds_read2_b32 v[2:3], v32 offset0:65 offset1:195
	v_and_or_b32 v18, v4, s18, v33
	ds_read2_b32 v[12:13], v42 offset0:4 offset1:134
	ds_read2_b32 v[4:5], v43 offset0:69 offset1:199
	ds_read2_b32 v[16:17], v44 offset0:8 offset1:138
	ds_read2_b32 v[10:11], v45 offset0:73 offset1:203
	s_waitcnt lgkmcnt(5)
	v_mov_b32_e32 v6, v8
	s_waitcnt lgkmcnt(4)
	v_mov_b32_e32 v7, v2
	v_mov_b32_e32 v2, v9
	s_waitcnt lgkmcnt(3)
	v_mov_b32_e32 v8, v12
	s_waitcnt lgkmcnt(2)
	v_mov_b32_e32 v9, v4
	v_mov_b32_e32 v4, v13
	ds_read2_b32 v[22:23], v46 offset0:12 offset1:142
	ds_read2_b32 v[12:13], v47 offset0:77 offset1:207
	v_readlane_b32 s2, v211, 36
	v_lshlrev_b32_e32 v18, 11, v18
	v_readlane_b32 s3, v211, 37
	s_waitcnt lgkmcnt(3)
	v_mov_b32_e32 v14, v16
	s_waitcnt lgkmcnt(2)
	v_mov_b32_e32 v15, v10
	v_mov_b32_e32 v10, v17
	s_waitcnt lgkmcnt(1)
	v_mov_b32_e32 v16, v22
	s_waitcnt lgkmcnt(0)
	v_mov_b32_e32 v17, v12
	v_mov_b32_e32 v12, v23
	v_lshl_add_u64 v[22:23], s[2:3], 0, v[18:19]
	s_or_b64 s[6:7], s[6:7], exec

; __device__ __forceinline__ void conv_tile(const float* __restrict__ W, int K, int N, int Npad, bf16_t* __restrict__ dst, int mode,
;                           int kt, int nt, char* smem) {
;   float* T = (float*)smem;
;   const int tid = threadIdx.x;
;   const int k0 = kt * 64, n0 = nt * 64;
;   __syncthreads();
;   {
;     const int r = tid >> 4, c4 = (tid & 15) * 4;
; #pragma unroll
;     for (int i = 0; i < 4; ++i) {
;       const int k = r + 16 * i, n = n0 + c4;
;       float4 v = make_float4(0.f, 0.f, 0.f, 0.f);
;       if (n < N) v = *(const float4*)(W + (size_t)(k0 + k) * N + n);
;       T[k * 65 + c4 + 0] = v.x;
;       T[k * 65 + c4 + 1] = v.y;
;       T[k * 65 + c4 + 2] = v.z;
;       T[k * 65 + c4 + 3] = v.w;
;     }
;   }
;   __syncthreads();
;   {
;     const int n = tid >> 2, ks = (tid & 3) * 16;
;     const int gn = n0 + n;
;     if (gn < Npad) {
;       const int drow = mode == 0 ? gn : ((gn >> 5) * 64 + (gn & 31) + (mode == 2 ? 32 : 0));
;       uint32_t w[8];
; #pragma unroll
;       for (int q = 0; q < 8; ++q) w[q] = pack2(T[(ks + 2 * q) * 65 + n], T[(ks + 2 * q + 1) * 65 + n]);
;       uint4* d = (uint4*)(dst + (size_t)drow * K + k0 + ks);
;       d[0] = make_uint4(w[0], w[1], w[2], w[3]);
;       d[1] = make_uint4(w[4], w[5], w[6], w[7]);
;     }
;   }
; }
; __device__ __forceinline__ void phase_conv(const Params& P, int layer, char* smem, int part, int rank, int nrank) {
;     ...
;     } else if (t < t_in + 256) {
;       const int q = t - t_in;
;       conv_tile(w_out, 1024, 1024, 1024, (bf16_t*)(ws + OFF_WOUT), 0, q >> 4, q & 15, smem);
.LBB0_27:
	s_load_dwordx16 s[36:51], s[0:1], 0x40
	s_and_b32 s2, s14, 0xfc0
	s_add_i32 s4, s2, 0xfffff700
	s_and_b32 s2, s12, 0x3c0
	v_or_b32_e32 v2, s2, v26
	v_lshlrev_b32_e32 v18, 2, v2
	s_waitcnt lgkmcnt(0)
	v_lshl_add_u64 v[14:15], s[44:45], 0, v[18:19]
	v_or_b32_e32 v18, s4, v1
	v_lshlrev_b64 v[2:3], 12, v[18:19]
	v_add_u32_e32 v18, s4, v27
	v_lshlrev_b64 v[4:5], 12, v[18:19]
	v_lshl_add_u64 v[2:3], v[14:15], 0, v[2:3]
	v_lshl_add_u64 v[6:7], v[14:15], 0, v[4:5]
	s_barrier
	global_load_dwordx4 v[2:5], v[2:3], off
	global_load_dwordx4 v[6:9], v[6:7], off
	v_add_u32_e32 v18, s4, v28
	v_lshlrev_b64 v[10:11], 12, v[18:19]
	v_lshl_add_u64 v[10:11], v[14:15], 0, v[10:11]
	v_add_u32_e32 v18, s4, v29
	global_load_dwordx4 v[10:13], v[10:11], off
	v_lshlrev_b64 v[16:17], 12, v[18:19]
	v_lshl_add_u64 v[14:15], v[14:15], 0, v[16:17]
	global_load_dwordx4 v[14:17], v[14:15], off
	v_add_u32_e32 v18, s2, v30
	v_cmp_gt_u32_e32 vcc, s16, v18
	s_waitcnt vmcnt(3)
	ds_write2_b32 v35, v2, v3 offset1:1
	ds_write2_b32 v35, v4, v5 offset0:2 offset1:3
	s_waitcnt vmcnt(2)
	ds_write2_b32 v36, v6, v7 offset1:1
	ds_write2_b32 v37, v8, v9 offset1:1
	s_waitcnt vmcnt(1)
	ds_write2_b32 v38, v10, v11 offset1:1
	ds_write2_b32 v39, v12, v13 offset1:1
	s_waitcnt vmcnt(0)
	ds_write2_b32 v40, v14, v15 offset1:1
	ds_write2_b32 v41, v16, v17 offset1:1
	s_waitcnt lgkmcnt(0)
	s_barrier
	s_and_saveexec_b64 s[2:3], vcc
	s_xor_b64 s[8:9], exec, s[2:3]
	s_cbranch_execz .LBB0_29
	ds_read2_b32 v[8:9], v31 offset1:130
	ds_read2_b32 v[2:3], v32 offset0:65 offset1:195
	ds_read2_b32 v[12:13], v42 offset0:4 offset1:134
	ds_read2_b32 v[4:5], v43 offset0:69 offset1:199
	ds_read2_b32 v[16:17], v44 offset0:8 offset1:138
	ds_read2_b32 v[10:11], v45 offset0:73 offset1:203
	s_waitcnt lgkmcnt(5)
	v_mov_b32_e32 v6, v8
	s_waitcnt lgkmcnt(4)
	v_mov_b32_e32 v7, v2
	v_mov_b32_e32 v2, v9
	s_waitcnt lgkmcnt(3)
	v_mov_b32_e32 v8, v12
	s_waitcnt lgkmcnt(2)
	v_mov_b32_e32 v9, v4
	v_mov_b32_e32 v4, v13
	ds_read2_b32 v[22:23], v46 offset0:12 offset1:142
	ds_read2_b32 v[12:13], v47 offset0:77 offset1:207
	v_readlane_b32 s2, v211, 34
	v_lshlrev_b32_e32 v18, 11, v18
	v_readlane_b32 s3, v211, 35
	s_waitcnt lgkmcnt(3)
	v_mov_b32_e32 v14, v16
	s_waitcnt lgkmcnt(2)
	v_mov_b32_e32 v15, v10
	v_mov_b32_e32 v10, v17
	s_waitcnt lgkmcnt(1)
	v_mov_b32_e32 v16, v22
	s_waitcnt lgkmcnt(0)
	v_mov_b32_e32 v17, v12
	v_mov_b32_e32 v12, v23
	v_lshl_add_u64 v[22:23], s[2:3], 0, v[18:19]
	s_or_b64 s[6:7], s[6:7], exec

; __device__ __forceinline__ void conv_tile(const float* __restrict__ W, int K, int N, int Npad, bf16_t* __restrict__ dst, int mode,
;                           int kt, int nt, char* smem) {
;   float* T = (float*)smem;
;   const int tid = threadIdx.x;
;   const int k0 = kt * 64, n0 = nt * 64;
;   __syncthreads();
;   {
;     const int r = tid >> 4, c4 = (tid & 15) * 4;
; #pragma unroll
;     for (int i = 0; i < 4; ++i) {
;       const int k = r + 16 * i, n = n0 + c4;
;       float4 v = make_float4(0.f, 0.f, 0.f, 0.f);
;       if (n < N) v = *(const float4*)(W + (size_t)(k0 + k) * N + n);
;       T[k * 65 + c4 + 0] = v.x;
;       T[k * 65 + c4 + 1] = v.y;
;       T[k * 65 + c4 + 2] = v.z;
;       T[k * 65 + c4 + 3] = v.w;
;     }
;   }
;   __syncthreads();
;   {
;     const int n = tid >> 2, ks = (tid & 3) * 16;
;     const int gn = n0 + n;
;     if (gn < Npad) {
;       const int drow = mode == 0 ? gn : ((gn >> 5) * 64 + (gn & 31) + (mode == 2 ? 32 : 0));
;       uint32_t w[8];
; #pragma unroll
;       for (int q = 0; q < 8; ++q) w[q] = pack2(T[(ks + 2 * q) * 65 + n], T[(ks + 2 * q + 1) * 65 + n]);
;       uint4* d = (uint4*)(dst + (size_t)drow * K + k0 + ks);
;       d[0] = make_uint4(w[0], w[1], w[2], w[3]);
;       d[1] = make_uint4(w[4], w[5], w[6], w[7]);
;     }
;   }
; }
; __device__ __forceinline__ void phase_conv(const Params& P, int layer, char* smem, int part, int rank, int nrank) {
;     ...
;     if (t < t_in) {
;       conv_tile(w_in, 1024, n_in, np_in, (bf16_t*)(ws + OFF_WIN), 0, t / nt_in, t % nt_in, smem);
.LBB0_31:
	s_mul_hi_i32 s2, s21, 0x38e38e39
	s_lshr_b32 s3, s2, 31
	s_ashr_i32 s2, s2, 3
	s_add_i32 s2, s2, s3
	s_mul_i32 s5, s2, 0xfffff700
	s_add_i32 s5, s5, s12
	v_add_u32_e32 v22, s5, v26
	s_lshl_b32 s4, s2, 6
	v_cmp_gt_i32_e32 vcc, s19, v22
	v_mov_b32_e32 v2, 0
	v_mov_b32_e32 v3, 0
	v_mov_b32_e32 v4, 0
	v_mov_b32_e32 v5, 0
	v_mov_b32_e32 v6, 0
	v_mov_b32_e32 v7, 0
	v_mov_b32_e32 v8, 0
	v_mov_b32_e32 v9, 0
	v_mov_b32_e32 v10, 0
	v_mov_b32_e32 v11, 0
	v_mov_b32_e32 v12, 0
	v_mov_b32_e32 v13, 0
	v_mov_b32_e32 v14, 0
	v_mov_b32_e32 v15, 0
	v_mov_b32_e32 v16, 0
	v_mov_b32_e32 v17, 0
	s_barrier
	s_and_saveexec_b64 s[2:3], vcc
	s_cbranch_execz .LBB0_33
	s_load_dwordx16 s[36:51], s[0:1], 0x40
	v_ashrrev_i32_e32 v23, 31, v22
	v_or_b32_e32 v2, s4, v1
	v_add_u32_e32 v4, s4, v27
	v_add_u32_e32 v12, s4, v28
	s_waitcnt lgkmcnt(0)
	v_lshl_add_u64 v[10:11], v[22:23], 2, s[42:43]
	v_add_u32_e32 v14, s4, v29
	v_mad_i64_i32 v[2:3], s[8:9], v2, s20, v[10:11]
	v_mad_i64_i32 v[6:7], s[8:9], v4, s20, v[10:11]
	v_mad_i64_i32 v[12:13], s[8:9], v12, s20, v[10:11]
	v_mad_i64_i32 v[14:15], s[8:9], v14, s20, v[10:11]
	global_load_dwordx4 v[2:5], v[2:3], off
	global_load_dwordx4 v[6:9], v[6:7], off
	global_load_dwordx4 v[10:13], v[12:13], off
	global_load_dwordx4 v[14:17], v[14:15], off

; __device__ __forceinline__ void phase_norm(const float* lat_src, const float* ctx_src, const float* gain, const float* modl,
;                                            int sh_off, int sc_off, bf16_t* A, bool lat_only) {
;     ...
;   for (int idx0 = (blockIdx.x * 4 + wave) * 2; idx0 < total; idx0 += gridDim.x * 8) {
;     float4 xv[2][4];
;     const float* md[2];
;     int rowi[2];
; #pragma unroll
;     for (int u = 0; u < 2; ++u) {
;       const int idx = idx0 + u;
;       const int row = lat_only ? ((idx >> 14) * TPB + 256 + (idx & 16383)) : idx;
;       const int b = row / TPB, kidx = row - b * TPB;
;       const bool isc = kidx < 256;
;       const float* src = isc ? ctx_src + (size_t)(b * 256 + kidx) * DM : lat_src + (size_t)(b * 16384 + kidx - 256) * DM;
;       md[u] = modl + (isc ? 2 : b) * 6144;
;       rowi[u] = row;
; #pragma unroll
;       for (int i = 0; i < 4; ++i) xv[u][i] = *(const float4*)(src + i * 256 + lane * 4);
;     }
; #pragma unroll
;     for (int u = 0; u < 2; ++u) {
;       float ss = 0.f;
; #pragma unroll
;       for (int i = 0; i < 4; ++i) ss += xv[u][i].x * xv[u][i].x + xv[u][i].y * xv[u][i].y + xv[u][i].z * xv[u][i].z + xv[u][i].w * xv[u][i].w;
;       ss = wave_sum(ss);
;       const float rstd = rsqrtf(ss * (1.0f / 1024.0f) + 1e-6f);
; #pragma unroll
;       for (int i = 0; i < 4; ++i) {
;         const int c = i * 256 + lane * 4;
;         const float4 g = *(const float4*)(gain + c);
;         const float4 sh = *(const float4*)(md[u] + sh_off + c);
;         const float4 sc = *(const float4*)(md[u] + sc_off + c);
;         uint2 w;
;         w.x = pack2(xv[u][i].x * rstd * g.x * (1.f + sc.x) + sh.x, xv[u][i].y * rstd * g.y * (1.f + sc.y) + sh.y);
;         w.y = pack2(xv[u][i].z * rstd * g.z * (1.f + sc.z) + sh.z, xv[u][i].w * rstd * g.w * (1.f + sc.w) + sh.w);
;         *(uint2*)(A + (size_t)rowi[u] * DM + c) = w;
;       }
;     }
.LBB0_74:
	s_or_b64 exec, exec, s[2:3]
	v_lshl_add_u64 v[8:9], v[8:9], 0, v[32:33]
	global_load_dwordx4 v[28:31], v[8:9], off
	global_load_dwordx4 v[20:23], v[8:9], off offset:1024
	global_load_dwordx4 v[16:19], v[8:9], off offset:2048
	global_load_dwordx4 v[8:11], v[8:9], off offset:3072
	s_waitcnt vmcnt(7)
	v_mov_b32_e32 v66, v25
	s_waitcnt vmcnt(6)
	v_mov_b32_e32 v67, v13
	s_waitcnt vmcnt(5)
	v_mov_b32_e32 v74, v5
	s_waitcnt vmcnt(4)
	v_mov_b32_e32 v75, v1
	v_lshl_add_u64 v[52:53], v[52:53], 2, s[14:15]
	v_mov_b32_e32 v64, v24
	v_mov_b32_e32 v65, v12
	v_mov_b32_e32 v70, v4
	v_mov_b32_e32 v71, v0
	v_pk_mul_f32 v[66:67], v[66:67], v[66:67]
	v_pk_mul_f32 v[74:75], v[74:75], v[74:75]
	v_lshl_add_u64 v[80:81], v[52:53], 0, s[6:7]
	v_mov_b32_e32 v68, v26
	v_mov_b32_e32 v69, v14
	v_mov_b32_e32 v76, v6
	v_mov_b32_e32 v77, v2
	v_lshl_add_u64 v[52:53], v[52:53], 0, v[32:33]
	v_pk_fma_f32 v[64:65], v[64:65], v[64:65], v[66:67]
	v_pk_fma_f32 v[66:67], v[70:71], v[70:71], v[74:75]
	v_lshl_add_u64 v[70:71], v[80:81], 0, v[32:33]
	global_load_dwordx4 v[60:63], v[34:35], off
	v_pk_fma_f32 v[74:75], v[68:69], v[68:69], v[64:65]
	v_pk_fma_f32 v[76:77], v[76:77], v[76:77], v[66:67]
	global_load_dwordx4 v[64:67], v[52:53], off
	global_load_dwordx4 v[68:71], v[70:71], off
	v_mov_b32_e32 v72, v27
	v_mov_b32_e32 v73, v15
	v_mov_b32_e32 v78, v7
	v_mov_b32_e32 v79, v3
	v_pk_fma_f32 v[72:73], v[72:73], v[72:73], v[74:75]
	v_pk_fma_f32 v[74:75], v[78:79], v[78:79], v[76:77]
	v_mov_b32_e32 v77, v72
	v_mov_b32_e32 v79, v74
	s_mov_b32 s2, 0x3a800000
	v_ashrrev_i32_e32 v47, 31, v46
	v_mov_b32_e32 v39, v33
	v_lshl_add_u64 v[50:51], v[50:51], 2, s[14:15]
	v_ashrrev_i32_e32 v49, 31, v48
	s_waitcnt vmcnt(6)
	v_mov_b32_e32 v84, v29
	s_waitcnt vmcnt(5)
	v_mov_b32_e32 v85, v21
	v_mov_b32_e32 v82, v28
	v_mov_b32_e32 v83, v20
	s_waitcnt vmcnt(4)
	v_mov_b32_e32 v88, v17
	s_waitcnt vmcnt(3)
	v_mov_b32_e32 v89, v9
	v_pk_mul_f32 v[84:85], v[84:85], v[84:85]
	v_mov_b32_e32 v86, v16
	v_mov_b32_e32 v87, v8
	v_mov_b32_e32 v90, v30
	v_mov_b32_e32 v91, v22
	v_pk_mul_f32 v[88:89], v[88:89], v[88:89]
	v_pk_fma_f32 v[82:83], v[82:83], v[82:83], v[84:85]
	v_mov_b32_e32 v92, v18
	v_mov_b32_e32 v93, v10
	v_mov_b32_e32 v94, v31
	v_mov_b32_e32 v95, v23
	v_pk_fma_f32 v[84:85], v[86:87], v[86:87], v[88:89]
	v_pk_fma_f32 v[82:83], v[90:91], v[90:91], v[82:83]
	v_mov_b32_e32 v96, v19
	v_mov_b32_e32 v97, v11
	v_pk_fma_f32 v[84:85], v[92:93], v[92:93], v[84:85]
	v_pk_fma_f32 v[82:83], v[94:95], v[94:95], v[82:83]
	v_pk_fma_f32 v[84:85], v[96:97], v[96:97], v[84:85]
	v_mov_b32_e32 v76, v82
	v_mov_b32_e32 v72, v83
	v_mov_b32_e32 v78, v84
	v_pk_add_f32 v[72:73], v[76:77], v[72:73]
	v_mov_b32_e32 v74, v85
	v_pk_add_f32 v[72:73], v[72:73], v[78:79]
	v_lshlrev_b64 v[76:77], 11, v[46:47]
	v_pk_add_f32 v[72:73], v[72:73], v[74:75]
	ds_bpermute_b32 v75, v45, v73
	ds_bpermute_b32 v74, v45, v72
	s_waitcnt vmcnt(0)
	v_pk_add_f32 v[68:69], v[68:69], 1.0 op_sel_hi:[1,0]
	v_pk_add_f32 v[70:71], v[70:71], 1.0 op_sel_hi:[1,0]
	v_add_u32_e32 v46, s8, v46
	s_waitcnt lgkmcnt(0)
	v_pk_add_f32 v[72:73], v[72:73], v[74:75]
	ds_bpermute_b32 v75, v54, v73
	ds_bpermute_b32 v74, v54, v72
	s_waitcnt lgkmcnt(0)
	v_pk_add_f32 v[72:73], v[72:73], v[74:75]
	ds_bpermute_b32 v75, v55, v73
	ds_bpermute_b32 v74, v55, v72
	s_waitcnt lgkmcnt(0)
	v_pk_add_f32 v[72:73], v[72:73], v[74:75]
	ds_bpermute_b32 v75, v56, v73
	ds_bpermute_b32 v74, v56, v72
	s_waitcnt lgkmcnt(0)
	v_pk_add_f32 v[72:73], v[72:73], v[74:75]
	ds_bpermute_b32 v75, v57, v73
	ds_bpermute_b32 v74, v57, v72
	s_waitcnt lgkmcnt(0)
	v_pk_add_f32 v[72:73], v[72:73], v[74:75]
	ds_bpermute_b32 v75, v58, v73
	ds_bpermute_b32 v74, v58, v72
	s_waitcnt lgkmcnt(0)
	v_pk_add_f32 v[72:73], v[72:73], v[74:75]
	s_nop 0
	v_pk_fma_f32 v[72:73], v[72:73], s[2:3], v[44:45] op_sel_hi:[1,0,0]
	v_lshl_add_u64 v[74:75], v[36:37], 0, v[76:77]
	v_mul_f32_e32 v41, 0x4b800000, v73
	v_cmp_gt_f32_e32 vcc, s12, v73
	s_mov_b32 s2, 0x81ff
	s_nop 0
	v_cndmask_b32_e32 v41, v73, v41, vcc
	v_rsq_f32_e32 v41, v41
	s_nop 0
	v_mul_f32_e32 v43, 0x45800000, v41
	v_cndmask_b32_e32 v76, v41, v43, vcc
	v_pk_mul_f32 v[24:25], v[24:25], v[76:77] op_sel_hi:[1,0]
	v_pk_mul_f32 v[26:27], v[26:27], v[76:77] op_sel_hi:[1,0]
	v_pk_mul_f32 v[24:25], v[60:61], v[24:25]
	v_pk_mul_f32 v[26:27], v[62:63], v[26:27]
	v_pk_fma_f32 v[24:25], v[68:69], v[24:25], v[64:65]
	v_pk_fma_f32 v[26:27], v[26:27], v[70:71], v[66:67]
	v_cvt_pk_bf16_f32 v24, v24, v25
	v_cvt_pk_bf16_f32 v25, v26, v27
	global_store_dwordx2 v[74:75], v[24:25], off
	global_load_dwordx4 v[24:27], v[34:35], off offset:1024
	v_lshl_add_u64 v[60:61], v[80:81], 0, v[38:39]
	global_load_dwordx4 v[60:63], v[60:61], off
	global_load_dwordx4 v[64:67], v[52:53], off offset:1024
	v_pk_mul_f32 v[12:13], v[12:13], v[76:77] op_sel_hi:[1,0]
	v_pk_mul_f32 v[14:15], v[14:15], v[76:77] op_sel_hi:[1,0]
	v_mov_b32_e32 v41, v33
	v_lshl_add_u64 v[68:69], v[80:81], 0, v[40:41]
	v_pk_mul_f32 v[4:5], v[4:5], v[76:77] op_sel_hi:[1,0]
	v_pk_mul_f32 v[6:7], v[6:7], v[76:77] op_sel_hi:[1,0]
	v_mov_b32_e32 v43, v33
	v_pk_mul_f32 v[0:1], v[0:1], v[76:77] op_sel_hi:[1,0]
	v_pk_mul_f32 v[2:3], v[2:3], v[76:77] op_sel_hi:[1,0]
	v_cmp_gt_f32_e32 vcc, s12, v72
	s_waitcnt vmcnt(2)
	v_pk_mul_f32 v[12:13], v[12:13], v[24:25]
	v_pk_mul_f32 v[14:15], v[14:15], v[26:27]
	s_waitcnt vmcnt(1)
	v_pk_add_f32 v[24:25], v[60:61], 1.0 op_sel_hi:[1,0]
	v_pk_add_f32 v[26:27], v[62:63], 1.0 op_sel_hi:[1,0]
	s_waitcnt vmcnt(0)
; __device__ __forceinline__ void phase_norm(const float* lat_src, const float* ctx_src, const float* gain, const float* modl,
;                                            int sh_off, int sc_off, bf16_t* A, bool lat_only) {
;     ...
;   for (int idx0 = (blockIdx.x * 4 + wave) * 2; idx0 < total; idx0 += gridDim.x * 8) {
;     float4 xv[2][4];
;     const float* md[2];
;     int rowi[2];
; #pragma unroll
;     for (int u = 0; u < 2; ++u) {
;       const int idx = idx0 + u;
;       const int row = lat_only ? ((idx >> 14) * TPB + 256 + (idx & 16383)) : idx;
;       const int b = row / TPB, kidx = row - b * TPB;
;       const bool isc = kidx < 256;
;       const float* src = isc ? ctx_src + (size_t)(b * 256 + kidx) * DM : lat_src + (size_t)(b * 16384 + kidx - 256) * DM;
;       md[u] = modl + (isc ? 2 : b) * 6144;
;       rowi[u] = row;
; #pragma unroll
;       for (int i = 0; i < 4; ++i) xv[u][i] = *(const float4*)(src + i * 256 + lane * 4);
;     }
; #pragma unroll
;     for (int u = 0; u < 2; ++u) {
;       float ss = 0.f;
; #pragma unroll
;       for (int i = 0; i < 4; ++i) ss += xv[u][i].x * xv[u][i].x + xv[u][i].y * xv[u][i].y + xv[u][i].z * xv[u][i].z + xv[u][i].w * xv[u][i].w;
;       ss = wave_sum(ss);
;       const float rstd = rsqrtf(ss * (1.0f / 1024.0f) + 1e-6f);
; #pragma unroll
;       for (int i = 0; i < 4; ++i) {
;         const int c = i * 256 + lane * 4;
;         const float4 g = *(const float4*)(gain + c);
;         const float4 sh = *(const float4*)(md[u] + sh_off + c);
;         const float4 sc = *(const float4*)(md[u] + sc_off + c);
;         uint2 w;
;         w.x = pack2(xv[u][i].x * rstd * g.x * (1.f + sc.x) + sh.x, xv[u][i].y * rstd * g.y * (1.f + sc.y) + sh.y);
;         w.y = pack2(xv[u][i].z * rstd * g.z * (1.f + sc.z) + sh.z, xv[u][i].w * rstd * g.w * (1.f + sc.w) + sh.w);
;         *(uint2*)(A + (size_t)rowi[u] * DM + c) = w;
;       }
;     }
	v_pk_fma_f32 v[12:13], v[12:13], v[24:25], v[64:65]
	v_pk_fma_f32 v[14:15], v[14:15], v[26:27], v[66:67]
	v_cvt_pk_bf16_f32 v12, v12, v13
	v_cvt_pk_bf16_f32 v13, v14, v15
	global_store_dwordx2 v[74:75], v[12:13], off offset:512
	global_load_dwordx4 v[12:15], v[34:35], off offset:2048
	global_load_dwordx4 v[24:27], v[68:69], off
	global_load_dwordx4 v[60:63], v[52:53], off offset:2048
	v_lshl_add_u64 v[64:65], v[80:81], 0, v[42:43]
	s_waitcnt vmcnt(2)
	v_pk_mul_f32 v[4:5], v[4:5], v[12:13]
	s_waitcnt vmcnt(1)
	v_pk_add_f32 v[12:13], v[24:25], 1.0 op_sel_hi:[1,0]
	v_pk_mul_f32 v[6:7], v[6:7], v[14:15]
	v_pk_add_f32 v[14:15], v[26:27], 1.0 op_sel_hi:[1,0]
	s_waitcnt vmcnt(0)
	v_pk_fma_f32 v[4:5], v[4:5], v[12:13], v[60:61]
	v_pk_fma_f32 v[6:7], v[6:7], v[14:15], v[62:63]
	v_cvt_pk_bf16_f32 v4, v4, v5
	v_cvt_pk_bf16_f32 v5, v6, v7
	global_store_dwordx2 v[74:75], v[4:5], off offset:1024
	global_load_dwordx4 v[4:7], v[34:35], off offset:3072
	global_load_dwordx4 v[12:15], v[64:65], off
	global_load_dwordx4 v[24:27], v[52:53], off offset:3072
	v_lshl_add_u64 v[52:53], v[50:51], 0, s[6:7]
	v_lshl_add_u64 v[60:61], v[52:53], 0, v[32:33]
	s_waitcnt vmcnt(2)
	v_pk_mul_f32 v[0:1], v[0:1], v[4:5]
	s_waitcnt vmcnt(1)
	v_pk_add_f32 v[4:5], v[12:13], 1.0 op_sel_hi:[1,0]
	v_pk_mul_f32 v[2:3], v[2:3], v[6:7]
	v_pk_add_f32 v[6:7], v[14:15], 1.0 op_sel_hi:[1,0]
	s_waitcnt vmcnt(0)
	v_pk_fma_f32 v[0:1], v[0:1], v[4:5], v[24:25]
	v_pk_fma_f32 v[2:3], v[2:3], v[6:7], v[26:27]
	v_cvt_pk_bf16_f32 v0, v0, v1
	v_cvt_pk_bf16_f32 v1, v2, v3
	global_store_dwordx2 v[74:75], v[0:1], off offset:1536
	global_load_dwordx4 v[0:3], v[34:35], off
	global_load_dwordx4 v[4:7], v[60:61], off
	v_lshl_add_u64 v[24:25], v[50:51], 0, v[32:33]
	global_load_dwordx4 v[12:15], v[24:25], off
	v_mul_f32_e32 v26, 0x4b800000, v72
	v_cndmask_b32_e32 v26, v72, v26, vcc
	v_rsq_f32_e32 v47, v26
	v_lshlrev_b64 v[26:27], 11, v[48:49]
	v_lshl_add_u64 v[48:49], v[52:53], 0, v[38:39]
	v_lshl_add_u64 v[26:27], v[36:37], 0, v[26:27]
	v_mul_f32_e32 v39, 0x45800000, v47
	v_cndmask_b32_e32 v50, v47, v39, vcc
	v_pk_mul_f32 v[28:29], v[28:29], v[50:51] op_sel_hi:[1,0]
	v_pk_mul_f32 v[30:31], v[30:31], v[50:51] op_sel_hi:[1,0]
	v_pk_mul_f32 v[20:21], v[20:21], v[50:51] op_sel_hi:[1,0]
	v_pk_mul_f32 v[22:23], v[22:23], v[50:51] op_sel_hi:[1,0]
	v_pk_mul_f32 v[16:17], v[16:17], v[50:51] op_sel_hi:[1,0]
	v_pk_mul_f32 v[18:19], v[18:19], v[50:51] op_sel_hi:[1,0]
	v_pk_mul_f32 v[8:9], v[8:9], v[50:51] op_sel_hi:[1,0]
	v_pk_mul_f32 v[10:11], v[10:11], v[50:51] op_sel_hi:[1,0]
	v_cmp_lt_i32_e32 vcc, s2, v46
	s_or_b64 s[4:5], vcc, s[4:5]
	s_waitcnt vmcnt(2)
	v_pk_mul_f32 v[0:1], v[0:1], v[28:29]
	s_waitcnt vmcnt(1)
	v_pk_add_f32 v[4:5], v[4:5], 1.0 op_sel_hi:[1,0]
	v_pk_mul_f32 v[2:3], v[2:3], v[30:31]
	v_pk_add_f32 v[6:7], v[6:7], 1.0 op_sel_hi:[1,0]
	s_waitcnt vmcnt(0)
	v_pk_fma_f32 v[0:1], v[4:5], v[0:1], v[12:13]
	v_pk_fma_f32 v[2:3], v[2:3], v[6:7], v[14:15]
	v_cvt_pk_bf16_f32 v0, v0, v1
	v_cvt_pk_bf16_f32 v1, v2, v3
	global_store_dwordx2 v[26:27], v[0:1], off
	global_load_dwordx4 v[0:3], v[34:35], off offset:1024
	global_load_dwordx4 v[4:7], v[48:49], off
	global_load_dwordx4 v[12:15], v[24:25], off offset:1024
	v_lshl_add_u64 v[28:29], v[52:53], 0, v[40:41]
	s_waitcnt vmcnt(2)
	v_pk_mul_f32 v[0:1], v[20:21], v[0:1]
	s_waitcnt vmcnt(1)
	v_pk_add_f32 v[4:5], v[4:5], 1.0 op_sel_hi:[1,0]
	v_pk_mul_f32 v[2:3], v[22:23], v[2:3]
	v_pk_add_f32 v[6:7], v[6:7], 1.0 op_sel_hi:[1,0]
	s_waitcnt vmcnt(0)
	v_pk_fma_f32 v[0:1], v[0:1], v[4:5], v[12:13]
	v_pk_fma_f32 v[2:3], v[2:3], v[6:7], v[14:15]
	v_cvt_pk_bf16_f32 v0, v0, v1
	v_cvt_pk_bf16_f32 v1, v2, v3
	global_store_dwordx2 v[26:27], v[0:1], off offset:512
	global_load_dwordx4 v[0:3], v[34:35], off offset:2048
	global_load_dwordx4 v[4:7], v[28:29], off
	global_load_dwordx4 v[12:15], v[24:25], off offset:2048
	v_lshl_add_u64 v[20:21], v[52:53], 0, v[42:43]
	s_waitcnt vmcnt(2)
	v_pk_mul_f32 v[0:1], v[16:17], v[0:1]
	s_waitcnt vmcnt(1)
	v_pk_add_f32 v[4:5], v[4:5], 1.0 op_sel_hi:[1,0]
	v_pk_mul_f32 v[2:3], v[18:19], v[2:3]
	v_pk_add_f32 v[6:7], v[6:7], 1.0 op_sel_hi:[1,0]
	s_waitcnt vmcnt(0)
	v_pk_fma_f32 v[0:1], v[0:1], v[4:5], v[12:13]
	v_pk_fma_f32 v[2:3], v[2:3], v[6:7], v[14:15]
	v_cvt_pk_bf16_f32 v0, v0, v1
	v_cvt_pk_bf16_f32 v1, v2, v3
	global_store_dwordx2 v[26:27], v[0:1], off offset:1024
	global_load_dwordx4 v[0:3], v[34:35], off offset:3072
	global_load_dwordx4 v[4:7], v[20:21], off
	global_load_dwordx4 v[12:15], v[24:25], off offset:3072
	s_waitcnt vmcnt(2)
	v_pk_mul_f32 v[0:1], v[8:9], v[0:1]
	s_waitcnt vmcnt(1)
	v_pk_add_f32 v[4:5], v[4:5], 1.0 op_sel_hi:[1,0]
	v_pk_mul_f32 v[2:3], v[10:11], v[2:3]
	v_pk_add_f32 v[6:7], v[6:7], 1.0 op_sel_hi:[1,0]
	s_waitcnt vmcnt(0)
	v_pk_fma_f32 v[0:1], v[0:1], v[4:5], v[12:13]
	v_pk_fma_f32 v[2:3], v[2:3], v[6:7], v[14:15]
	v_cvt_pk_bf16_f32 v0, v0, v1
	v_cvt_pk_bf16_f32 v1, v2, v3
	global_store_dwordx2 v[26:27], v[0:1], off offset:1536
	s_andn2_b64 exec, exec, s[4:5]
	s_cbranch_execz .LBB0_83
.LBB0_75:
	v_mul_hi_i32 v0, v46, s9
	v_lshrrev_b32_e32 v1, 31, v0
	v_ashrrev_i32_e32 v0, 13, v0
	v_add_u32_e32 v2, v0, v1
	v_mad_i32_i24 v0, v2, s10, v46
	v_mul_i32_i24_e32 v3, 0xffffbf00, v2
	v_cmp_lt_i32_e32 vcc, s11, v0
	s_and_saveexec_b64 s[2:3], vcc
	s_xor_b64 s[2:3], exec, s[2:3]
	v_lshl_add_u32 v0, v2, 14, v3
	s_movk_i32 s13, 0xff00
	v_add3_u32 v0, v46, v0, s13
	v_ashrrev_i32_e32 v1, 31, v0
	v_lshlrev_b64 v[0:1], 12, v[0:1]
	v_mul_i32_i24_e32 v52, 0x1800, v2
	v_lshl_add_u64 v[0:1], s[36:37], 0, v[0:1]
	v_ashrrev_i32_e32 v53, 31, v52
	s_andn2_saveexec_b64 s[2:3], s[2:3]
	v_lshlrev_b32_e32 v0, 8, v2
	v_add3_u32 v0, v3, v0, v46
	v_ashrrev_i32_e32 v1, 31, v0
	v_lshlrev_b64 v[0:1], 12, v[0:1]
	v_lshl_add_u64 v[0:1], s[40:41], 0, v[0:1]
	v_mov_b64_e32 v[52:53], 0x3000
	s_or_b64 exec, exec, s[2:3]
	v_lshl_add_u64 v[0:1], v[0:1], 0, v[32:33]
	global_load_dwordx4 v[24:27], v[0:1], off
	global_load_dwordx4 v[12:15], v[0:1], off offset:1024
	global_load_dwordx4 v[4:7], v[0:1], off offset:2048
	global_load_dwordx4 v[0:3], v[0:1], off offset:3072
	v_add_u32_e32 v48, 1, v46
	v_mul_hi_i32 v8, v48, s9
	v_lshrrev_b32_e32 v9, 31, v8
	v_ashrrev_i32_e32 v8, 13, v8
	v_add_u32_e32 v10, v8, v9
	v_mad_i32_i24 v8, v10, s10, v48
	v_mul_i32_i24_e32 v11, 0xffffbf00, v10
	v_cmp_lt_i32_e32 vcc, s11, v8
	s_and_saveexec_b64 s[2:3], vcc
	s_xor_b64 s[2:3], exec, s[2:3]
	v_lshl_add_u32 v8, v10, 14, v11
	s_movk_i32 s13, 0xff01
	v_add3_u32 v8, v46, v8, s13
	v_ashrrev_i32_e32 v9, 31, v8
	v_lshlrev_b64 v[8:9], 12, v[8:9]
	v_mul_i32_i24_e32 v50, 0x1800, v10
	v_lshl_add_u64 v[8:9], s[36:37], 0, v[8:9]
	v_ashrrev_i32_e32 v51, 31, v50
	s_andn2_saveexec_b64 s[2:3], s[2:3]
	s_cbranch_execz .LBB0_74
	v_lshl_add_u32 v8, v10, 8, v11
	v_add3_u32 v8, v46, v8, 1
	v_ashrrev_i32_e32 v9, 31, v8
	v_lshlrev_b64 v[8:9], 12, v[8:9]
	v_lshl_add_u64 v[8:9], s[40:41], 0, v[8:9]
	v_mov_b64_e32 v[50:51], 0x3000
	s_branch .LBB0_74

; template <bool DEEP, class Epi>
; __device__ __forceinline__ void gemm_phase(const bf16_t* __restrict__ A, int lda, const bf16_t* __restrict__ Wt,
;                                            int K, int ntn, bool lat_only, const Epi& epi, char* smem) {
;     ...
;     for (int kt = 0; kt < nk; ++kt) {
;       __syncthreads();
;       GEMM_STORE(ra0, ra1, ra2, ra3, rb0, rb1, rb2, rb3, 0)
;       __syncthreads();
;       {
;         bf16x8 af0[4], bf0[4], af1[4], bf1[4];
;         __builtin_amdgcn_s_setprio(1);
; #pragma unroll
;         for (int i = 0; i < 4; ++i) af0[i] = *(const bf16x8*)(sA + (wm * 64 + i * 16 + l15) * LSTR + quad * 8);
; #pragma unroll
;         for (int j = 0; j < 4; ++j) bf0[j] = *(const bf16x8*)(sB + (wn * 64 + j * 16 + l15) * LSTR + quad * 8);
; #pragma unroll
;         for (int i = 0; i < 4; ++i) af1[i] = *(const bf16x8*)(sA + (wm * 64 + i * 16 + l15) * LSTR + 32 + quad * 8);
; #pragma unroll
;         for (int j = 0; j < 4; ++j) bf1[j] = *(const bf16x8*)(sB + (wn * 64 + j * 16 + l15) * LSTR + 32 + quad * 8);
;         __builtin_amdgcn_sched_barrier(0);
;         if (kt + 1 < nk) GEMM_LOAD(ra0, ra1, ra2, ra3, rb0, rb1, rb2, rb3, (kt + 1) * 64)
.LBB0_140:
	s_barrier
	s_waitcnt vmcnt(7)
	ds_write_b128 v165, v[64:67]
	s_waitcnt vmcnt(6)
	ds_write_b128 v165, v[68:71] offset:5120
	s_waitcnt vmcnt(5)
	ds_write_b128 v165, v[72:75] offset:10240
	s_waitcnt vmcnt(4)
	ds_write_b128 v165, v[76:79] offset:15360
	s_waitcnt vmcnt(3)
	ds_write_b128 v165, v[80:83] offset:20480
	s_waitcnt vmcnt(2)
	ds_write_b128 v165, v[84:87] offset:25600
	s_waitcnt vmcnt(1)
	ds_write_b128 v165, v[88:91] offset:30720
	s_waitcnt vmcnt(0)
	ds_write_b128 v165, v[92:95] offset:35840
	v_add_u32_e32 v96, v173, v175
	s_waitcnt lgkmcnt(0)
	s_barrier
	s_setprio 1
	ds_read_b128 v[156:159], v96
	ds_read_b128 v[152:155], v96 offset:2560
	ds_read_b128 v[132:135], v96 offset:5120
	ds_read_b128 v[124:127], v96 offset:7680
	ds_read_b128 v[136:139], v181 offset:20480
	ds_read_b128 v[140:143], v181 offset:23040
	ds_read_b128 v[144:147], v181 offset:25600
	ds_read_b128 v[148:151], v181 offset:28160
	ds_read_b128 v[128:131], v183 offset:64
	ds_read_b128 v[120:123], v183 offset:2624
	ds_read_b128 v[100:103], v183 offset:5184
	ds_read_b128 v[96:99], v183 offset:7744
	ds_read_b128 v[104:107], v185 offset:20544
	ds_read_b128 v[108:111], v185 offset:23104
	ds_read_b128 v[112:115], v185 offset:25664
	ds_read_b128 v[116:119], v185 offset:28224
	s_cmpk_eq_i32 s0, 0x780
	s_cbranch_scc1 .LBB0_139
	v_lshl_add_u64 v[72:73], v[238:239], 0, s[0:1]
	v_add_co_u32_e32 v64, vcc, 0x1d00000, v72
	v_lshl_add_u64 v[88:89], v[240:241], 0, s[0:1]
	s_nop 0
	v_addc_co_u32_e32 v65, vcc, 0, v73, vcc
	v_add_co_u32_e32 v68, vcc, 0x1d10000, v72
	s_nop 1
	v_addc_co_u32_e32 v69, vcc, 0, v73, vcc
	v_add_co_u32_e32 v74, vcc, 0x1d20000, v72
	global_load_dwordx4 v[64:67], v[64:65], off offset:128
	global_load_dwordx4 v[68:71], v[68:69], off offset:128
	v_addc_co_u32_e32 v75, vcc, 0, v73, vcc
	v_add_co_u32_e32 v76, vcc, 0x1d30000, v72
	s_nop 1
	v_addc_co_u32_e32 v77, vcc, 0, v73, vcc
	v_add_co_u32_e32 v84, vcc, 0x10000, v88
	global_load_dwordx4 v[72:75], v[74:75], off offset:128
	global_load_dwordx4 v[76:79], v[76:77], off offset:128
	v_addc_co_u32_e32 v85, vcc, 0, v89, vcc
	v_add_co_u32_e32 v90, vcc, 0x20000, v88
	global_load_dwordx4 v[80:83], v[88:89], off offset:128
	global_load_dwordx4 v[84:87], v[84:85], off offset:128
	v_addc_co_u32_e32 v91, vcc, 0, v89, vcc
	v_add_co_u32_e32 v92, vcc, 0x30000, v88
	s_nop 1
	v_addc_co_u32_e32 v93, vcc, 0, v89, vcc
	global_load_dwordx4 v[88:91], v[90:91], off offset:128
	global_load_dwordx4 v[92:95], v[92:93], off offset:128
	s_branch .LBB0_139

;   __device__ __forceinline__ void operator()(const f32x4 (&acc)[4][4], int row0w, int col0w, int l15, int quad) const {
;     ...
;       if (gain) {
;         float ss = 0.f;
; #pragma unroll
;         for (int j = 0; j < 4; ++j)
; #pragma unroll
;           for (int e = 0; e < 4; ++e) ss += v[j][e] * v[j][e];
;         ss += __shfl_xor(ss, 16);
;         ss += __shfl_xor(ss, 32);
;         const float rstd = rsqrtf(ss * (1.0f / 64.0f) + 1e-6f);
; #pragma unroll
;         for (int j = 0; j < 4; ++j)
; #pragma unroll
;           for (int e = 0; e < 4; ++e) v[j][e] *= rstd * gain[j * 16 + quad * 4 + e];
;         if (kidx >= 256) {
;           const int t = kidx - 256, pr = t >> 6, pc = t & 63;
; #pragma unroll
;           for (int e = 0; e < 4; ++e) {
;             const int f = quad * 4 + e;
;             const float cr = rope[(pr * 16 + f) * 2], sr = rope[(pr * 16 + f) * 2 + 1];
;             const float cc = rope[(pc * 16 + f) * 2], sc = rope[(pc * 16 + f) * 2 + 1];
;             float x1 = v[0][e], x2 = v[1][e];
;             v[0][e] = x1 * cr - x2 * sr;
;             v[1][e] = x2 * cr + x1 * sr;
;             x1 = v[2][e]; x2 = v[3][e];
;             v[2][e] = x1 * cc - x2 * sc;
;             v[3][e] = x2 * cc + x1 * sc;
;           }
;         }
.LBB0_148:
	s_or_b64 exec, exec, s[10:11]
	v_add_u32_e32 v68, s18, v171
	v_cmp_ne_u64_e64 s[0:1], 0, v[66:67]
	v_mul_hi_i32 v65, v68, s89
	v_lshrrev_b32_e32 v70, 31, v65
	v_ashrrev_i32_e32 v65, 13, v65
	v_add_u32_e32 v71, v65, v70
	v_mad_i32_i24 v70, v71, s96, v68
	v_lshlrev_b32_e32 v168, 2, v170
	s_and_saveexec_b64 s[18:19], s[0:1]
	s_cbranch_execz .LBB0_154
	s_waitcnt vmcnt(2)
	v_lshl_add_u64 v[84:85], v[66:67], 0, v[168:169]
	global_load_dwordx4 v[72:75], v[84:85], off
	global_load_dwordx4 v[76:79], v[84:85], off offset:64
	global_load_dwordx4 v[80:83], v[84:85], off offset:128
	global_load_dwordx4 v[84:87], v[84:85], off offset:192
	v_mul_f32_e32 v65, v61, v61
	v_fmac_f32_e32 v65, v60, v60
	v_fmac_f32_e32 v65, v62, v62
	v_fmac_f32_e32 v65, v63, v63
	v_fmac_f32_e32 v65, v56, v56
	v_fmac_f32_e32 v65, v57, v57
	v_fmac_f32_e32 v65, v58, v58
	s_waitcnt vmcnt(5)
	v_pk_mul_f32 v[90:91], v[52:53], v[52:53]
	v_fmac_f32_e32 v65, v59, v59
	v_add_f32_e32 v65, v90, v65
	v_pk_mul_f32 v[88:89], v[54:55], v[54:55]
	v_add_f32_e32 v65, v91, v65
	v_add_f32_e32 v65, v88, v65
	s_waitcnt vmcnt(4)
	v_pk_mul_f32 v[94:95], v[48:49], v[48:49]
	v_and_b32_e32 v97, 64, v189
	v_add_f32_e32 v65, v89, v65
	v_xor_b32_e32 v96, 16, v189
	v_add_u32_e32 v97, 64, v97
	v_add_f32_e32 v65, v94, v65
	v_pk_mul_f32 v[92:93], v[50:51], v[50:51]
	v_cmp_lt_i32_e64 s[4:5], v96, v97
	v_add_f32_e32 v65, v95, v65
	v_add_f32_e32 v65, v92, v65
	v_cndmask_b32_e64 v96, v189, v96, s[4:5]
	v_lshlrev_b32_e32 v96, 2, v96
	v_add_f32_e32 v65, v93, v65
	ds_bpermute_b32 v88, v96, v65
	v_xor_b32_e32 v89, 32, v189
	v_cmp_lt_i32_e64 s[4:5], v89, v97
	s_waitcnt lgkmcnt(0)
	v_add_f32_e32 v65, v65, v88
	v_cndmask_b32_e64 v89, v189, v89, s[4:5]
	v_lshlrev_b32_e32 v89, 2, v89
	ds_bpermute_b32 v88, v89, v65
	s_waitcnt lgkmcnt(0)
	v_add_f32_e32 v65, v65, v88
	v_fmamk_f32 v65, v65, 0x3c800000, v187
	v_mul_f32_e32 v88, 0x4b800000, v65
	v_cmp_gt_f32_e64 s[4:5], s97, v65
	s_nop 1
	v_cndmask_b32_e64 v65, v65, v88, s[4:5]
	v_rsq_f32_e32 v65, v65
	s_nop 0
	v_mul_f32_e32 v88, 0x45800000, v65
	v_cndmask_b32_e64 v88, v65, v88, s[4:5]
	v_cmp_lt_i32_e64 s[4:5], s30, v70
	s_waitcnt vmcnt(3)
	v_pk_mul_f32 v[72:73], v[72:73], v[88:89] op_sel_hi:[1,0]
	s_waitcnt vmcnt(2)
	v_pk_mul_f32 v[76:77], v[76:77], v[88:89] op_sel_hi:[1,0]
	v_pk_mul_f32 v[74:75], v[74:75], v[88:89] op_sel_hi:[1,0]
	v_pk_mul_f32 v[78:79], v[78:79], v[88:89] op_sel_hi:[1,0]
	s_waitcnt vmcnt(1)
	v_pk_mul_f32 v[80:81], v[88:89], v[80:81] op_sel_hi:[0,1]
	s_waitcnt vmcnt(0)
	v_pk_mul_f32 v[84:85], v[88:89], v[84:85] op_sel_hi:[0,1]
	v_pk_mul_f32 v[82:83], v[88:89], v[82:83] op_sel_hi:[0,1]
	v_pk_mul_f32 v[86:87], v[88:89], v[86:87] op_sel_hi:[0,1]
	v_pk_mul_f32 v[60:61], v[60:61], v[72:73]
	v_pk_mul_f32 v[56:57], v[56:57], v[76:77]
	v_pk_mul_f32 v[62:63], v[62:63], v[74:75]
	v_pk_mul_f32 v[58:59], v[58:59], v[78:79]
	v_pk_mul_f32 v[52:53], v[52:53], v[80:81]
	v_pk_mul_f32 v[48:49], v[48:49], v[84:85]
	v_pk_mul_f32 v[54:55], v[54:55], v[82:83]
	v_pk_mul_f32 v[50:51], v[50:51], v[86:87]
	s_and_saveexec_b64 s[10:11], s[4:5]
	s_cbranch_execz .LBB0_151
	v_add_u32_e32 v65, 0xffffff00, v70
	v_lshrrev_b32_e32 v65, 2, v65
	v_and_or_b32 v65, v65, s17, v170
	global_load_dwordx4 v[72:75], v[234:235], off
	global_load_dwordx4 v[76:79], v[234:235], off offset:16
	v_mov_b32_e32 v81, v169
	v_lshlrev_b32_e32 v80, 1, v65
	v_lshl_add_u64 v[84:85], v[80:81], 2, s[8:9]
	global_load_dwordx4 v[80:83], v[84:85], off
	global_load_dwordx4 v[84:87], v[84:85], off offset:16
	s_waitcnt vmcnt(3)
	v_mov_b32_e32 v89, v74
	v_mov_b32_e32 v74, v73
	s_waitcnt vmcnt(2)
	v_mov_b32_e32 v73, v78
	v_mov_b32_e32 v78, v77
	v_mov_b32_e32 v88, v72
	v_mov_b32_e32 v72, v76
	v_pk_mul_f32 v[76:77], v[48:49], v[74:75]
	v_pk_mul_f32 v[74:75], v[52:53], v[74:75]
	v_pk_mul_f32 v[90:91], v[50:51], v[78:79]
	v_pk_mul_f32 v[78:79], v[54:55], v[78:79]
	v_pk_fma_f32 v[48:49], v[48:49], v[88:89], v[74:75]
	v_pk_fma_f32 v[54:55], v[54:55], v[72:73], v[90:91] neg_lo:[0,0,1] neg_hi:[0,0,1]
	v_pk_fma_f32 v[50:51], v[50:51], v[72:73], v[78:79]
	s_waitcnt vmcnt(1)
	v_mov_b32_e32 v73, v82
	v_mov_b32_e32 v82, v81
	s_waitcnt vmcnt(0)
	v_mov_b32_e32 v75, v86
	v_mov_b32_e32 v86, v85
	v_pk_fma_f32 v[52:53], v[52:53], v[88:89], v[76:77] neg_lo:[0,0,1] neg_hi:[0,0,1]
	v_mov_b32_e32 v72, v80
	v_mov_b32_e32 v74, v84
	v_pk_mul_f32 v[76:77], v[56:57], v[82:83]
	v_pk_mul_f32 v[78:79], v[60:61], v[82:83]
	v_pk_mul_f32 v[80:81], v[58:59], v[86:87]
	v_pk_mul_f32 v[82:83], v[62:63], v[86:87]
	v_pk_fma_f32 v[60:61], v[60:61], v[72:73], v[76:77] neg_lo:[0,0,1] neg_hi:[0,0,1]
	v_pk_fma_f32 v[56:57], v[56:57], v[72:73], v[78:79]
	v_pk_fma_f32 v[62:63], v[62:63], v[74:75], v[80:81] neg_lo:[0,0,1] neg_hi:[0,0,1]
	v_pk_fma_f32 v[58:59], v[58:59], v[74:75], v[82:83]

;   __device__ __forceinline__ void operator()(const f32x4 (&acc)[4][4], int row0w, int col0w, int l15, int quad) const {
;     ...
;       if (gain) {
;         float ss = 0.f;
; #pragma unroll
;         for (int j = 0; j < 4; ++j)
; #pragma unroll
;           for (int e = 0; e < 4; ++e) ss += v[j][e] * v[j][e];
;         ss += __shfl_xor(ss, 16);
;         ss += __shfl_xor(ss, 32);
;         const float rstd = rsqrtf(ss * (1.0f / 64.0f) + 1e-6f);
; #pragma unroll
;         for (int j = 0; j < 4; ++j)
; #pragma unroll
;           for (int e = 0; e < 4; ++e) v[j][e] *= rstd * gain[j * 16 + quad * 4 + e];
;         if (kidx >= 256) {
;           const int t = kidx - 256, pr = t >> 6, pc = t & 63;
; #pragma unroll
;           for (int e = 0; e < 4; ++e) {
;             const int f = quad * 4 + e;
;             const float cr = rope[(pr * 16 + f) * 2], sr = rope[(pr * 16 + f) * 2 + 1];
;             const float cc = rope[(pc * 16 + f) * 2], sc = rope[(pc * 16 + f) * 2 + 1];
;             float x1 = v[0][e], x2 = v[1][e];
;             v[0][e] = x1 * cr - x2 * sr;
;             v[1][e] = x2 * cr + x1 * sr;
;             x1 = v[2][e]; x2 = v[3][e];
;             v[2][e] = x1 * cc - x2 * sc;
;             v[3][e] = x2 * cc + x1 * sc;
;           }
;         }
.LBB0_207:
	v_lshl_add_u64 v[48:49], v[66:67], 0, v[168:169]
	global_load_dwordx4 v[36:39], v[48:49], off
	global_load_dwordx4 v[40:43], v[48:49], off offset:64
	global_load_dwordx4 v[44:47], v[48:49], off offset:128
	global_load_dwordx4 v[48:51], v[48:49], off offset:192
	v_mul_f32_e32 v35, v29, v29
	v_fmac_f32_e32 v35, v28, v28
	v_fmac_f32_e32 v35, v30, v30
	v_fmac_f32_e32 v35, v31, v31
	v_fmac_f32_e32 v35, v24, v24
	v_fmac_f32_e32 v35, v25, v25
	v_fmac_f32_e32 v35, v26, v26
	v_pk_mul_f32 v[54:55], v[20:21], v[20:21]
	v_fmac_f32_e32 v35, v27, v27
	v_add_f32_e32 v35, v54, v35
	v_pk_mul_f32 v[52:53], v[22:23], v[22:23]
	v_add_f32_e32 v35, v55, v35
	v_add_f32_e32 v35, v52, v35
	v_pk_mul_f32 v[58:59], v[16:17], v[16:17]
	v_and_b32_e32 v61, 64, v189
	v_add_f32_e32 v35, v53, v35
	v_xor_b32_e32 v60, 16, v189
	v_add_u32_e32 v61, 64, v61
	v_add_f32_e32 v35, v58, v35
	v_pk_mul_f32 v[56:57], v[18:19], v[18:19]
	v_cmp_lt_i32_e64 s[4:5], v60, v61
	v_add_f32_e32 v35, v59, v35
	v_add_f32_e32 v35, v56, v35
	v_cndmask_b32_e64 v60, v189, v60, s[4:5]
	v_lshlrev_b32_e32 v60, 2, v60
	v_add_f32_e32 v35, v57, v35
	ds_bpermute_b32 v52, v60, v35
	v_xor_b32_e32 v53, 32, v189
	v_cmp_lt_i32_e64 s[4:5], v53, v61
	s_waitcnt lgkmcnt(0)
	v_add_f32_e32 v35, v35, v52
	v_cndmask_b32_e64 v53, v189, v53, s[4:5]
	v_lshlrev_b32_e32 v53, 2, v53
	ds_bpermute_b32 v52, v53, v35
	s_waitcnt lgkmcnt(0)
	v_add_f32_e32 v35, v35, v52
	v_fmamk_f32 v35, v35, 0x3c800000, v187
	v_mul_f32_e32 v52, 0x4b800000, v35
	v_cmp_gt_f32_e64 s[4:5], s97, v35
	s_nop 1
	v_cndmask_b32_e64 v35, v35, v52, s[4:5]
	v_rsq_f32_e32 v35, v35
	s_nop 0
	v_mul_f32_e32 v52, 0x45800000, v35
	v_cndmask_b32_e64 v52, v35, v52, s[4:5]
	v_cmp_lt_i32_e64 s[4:5], s30, v34
	s_waitcnt vmcnt(3)
	v_pk_mul_f32 v[36:37], v[36:37], v[52:53] op_sel_hi:[1,0]
	s_waitcnt vmcnt(2)
	v_pk_mul_f32 v[40:41], v[40:41], v[52:53] op_sel_hi:[1,0]
	v_pk_mul_f32 v[38:39], v[38:39], v[52:53] op_sel_hi:[1,0]
	v_pk_mul_f32 v[42:43], v[42:43], v[52:53] op_sel_hi:[1,0]
	s_waitcnt vmcnt(1)
	v_pk_mul_f32 v[44:45], v[52:53], v[44:45] op_sel_hi:[0,1]
	s_waitcnt vmcnt(0)
	v_pk_mul_f32 v[48:49], v[52:53], v[48:49] op_sel_hi:[0,1]
	v_pk_mul_f32 v[46:47], v[52:53], v[46:47] op_sel_hi:[0,1]
	v_pk_mul_f32 v[50:51], v[52:53], v[50:51] op_sel_hi:[0,1]
	v_pk_mul_f32 v[28:29], v[28:29], v[36:37]
	v_pk_mul_f32 v[24:25], v[24:25], v[40:41]
	v_pk_mul_f32 v[30:31], v[30:31], v[38:39]
	v_pk_mul_f32 v[26:27], v[26:27], v[42:43]
	v_pk_mul_f32 v[20:21], v[20:21], v[44:45]
	v_pk_mul_f32 v[16:17], v[16:17], v[48:49]
	v_pk_mul_f32 v[22:23], v[22:23], v[46:47]
	v_pk_mul_f32 v[18:19], v[18:19], v[50:51]
	s_and_saveexec_b64 s[10:11], s[4:5]
	s_cbranch_execz .LBB0_209
	v_lshlrev_b32_e32 v35, 4, v32
	s_movk_i32 s2, 0x2f0
	v_and_or_b32 v35, v35, s2, v170
	v_lshlrev_b32_e32 v35, 3, v35
	global_load_dwordx4 v[36:39], v35, s[8:9]
	global_load_dwordx4 v[40:43], v35, s[8:9] offset:16
	v_add_u32_e32 v35, 0xffffff00, v34
	v_lshrrev_b32_e32 v35, 2, v35
	v_and_or_b32 v35, v35, s17, v170
	v_mov_b32_e32 v45, v169
	v_lshlrev_b32_e32 v44, 1, v35
	v_lshl_add_u64 v[48:49], v[44:45], 2, s[8:9]
	global_load_dwordx4 v[44:47], v[48:49], off
	global_load_dwordx4 v[48:51], v[48:49], off offset:16
	s_waitcnt vmcnt(3)
	v_mov_b32_e32 v53, v38
	v_mov_b32_e32 v38, v37
	v_mov_b32_e32 v52, v36
	s_waitcnt vmcnt(2)
	v_mov_b32_e32 v36, v40
	v_mov_b32_e32 v37, v42
	v_mov_b32_e32 v42, v41
	v_pk_mul_f32 v[40:41], v[16:17], v[38:39]
	v_pk_mul_f32 v[38:39], v[20:21], v[38:39]
	v_pk_mul_f32 v[54:55], v[18:19], v[42:43]
	v_pk_mul_f32 v[42:43], v[22:23], v[42:43]
	s_waitcnt vmcnt(1)
	v_mov_b32_e32 v57, v46
	v_mov_b32_e32 v46, v45
	v_pk_fma_f32 v[16:17], v[16:17], v[52:53], v[38:39]
	s_waitcnt vmcnt(0)
	v_mov_b32_e32 v39, v50
	v_mov_b32_e32 v50, v49
	v_mov_b32_e32 v56, v44
	v_pk_fma_f32 v[20:21], v[20:21], v[52:53], v[40:41] neg_lo:[0,0,1] neg_hi:[0,0,1]
	v_mov_b32_e32 v38, v48
	v_pk_fma_f32 v[22:23], v[22:23], v[36:37], v[54:55] neg_lo:[0,0,1] neg_hi:[0,0,1]
	v_pk_fma_f32 v[18:19], v[18:19], v[36:37], v[42:43]
	v_pk_mul_f32 v[36:37], v[24:25], v[46:47]
	v_pk_mul_f32 v[40:41], v[28:29], v[46:47]
	v_pk_mul_f32 v[42:43], v[26:27], v[50:51]
	v_pk_mul_f32 v[44:45], v[30:31], v[50:51]
	v_pk_fma_f32 v[28:29], v[28:29], v[56:57], v[36:37] neg_lo:[0,0,1] neg_hi:[0,0,1]
	v_pk_fma_f32 v[24:25], v[24:25], v[56:57], v[40:41]
	v_pk_fma_f32 v[30:31], v[30:31], v[38:39], v[42:43] neg_lo:[0,0,1] neg_hi:[0,0,1]
	v_pk_fma_f32 v[26:27], v[26:27], v[38:39], v[44:45]

;   __device__ __forceinline__ void operator()(const f32x4 (&acc)[4][4], int row0w, int col0w, int l15, int quad) const {
;     ...
;       if (gain) {
;         float ss = 0.f;
; #pragma unroll
;         for (int j = 0; j < 4; ++j)
; #pragma unroll
;           for (int e = 0; e < 4; ++e) ss += v[j][e] * v[j][e];
;         ss += __shfl_xor(ss, 16);
;         ss += __shfl_xor(ss, 32);
;         const float rstd = rsqrtf(ss * (1.0f / 64.0f) + 1e-6f);
; #pragma unroll
;         for (int j = 0; j < 4; ++j)
; #pragma unroll
;           for (int e = 0; e < 4; ++e) v[j][e] *= rstd * gain[j * 16 + quad * 4 + e];
;         if (kidx >= 256) {
;           const int t = kidx - 256, pr = t >> 6, pc = t & 63;
; #pragma unroll
;           for (int e = 0; e < 4; ++e) {
;             const int f = quad * 4 + e;
;             const float cr = rope[(pr * 16 + f) * 2], sr = rope[(pr * 16 + f) * 2 + 1];
;             const float cc = rope[(pc * 16 + f) * 2], sc = rope[(pc * 16 + f) * 2 + 1];
;             float x1 = v[0][e], x2 = v[1][e];
;             v[0][e] = x1 * cr - x2 * sr;
;             v[1][e] = x2 * cr + x1 * sr;
;             x1 = v[2][e]; x2 = v[3][e];
;             v[2][e] = x1 * cc - x2 * sc;
;             v[3][e] = x2 * cc + x1 * sc;
;           }
;         }
.LBB0_229:
	v_lshl_add_u64 v[32:33], v[66:67], 0, v[168:169]
	global_load_dwordx4 v[20:23], v[32:33], off
	global_load_dwordx4 v[24:27], v[32:33], off offset:64
	global_load_dwordx4 v[28:31], v[32:33], off offset:128
	global_load_dwordx4 v[32:35], v[32:33], off offset:192
	v_mul_f32_e32 v19, v13, v13
	v_fmac_f32_e32 v19, v12, v12
	v_fmac_f32_e32 v19, v14, v14
	v_fmac_f32_e32 v19, v15, v15
	v_fmac_f32_e32 v19, v8, v8
	v_fmac_f32_e32 v19, v9, v9
	v_fmac_f32_e32 v19, v10, v10
	v_pk_mul_f32 v[38:39], v[4:5], v[4:5]
	v_fmac_f32_e32 v19, v11, v11
	v_add_f32_e32 v19, v38, v19
	v_pk_mul_f32 v[36:37], v[6:7], v[6:7]
	v_add_f32_e32 v19, v39, v19
	v_add_f32_e32 v19, v36, v19
	v_pk_mul_f32 v[42:43], v[0:1], v[0:1]
	v_and_b32_e32 v45, 64, v189
	v_add_f32_e32 v19, v37, v19
	v_xor_b32_e32 v44, 16, v189
	v_add_u32_e32 v45, 64, v45
	v_add_f32_e32 v19, v42, v19
	v_pk_mul_f32 v[40:41], v[2:3], v[2:3]
	v_cmp_lt_i32_e64 s[0:1], v44, v45
	v_add_f32_e32 v19, v43, v19
	v_add_f32_e32 v19, v40, v19
	v_cndmask_b32_e64 v44, v189, v44, s[0:1]
	v_lshlrev_b32_e32 v44, 2, v44
	v_add_f32_e32 v19, v41, v19
	ds_bpermute_b32 v36, v44, v19
	v_xor_b32_e32 v37, 32, v189
	v_cmp_lt_i32_e64 s[0:1], v37, v45
	s_waitcnt lgkmcnt(0)
	v_add_f32_e32 v19, v19, v36
	v_cndmask_b32_e64 v37, v189, v37, s[0:1]
	v_lshlrev_b32_e32 v37, 2, v37
	ds_bpermute_b32 v36, v37, v19
	s_waitcnt lgkmcnt(0)
	v_add_f32_e32 v19, v19, v36
	v_fmamk_f32 v19, v19, 0x3c800000, v187
	v_mul_f32_e32 v36, 0x4b800000, v19
	v_cmp_gt_f32_e64 s[0:1], s97, v19
	s_nop 1
	v_cndmask_b32_e64 v19, v19, v36, s[0:1]
	v_rsq_f32_e32 v19, v19
	s_nop 0
	v_mul_f32_e32 v36, 0x45800000, v19
	v_cndmask_b32_e64 v36, v19, v36, s[0:1]
	v_cmp_lt_i32_e64 s[0:1], s30, v18
	s_waitcnt vmcnt(3)
	v_pk_mul_f32 v[20:21], v[20:21], v[36:37] op_sel_hi:[1,0]
	s_waitcnt vmcnt(2)
	v_pk_mul_f32 v[24:25], v[24:25], v[36:37] op_sel_hi:[1,0]
	v_pk_mul_f32 v[22:23], v[22:23], v[36:37] op_sel_hi:[1,0]
	v_pk_mul_f32 v[26:27], v[26:27], v[36:37] op_sel_hi:[1,0]
	s_waitcnt vmcnt(1)
	v_pk_mul_f32 v[28:29], v[36:37], v[28:29] op_sel_hi:[0,1]
	s_waitcnt vmcnt(0)
	v_pk_mul_f32 v[32:33], v[36:37], v[32:33] op_sel_hi:[0,1]
	v_pk_mul_f32 v[30:31], v[36:37], v[30:31] op_sel_hi:[0,1]
	v_pk_mul_f32 v[34:35], v[36:37], v[34:35] op_sel_hi:[0,1]
	v_pk_mul_f32 v[12:13], v[12:13], v[20:21]
	v_pk_mul_f32 v[8:9], v[8:9], v[24:25]
	v_pk_mul_f32 v[14:15], v[14:15], v[22:23]
	v_pk_mul_f32 v[10:11], v[10:11], v[26:27]
	v_pk_mul_f32 v[4:5], v[4:5], v[28:29]
	v_pk_mul_f32 v[0:1], v[0:1], v[32:33]
	v_pk_mul_f32 v[6:7], v[6:7], v[30:31]
	v_pk_mul_f32 v[2:3], v[2:3], v[34:35]
	s_and_saveexec_b64 s[10:11], s[0:1]
	s_cbranch_execz .LBB0_231
	v_lshlrev_b32_e32 v19, 4, v16
	s_movk_i32 s0, 0x3f0
	v_and_or_b32 v19, v19, s0, v170
	v_lshlrev_b32_e32 v19, 3, v19
	global_load_dwordx4 v[20:23], v19, s[8:9]
	global_load_dwordx4 v[24:27], v19, s[8:9] offset:16
	v_add_u32_e32 v19, 0xffffff00, v18
	v_lshrrev_b32_e32 v19, 2, v19
	v_and_or_b32 v19, v19, s17, v170
	v_lshlrev_b32_e32 v168, 1, v19
	v_lshl_add_u64 v[32:33], v[168:169], 2, s[8:9]
	global_load_dwordx4 v[28:31], v[32:33], off
	global_load_dwordx4 v[32:35], v[32:33], off offset:16
	s_waitcnt vmcnt(3)
	v_mov_b32_e32 v37, v22
	v_mov_b32_e32 v22, v21
	v_mov_b32_e32 v36, v20
	s_waitcnt vmcnt(2)
	v_mov_b32_e32 v20, v24
	v_mov_b32_e32 v21, v26
	v_mov_b32_e32 v26, v25
	v_pk_mul_f32 v[24:25], v[0:1], v[22:23]
	v_pk_mul_f32 v[22:23], v[4:5], v[22:23]
	v_pk_mul_f32 v[38:39], v[2:3], v[26:27]
	v_pk_mul_f32 v[26:27], v[6:7], v[26:27]
	s_waitcnt vmcnt(1)
	v_mov_b32_e32 v41, v30
	v_mov_b32_e32 v30, v29
	v_pk_fma_f32 v[0:1], v[0:1], v[36:37], v[22:23]
	s_waitcnt vmcnt(0)
	v_mov_b32_e32 v23, v34
	v_mov_b32_e32 v34, v33
	v_mov_b32_e32 v40, v28
	v_pk_fma_f32 v[4:5], v[4:5], v[36:37], v[24:25] neg_lo:[0,0,1] neg_hi:[0,0,1]
	v_mov_b32_e32 v22, v32
	v_pk_fma_f32 v[6:7], v[6:7], v[20:21], v[38:39] neg_lo:[0,0,1] neg_hi:[0,0,1]
	v_pk_fma_f32 v[2:3], v[2:3], v[20:21], v[26:27]
	v_pk_mul_f32 v[20:21], v[8:9], v[30:31]
	v_pk_mul_f32 v[24:25], v[12:13], v[30:31]
	v_pk_mul_f32 v[26:27], v[10:11], v[34:35]
	v_pk_mul_f32 v[28:29], v[14:15], v[34:35]
	v_pk_fma_f32 v[12:13], v[12:13], v[40:41], v[20:21] neg_lo:[0,0,1] neg_hi:[0,0,1]
	v_pk_fma_f32 v[8:9], v[8:9], v[40:41], v[24:25]
	v_pk_fma_f32 v[14:15], v[14:15], v[22:23], v[26:27] neg_lo:[0,0,1] neg_hi:[0,0,1]
	v_pk_fma_f32 v[10:11], v[10:11], v[22:23], v[28:29]

; __device__ __forceinline__ float fexp2(float x) { return __builtin_amdgcn_exp2f(x); }
; template <int NMAP, int NDT, int MODE, bool FIXED> ...
;     ...
;         const float mnew = fmaxf(m[c], mx);
;         const float alpha = fexp2(m[c] - mnew);
;         m[c] = mnew;
;         float ls = 0.f;
; #pragma unroll
;         for (int kt = 0; kt < 4; ++kt)
; #pragma unroll
;           for (int e = 0; e < 4; ++e) {
;             s[kt][e] = fexp2(s[kt][e] - mnew);
;             ls += s[kt][e];
;           }
;         l[c] = l[c] * alpha + ls;
;         if (__ballot(alpha != 1.0f) != 0ull) {
; #pragma unroll
;           for (int dt = 0; dt < NDT; ++dt) o[c][dt] *= alpha;
;         }
;       }
;       __builtin_amdgcn_sched_barrier(0);
; #pragma unroll
;       for (int ks2 = 0; ks2 < 2; ++ks2) {
;         union { uint32_t u[4]; bf16x8 v; } pk;
;         pk.u[0] = pack2(s[2 * ks2][0], s[2 * ks2][1]);
;         pk.u[1] = pack2(s[2 * ks2][2], s[2 * ks2][3]);
;         pk.u[2] = pack2(s[2 * ks2 + 1][0], s[2 * ks2 + 1][1]);
;         pk.u[3] = pack2(s[2 * ks2 + 1][2], s[2 * ks2 + 1][3]);
;         pf[c][ks2] = pk.v;
;       }
;     }
;     if (n + 1 < ntiles) {
;       ATTN_LOAD_V(knext)
;     }
.LBB0_318:
	v_sub_f32_e32 v100, v100, v186
	v_sub_f32_e32 v101, v101, v186
	v_sub_f32_e32 v124, v124, v189
	v_exp_f32_e32 v100, v100
	v_exp_f32_e32 v101, v101
	v_exp_f32_e32 v192, v124
	v_sub_f32_e32 v124, v125, v189
	v_sub_f32_e32 v102, v102, v186
	v_exp_f32_e32 v193, v124
	v_sub_f32_e32 v124, v126, v189
	v_exp_f32_e32 v102, v102
	v_sub_f32_e32 v103, v103, v186
	v_exp_f32_e32 v194, v124
	v_sub_f32_e32 v124, v127, v189
	v_exp_f32_e32 v103, v103
	v_sub_f32_e32 v104, v104, v186
	v_exp_f32_e32 v127, v124
	v_sub_f32_e32 v125, v128, v189
	v_exp_f32_e32 v104, v104
	v_sub_f32_e32 v105, v105, v186
	v_cvt_pk_bf16_f32 v120, v100, v101
	v_add_f32_e32 v124, 0, v192
	v_exp_f32_e32 v128, v125
	v_sub_f32_e32 v125, v129, v189
	v_add_f32_e32 v100, 0, v100
	v_exp_f32_e32 v105, v105
	v_sub_f32_e32 v106, v106, v186
	v_add_f32_e32 v124, v193, v124
	v_exp_f32_e32 v129, v125
	v_sub_f32_e32 v125, v130, v189
	v_add_f32_e32 v100, v101, v100
	v_exp_f32_e32 v106, v106
	v_sub_f32_e32 v107, v107, v186
	v_add_f32_e32 v124, v194, v124
	v_exp_f32_e32 v130, v125
	v_sub_f32_e32 v125, v131, v189
	v_add_f32_e32 v100, v102, v100
	v_exp_f32_e32 v107, v107
	v_sub_f32_e32 v108, v108, v186
	v_add_f32_e32 v124, v127, v124
	v_exp_f32_e32 v131, v125
	v_sub_f32_e32 v125, v132, v189
	v_add_f32_e32 v100, v103, v100
	v_exp_f32_e32 v108, v108
	v_sub_f32_e32 v109, v109, v186
	v_add_f32_e32 v124, v128, v124
	v_exp_f32_e32 v132, v125
	v_sub_f32_e32 v125, v133, v189
	v_add_f32_e32 v100, v104, v100
	v_exp_f32_e32 v109, v109
	v_sub_f32_e32 v110, v110, v186
	v_add_f32_e32 v124, v129, v124
	v_exp_f32_e32 v133, v125
	v_sub_f32_e32 v125, v134, v189
	v_add_f32_e32 v100, v105, v100
	v_exp_f32_e32 v110, v110
	v_sub_f32_e32 v111, v111, v186
	v_add_f32_e32 v124, v130, v124
	v_exp_f32_e32 v134, v125
	v_sub_f32_e32 v125, v135, v189
	v_add_f32_e32 v100, v106, v100
	v_exp_f32_e32 v111, v111
	v_sub_f32_e32 v112, v112, v186
	v_add_f32_e32 v124, v131, v124
	v_exp_f32_e32 v135, v125
	v_sub_f32_e32 v125, v136, v189
	v_add_f32_e32 v100, v107, v100
	v_exp_f32_e32 v112, v112
	v_sub_f32_e32 v113, v113, v186
	v_add_f32_e32 v124, v132, v124
	v_exp_f32_e32 v136, v125
	v_sub_f32_e32 v125, v137, v189
	v_add_f32_e32 v100, v108, v100
	v_exp_f32_e32 v113, v113
	v_sub_f32_e32 v114, v114, v186
	v_add_f32_e32 v124, v133, v124
	v_exp_f32_e32 v137, v125
	v_sub_f32_e32 v125, v138, v189
	v_add_f32_e32 v100, v109, v100
	v_exp_f32_e32 v114, v114
	v_sub_f32_e32 v115, v115, v186
	v_add_f32_e32 v124, v134, v124
	v_exp_f32_e32 v138, v125
	v_sub_f32_e32 v125, v139, v189
	v_add_f32_e32 v100, v110, v100
	v_exp_f32_e32 v115, v115
	v_add_f32_e32 v124, v135, v124
	v_exp_f32_e32 v139, v125
	v_add_f32_e32 v100, v111, v100
	v_add_f32_e32 v124, v136, v124
	v_add_f32_e32 v100, v112, v100
	v_add_f32_e32 v124, v137, v124
	v_add_f32_e32 v100, v113, v100
	v_add_f32_e32 v124, v138, v124
	v_add_f32_e32 v100, v114, v100
	v_add_f32_e32 v125, v139, v124
	v_add_f32_e32 v124, v115, v100
	v_fmac_f32_e32 v125, v191, v170
	v_fmac_f32_e32 v124, v190, v168
	v_cvt_pk_bf16_f32 v121, v102, v103
	v_cvt_pk_bf16_f32 v122, v104, v105
	v_cvt_pk_bf16_f32 v123, v106, v107
	v_cvt_pk_bf16_f32 v116, v108, v109
	v_cvt_pk_bf16_f32 v117, v110, v111
	v_cvt_pk_bf16_f32 v118, v112, v113
	v_cvt_pk_bf16_f32 v119, v114, v115
	v_lshl_add_u64 v[108:109], s[94:95], 0, v[154:155]
	v_add_co_u32_e32 v108, vcc, s13, v108
	v_lshl_add_u64 v[110:111], s[94:95], 0, v[156:157]
	s_nop 0
	v_addc_co_u32_e32 v109, vcc, 0, v109, vcc
	v_add_co_u32_e32 v112, vcc, s13, v110
	v_lshl_add_u64 v[100:101], s[94:95], 0, v[150:151]
	v_lshl_add_u64 v[104:105], s[94:95], 0, v[152:153]
	v_addc_co_u32_e32 v113, vcc, 0, v111, vcc
	global_load_dwordx4 v[100:103], v[100:101], off
	global_load_dwordx4 v[104:107], v[104:105], off
	global_load_dwordx4 v[108:111], v[108:109], off offset:128
	global_load_dwordx4 v[112:115], v[112:113], off offset:128
	v_cvt_pk_bf16_f32 v126, v192, v193
	v_cvt_pk_bf16_f32 v127, v194, v127
	v_cvt_pk_bf16_f32 v128, v128, v129
	v_cvt_pk_bf16_f32 v129, v130, v131
	v_cvt_pk_bf16_f32 v130, v132, v133
	v_cvt_pk_bf16_f32 v131, v134, v135
	v_cvt_pk_bf16_f32 v132, v136, v137
	v_cvt_pk_bf16_f32 v133, v138, v139
	ds_read_b128 v[134:137], v182 offset:20480
	s_waitcnt lgkmcnt(0)
; template <int NMAP, int NDT, int MODE, bool FIXED> ...
;     ...
; #pragma unroll
;     for (int ks2 = 0; ks2 < 2; ++ks2) {
;       __builtin_amdgcn_sched_barrier(0);
; #pragma unroll
;       for (int dt = 0; dt < NDT; ++dt) {
;         const bf16x8 vf = *(const bf16x8*)(sVt + (dt * 16 + l15) * LSTR + 32 * ks2 + quad * 8);
; #pragma unroll
;         for (int c = 0; c < NMAP; ++c) o[c][dt] = __builtin_amdgcn_mfma_f32_16x16x32_bf16(vf, pf[c][ks2], o[c][dt], 0, 0, 0);
;       }
;     }
	v_mfma_f32_16x16x32_bf16 v[64:67], v[134:137], v[120:123], v[64:67]
	v_mfma_f32_16x16x32_bf16 v[52:55], v[134:137], v[126:129], v[52:55]
	ds_read_b128 v[134:137], v182 offset:23040
	s_waitcnt lgkmcnt(0)
	v_mfma_f32_16x16x32_bf16 v[60:63], v[134:137], v[120:123], v[60:63]
	v_mfma_f32_16x16x32_bf16 v[44:47], v[134:137], v[126:129], v[44:47]
	ds_read_b128 v[134:137], v182 offset:25600
	s_waitcnt lgkmcnt(0)
	v_mfma_f32_16x16x32_bf16 v[56:59], v[134:137], v[120:123], v[56:59]
	v_mfma_f32_16x16x32_bf16 v[36:39], v[134:137], v[126:129], v[36:39]
	ds_read_b128 v[134:137], v182 offset:28160
	s_waitcnt lgkmcnt(0)
	v_mfma_f32_16x16x32_bf16 v[48:51], v[134:137], v[120:123], v[48:51]
	v_mfma_f32_16x16x32_bf16 v[28:31], v[134:137], v[126:129], v[28:31]
	ds_read_b128 v[134:137], v182 offset:30720
	s_waitcnt lgkmcnt(0)
	v_mfma_f32_16x16x32_bf16 v[40:43], v[134:137], v[120:123], v[40:43]
	v_mfma_f32_16x16x32_bf16 v[20:23], v[134:137], v[126:129], v[20:23]
	ds_read_b128 v[134:137], v182 offset:33280
	s_waitcnt lgkmcnt(0)
	v_mfma_f32_16x16x32_bf16 v[32:35], v[134:137], v[120:123], v[32:35]
	v_mfma_f32_16x16x32_bf16 v[16:19], v[134:137], v[126:129], v[16:19]
	ds_read_b128 v[134:137], v182 offset:35840
	s_waitcnt lgkmcnt(0)
	v_mfma_f32_16x16x32_bf16 v[24:27], v[134:137], v[120:123], v[24:27]
	v_mfma_f32_16x16x32_bf16 v[12:15], v[134:137], v[126:129], v[12:15]
	ds_read_b128 v[134:137], v182 offset:38400
	s_waitcnt lgkmcnt(0)
	v_mfma_f32_16x16x32_bf16 v[8:11], v[134:137], v[120:123], v[8:11]
	v_mfma_f32_16x16x32_bf16 v[4:7], v[134:137], v[126:129], v[4:7]
	ds_read_b128 v[120:123], v182 offset:20544
	s_add_i32 s0, s0, -1
	v_lshl_add_u64 v[150:151], v[150:151], 0, s[24:25]
	v_lshl_add_u64 v[152:153], v[152:153], 0, s[24:25]
	v_lshl_add_u64 v[154:155], v[154:155], 0, s[24:25]
	v_lshl_add_u64 v[156:157], v[156:157], 0, s[24:25]
	v_lshl_add_u64 v[158:159], v[158:159], 0, s[26:27]
	v_lshl_add_u64 v[166:167], v[166:167], 0, s[26:27]
	s_cmp_eq_u32 s0, 0
	s_waitcnt lgkmcnt(0)
	v_mfma_f32_16x16x32_bf16 v[64:67], v[120:123], v[116:119], v[64:67]
	v_mfma_f32_16x16x32_bf16 v[52:55], v[120:123], v[130:133], v[52:55]
	ds_read_b128 v[120:123], v182 offset:23104
	s_waitcnt lgkmcnt(0)
	v_mfma_f32_16x16x32_bf16 v[60:63], v[120:123], v[116:119], v[60:63]
	v_mfma_f32_16x16x32_bf16 v[44:47], v[120:123], v[130:133], v[44:47]
	ds_read_b128 v[120:123], v182 offset:25664
	s_waitcnt lgkmcnt(0)
	v_mfma_f32_16x16x32_bf16 v[56:59], v[120:123], v[116:119], v[56:59]
	v_mfma_f32_16x16x32_bf16 v[36:39], v[120:123], v[130:133], v[36:39]
	ds_read_b128 v[120:123], v182 offset:28224
	s_waitcnt lgkmcnt(0)
	v_mfma_f32_16x16x32_bf16 v[48:51], v[120:123], v[116:119], v[48:51]
	v_mfma_f32_16x16x32_bf16 v[28:31], v[120:123], v[130:133], v[28:31]
	ds_read_b128 v[120:123], v182 offset:30784
	s_waitcnt lgkmcnt(0)
	v_mfma_f32_16x16x32_bf16 v[40:43], v[120:123], v[116:119], v[40:43]
	v_mfma_f32_16x16x32_bf16 v[20:23], v[120:123], v[130:133], v[20:23]
	ds_read_b128 v[120:123], v182 offset:33344
	s_waitcnt lgkmcnt(0)
	v_mfma_f32_16x16x32_bf16 v[32:35], v[120:123], v[116:119], v[32:35]
	v_mfma_f32_16x16x32_bf16 v[16:19], v[120:123], v[130:133], v[16:19]
	ds_read_b128 v[120:123], v182 offset:35904
	s_waitcnt lgkmcnt(0)
	v_mfma_f32_16x16x32_bf16 v[24:27], v[120:123], v[116:119], v[24:27]
	v_mfma_f32_16x16x32_bf16 v[12:15], v[120:123], v[130:133], v[12:15]
	ds_read_b128 v[120:123], v182 offset:38464
	s_waitcnt lgkmcnt(0)
	v_mfma_f32_16x16x32_bf16 v[8:11], v[120:123], v[116:119], v[8:11]
	v_mfma_f32_16x16x32_bf16 v[4:7], v[120:123], v[130:133], v[4:7]
	s_cbranch_scc1 .LBB0_321
	v_mov_b32_e32 v116, v189
	v_mov_b32_e32 v191, v125
	v_mov_b32_e32 v190, v124
	s_branch .LBB0_314

; __device__ __forceinline__ void attn_diff32(const bf16_t* __restrict__ Qp, const bf16_t* __restrict__ Kp,
;                                             const bf16_t* __restrict__ Vtp, int ntiles, float negM,
;                                             f32x4 (&o)[2][8], float (&l)[2], char* smem) {
;     ...
;   asm volatile("" : "+v"(tid));
;   const int lane = tid & 63, wave = tid >> 6;
;   const int l15 = lane & 15, quad = lane >> 4;
;   const int cmap = wave >> 1, qg = wave & 1;
;   bf16x8 qf[2][2];
; #pragma unroll
;   for (int qt = 0; qt < 2; ++qt) {
;     const bf16_t* qrow = Qp + (size_t)(qg * 32 + qt * 16 + l15) * 512 + cmap * 64;
; #pragma unroll
;     for (int ks = 0; ks < 2; ++ks) qf[qt][ks] = *(const bf16x8*)(qrow + ks * 32 + quad * 8);
;   }
; #pragma unroll
;   for (int qt = 0; qt < 2; ++qt) {
;     l[qt] = 0.f;
; #pragma unroll
;     for (int dt = 0; dt < 8; ++dt) o[qt][dt] = (f32x4){0.f, 0.f, 0.f, 0.f};
;   }
;   uint4 rk00, rk01, rk10, rk11, rv0, rv1, rv2, rv3;
;   const int lr = tid >> 3, lch = (tid & 7) * 8;
;   const uint32_t koff0 = (uint32_t)(lr * 512 + lch) * 2u, koff1 = (uint32_t)((lr + 32) * 512 + lch) * 2u;
;   const uint32_t voff0 = (uint32_t)(lr * TPB + lch) * 2u, voff1 = (uint32_t)((lr + 32) * TPB + lch) * 2u,
;                  voff2 = (uint32_t)((lr + 64) * TPB + lch) * 2u, voff3 = (uint32_t)((lr + 96) * TPB + lch) * 2u;
;     ...
;   AD_LOAD_K(0)
;   AD_LOAD_V(0)
;   const bf16_t* sKc = sK + cmap * 64 * LSTR;
.LBB0_326:
	v_mov_b32_e32 v34, v160
	v_mov_b32_e32 v21, v145
	v_and_b32_e32 v36, 15, v34
	v_ashrrev_i32_e32 v35, 7, v34
	v_lshrrev_b32_e32 v4, 1, v34
	v_and_or_b32 v6, v4, 32, v36
	v_lshlrev_b32_e32 v4, 6, v35
	v_ashrrev_i32_e32 v5, 31, v4
	v_lshl_add_u64 v[4:5], v[4:5], 1, s[70:71]
	v_and_b32_e32 v20, 48, v34
	v_lshl_add_u64 v[4:5], v[4:5], 0, v[20:21]
	v_lshlrev_b32_e32 v6, 10, v6
	v_mov_b32_e32 v7, v145
	v_lshlrev_b32_e32 v22, 3, v34
	v_lshl_add_u64 v[8:9], v[4:5], 0, v[6:7]
	s_movk_i32 s0, 0x4000
	v_ashrrev_i32_e32 v21, 3, v34
	v_and_b32_e32 v23, 56, v22
	global_load_dwordx4 v[12:15], v[8:9], off
	global_load_dwordx4 v[4:7], v[8:9], off offset:64
	v_add_co_u32_e32 v8, vcc, s0, v8
	v_lshlrev_b32_e32 v37, 1, v23
	v_mul_lo_u32 v25, v21, s10
	v_addc_co_u32_e32 v9, vcc, 0, v9, vcc
	v_lshl_or_b32 v22, v21, 10, v37
	v_or_b32_e32 v23, v25, v23
	global_load_dwordx4 v[16:19], v[8:9], off
	global_load_dwordx4 v[8:11], v[8:9], off offset:64
	v_add_u32_e32 v24, 0x8000, v22
	v_lshlrev_b32_e32 v26, 1, v23
	global_load_dwordx4 v[52:55], v22, s[68:69]
	global_load_dwordx4 v[56:59], v22, s[68:69] offset:128
	global_load_dwordx4 v[72:75], v24, s[68:69]
	global_load_dwordx4 v[60:63], v24, s[68:69] offset:128
	v_add_u32_e32 v30, 0x208000, v26
	v_add_u32_e32 v28, 0x104000, v26
	v_add_u32_e32 v32, 0x30c000, v26
	global_load_dwordx4 v[100:103], v26, s[38:39]
	global_load_dwordx4 v[104:107], v28, s[38:39]
	global_load_dwordx4 v[108:111], v30, s[38:39]
	global_load_dwordx4 v[112:115], v32, s[38:39]
	v_mul_lo_u32 v21, v21, s11
	v_add3_u32 v158, 16, v21, v37
	v_lshlrev_b32_e32 v21, 1, v34
	v_and_b32_e32 v34, 3, v34
	v_and_or_b32 v21, v21, 24, v34
	v_add_u32_e32 v20, 16, v20
	s_movk_i32 s0, 0x2800
	v_mad_u64_u32 v[34:35], s[2:3], v35, s0, v[20:21]
	s_add_i32 s2, s72, s18
	s_add_i32 s0, s33, 3
	s_mul_hi_u32 s3, s2, 0x410000
	s_mul_i32 s2, s2, 0x410000
	s_add_u32 s2, s2, 0x9f00080
	v_mov_b32_e32 v27, v145
	v_mov_b32_e32 v29, v145
	v_mov_b32_e32 v31, v145
	v_mov_b32_e32 v33, v145
	s_addc_u32 s3, s3, 0
	v_lshl_add_u64 v[134:135], s[2:3], 0, v[26:27]
	v_lshl_add_u64 v[136:137], s[2:3], 0, v[28:29]
	v_lshl_add_u64 v[138:139], s[2:3], 0, v[30:31]
	v_lshl_add_u64 v[150:151], s[2:3], 0, v[32:33]
	s_add_u32 s2, s34, s19
	v_mov_b32_e32 v23, v145
	v_mov_b32_e32 v25, v145
	v_mul_u32_u24_e32 v35, 0xa0, v36
	v_mul_u32_u24_e32 v21, 0xa0, v21
	s_addc_u32 s3, s35, 0
	v_mov_b32_e32 v92, 0
	v_add_u32_e32 v159, 0x1400, v158
	v_add_u32_e32 v166, 0x2800, v158
	v_add_u32_e32 v167, 0x3c00, v158
	v_lshl_add_u64 v[152:153], s[2:3], 0, v[22:23]
	v_lshl_add_u64 v[154:155], s[2:3], 0, v[24:25]
	v_add_u32_e32 v157, v34, v21
	v_add_u32_e32 v156, v20, v35
	v_mov_b32_e32 v93, v92
	v_mov_b32_e32 v94, v92
	v_mov_b32_e32 v95, v92
	v_mov_b32_e32 v64, v92
	v_mov_b32_e32 v65, v92
	v_mov_b32_e32 v66, v92
	v_mov_b32_e32 v67, v92
	v_mov_b32_e32 v44, v92
	v_mov_b32_e32 v45, v92
	v_mov_b32_e32 v46, v92
	v_mov_b32_e32 v47, v92
	v_mov_b32_e32 v36, v92
	v_mov_b32_e32 v37, v92
	v_mov_b32_e32 v38, v92
	v_mov_b32_e32 v39, v92
	v_mov_b32_e32 v32, v92
	v_mov_b32_e32 v33, v92
	v_mov_b32_e32 v34, v92
	v_mov_b32_e32 v35, v92
	v_mov_b32_e32 v28, v92
	v_mov_b32_e32 v29, v92
	v_mov_b32_e32 v30, v92
	v_mov_b32_e32 v31, v92
	v_mov_b32_e32 v24, v92
	v_mov_b32_e32 v25, v92
	v_mov_b32_e32 v26, v92
	v_mov_b32_e32 v27, v92
	v_mov_b32_e32 v20, v92
	v_mov_b32_e32 v21, v92
	v_mov_b32_e32 v22, v92
	v_mov_b32_e32 v23, v92
	v_mov_b32_e32 v96, v92
	v_mov_b32_e32 v97, v92
	v_mov_b32_e32 v98, v92
	v_mov_b32_e32 v99, v92
	v_mov_b32_e32 v88, v92
	v_mov_b32_e32 v89, v92
	v_mov_b32_e32 v90, v92
	v_mov_b32_e32 v91, v92
	v_mov_b32_e32 v84, v92
	v_mov_b32_e32 v85, v92
	v_mov_b32_e32 v86, v92
	v_mov_b32_e32 v87, v92
	v_mov_b32_e32 v80, v92
	v_mov_b32_e32 v81, v92
	v_mov_b32_e32 v82, v92
	v_mov_b32_e32 v83, v92
	v_mov_b32_e32 v76, v92
	v_mov_b32_e32 v77, v92
	v_mov_b32_e32 v78, v92
	v_mov_b32_e32 v79, v92
	v_mov_b32_e32 v68, v92
	v_mov_b32_e32 v69, v92
	v_mov_b32_e32 v70, v92
	v_mov_b32_e32 v71, v92
	v_mov_b32_e32 v48, v92
	v_mov_b32_e32 v49, v92
	v_mov_b32_e32 v50, v92
	v_mov_b32_e32 v51, v92
	v_mov_b32_e32 v40, v92
	v_mov_b32_e32 v41, v92
	v_mov_b32_e32 v42, v92
	v_mov_b32_e32 v43, v92
	v_mov_b32_e32 v132, v92
	v_mov_b32_e32 v133, v92
	s_mov_b32 s98, s12
	s_mov_b32 s99, 0
	v_lshl_add_u64 v[152:153], s[94:95], 0, v[152:153]
	v_lshl_add_u64 v[154:155], s[94:95], 0, v[154:155]
	v_lshl_add_u64 v[134:135], s[94:95], 0, v[134:135]
	v_lshl_add_u64 v[136:137], s[94:95], 0, v[136:137]
	v_lshl_add_u64 v[138:139], s[94:95], 0, v[138:139]
	v_lshl_add_u64 v[150:151], s[94:95], 0, v[150:151]
	v_lshl_add_u64 v[152:153], v[152:153], 0, s[98:99]
	v_lshl_add_u64 v[154:155], v[154:155], 0, s[98:99]
; __device__ __forceinline__ void attn_diff32(const bf16_t* __restrict__ Qp, const bf16_t* __restrict__ Kp,
;                                             const bf16_t* __restrict__ Vtp, int ntiles, float negM,
;                                             f32x4 (&o)[2][8], float (&l)[2], char* smem) {
;     ...
;   for (int n = 0; n < ntiles; ++n) {
;     __syncthreads();
;     *(uint4*)(sK + (lr) * LSTR + lch) = rk00;
;     *(uint4*)(sK + (lr + 32) * LSTR + lch) = rk01;
;     *(uint4*)(sK + (64 + lr) * LSTR + lch) = rk10;
;     *(uint4*)(sK + (64 + lr + 32) * LSTR + lch) = rk11;
;     *(uint4*)(sVt + (lr) * LSTR + lch) = rv0;
;     *(uint4*)(sVt + (lr + 32) * LSTR + lch) = rv1;
;     *(uint4*)(sVt + (lr + 64) * LSTR + lch) = rv2;
;     *(uint4*)(sVt + (lr + 96) * LSTR + lch) = rv3;
;     __syncthreads();
;     const int knext = (n + 1) * 64;
;     if (n + 1 < ntiles) { AD_LOAD_K(knext) }
;     f32x4 s[2][4];
;     __builtin_amdgcn_s_setprio(1);
; #pragma unroll
;     for (int kt = 0; kt < 4; ++kt) {
;       s[0][kt] = (f32x4){negM, negM, negM, negM};
;       s[1][kt] = (f32x4){negM, negM, negM, negM};
;       const int krow = 32 * (kt >> 1) + (l15 >> 2) * 8 + (kt & 1) * 4 + (l15 & 3);
; #pragma unroll
;       for (int ks = 0; ks < 2; ++ks) {
;         const bf16x8 kf = *(const bf16x8*)(sKc + krow * LSTR + ks * 32 + quad * 8);
;         s[0][kt] = __builtin_amdgcn_mfma_f32_16x16x32_bf16(kf, qf[0][ks], s[0][kt], 0, 0, 0);
;         s[1][kt] = __builtin_amdgcn_mfma_f32_16x16x32_bf16(kf, qf[1][ks], s[1][kt], 0, 0, 0);
;       }
;     }
;     __builtin_amdgcn_s_setprio(0);
;     bf16x8 pf[2][2];
; #pragma unroll
;     for (int qt = 0; qt < 2; ++qt) {
;       float ls = 0.f;
; #pragma unroll
;       for (int kt = 0; kt < 4; ++kt)
; #pragma unroll
;         for (int e = 0; e < 4; ++e) {
;           s[qt][kt][e] = fexp2(s[qt][kt][e]);
;           ls += s[qt][kt][e];
;         }
;       l[qt] += ls;
; #pragma unroll
;       for (int ks2 = 0; ks2 < 2; ++ks2) {
;         union { uint32_t u[4]; bf16x8 v; } pk;
;         pk.u[0] = pack2(s[qt][2 * ks2][0], s[qt][2 * ks2][1]);
;         pk.u[1] = pack2(s[qt][2 * ks2][2], s[qt][2 * ks2][3]);
;         pk.u[2] = pack2(s[qt][2 * ks2 + 1][0], s[qt][2 * ks2 + 1][1]);
;         pk.u[3] = pack2(s[qt][2 * ks2 + 1][2], s[qt][2 * ks2 + 1][3]);
;         pf[qt][ks2] = pk.v;
;       }
;     }
;     if (n + 1 < ntiles) { AD_LOAD_V(knext) }
.LBB0_327:
	s_barrier
	s_waitcnt vmcnt(7)
	ds_write_b128 v158, v[52:55]
	s_waitcnt vmcnt(5)
	ds_write_b128 v159, v[72:75]
	ds_write_b128 v166, v[56:59]
	s_waitcnt vmcnt(4)
	ds_write_b128 v158, v[60:63] offset:15360
	s_waitcnt vmcnt(3)
	ds_write_b128 v158, v[100:103] offset:20480
	s_waitcnt vmcnt(2)
	ds_write_b128 v159, v[104:107] offset:20480
	s_waitcnt vmcnt(1)
	ds_write_b128 v166, v[108:111] offset:20480
	s_waitcnt vmcnt(0)
	ds_write_b128 v167, v[112:115] offset:20480
	s_waitcnt lgkmcnt(0)
	s_barrier
	s_setprio 1
	ds_read_b128 v[186:189], v157
	ds_read_b128 v[190:193], v157 offset:64
	ds_read_b128 v[194:197], v157 offset:640
	ds_read_b128 v[198:201], v157 offset:704
	ds_read_b128 v[202:205], v157 offset:5120
	ds_read_b128 v[128:131], v157 offset:5184
	ds_read_b128 v[242:245], v157 offset:5760
	ds_read_b128 v[246:249], v157 offset:5824
	global_load_dwordx4 v[52:55], v[152:153], off
	global_load_dwordx4 v[56:59], v[152:153], off offset:128
	global_load_dwordx4 v[72:75], v[154:155], off
	global_load_dwordx4 v[60:63], v[154:155], off offset:128
	s_waitcnt lgkmcnt(7)
	v_mfma_f32_16x16x32_bf16 v[108:111], v[186:189], v[12:15], v[0:3]
	v_mfma_f32_16x16x32_bf16 v[100:103], v[186:189], v[16:19], v[0:3]
	s_waitcnt lgkmcnt(6)
	v_mfma_f32_16x16x32_bf16 v[108:111], v[190:193], v[4:7], v[108:111]
	v_mfma_f32_16x16x32_bf16 v[100:103], v[190:193], v[8:11], v[100:103]
	s_waitcnt lgkmcnt(5)
	v_mfma_f32_16x16x32_bf16 v[116:119], v[194:197], v[12:15], v[0:3]
	v_mfma_f32_16x16x32_bf16 v[104:107], v[194:197], v[16:19], v[0:3]
	s_waitcnt lgkmcnt(4)
	v_mfma_f32_16x16x32_bf16 v[116:119], v[198:201], v[4:7], v[116:119]
	v_mfma_f32_16x16x32_bf16 v[104:107], v[198:201], v[8:11], v[104:107]
	s_waitcnt lgkmcnt(3)
	v_mfma_f32_16x16x32_bf16 v[124:127], v[202:205], v[12:15], v[0:3]
	v_mfma_f32_16x16x32_bf16 v[112:115], v[202:205], v[16:19], v[0:3]
	s_waitcnt lgkmcnt(2)
	v_mfma_f32_16x16x32_bf16 v[124:127], v[128:131], v[4:7], v[124:127]
	v_mfma_f32_16x16x32_bf16 v[112:115], v[128:131], v[8:11], v[112:115]
	s_waitcnt lgkmcnt(1)
	v_mfma_f32_16x16x32_bf16 v[182:185], v[242:245], v[12:15], v[0:3]
	v_mfma_f32_16x16x32_bf16 v[120:123], v[242:245], v[16:19], v[0:3]
	s_waitcnt lgkmcnt(0)
	v_mfma_f32_16x16x32_bf16 v[182:185], v[246:249], v[4:7], v[182:185]
	v_mfma_f32_16x16x32_bf16 v[120:123], v[246:249], v[8:11], v[120:123]
	ds_read_b128 v[242:245], v156 offset:20480
	ds_read_b128 v[246:249], v156 offset:23040
	ds_read_b128 v[250:253], v156 offset:25600
	s_setprio 0
	v_exp_f32_e32 v129, v108
	v_exp_f32_e32 v128, v100
	v_exp_f32_e32 v109, v109
	v_exp_f32_e32 v108, v101
	v_exp_f32_e32 v131, v110
	v_exp_f32_e32 v130, v102
	v_exp_f32_e32 v111, v111
	v_exp_f32_e32 v110, v103
	v_exp_f32_e32 v187, v116
	v_exp_f32_e32 v186, v104
	v_pk_add_f32 v[100:101], v[128:129], 0 op_sel_hi:[1,0]
	v_exp_f32_e32 v189, v117
	v_exp_f32_e32 v188, v105
	v_pk_add_f32 v[100:101], v[108:109], v[100:101]
	v_exp_f32_e32 v191, v118
	v_pk_add_f32 v[100:101], v[130:131], v[100:101]
	v_exp_f32_e32 v190, v106
	v_exp_f32_e32 v193, v119
	v_pk_add_f32 v[100:101], v[110:111], v[100:101]
	v_exp_f32_e32 v192, v107
	v_exp_f32_e32 v195, v124
	v_pk_add_f32 v[100:101], v[100:101], v[186:187]
	v_exp_f32_e32 v194, v112
	v_exp_f32_e32 v197, v125
	v_pk_add_f32 v[100:101], v[188:189], v[100:101]
	v_exp_f32_e32 v196, v113
	v_exp_f32_e32 v199, v126
	v_exp_f32_e32 v198, v114
	v_pk_add_f32 v[100:101], v[190:191], v[100:101]
	v_exp_f32_e32 v201, v127
	v_exp_f32_e32 v200, v115
	v_pk_add_f32 v[100:101], v[192:193], v[100:101]
	v_exp_f32_e32 v203, v182
	v_exp_f32_e32 v202, v120
	v_pk_add_f32 v[100:101], v[100:101], v[194:195]
	v_exp_f32_e32 v183, v183
	v_exp_f32_e32 v182, v121
	v_pk_add_f32 v[100:101], v[196:197], v[100:101]
	v_exp_f32_e32 v205, v184
	v_exp_f32_e32 v204, v122
	v_pk_add_f32 v[100:101], v[198:199], v[100:101]
	v_exp_f32_e32 v185, v185
	v_exp_f32_e32 v184, v123
	v_pk_add_f32 v[100:101], v[200:201], v[100:101]
	v_cvt_pk_bf16_f32 v124, v129, v109
	v_pk_add_f32 v[100:101], v[100:101], v[202:203]
	v_cvt_pk_bf16_f32 v128, v128, v108
	v_pk_add_f32 v[100:101], v[182:183], v[100:101]
	v_pk_add_f32 v[100:101], v[204:205], v[100:101]
	v_pk_add_f32 v[100:101], v[184:185], v[100:101]
	v_pk_add_f32 v[132:133], v[132:133], v[100:101]
	v_cvt_pk_bf16_f32 v125, v131, v111
	v_cvt_pk_bf16_f32 v129, v130, v110
	global_load_dwordx4 v[100:103], v[134:135], off
	global_load_dwordx4 v[104:107], v[136:137], off
	global_load_dwordx4 v[108:111], v[138:139], off
	global_load_dwordx4 v[112:115], v[150:151], off
	v_cvt_pk_bf16_f32 v126, v187, v189
	v_cvt_pk_bf16_f32 v127, v191, v193
	v_cvt_pk_bf16_f32 v116, v195, v197
	v_cvt_pk_bf16_f32 v117, v199, v201
	v_cvt_pk_bf16_f32 v118, v203, v183
	v_cvt_pk_bf16_f32 v119, v205, v185
	v_cvt_pk_bf16_f32 v130, v186, v188
	v_cvt_pk_bf16_f32 v131, v190, v192
	v_cvt_pk_bf16_f32 v120, v194, v196
	v_cvt_pk_bf16_f32 v121, v198, v200
	v_cvt_pk_bf16_f32 v122, v202, v182
	v_cvt_pk_bf16_f32 v123, v204, v184
	s_setprio 1
	ds_read_b128 v[182:185], v156 offset:28160
	ds_read_b128 v[186:189], v156 offset:30720
	ds_read_b128 v[190:193], v156 offset:33280
	ds_read_b128 v[194:197], v156 offset:35840
	ds_read_b128 v[198:201], v156 offset:38400
	ds_read_b128 v[202:205], v156 offset:20544
	s_waitcnt lgkmcnt(8)
	v_mfma_f32_16x16x32_bf16 v[40:43], v[242:245], v[124:127], v[40:43]
	v_mfma_f32_16x16x32_bf16 v[20:23], v[242:245], v[128:131], v[20:23]
	ds_read_b128 v[242:245], v156 offset:23104
	v_lshl_add_u64 v[134:135], v[134:135], 0, s[24:25]
	s_waitcnt lgkmcnt(8)
	v_mfma_f32_16x16x32_bf16 v[48:51], v[246:249], v[124:127], v[48:51]
	v_mfma_f32_16x16x32_bf16 v[24:27], v[246:249], v[128:131], v[24:27]
	ds_read_b128 v[246:249], v156 offset:25664
	v_lshl_add_u64 v[136:137], v[136:137], 0, s[24:25]
	s_waitcnt lgkmcnt(8)
; __device__ __forceinline__ void attn_diff32(const bf16_t* __restrict__ Qp, const bf16_t* __restrict__ Kp,
;                                             const bf16_t* __restrict__ Vtp, int ntiles, float negM,
;                                             f32x4 (&o)[2][8], float (&l)[2], char* smem) {
;     ...
;     __syncthreads();
;     *(uint4*)(sK + (lr) * LSTR + lch) = rk00;
;     *(uint4*)(sK + (lr + 32) * LSTR + lch) = rk01;
;     *(uint4*)(sK + (64 + lr) * LSTR + lch) = rk10;
;     *(uint4*)(sK + (64 + lr + 32) * LSTR + lch) = rk11;
;     *(uint4*)(sVt + (lr) * LSTR + lch) = rv0;
;     *(uint4*)(sVt + (lr + 32) * LSTR + lch) = rv1;
;     *(uint4*)(sVt + (lr + 64) * LSTR + lch) = rv2;
;     *(uint4*)(sVt + (lr + 96) * LSTR + lch) = rv3;
;     __syncthreads();
;     const int knext = (n + 1) * 64;
;     if (n + 1 < ntiles) { AD_LOAD_K(knext) }
;     f32x4 s[2][4];
;     __builtin_amdgcn_s_setprio(1);
; #pragma unroll
;     for (int kt = 0; kt < 4; ++kt) {
;       s[0][kt] = (f32x4){negM, negM, negM, negM};
;       s[1][kt] = (f32x4){negM, negM, negM, negM};
;       const int krow = 32 * (kt >> 1) + (l15 >> 2) * 8 + (kt & 1) * 4 + (l15 & 3);
; #pragma unroll
;       for (int ks = 0; ks < 2; ++ks) {
;         const bf16x8 kf = *(const bf16x8*)(sKc + krow * LSTR + ks * 32 + quad * 8);
;         s[0][kt] = __builtin_amdgcn_mfma_f32_16x16x32_bf16(kf, qf[0][ks], s[0][kt], 0, 0, 0);
;         s[1][kt] = __builtin_amdgcn_mfma_f32_16x16x32_bf16(kf, qf[1][ks], s[1][kt], 0, 0, 0);
;       }
;     }
;     ...
;     __builtin_amdgcn_s_setprio(1);
; #pragma unroll
;     for (int ks2 = 0; ks2 < 2; ++ks2)
; #pragma unroll
;       for (int dt = 0; dt < 8; ++dt) {
;         const bf16x8 vf = *(const bf16x8*)(sVt + (dt * 16 + l15) * LSTR + 32 * ks2 + quad * 8);
;         o[0][dt] = __builtin_amdgcn_mfma_f32_16x16x32_bf16(vf, pf[0][ks2], o[0][dt], 0, 0, 0);
;         o[1][dt] = __builtin_amdgcn_mfma_f32_16x16x32_bf16(vf, pf[1][ks2], o[1][dt], 0, 0, 0);
;       }
;     __builtin_amdgcn_s_setprio(0);
;   }
	v_mfma_f32_16x16x32_bf16 v[68:71], v[250:253], v[124:127], v[68:71]
	v_mfma_f32_16x16x32_bf16 v[28:31], v[250:253], v[128:131], v[28:31]
	ds_read_b128 v[250:253], v156 offset:28224
	v_lshl_add_u64 v[138:139], v[138:139], 0, s[24:25]
	s_waitcnt lgkmcnt(8)
	v_mfma_f32_16x16x32_bf16 v[76:79], v[182:185], v[124:127], v[76:79]
	v_mfma_f32_16x16x32_bf16 v[32:35], v[182:185], v[128:131], v[32:35]
	ds_read_b128 v[182:185], v156 offset:30784
	v_lshl_add_u64 v[150:151], v[150:151], 0, s[24:25]
	s_waitcnt lgkmcnt(8)
	v_mfma_f32_16x16x32_bf16 v[80:83], v[186:189], v[124:127], v[80:83]
	v_mfma_f32_16x16x32_bf16 v[36:39], v[186:189], v[128:131], v[36:39]
	ds_read_b128 v[186:189], v156 offset:33344
	v_lshl_add_u64 v[152:153], v[152:153], 0, s[26:27]
	s_waitcnt lgkmcnt(8)
	v_mfma_f32_16x16x32_bf16 v[84:87], v[190:193], v[124:127], v[84:87]
	v_mfma_f32_16x16x32_bf16 v[44:47], v[190:193], v[128:131], v[44:47]
	ds_read_b128 v[190:193], v156 offset:35904
	v_lshl_add_u64 v[154:155], v[154:155], 0, s[26:27]
	s_waitcnt lgkmcnt(8)
	v_mfma_f32_16x16x32_bf16 v[88:91], v[194:197], v[124:127], v[88:91]
	v_mfma_f32_16x16x32_bf16 v[64:67], v[194:197], v[128:131], v[64:67]
	ds_read_b128 v[194:197], v156 offset:38464
	s_waitcnt lgkmcnt(8)
	v_mfma_f32_16x16x32_bf16 v[96:99], v[198:201], v[124:127], v[96:99]
	v_mfma_f32_16x16x32_bf16 v[92:95], v[198:201], v[128:131], v[92:95]
	s_waitcnt lgkmcnt(7)
	v_mfma_f32_16x16x32_bf16 v[40:43], v[202:205], v[116:119], v[40:43]
	v_mfma_f32_16x16x32_bf16 v[20:23], v[202:205], v[120:123], v[20:23]
	s_waitcnt lgkmcnt(6)
	v_mfma_f32_16x16x32_bf16 v[48:51], v[242:245], v[116:119], v[48:51]
	v_mfma_f32_16x16x32_bf16 v[24:27], v[242:245], v[120:123], v[24:27]
	s_waitcnt lgkmcnt(5)
	v_mfma_f32_16x16x32_bf16 v[68:71], v[246:249], v[116:119], v[68:71]
	v_mfma_f32_16x16x32_bf16 v[28:31], v[246:249], v[120:123], v[28:31]
	s_waitcnt lgkmcnt(4)
	v_mfma_f32_16x16x32_bf16 v[76:79], v[250:253], v[116:119], v[76:79]
	v_mfma_f32_16x16x32_bf16 v[32:35], v[250:253], v[120:123], v[32:35]
	s_waitcnt lgkmcnt(3)
	v_mfma_f32_16x16x32_bf16 v[80:83], v[182:185], v[116:119], v[80:83]
	v_mfma_f32_16x16x32_bf16 v[36:39], v[182:185], v[120:123], v[36:39]
	s_waitcnt lgkmcnt(2)
	v_mfma_f32_16x16x32_bf16 v[84:87], v[186:189], v[116:119], v[84:87]
	v_mfma_f32_16x16x32_bf16 v[44:47], v[186:189], v[120:123], v[44:47]
	s_waitcnt lgkmcnt(1)
	v_mfma_f32_16x16x32_bf16 v[88:91], v[190:193], v[116:119], v[88:91]
	v_mfma_f32_16x16x32_bf16 v[64:67], v[190:193], v[120:123], v[64:67]
	s_waitcnt lgkmcnt(0)
	v_mfma_f32_16x16x32_bf16 v[96:99], v[194:197], v[116:119], v[96:99]
	v_mfma_f32_16x16x32_bf16 v[92:95], v[194:197], v[120:123], v[92:95]
	s_setprio 0
	s_add_i32 s0, s0, -1
	s_cmp_lg_u32 s0, 0
	s_cbranch_scc1 .LBB0_327
	s_barrier
	s_waitcnt vmcnt(7)
	ds_write_b128 v158, v[52:55]
	s_waitcnt vmcnt(5)
	ds_write_b128 v159, v[72:75]
	ds_write_b128 v166, v[56:59]
	s_waitcnt vmcnt(4)
	ds_write_b128 v158, v[60:63] offset:15360
	s_waitcnt vmcnt(3)
	ds_write_b128 v158, v[100:103] offset:20480
	s_waitcnt vmcnt(2)
	ds_write_b128 v159, v[104:107] offset:20480
	s_waitcnt vmcnt(1)
	ds_write_b128 v166, v[108:111] offset:20480
	s_waitcnt vmcnt(0)
	ds_write_b128 v167, v[112:115] offset:20480
	s_waitcnt lgkmcnt(0)
	s_barrier
	s_setprio 1
	ds_read_b128 v[52:55], v157
	ds_read_b128 v[60:63], v157 offset:64
	s_waitcnt lgkmcnt(1)
	v_mfma_f32_16x16x32_bf16 v[56:59], v[52:55], v[12:15], v[0:3]
	ds_read_b128 v[100:103], v157 offset:704
	ds_read_b128 v[108:111], v157 offset:5184
	v_mfma_f32_16x16x32_bf16 v[52:55], v[52:55], v[16:19], v[0:3]
	s_waitcnt lgkmcnt(2)
	v_mfma_f32_16x16x32_bf16 v[56:59], v[60:63], v[4:7], v[56:59]
	v_mfma_f32_16x16x32_bf16 v[52:55], v[60:63], v[8:11], v[52:55]
	ds_read_b128 v[60:63], v157 offset:640
	s_waitcnt lgkmcnt(0)
	v_mfma_f32_16x16x32_bf16 v[72:75], v[60:63], v[12:15], v[0:3]
	v_mfma_f32_16x16x32_bf16 v[60:63], v[60:63], v[16:19], v[0:3]
	v_mfma_f32_16x16x32_bf16 v[72:75], v[100:103], v[4:7], v[72:75]
	v_mfma_f32_16x16x32_bf16 v[60:63], v[100:103], v[8:11], v[60:63]
	ds_read_b128 v[100:103], v157 offset:5120
	s_waitcnt lgkmcnt(0)
	v_mfma_f32_16x16x32_bf16 v[104:107], v[100:103], v[12:15], v[0:3]
	v_mfma_f32_16x16x32_bf16 v[100:103], v[100:103], v[16:19], v[0:3]
	v_mfma_f32_16x16x32_bf16 v[104:107], v[108:111], v[4:7], v[104:107]
	v_mfma_f32_16x16x32_bf16 v[100:103], v[108:111], v[8:11], v[100:103]
	ds_read_b128 v[108:111], v157 offset:5760
	s_waitcnt lgkmcnt(0)
	v_mfma_f32_16x16x32_bf16 v[12:15], v[108:111], v[12:15], v[0:3]
	v_mfma_f32_16x16x32_bf16 v[16:19], v[108:111], v[16:19], v[0:3]
	ds_read_b128 v[108:111], v157 offset:5824
	s_waitcnt lgkmcnt(0)
; __device__ __forceinline__ float fexp2(float x) { return __builtin_amdgcn_exp2f(x); }
; __device__ __forceinline__ void attn_diff32(const bf16_t* __restrict__ Qp, const bf16_t* __restrict__ Kp,
;                                             const bf16_t* __restrict__ Vtp, int ntiles, float negM,
;                                             f32x4 (&o)[2][8], float (&l)[2], char* smem) {
;     ...
;     bf16x8 pf[2][2];
; #pragma unroll
;     for (int qt = 0; qt < 2; ++qt) {
;       float ls = 0.f;
; #pragma unroll
;       for (int kt = 0; kt < 4; ++kt)
; #pragma unroll
;         for (int e = 0; e < 4; ++e) {
;           s[qt][kt][e] = fexp2(s[qt][kt][e]);
;           ls += s[qt][kt][e];
;         }
;       l[qt] += ls;
; #pragma unroll
;       for (int ks2 = 0; ks2 < 2; ++ks2) {
;         union { uint32_t u[4]; bf16x8 v; } pk;
;         pk.u[0] = pack2(s[qt][2 * ks2][0], s[qt][2 * ks2][1]);
;         pk.u[1] = pack2(s[qt][2 * ks2][2], s[qt][2 * ks2][3]);
;         pk.u[2] = pack2(s[qt][2 * ks2 + 1][0], s[qt][2 * ks2 + 1][1]);
;         pk.u[3] = pack2(s[qt][2 * ks2 + 1][2], s[qt][2 * ks2 + 1][3]);
;         pf[qt][ks2] = pk.v;
;       }
;     }
;     if (n + 1 < ntiles) { AD_LOAD_V(knext) }
;     __builtin_amdgcn_s_setprio(1);
; #pragma unroll
;     for (int ks2 = 0; ks2 < 2; ++ks2)
; #pragma unroll
;       for (int dt = 0; dt < 8; ++dt) {
;         const bf16x8 vf = *(const bf16x8*)(sVt + (dt * 16 + l15) * LSTR + 32 * ks2 + quad * 8);
;         o[0][dt] = __builtin_amdgcn_mfma_f32_16x16x32_bf16(vf, pf[0][ks2], o[0][dt], 0, 0, 0);
;         o[1][dt] = __builtin_amdgcn_mfma_f32_16x16x32_bf16(vf, pf[1][ks2], o[1][dt], 0, 0, 0);
;       }
;     __builtin_amdgcn_s_setprio(0);
	v_mfma_f32_16x16x32_bf16 v[4:7], v[108:111], v[4:7], v[12:15]
	v_mfma_f32_16x16x32_bf16 v[8:11], v[108:111], v[8:11], v[16:19]
	s_setprio 0
	s_nop 1
	v_exp_f32_e32 v12, v56
	v_exp_f32_e32 v13, v57
	v_exp_f32_e32 v14, v58
	v_exp_f32_e32 v15, v59
	v_add_f32_e32 v16, 0, v12
	v_exp_f32_e32 v17, v72
	v_add_f32_e32 v16, v13, v16
	v_exp_f32_e32 v18, v73
	v_add_f32_e32 v16, v14, v16
	v_exp_f32_e32 v19, v74
	v_add_f32_e32 v16, v15, v16
	v_exp_f32_e32 v56, v75
	v_add_f32_e32 v16, v16, v17
	v_exp_f32_e32 v57, v104
	v_add_f32_e32 v16, v18, v16
	v_exp_f32_e32 v58, v105
	v_add_f32_e32 v16, v19, v16
	v_exp_f32_e32 v59, v106
	v_add_f32_e32 v16, v56, v16
	v_exp_f32_e32 v72, v107
	v_add_f32_e32 v16, v16, v57
	v_exp_f32_e32 v73, v4
	v_add_f32_e32 v16, v58, v16
	v_exp_f32_e32 v74, v5
	v_add_f32_e32 v16, v59, v16
	v_exp_f32_e32 v75, v6
	v_add_f32_e32 v16, v72, v16
	v_exp_f32_e32 v104, v7
	v_add_f32_e32 v4, v16, v73
	v_exp_f32_e32 v16, v52
	v_add_f32_e32 v4, v74, v4
	v_exp_f32_e32 v52, v53
	v_add_f32_e32 v4, v75, v4
	v_exp_f32_e32 v53, v54
	v_add_f32_e32 v4, v104, v4
	v_exp_f32_e32 v54, v55
	v_add_f32_e32 v108, v133, v4
	v_add_f32_e32 v4, 0, v16
	v_exp_f32_e32 v55, v60
	v_add_f32_e32 v4, v52, v4
	v_exp_f32_e32 v60, v61
	v_add_f32_e32 v4, v53, v4
	v_exp_f32_e32 v61, v62
	v_add_f32_e32 v4, v54, v4
	v_exp_f32_e32 v62, v63
	v_add_f32_e32 v4, v4, v55
	v_exp_f32_e32 v5, v100
	v_add_f32_e32 v4, v60, v4
	v_exp_f32_e32 v6, v101
	v_add_f32_e32 v4, v61, v4
	v_exp_f32_e32 v7, v102
	v_add_f32_e32 v4, v62, v4
	v_exp_f32_e32 v63, v103
	v_add_f32_e32 v4, v4, v5
	v_exp_f32_e32 v8, v8
	v_add_f32_e32 v4, v6, v4
	v_exp_f32_e32 v9, v9
	v_add_f32_e32 v4, v7, v4
	v_exp_f32_e32 v10, v10
	v_add_f32_e32 v4, v63, v4
	v_exp_f32_e32 v11, v11
	v_add_f32_e32 v4, v4, v8
	v_add_f32_e32 v4, v9, v4
	v_add_f32_e32 v4, v10, v4
	v_add_f32_e32 v4, v11, v4
	v_add_f32_e32 v109, v132, v4
	v_cvt_pk_bf16_f32 v4, v5, v6
	v_cvt_pk_bf16_f32 v5, v7, v63
	v_cvt_pk_bf16_f32 v6, v8, v9
	v_cvt_pk_bf16_f32 v7, v10, v11
	v_cvt_pk_bf16_f32 v8, v16, v52
	v_cvt_pk_bf16_f32 v9, v53, v54
	v_cvt_pk_bf16_f32 v10, v55, v60
	v_cvt_pk_bf16_f32 v11, v61, v62
	v_cvt_pk_bf16_f32 v60, v57, v58
	v_cvt_pk_bf16_f32 v61, v59, v72
	v_cvt_pk_bf16_f32 v62, v73, v74
	v_cvt_pk_bf16_f32 v63, v75, v104
	v_cvt_pk_bf16_f32 v12, v12, v13
	v_cvt_pk_bf16_f32 v13, v14, v15
	v_cvt_pk_bf16_f32 v14, v17, v18
	v_cvt_pk_bf16_f32 v15, v19, v56
	s_setprio 1
	ds_read_b128 v[16:19], v156 offset:20480
	s_waitcnt lgkmcnt(0)
	v_mfma_f32_16x16x32_bf16 v[40:43], v[16:19], v[12:15], v[40:43]
	v_mfma_f32_16x16x32_bf16 v[16:19], v[16:19], v[8:11], v[20:23]
	s_nop 2
	ds_read_b128 v[20:23], v156 offset:23040
	s_waitcnt lgkmcnt(0)
	v_mfma_f32_16x16x32_bf16 v[48:51], v[20:23], v[12:15], v[48:51]
	v_mfma_f32_16x16x32_bf16 v[20:23], v[20:23], v[8:11], v[24:27]
	s_nop 2
	ds_read_b128 v[24:27], v156 offset:25600
	s_waitcnt lgkmcnt(0)
	v_mfma_f32_16x16x32_bf16 v[52:55], v[24:27], v[12:15], v[68:71]
	v_mfma_f32_16x16x32_bf16 v[24:27], v[24:27], v[8:11], v[28:31]
	s_nop 2
	ds_read_b128 v[28:31], v156 offset:28160
	s_waitcnt lgkmcnt(0)
	v_mfma_f32_16x16x32_bf16 v[68:71], v[28:31], v[12:15], v[76:79]
	v_mfma_f32_16x16x32_bf16 v[72:75], v[28:31], v[8:11], v[32:35]
	ds_read_b128 v[28:31], v156 offset:30720
	s_waitcnt lgkmcnt(0)
	v_mfma_f32_16x16x32_bf16 v[76:79], v[28:31], v[12:15], v[80:83]
	v_mfma_f32_16x16x32_bf16 v[80:83], v[28:31], v[8:11], v[36:39]
	ds_read_b128 v[28:31], v156 offset:33280
	s_waitcnt lgkmcnt(0)
	v_mfma_f32_16x16x32_bf16 v[84:87], v[28:31], v[12:15], v[84:87]
	v_mfma_f32_16x16x32_bf16 v[100:103], v[28:31], v[8:11], v[44:47]
	ds_read_b128 v[28:31], v156 offset:35840
	s_waitcnt lgkmcnt(0)
	v_mfma_f32_16x16x32_bf16 v[88:91], v[28:31], v[12:15], v[88:91]
	v_mfma_f32_16x16x32_bf16 v[104:107], v[28:31], v[8:11], v[64:67]
	ds_read_b128 v[28:31], v156 offset:38400
	s_waitcnt lgkmcnt(0)
	v_mfma_f32_16x16x32_bf16 v[92:95], v[28:31], v[8:11], v[92:95]
	ds_read_b128 v[8:11], v156 offset:20544
	s_waitcnt lgkmcnt(0)
	v_mfma_f32_16x16x32_bf16 v[64:67], v[8:11], v[60:63], v[40:43]
	v_mfma_f32_16x16x32_bf16 v[32:35], v[8:11], v[4:7], v[16:19]
	ds_read_b128 v[8:11], v156 offset:23104
	v_mfma_f32_16x16x32_bf16 v[96:99], v[28:31], v[12:15], v[96:99]
	s_waitcnt lgkmcnt(0)
	v_mfma_f32_16x16x32_bf16 v[56:59], v[8:11], v[60:63], v[48:51]
	v_mfma_f32_16x16x32_bf16 v[28:31], v[8:11], v[4:7], v[20:23]
	ds_read_b128 v[8:11], v156 offset:25664
	s_waitcnt lgkmcnt(0)
	v_mfma_f32_16x16x32_bf16 v[52:55], v[8:11], v[60:63], v[52:55]
	v_mfma_f32_16x16x32_bf16 v[24:27], v[8:11], v[4:7], v[24:27]
	ds_read_b128 v[8:11], v156 offset:28224
	s_waitcnt lgkmcnt(0)
	v_mfma_f32_16x16x32_bf16 v[36:39], v[8:11], v[60:63], v[68:71]
	s_nop 2
	ds_read_b128 v[68:71], v156 offset:38464
	v_mfma_f32_16x16x32_bf16 v[20:23], v[8:11], v[4:7], v[72:75]
	ds_read_b128 v[8:11], v156 offset:30784
	s_waitcnt lgkmcnt(0)
	v_mfma_f32_16x16x32_bf16 v[40:43], v[8:11], v[60:63], v[76:79]
	v_mfma_f32_16x16x32_bf16 v[16:19], v[8:11], v[4:7], v[80:83]
	ds_read_b128 v[8:11], v156 offset:33344
	s_waitcnt lgkmcnt(0)
	v_mfma_f32_16x16x32_bf16 v[44:47], v[8:11], v[60:63], v[84:87]
	v_mfma_f32_16x16x32_bf16 v[12:15], v[8:11], v[4:7], v[100:103]
	ds_read_b128 v[8:11], v156 offset:35904
	s_waitcnt lgkmcnt(0)
	v_mfma_f32_16x16x32_bf16 v[48:51], v[8:11], v[60:63], v[88:91]
	v_mfma_f32_16x16x32_bf16 v[8:11], v[8:11], v[4:7], v[104:107]
	v_mfma_f32_16x16x32_bf16 v[60:63], v[68:71], v[60:63], v[96:99]
	v_mfma_f32_16x16x32_bf16 v[4:7], v[68:71], v[4:7], v[92:95]
	s_setprio 0
	v_cmp_lt_i32_e32 vcc, v173, v174
	s_barrier
; __device__ __forceinline__ void attn_diff32(const bf16_t* __restrict__ Qp, const bf16_t* __restrict__ Kp,
;                                             const bf16_t* __restrict__ Vtp, int ntiles, float negM,
;                                             f32x4 (&o)[2][8], float (&l)[2], char* smem) {
;     ...
; #pragma unroll
;   for (int qt = 0; qt < 2; ++qt) {
;     l[qt] += __shfl_xor(l[qt], 16);
;     l[qt] += __shfl_xor(l[qt], 32);
;   }
; }
; __device__ __forceinline__ void phase_attn0(const Params& P, char* smem) {
;   char* ws = P.ws;
;   const bf16_t* AQ = (const bf16_t*)(ws + OFF_AQ);
;   const bf16_t* AK = (const bf16_t*)(ws + OFF_AK);
;   const bf16_t* AVT = (const bf16_t*)(ws + OFF_AVT);
;   const bf16_t* BQ = (const bf16_t*)(ws + OFF_BQ);
;   const bf16_t* BK = (const bf16_t*)(ws + OFF_BK);
;   const bf16_t* BVT = (const bf16_t*)(ws + OFF_BVT);
;   bf16_t* Acat = (bf16_t*)(ws + OFF_A);
;   const float lam = ((const float*)(ws + OFF_LAM))[0];
;   const float negM = -((const float*)(ws + OFF_LAM))[1];
;   const bool fixed_ok = ((const float*)(ws + OFF_LAM))[1] < 60.0f;
;   const float lambda_init = 0.2f;
;   const int lane = threadIdx.x & 63, wave = threadIdx.x >> 6, l15 = lane & 15, quad = lane >> 4;
;   for (int u = blockIdx.x; u < 2080; u += gridDim.x) {
;     int b, head, qb;
;     if (u < 2048) {
;       const int bh = u & 7;
;       b = bh >> 2; head = bh & 3; qb = 4 + (u >> 3);
;     }
;     else { const int cu = u - 2048; b = cu >> 4; head = (cu >> 2) & 3; qb = cu & 3; }
;     const int qk0 = qb * 64;
;     const int nseg = qb >= 4 ? 256 : 0;
;     f32x4 o[2][8];
;     float m[2], l[2];
;     if (fixed_ok) {
;       f32x4 o2[2][8];
;       float l2[2];
;       attn_diff32(AQ + (size_t)(b * TPB + qk0) * 512 + head * 128, AK + (size_t)(b * TPB) * 512 + head * 128,
;                   AVT + (size_t)(b * 4 + head) * 128 * TPB, 4 + nseg, negM, o2, l2, smem);
;       float* xch = (float*)smem;
;       const int cmap = wave >> 1, qg = wave & 1;
;       __syncthreads();
;       if (cmap == 1) {
; #pragma unroll
;         for (int qt = 0; qt < 2; ++qt) {
;           const float i1 = lam / l2[qt];
; #pragma unroll
;           for (int dt = 0; dt < 8; ++dt)
;             *(f32x4*)(xch + (size_t)((qg * 32 + qt * 16 + l15) * 128 + dt * 16 + quad * 4)) = o2[qt][dt] * i1;
;         }
;       }
	s_nop 0
	v_cndmask_b32_e32 v68, v172, v173, vcc
	v_cmp_lt_i32_e32 vcc, v175, v174
	v_lshlrev_b32_e32 v84, 2, v68
	s_nop 0
	v_cndmask_b32_e32 v68, v172, v175, vcc
	v_lshlrev_b32_e32 v85, 2, v68
	ds_bpermute_b32 v68, v84, v108
	s_waitcnt lgkmcnt(0)
	v_add_f32_e32 v68, v108, v68
	ds_bpermute_b32 v69, v85, v68
	s_waitcnt lgkmcnt(0)
	v_add_f32_e32 v74, v68, v69
	ds_bpermute_b32 v68, v84, v109
	s_waitcnt lgkmcnt(0)
	v_add_f32_e32 v68, v109, v68
	ds_bpermute_b32 v69, v85, v68
	s_waitcnt lgkmcnt(0)
	v_add_f32_e32 v86, v68, v69
	s_and_saveexec_b64 s[18:19], s[6:7]
	s_cbranch_execz .LBB0_330
	v_div_scale_f32 v68, s[2:3], v74, v74, v142
	v_rcp_f32_e32 v69, v68
	s_nop 0
	v_fma_f32 v70, -v68, v69, 1.0
	v_fmac_f32_e32 v69, v70, v69
	v_div_scale_f32 v70, vcc, v142, v74, v142
	v_mul_f32_e32 v71, v70, v69
	v_fma_f32 v72, -v68, v71, v70
	v_fmac_f32_e32 v71, v72, v69
	v_fma_f32 v68, -v68, v71, v70
	v_div_fmas_f32 v68, v68, v69, v71
	v_div_fixup_f32 v72, v68, v74, v142
	v_pk_mul_f32 v[70:71], v[66:67], v[72:73] op_sel_hi:[1,0]
	v_pk_mul_f32 v[68:69], v[64:65], v[72:73] op_sel_hi:[1,0]
	ds_write_b128 v169, v[68:71]
	v_pk_mul_f32 v[70:71], v[58:59], v[72:73] op_sel_hi:[1,0]
	v_pk_mul_f32 v[68:69], v[56:57], v[72:73] op_sel_hi:[1,0]
	ds_write_b128 v169, v[68:71] offset:64
	v_pk_mul_f32 v[70:71], v[54:55], v[72:73] op_sel_hi:[1,0]
	v_pk_mul_f32 v[68:69], v[52:53], v[72:73] op_sel_hi:[1,0]
	ds_write_b128 v169, v[68:71] offset:128
	v_pk_mul_f32 v[70:71], v[38:39], v[72:73] op_sel_hi:[1,0]
	v_pk_mul_f32 v[68:69], v[36:37], v[72:73] op_sel_hi:[1,0]
	ds_write_b128 v169, v[68:71] offset:192
	v_pk_mul_f32 v[70:71], v[42:43], v[72:73] op_sel_hi:[1,0]
	v_pk_mul_f32 v[68:69], v[40:41], v[72:73] op_sel_hi:[1,0]
	ds_write_b128 v169, v[68:71] offset:256
	v_pk_mul_f32 v[70:71], v[46:47], v[72:73] op_sel_hi:[1,0]
	v_pk_mul_f32 v[68:69], v[44:45], v[72:73] op_sel_hi:[1,0]
	ds_write_b128 v169, v[68:71] offset:320
	v_pk_mul_f32 v[70:71], v[50:51], v[72:73] op_sel_hi:[1,0]
	v_pk_mul_f32 v[68:69], v[48:49], v[72:73] op_sel_hi:[1,0]
	ds_write_b128 v169, v[68:71] offset:384
	v_pk_mul_f32 v[70:71], v[62:63], v[72:73] op_sel_hi:[1,0]
	v_pk_mul_f32 v[68:69], v[60:61], v[72:73] op_sel_hi:[1,0]
	ds_write_b128 v169, v[68:71] offset:448
	v_div_scale_f32 v68, s[2:3], v86, v86, v142
	v_rcp_f32_e32 v69, v68
	s_nop 0
	v_fma_f32 v70, -v68, v69, 1.0
	v_fmac_f32_e32 v69, v70, v69
	v_div_scale_f32 v70, vcc, v142, v86, v142
	v_mul_f32_e32 v71, v70, v69
	v_fma_f32 v72, -v68, v71, v70
	v_fmac_f32_e32 v71, v72, v69
	v_fma_f32 v68, -v68, v71, v70
	v_div_fmas_f32 v68, v68, v69, v71
	v_div_fixup_f32 v72, v68, v86, v142
	v_pk_mul_f32 v[70:71], v[34:35], v[72:73] op_sel_hi:[1,0]
	v_pk_mul_f32 v[68:69], v[32:33], v[72:73] op_sel_hi:[1,0]
	ds_write_b128 v169, v[68:71] offset:8192
	v_pk_mul_f32 v[70:71], v[30:31], v[72:73] op_sel_hi:[1,0]
	v_pk_mul_f32 v[68:69], v[28:29], v[72:73] op_sel_hi:[1,0]
	ds_write_b128 v169, v[68:71] offset:8256
	v_pk_mul_f32 v[70:71], v[26:27], v[72:73] op_sel_hi:[1,0]
	v_pk_mul_f32 v[68:69], v[24:25], v[72:73] op_sel_hi:[1,0]
	ds_write_b128 v169, v[68:71] offset:8320
	v_pk_mul_f32 v[70:71], v[22:23], v[72:73] op_sel_hi:[1,0]
	v_pk_mul_f32 v[68:69], v[20:21], v[72:73] op_sel_hi:[1,0]
	ds_write_b128 v169, v[68:71] offset:8384
	v_pk_mul_f32 v[70:71], v[18:19], v[72:73] op_sel_hi:[1,0]
	v_pk_mul_f32 v[68:69], v[16:17], v[72:73] op_sel_hi:[1,0]
	ds_write_b128 v169, v[68:71] offset:8448
	v_pk_mul_f32 v[70:71], v[14:15], v[72:73] op_sel_hi:[1,0]
	v_pk_mul_f32 v[68:69], v[12:13], v[72:73] op_sel_hi:[1,0]
	ds_write_b128 v169, v[68:71] offset:8512
	v_pk_mul_f32 v[70:71], v[10:11], v[72:73] op_sel_hi:[1,0]
	v_pk_mul_f32 v[68:69], v[8:9], v[72:73] op_sel_hi:[1,0]
	ds_write_b128 v169, v[68:71] offset:8576
	v_pk_mul_f32 v[70:71], v[6:7], v[72:73] op_sel_hi:[1,0]
	v_pk_mul_f32 v[68:69], v[4:5], v[72:73] op_sel_hi:[1,0]
	ds_write_b128 v169, v[68:71] offset:8640

; __device__ __forceinline__ float fexp2(float x) { return __builtin_amdgcn_exp2f(x); }
; template <int NMAP, int NDT, int MODE, bool FIXED> ...
;     ...
;     __syncthreads();
;     *(uint4*)(sK + (lr) * LSTR + lch) = rk00;
;     *(uint4*)(sK + (lr + 32) * LSTR + lch) = rk01;
;     if (NMAP > 1) {
;       *(uint4*)(sK + (64 + lr) * LSTR + lch) = rk10;
;       *(uint4*)(sK + (64 + lr + 32) * LSTR + lch) = rk11;
;     }
;     *(uint4*)(sVt + (lr) * LSTR + lch) = rv0;
;     *(uint4*)(sVt + (lr + 32) * LSTR + lch) = rv1;
;     if (NVL > 2) {
;       *(uint4*)(sVt + (lr + 64) * LSTR + lch) = rv2;
;       *(uint4*)(sVt + (lr + 96) * LSTR + lch) = rv3;
;     }
;     __syncthreads();
;     const int knext = (MODE == 0) ? (n + 1) * 64 : ((n + 1) < 4 ? (n + 1) * 64 : seg_lo + (n + 1 - 4) * 64);
;     if (n + 1 < ntiles) {
;       ATTN_LOAD_K(knext)
;     }
;     ...
;         const float mnew = fmaxf(m[c], mx);
;         const float alpha = fexp2(m[c] - mnew);
;         m[c] = mnew;
;         float ls = 0.f;
; #pragma unroll
;         for (int kt = 0; kt < 4; ++kt)
; #pragma unroll
;           for (int e = 0; e < 4; ++e) {
;             s[kt][e] = fexp2(s[kt][e] - mnew);
;             ls += s[kt][e];
;           }
;         l[c] = l[c] * alpha + ls;
;         if (__ballot(alpha != 1.0f) != 0ull) {
; #pragma unroll
;           for (int dt = 0; dt < NDT; ++dt) o[c][dt] *= alpha;
;         }
;       }
;       __builtin_amdgcn_sched_barrier(0);
; #pragma unroll
;       for (int ks2 = 0; ks2 < 2; ++ks2) {
;         union { uint32_t u[4]; bf16x8 v; } pk;
;         pk.u[0] = pack2(s[2 * ks2][0], s[2 * ks2][1]);
;         pk.u[1] = pack2(s[2 * ks2][2], s[2 * ks2][3]);
;         pk.u[2] = pack2(s[2 * ks2 + 1][0], s[2 * ks2 + 1][1]);
;         pk.u[3] = pack2(s[2 * ks2 + 1][2], s[2 * ks2 + 1][3]);
;         pf[c][ks2] = pk.v;
;       }
;     }
;     if (n + 1 < ntiles) {
;       ATTN_LOAD_V(knext)
;     }
; #pragma unroll
;     for (int ks2 = 0; ks2 < 2; ++ks2) {
;       __builtin_amdgcn_sched_barrier(0);
; #pragma unroll
;       for (int dt = 0; dt < NDT; ++dt) {
;         const bf16x8 vf = *(const bf16x8*)(sVt + (dt * 16 + l15) * LSTR + 32 * ks2 + quad * 8);
; #pragma unroll
;         for (int c = 0; c < NMAP; ++c) o[c][dt] = __builtin_amdgcn_mfma_f32_16x16x32_bf16(vf, pf[c][ks2], o[c][dt], 0, 0, 0);
;       }
;     }
.LBB0_346:
	v_sub_f32_e32 v12, v12, v70
	v_exp_f32_e32 v12, v12
	v_sub_f32_e32 v13, v13, v70
	v_exp_f32_e32 v13, v13
	v_sub_f32_e32 v14, v14, v70
	v_exp_f32_e32 v14, v14
	v_sub_f32_e32 v15, v15, v70
	v_exp_f32_e32 v15, v15
	v_sub_f32_e32 v8, v8, v70
	v_add_f32_e32 v44, 0, v12
	v_exp_f32_e32 v8, v8
	v_sub_f32_e32 v9, v9, v70
	v_add_f32_e32 v44, v13, v44
	v_exp_f32_e32 v9, v9
	v_sub_f32_e32 v10, v10, v70
	v_add_f32_e32 v44, v14, v44
	v_exp_f32_e32 v10, v10
	v_sub_f32_e32 v11, v11, v70
	v_add_f32_e32 v44, v15, v44
	v_exp_f32_e32 v11, v11
	v_sub_f32_e32 v4, v4, v70
	v_add_f32_e32 v44, v8, v44
	v_exp_f32_e32 v45, v4
	v_sub_f32_e32 v4, v5, v70
	v_add_f32_e32 v44, v9, v44
	v_exp_f32_e32 v46, v4
	v_sub_f32_e32 v4, v6, v70
	v_add_f32_e32 v44, v10, v44
	v_exp_f32_e32 v47, v4
	v_sub_f32_e32 v4, v7, v70
	v_add_f32_e32 v44, v11, v44
	v_exp_f32_e32 v48, v4
	v_sub_f32_e32 v0, v0, v70
	v_add_f32_e32 v4, v45, v44
	v_exp_f32_e32 v44, v0
	v_sub_f32_e32 v0, v1, v70
	v_add_f32_e32 v4, v46, v4
	v_exp_f32_e32 v49, v0
	v_sub_f32_e32 v0, v2, v70
	v_add_f32_e32 v4, v47, v4
	v_exp_f32_e32 v50, v0
	v_sub_f32_e32 v0, v3, v70
	v_add_f32_e32 v4, v48, v4
	v_exp_f32_e32 v51, v0
	v_add_f32_e32 v0, v44, v4
	v_add_f32_e32 v0, v49, v0
	v_add_f32_e32 v0, v50, v0
	s_cmp_lg_u64 s[0:1], 0
	v_add_f32_e32 v87, v51, v0
	v_mul_f32_e32 v0, 0, v42
	s_cselect_b64 vcc, -1, 0
	v_cndmask_b32_e32 v0, 0, v0, vcc
	v_fmac_f32_e32 v87, 0, v42
	v_mov_b32_e32 v1, v0
	v_mov_b32_e32 v2, v0
	v_mov_b32_e32 v3, v0
	v_cvt_pk_bf16_f32 v4, v12, v13
	v_cvt_pk_bf16_f32 v5, v14, v15
	v_cvt_pk_bf16_f32 v6, v8, v9
	v_cvt_pk_bf16_f32 v7, v10, v11
	v_cvt_pk_bf16_f32 v8, v45, v46
	v_cvt_pk_bf16_f32 v9, v47, v48
	v_cvt_pk_bf16_f32 v10, v44, v49
	v_cvt_pk_bf16_f32 v11, v50, v51
	s_add_i32 s2, s13, 4
	v_mul_u32_u24_e32 v43, 0xa0, v86
	v_add_u32_e32 v82, v40, v43
	ds_read_b128 v[12:15], v82 offset:10240
	ds_read_b128 v[42:45], v82 offset:12800
	ds_read_b128 v[46:49], v82 offset:15360
	ds_read_b128 v[50:53], v82 offset:17920
	s_waitcnt lgkmcnt(3)
	v_mfma_f32_16x16x32_bf16 v[12:15], v[12:15], v[4:7], v[0:3]
	s_waitcnt lgkmcnt(2)
	v_mfma_f32_16x16x32_bf16 v[42:45], v[42:45], v[4:7], v[0:3]
	s_waitcnt lgkmcnt(1)
	v_mfma_f32_16x16x32_bf16 v[46:49], v[46:49], v[4:7], v[0:3]
	s_waitcnt lgkmcnt(0)
	v_mfma_f32_16x16x32_bf16 v[50:53], v[50:53], v[4:7], v[0:3]
	s_nop 2
	ds_read_b128 v[0:3], v82 offset:10304
	ds_read_b128 v[4:7], v82 offset:12864
	s_cmp_eq_u32 s2, 1
	s_waitcnt lgkmcnt(1)
	v_mfma_f32_16x16x32_bf16 v[0:3], v[0:3], v[8:11], v[12:15]
	s_nop 2
	ds_read_b128 v[12:15], v82 offset:15424
	s_waitcnt lgkmcnt(1)
	v_mfma_f32_16x16x32_bf16 v[4:7], v[4:7], v[8:11], v[42:45]
	s_nop 2
	ds_read_b128 v[42:45], v82 offset:17984
	s_waitcnt lgkmcnt(1)
	v_mfma_f32_16x16x32_bf16 v[12:15], v[12:15], v[8:11], v[46:49]
	s_waitcnt lgkmcnt(0)
	v_mfma_f32_16x16x32_bf16 v[8:11], v[42:45], v[8:11], v[50:53]
	s_cbranch_scc1 .LBB0_338
	s_cmp_gt_i32 s13, -2
	s_cselect_b64 s[0:1], -1, 0
	s_cmp_lt_i32 s13, -1
	s_barrier
	s_waitcnt vmcnt(1)
	ds_write_b128 v79, v[36:39]
	s_waitcnt vmcnt(0)
	ds_write_b128 v79, v[32:35] offset:5120
	ds_write_b128 v79, v[28:31] offset:10240
	ds_write_b128 v79, v[24:27] offset:15360
	s_waitcnt lgkmcnt(0)
	s_barrier
	s_cbranch_scc1 .LBB0_349
	s_add_u32 s16, s22, 0x8000
	s_addc_u32 s17, s23, 0
	v_lshl_add_u64 v[32:33], s[16:17], 0, v[60:61]
	v_lshl_add_u64 v[34:35], s[16:17], 0, v[62:63]
	global_load_dwordx4 v[36:39], v[32:33], off
	global_load_dwordx4 v[32:35], v[34:35], off

; __device__ __forceinline__ float fexp2(float x) { return __builtin_amdgcn_exp2f(x); }
; template <int NMAP, int NDT, int MODE, bool FIXED> ...
;     ...
;     __syncthreads();
;     *(uint4*)(sK + (lr) * LSTR + lch) = rk00;
;     *(uint4*)(sK + (lr + 32) * LSTR + lch) = rk01;
;     if (NMAP > 1) {
;       *(uint4*)(sK + (64 + lr) * LSTR + lch) = rk10;
;       *(uint4*)(sK + (64 + lr + 32) * LSTR + lch) = rk11;
;     }
;     *(uint4*)(sVt + (lr) * LSTR + lch) = rv0;
;     *(uint4*)(sVt + (lr + 32) * LSTR + lch) = rv1;
;     if (NVL > 2) {
;       *(uint4*)(sVt + (lr + 64) * LSTR + lch) = rv2;
;       *(uint4*)(sVt + (lr + 96) * LSTR + lch) = rv3;
;     }
;     __syncthreads();
;     const int knext = (MODE == 0) ? (n + 1) * 64 : ((n + 1) < 4 ? (n + 1) * 64 : seg_lo + (n + 1 - 4) * 64);
;     if (n + 1 < ntiles) {
;       ATTN_LOAD_K(knext)
;     }
;     ...
;         const float mnew = fmaxf(m[c], mx);
;         const float alpha = fexp2(m[c] - mnew);
;         m[c] = mnew;
;         float ls = 0.f;
; #pragma unroll
;         for (int kt = 0; kt < 4; ++kt)
; #pragma unroll
;           for (int e = 0; e < 4; ++e) {
;             s[kt][e] = fexp2(s[kt][e] - mnew);
;             ls += s[kt][e];
;           }
;         l[c] = l[c] * alpha + ls;
;         if (__ballot(alpha != 1.0f) != 0ull) {
; #pragma unroll
;           for (int dt = 0; dt < NDT; ++dt) o[c][dt] *= alpha;
;         }
;       }
;       __builtin_amdgcn_sched_barrier(0);
; #pragma unroll
;       for (int ks2 = 0; ks2 < 2; ++ks2) {
;         union { uint32_t u[4]; bf16x8 v; } pk;
;         pk.u[0] = pack2(s[2 * ks2][0], s[2 * ks2][1]);
;         pk.u[1] = pack2(s[2 * ks2][2], s[2 * ks2][3]);
;         pk.u[2] = pack2(s[2 * ks2 + 1][0], s[2 * ks2 + 1][1]);
;         pk.u[3] = pack2(s[2 * ks2 + 1][2], s[2 * ks2 + 1][3]);
;         pf[c][ks2] = pk.v;
;       }
;     }
;     if (n + 1 < ntiles) {
;       ATTN_LOAD_V(knext)
;     }
; #pragma unroll
;     for (int ks2 = 0; ks2 < 2; ++ks2) {
;       __builtin_amdgcn_sched_barrier(0);
; #pragma unroll
;       for (int dt = 0; dt < NDT; ++dt) {
;         const bf16x8 vf = *(const bf16x8*)(sVt + (dt * 16 + l15) * LSTR + 32 * ks2 + quad * 8);
; #pragma unroll
;         for (int c = 0; c < NMAP; ++c) o[c][dt] = __builtin_amdgcn_mfma_f32_16x16x32_bf16(vf, pf[c][ks2], o[c][dt], 0, 0, 0);
;       }
;     }
.LBB0_353:
	v_sub_f32_e32 v40, v40, v89
	v_exp_f32_e32 v88, v40
	v_sub_f32_e32 v40, v41, v89
	v_exp_f32_e32 v90, v40
	v_sub_f32_e32 v40, v42, v89
	v_exp_f32_e32 v91, v40
	v_sub_f32_e32 v40, v43, v89
	v_exp_f32_e32 v92, v40
	v_sub_f32_e32 v40, v44, v89
	v_exp_f32_e32 v93, v40
	v_sub_f32_e32 v40, v45, v89
	v_exp_f32_e32 v94, v40
	v_sub_f32_e32 v40, v46, v89
	v_exp_f32_e32 v95, v40
	v_sub_f32_e32 v40, v47, v89
	v_exp_f32_e32 v96, v40
	v_sub_f32_e32 v40, v48, v89
	v_exp_f32_e32 v48, v40
	v_sub_f32_e32 v40, v49, v89
	v_exp_f32_e32 v49, v40
	v_sub_f32_e32 v40, v50, v89
	v_exp_f32_e32 v50, v40
	v_sub_f32_e32 v40, v51, v89
	v_exp_f32_e32 v51, v40
	v_sub_f32_e32 v40, v52, v89
	v_exp_f32_e32 v52, v40
	v_sub_f32_e32 v40, v53, v89
	v_exp_f32_e32 v53, v40
	v_sub_f32_e32 v40, v54, v89
	v_exp_f32_e32 v54, v40
	v_sub_f32_e32 v40, v55, v89
	v_exp_f32_e32 v55, v40
	v_cvt_pk_bf16_f32 v40, v88, v90
	v_add_f32_e32 v88, 0, v88
	v_add_f32_e32 v88, v90, v88
	v_add_f32_e32 v88, v91, v88
	v_add_f32_e32 v88, v92, v88
	v_add_f32_e32 v88, v93, v88
	v_add_f32_e32 v88, v94, v88
	v_add_f32_e32 v88, v95, v88
	v_add_f32_e32 v88, v96, v88
	v_cvt_pk_bf16_f32 v44, v48, v49
	v_add_f32_e32 v48, v48, v88
	v_add_f32_e32 v48, v49, v48
	v_add_f32_e32 v48, v50, v48
	v_add_f32_e32 v48, v51, v48
	v_add_f32_e32 v48, v52, v48
	v_add_f32_e32 v48, v53, v48
	v_add_f32_e32 v48, v54, v48
	v_add_f32_e32 v88, v55, v48
	v_fmac_f32_e32 v88, v87, v70
	v_cvt_pk_bf16_f32 v41, v91, v92
	v_cvt_pk_bf16_f32 v42, v93, v94
	v_cvt_pk_bf16_f32 v43, v95, v96
	v_cvt_pk_bf16_f32 v45, v50, v51
	v_cvt_pk_bf16_f32 v46, v52, v53
	v_cvt_pk_bf16_f32 v47, v54, v55
	ds_read_b128 v[48:51], v82 offset:10240
	s_waitcnt lgkmcnt(0)
	v_mfma_f32_16x16x32_bf16 v[0:3], v[48:51], v[40:43], v[0:3]
	ds_read_b128 v[48:51], v82 offset:12800
	s_waitcnt lgkmcnt(0)
	v_mfma_f32_16x16x32_bf16 v[4:7], v[48:51], v[40:43], v[4:7]
	ds_read_b128 v[48:51], v82 offset:15360
	s_waitcnt lgkmcnt(0)
	v_mfma_f32_16x16x32_bf16 v[12:15], v[48:51], v[40:43], v[12:15]
	ds_read_b128 v[48:51], v82 offset:17920
	s_waitcnt lgkmcnt(0)
	v_mfma_f32_16x16x32_bf16 v[8:11], v[48:51], v[40:43], v[8:11]
	ds_read_b128 v[40:43], v82 offset:10304
	s_cmp_eq_u32 s2, 2
	s_waitcnt lgkmcnt(0)
	v_mfma_f32_16x16x32_bf16 v[0:3], v[40:43], v[44:47], v[0:3]
	ds_read_b128 v[40:43], v82 offset:12864
	s_waitcnt lgkmcnt(0)
	v_mfma_f32_16x16x32_bf16 v[4:7], v[40:43], v[44:47], v[4:7]
	ds_read_b128 v[40:43], v82 offset:15424
	s_waitcnt lgkmcnt(0)
	v_mfma_f32_16x16x32_bf16 v[12:15], v[40:43], v[44:47], v[12:15]
	ds_read_b128 v[40:43], v82 offset:17984
	s_waitcnt lgkmcnt(0)
	v_mfma_f32_16x16x32_bf16 v[8:11], v[40:43], v[44:47], v[8:11]
	s_cbranch_scc1 .LBB0_380
	s_cmp_gt_i32 s13, -1
	s_cselect_b64 s[0:1], -1, 0
	s_cmp_lt_i32 s13, 0
	s_barrier
	s_waitcnt vmcnt(1)
	ds_write_b128 v79, v[36:39]
	s_waitcnt vmcnt(0)
	ds_write_b128 v79, v[32:35] offset:5120
	ds_write_b128 v79, v[28:31] offset:10240
	ds_write_b128 v79, v[24:27] offset:15360
	s_waitcnt lgkmcnt(0)
	s_barrier
	s_cbranch_scc1 .LBB0_356
	s_add_u32 s16, s22, 0xc000
	s_addc_u32 s17, s23, 0
	v_lshl_add_u64 v[32:33], s[16:17], 0, v[60:61]
	v_lshl_add_u64 v[34:35], s[16:17], 0, v[62:63]
	global_load_dwordx4 v[36:39], v[32:33], off
	global_load_dwordx4 v[32:35], v[34:35], off

; __device__ __forceinline__ float fexp2(float x) { return __builtin_amdgcn_exp2f(x); }
; template <int NMAP, int NDT, int MODE, bool FIXED> ...
;     ...
;     __syncthreads();
;     *(uint4*)(sK + (lr) * LSTR + lch) = rk00;
;     *(uint4*)(sK + (lr + 32) * LSTR + lch) = rk01;
;     if (NMAP > 1) {
;       *(uint4*)(sK + (64 + lr) * LSTR + lch) = rk10;
;       *(uint4*)(sK + (64 + lr + 32) * LSTR + lch) = rk11;
;     }
;     *(uint4*)(sVt + (lr) * LSTR + lch) = rv0;
;     *(uint4*)(sVt + (lr + 32) * LSTR + lch) = rv1;
;     if (NVL > 2) {
;       *(uint4*)(sVt + (lr + 64) * LSTR + lch) = rv2;
;       *(uint4*)(sVt + (lr + 96) * LSTR + lch) = rv3;
;     }
;     __syncthreads();
;     const int knext = (MODE == 0) ? (n + 1) * 64 : ((n + 1) < 4 ? (n + 1) * 64 : seg_lo + (n + 1 - 4) * 64);
;     if (n + 1 < ntiles) {
;       ATTN_LOAD_K(knext)
;     }
;     ...
;         const float mnew = fmaxf(m[c], mx);
;         const float alpha = fexp2(m[c] - mnew);
;         m[c] = mnew;
;         float ls = 0.f;
; #pragma unroll
;         for (int kt = 0; kt < 4; ++kt)
; #pragma unroll
;           for (int e = 0; e < 4; ++e) {
;             s[kt][e] = fexp2(s[kt][e] - mnew);
;             ls += s[kt][e];
;           }
;         l[c] = l[c] * alpha + ls;
;         if (__ballot(alpha != 1.0f) != 0ull) {
; #pragma unroll
;           for (int dt = 0; dt < NDT; ++dt) o[c][dt] *= alpha;
;         }
;       }
;       __builtin_amdgcn_sched_barrier(0);
; #pragma unroll
;       for (int ks2 = 0; ks2 < 2; ++ks2) {
;         union { uint32_t u[4]; bf16x8 v; } pk;
;         pk.u[0] = pack2(s[2 * ks2][0], s[2 * ks2][1]);
;         pk.u[1] = pack2(s[2 * ks2][2], s[2 * ks2][3]);
;         pk.u[2] = pack2(s[2 * ks2 + 1][0], s[2 * ks2 + 1][1]);
;         pk.u[3] = pack2(s[2 * ks2 + 1][2], s[2 * ks2 + 1][3]);
;         pf[c][ks2] = pk.v;
;       }
;     }
;     if (n + 1 < ntiles) {
;       ATTN_LOAD_V(knext)
;     }
; #pragma unroll
;     for (int ks2 = 0; ks2 < 2; ++ks2) {
;       __builtin_amdgcn_sched_barrier(0);
; #pragma unroll
;       for (int dt = 0; dt < NDT; ++dt) {
;         const bf16x8 vf = *(const bf16x8*)(sVt + (dt * 16 + l15) * LSTR + 32 * ks2 + quad * 8);
; #pragma unroll
;         for (int c = 0; c < NMAP; ++c) o[c][dt] = __builtin_amdgcn_mfma_f32_16x16x32_bf16(vf, pf[c][ks2], o[c][dt], 0, 0, 0);
;       }
;     }
.LBB0_360:
	v_sub_f32_e32 v40, v40, v87
	v_exp_f32_e32 v66, v40
	v_sub_f32_e32 v40, v41, v87
	v_exp_f32_e32 v67, v40
	v_sub_f32_e32 v40, v42, v87
	v_exp_f32_e32 v68, v40
	v_sub_f32_e32 v40, v43, v87
	v_exp_f32_e32 v69, v40
	v_sub_f32_e32 v40, v44, v87
	v_exp_f32_e32 v89, v40
	v_sub_f32_e32 v40, v45, v87
	v_exp_f32_e32 v90, v40
	v_sub_f32_e32 v40, v46, v87
	v_exp_f32_e32 v91, v40
	v_sub_f32_e32 v40, v47, v87
	v_exp_f32_e32 v92, v40
	v_sub_f32_e32 v40, v48, v87
	v_exp_f32_e32 v48, v40
	v_sub_f32_e32 v40, v49, v87
	v_exp_f32_e32 v49, v40
	v_sub_f32_e32 v40, v50, v87
	v_exp_f32_e32 v50, v40
	v_sub_f32_e32 v40, v51, v87
	v_exp_f32_e32 v51, v40
	v_sub_f32_e32 v40, v52, v87
	v_exp_f32_e32 v52, v40
	v_sub_f32_e32 v40, v53, v87
	v_exp_f32_e32 v53, v40
	v_sub_f32_e32 v40, v54, v87
	v_exp_f32_e32 v54, v40
	v_sub_f32_e32 v40, v55, v87
	v_exp_f32_e32 v55, v40
	v_cvt_pk_bf16_f32 v40, v66, v67
	v_add_f32_e32 v66, 0, v66
	v_add_f32_e32 v66, v67, v66
	v_add_f32_e32 v66, v68, v66
	v_add_f32_e32 v66, v69, v66
	v_add_f32_e32 v66, v89, v66
	v_add_f32_e32 v66, v90, v66
	v_add_f32_e32 v66, v91, v66
	v_add_f32_e32 v66, v92, v66
	v_cvt_pk_bf16_f32 v44, v48, v49
	v_add_f32_e32 v48, v48, v66
	v_add_f32_e32 v48, v49, v48
	v_add_f32_e32 v48, v50, v48
	v_add_f32_e32 v48, v51, v48
	v_add_f32_e32 v48, v52, v48
	v_add_f32_e32 v48, v53, v48
	v_add_f32_e32 v48, v54, v48
	v_cvt_pk_bf16_f32 v41, v68, v69
	v_add_f32_e32 v68, v55, v48
	v_fmac_f32_e32 v68, v88, v70
	v_cvt_pk_bf16_f32 v42, v89, v90
	v_cvt_pk_bf16_f32 v43, v91, v92
	v_cvt_pk_bf16_f32 v45, v50, v51
	v_cvt_pk_bf16_f32 v46, v52, v53
	v_cvt_pk_bf16_f32 v47, v54, v55
	ds_read_b128 v[48:51], v82 offset:10240
	s_waitcnt lgkmcnt(0)
	v_mfma_f32_16x16x32_bf16 v[0:3], v[48:51], v[40:43], v[0:3]
	ds_read_b128 v[48:51], v82 offset:12800
	s_waitcnt lgkmcnt(0)
	v_mfma_f32_16x16x32_bf16 v[4:7], v[48:51], v[40:43], v[4:7]
	ds_read_b128 v[48:51], v82 offset:15360
	s_waitcnt lgkmcnt(0)
	v_mfma_f32_16x16x32_bf16 v[12:15], v[48:51], v[40:43], v[12:15]
	ds_read_b128 v[48:51], v82 offset:17920
	s_waitcnt lgkmcnt(0)
	v_mfma_f32_16x16x32_bf16 v[8:11], v[48:51], v[40:43], v[8:11]
	ds_read_b128 v[40:43], v82 offset:10304
	s_cmp_eq_u32 s2, 3
	s_waitcnt lgkmcnt(0)
	v_mfma_f32_16x16x32_bf16 v[0:3], v[40:43], v[44:47], v[0:3]
	ds_read_b128 v[40:43], v82 offset:12864
	s_waitcnt lgkmcnt(0)
	v_mfma_f32_16x16x32_bf16 v[4:7], v[40:43], v[44:47], v[4:7]
	ds_read_b128 v[40:43], v82 offset:15424
	s_waitcnt lgkmcnt(0)
	v_mfma_f32_16x16x32_bf16 v[12:15], v[40:43], v[44:47], v[12:15]
	ds_read_b128 v[40:43], v82 offset:17984
	s_waitcnt lgkmcnt(0)
	v_mfma_f32_16x16x32_bf16 v[8:11], v[40:43], v[44:47], v[8:11]
	s_cbranch_scc1 .LBB0_379
	s_addk_i32 s4, 0xff80
	s_and_b64 s[0:1], s[26:27], exec
	s_cselect_b32 s4, s4, 0x100
	s_cmp_lg_u32 s13, 0
	s_cselect_b64 s[26:27], -1, 0
	s_cmp_eq_u32 s13, 0
	s_barrier
	s_waitcnt vmcnt(1)
	ds_write_b128 v79, v[36:39]
	s_waitcnt vmcnt(0)
	ds_write_b128 v79, v[32:35] offset:5120
	ds_write_b128 v79, v[28:31] offset:10240
	ds_write_b128 v79, v[24:27] offset:15360
	s_waitcnt lgkmcnt(0)
	s_barrier
	s_cbranch_scc1 .LBB0_363
	s_lshl_b64 s[0:1], s[4:5], 8
	s_add_u32 s0, s22, s0
	s_addc_u32 s1, s23, s1
	v_lshl_add_u64 v[32:33], s[0:1], 0, v[60:61]
	v_lshl_add_u64 v[34:35], s[0:1], 0, v[62:63]
	global_load_dwordx4 v[36:39], v[32:33], off
	global_load_dwordx4 v[32:35], v[34:35], off

; template <int NMAP, int NDT, int MODE, bool FIXED> ...
;     ...
;     if (n + 1 < ntiles) {
;       ATTN_LOAD_V(knext)
;     }
.LBB0_365:
	v_cndmask_b32_e64 v69, 0, 1, s[26:27]
	v_cmp_ne_u32_e64 s[0:1], 1, v69
	s_andn2_b64 vcc, exec, s[26:27]
	s_cbranch_vccnz .LBB0_367
	s_lshl_b64 s[16:17], s[4:5], 1
	s_add_u32 s16, s24, s16
	s_addc_u32 s17, s25, s17
	v_lshl_add_u64 v[24:25], s[16:17], 0, v[56:57]
	v_lshl_add_u64 v[26:27], s[16:17], 0, v[64:65]
	global_load_dwordx4 v[28:31], v[24:25], off
	global_load_dwordx4 v[24:27], v[26:27], off

; template <int NMAP, int NDT, int MODE, bool FIXED> ...
;     ...
;   for (int n = 0; n < ntiles; ++n) {
;     const int kidx0 = (MODE == 0) ? n * 64 : (n < 4 ? n * 64 : seg_lo + (n - 4) * 64);
;     __syncthreads();
;     *(uint4*)(sK + (lr) * LSTR + lch) = rk00;
;     *(uint4*)(sK + (lr + 32) * LSTR + lch) = rk01;
;     if (NMAP > 1) {
;       *(uint4*)(sK + (64 + lr) * LSTR + lch) = rk10;
;       *(uint4*)(sK + (64 + lr + 32) * LSTR + lch) = rk11;
;     }
;     *(uint4*)(sVt + (lr) * LSTR + lch) = rv0;
;     *(uint4*)(sVt + (lr + 32) * LSTR + lch) = rv1;
;     if (NVL > 2) {
;       *(uint4*)(sVt + (lr + 64) * LSTR + lch) = rv2;
;       *(uint4*)(sVt + (lr + 96) * LSTR + lch) = rv3;
;     }
;     __syncthreads();
;     const int knext = (MODE == 0) ? (n + 1) * 64 : ((n + 1) < 4 ? (n + 1) * 64 : seg_lo + (n + 1 - 4) * 64);
;     if (n + 1 < ntiles) {
;       ATTN_LOAD_K(knext)
;     }
.LBB0_369:
	s_add_i32 s1, s3, 5
	s_cmp_lt_i32 s1, s2
	s_cselect_b64 s[26:27], -1, 0
	s_cmp_ge_i32 s1, s2
	s_barrier
	s_waitcnt vmcnt(1)
	ds_write_b128 v79, v[36:39]
	s_waitcnt vmcnt(0)
	ds_write_b128 v79, v[32:35] offset:5120
	ds_write_b128 v79, v[28:31] offset:10240
	ds_write_b128 v79, v[24:27] offset:15360
	s_waitcnt lgkmcnt(0)
	s_barrier
	s_cbranch_scc1 .LBB0_371
	s_ashr_i32 s1, s0, 31
	s_lshl_b64 s[16:17], s[0:1], 8
	s_add_u32 s16, s22, s16
	s_addc_u32 s17, s23, s17
	v_lshl_add_u64 v[32:33], s[16:17], 0, v[60:61]
	v_lshl_add_u64 v[34:35], s[16:17], 0, v[62:63]
	global_load_dwordx4 v[36:39], v[32:33], off
	global_load_dwordx4 v[32:35], v[34:35], off

; template <int NMAP, int NDT, int MODE, bool FIXED> ...
;     ...
;     if (n + 1 < ntiles) {
;       ATTN_LOAD_V(knext)
;     }
.LBB0_373:
	s_andn2_b64 vcc, exec, s[26:27]
	s_cbranch_vccnz .LBB0_375
	s_ashr_i32 s1, s0, 31
	s_lshl_b64 s[16:17], s[0:1], 1
	s_add_u32 s16, s24, s16
	s_addc_u32 s17, s25, s17
	v_lshl_add_u64 v[24:25], s[16:17], 0, v[56:57]
	v_lshl_add_u64 v[26:27], s[16:17], 0, v[64:65]
	global_load_dwordx4 v[28:31], v[24:25], off
	global_load_dwordx4 v[24:27], v[26:27], off

;   __device__ __forceinline__ void operator()(const f32x4 (&acc)[4][4], int row0w, int col0w, int l15, int quad) const {
; #pragma unroll
;     for (int i = 0; i < 4; ++i) {
;       const int row = row0w + i * 16 + l15;
;       const int b = row / TPB, kidx = row - b * TPB;
;       const bool isc = kidx < 256;
;       const size_t off = isc ? (size_t)(b * 256 + kidx) * DM : (size_t)(b * 16384 + kidx - 256) * DM;
;       const float* src = (isc ? ctx_src : lat_src) + off;
;       float* dst = (isc ? ctx_dst : lat_dst) + off;
;       const float* g = gate + (isc ? 2 : b) * 6144;
; #pragma unroll
;       for (int j = 0; j < 4; ++j) {
;         const int n = col0w + j * 16 + quad * 4;
;         const float4 xo = *(const float4*)(src + n);
;         const float4 g4 = *(const float4*)(g + n);
;         float4 o;
;         o.x = xo.x + g4.x * acc[i][j][0];
;         o.y = xo.y + g4.y * acc[i][j][1];
;         o.z = xo.z + g4.z * acc[i][j][2];
;         o.w = xo.w + g4.w * acc[i][j][3];
;         *(float4*)(dst + n) = o;
;       }
;     }
.LBB0_435:
	s_or_b64 exec, exec, s[0:1]
	v_mul_i32_i24_e32 v19, 0x1800, v19
	v_cndmask_b32_e32 v22, v19, v184, vcc
	v_ashrrev_i32_e32 v19, 31, v18
	v_lshlrev_b64 v[18:19], 12, v[18:19]
	v_ashrrev_i32_e32 v23, 31, v22
	v_lshl_add_u64 v[16:17], v[16:17], 0, v[18:19]
	v_lshl_add_u64 v[18:19], v[20:21], 0, v[18:19]
	v_lshl_add_u64 v[20:21], v[22:23], 2, s[6:7]
	v_lshl_add_u64 v[24:25], v[16:17], 0, v[64:65]
	v_lshl_add_u64 v[26:27], v[20:21], 0, v[64:65]
	v_lshl_add_u64 v[28:29], v[18:19], 0, v[64:65]
	global_load_dwordx4 v[16:19], v[24:25], off
	global_load_dwordx4 v[20:23], v[26:27], off
	s_add_i32 s22, s22, s90
	s_add_i32 s2, s2, s90
	s_cmp_ge_i32 s22, s84
	s_waitcnt vmcnt(0)
	v_pk_fma_f32 v[12:13], v[12:13], v[20:21], v[16:17]
	v_pk_fma_f32 v[14:15], v[14:15], v[22:23], v[18:19]
	global_store_dwordx4 v[28:29], v[12:15], off
	global_load_dwordx4 v[12:15], v[24:25], off offset:64
	global_load_dwordx4 v[16:19], v[26:27], off offset:64
	s_waitcnt vmcnt(0)
	v_pk_fma_f32 v[8:9], v[8:9], v[16:17], v[12:13]
	v_pk_fma_f32 v[10:11], v[10:11], v[18:19], v[14:15]
	global_store_dwordx4 v[28:29], v[8:11], off offset:64
	global_load_dwordx4 v[8:11], v[24:25], off offset:128
	global_load_dwordx4 v[12:15], v[26:27], off offset:128
	s_waitcnt vmcnt(0)
	v_pk_fma_f32 v[4:5], v[4:5], v[12:13], v[8:9]
	v_pk_fma_f32 v[6:7], v[6:7], v[14:15], v[10:11]
	global_store_dwordx4 v[28:29], v[4:7], off offset:128
	global_load_dwordx4 v[4:7], v[24:25], off offset:192
	global_load_dwordx4 v[8:11], v[26:27], off offset:192
	s_waitcnt vmcnt(0)
	v_pk_fma_f32 v[0:1], v[0:1], v[8:9], v[4:5]
	v_pk_fma_f32 v[2:3], v[2:3], v[10:11], v[6:7]
	global_store_dwordx4 v[28:29], v[0:3], off offset:192
	s_cbranch_scc1 .LBB0_456

; template <bool DEEP, class Epi>
; __device__ __forceinline__ void gemm_phase(const bf16_t* __restrict__ A, int lda, const bf16_t* __restrict__ Wt,
;                                            int K, int ntn, bool lat_only, const Epi& epi, char* smem) {
;     ...
;     for (int kt = 0; kt < nk; ++kt) {
;       __syncthreads();
;       GEMM_STORE(ra0, ra1, ra2, ra3, rb0, rb1, rb2, rb3, 0)
;       __syncthreads();
;       {
;         bf16x8 af0[4], bf0[4], af1[4], bf1[4];
;         __builtin_amdgcn_s_setprio(1);
; #pragma unroll
;         for (int i = 0; i < 4; ++i) af0[i] = *(const bf16x8*)(sA + (wm * 64 + i * 16 + l15) * LSTR + quad * 8);
; #pragma unroll
;         for (int j = 0; j < 4; ++j) bf0[j] = *(const bf16x8*)(sB + (wn * 64 + j * 16 + l15) * LSTR + quad * 8);
; #pragma unroll
;         for (int i = 0; i < 4; ++i) af1[i] = *(const bf16x8*)(sA + (wm * 64 + i * 16 + l15) * LSTR + 32 + quad * 8);
; #pragma unroll
;         for (int j = 0; j < 4; ++j) bf1[j] = *(const bf16x8*)(sB + (wn * 64 + j * 16 + l15) * LSTR + 32 + quad * 8);
;         __builtin_amdgcn_sched_barrier(0);
;         if (kt + 1 < nk) GEMM_LOAD(ra0, ra1, ra2, ra3, rb0, rb1, rb2, rb3, (kt + 1) * 64)
;         __builtin_amdgcn_sched_barrier(0);
;   __device__ __forceinline__ void operator()(const f32x4 (&acc)[4][4], int row0w, int col0w, int l15, int quad) const {
;     ...
;     for (int i = 0; i < 4; ++i) {
;       const int row = row0w + i * 16 + l15;
;       const int b = row / TPB, kidx = row - b * TPB;
;       const bool isc = kidx < 256;
;       const size_t off = isc ? (size_t)(b * 256 + kidx) * DM : (size_t)(b * 16384 + kidx - 256) * DM;
;       const float* src = (isc ? ctx_src : lat_src) + off;
;       float* dst = (isc ? ctx_dst : lat_dst) + off;
;       const float* g = gate + (isc ? 2 : b) * 6144;
; #pragma unroll
;       for (int j = 0; j < 4; ++j) {
;         const int n = col0w + j * 16 + quad * 4;
;         const float4 xo = *(const float4*)(src + n);
;         const float4 g4 = *(const float4*)(g + n);
;         float4 o;
;         o.x = xo.x + g4.x * acc[i][j][0];
;         o.y = xo.y + g4.y * acc[i][j][1];
;         o.z = xo.z + g4.z * acc[i][j][2];
;         o.w = xo.w + g4.w * acc[i][j][3];
;         *(float4*)(dst + n) = o;
;       }
.LBB0_438:
	s_waitcnt vmcnt(63) expcnt(7) lgkmcnt(15)
	s_barrier
	s_waitcnt vmcnt(0)
	ds_write_b128 v161, v[64:67]
	ds_write_b128 v161, v[68:71] offset:5120
	ds_write_b128 v161, v[80:83] offset:10240
	ds_write_b128 v161, v[88:91] offset:15360
	ds_write_b128 v161, v[72:75] offset:20480
	ds_write_b128 v161, v[76:79] offset:25600
	ds_write_b128 v161, v[84:87] offset:30720
	ds_write_b128 v161, v[92:95] offset:35840
	v_add_u32_e32 v96, v175, v178
	s_waitcnt lgkmcnt(0)
	s_barrier
	s_setprio 1
	ds_read_b128 v[156:159], v96
	ds_read_b128 v[152:155], v96 offset:2560
	ds_read_b128 v[132:135], v96 offset:5120
	ds_read_b128 v[124:127], v96 offset:7680
	ds_read_b128 v[136:139], v180 offset:20480
	ds_read_b128 v[140:143], v180 offset:23040
	ds_read_b128 v[144:147], v180 offset:25600
	ds_read_b128 v[148:151], v180 offset:28160
	ds_read_b128 v[128:131], v182 offset:64
	ds_read_b128 v[120:123], v182 offset:2624
	ds_read_b128 v[100:103], v182 offset:5184
	ds_read_b128 v[96:99], v182 offset:7744
	ds_read_b128 v[104:107], v183 offset:20544
	ds_read_b128 v[108:111], v183 offset:23104
	ds_read_b128 v[112:115], v183 offset:25664
	ds_read_b128 v[116:119], v183 offset:28224
	s_cmp_gt_u32 s1, 14
	s_cbranch_scc1 .LBB0_437
	v_lshl_add_u64 v[72:73], v[170:171], 0, s[12:13]
	v_add_co_u32_e32 v64, vcc, 0x1d00000, v72
	v_lshl_add_u64 v[84:85], v[172:173], 0, s[12:13]
	s_nop 0
	v_addc_co_u32_e32 v65, vcc, 0, v73, vcc
	v_add_co_u32_e32 v68, vcc, 0x1d10000, v72
	s_nop 1
	v_addc_co_u32_e32 v69, vcc, 0, v73, vcc
	v_add_co_u32_e32 v74, vcc, 0x1d20000, v72
	global_load_dwordx4 v[64:67], v[64:65], off offset:128
	global_load_dwordx4 v[68:71], v[68:69], off offset:128
	v_addc_co_u32_e32 v75, vcc, 0, v73, vcc
	v_add_co_u32_e32 v72, vcc, 0x1d30000, v72
	s_nop 1
	v_addc_co_u32_e32 v73, vcc, 0, v73, vcc
	global_load_dwordx4 v[80:83], v[74:75], off offset:128
	global_load_dwordx4 v[88:91], v[72:73], off offset:128
	v_add_co_u32_e32 v72, vcc, 0x680000, v84
	s_nop 1
	v_addc_co_u32_e32 v73, vcc, 0, v85, vcc
	v_add_co_u32_e32 v76, vcc, 0x690000, v84
	s_nop 1
	v_addc_co_u32_e32 v77, vcc, 0, v85, vcc
	v_add_co_u32_e32 v86, vcc, 0x6a0000, v84
	global_load_dwordx4 v[72:75], v[72:73], off offset:128
	global_load_dwordx4 v[76:79], v[76:77], off offset:128
	v_addc_co_u32_e32 v87, vcc, 0, v85, vcc
	v_add_co_u32_e32 v92, vcc, 0x6b0000, v84
	s_nop 1
	v_addc_co_u32_e32 v93, vcc, 0, v85, vcc
	global_load_dwordx4 v[84:87], v[86:87], off offset:128
	global_load_dwordx4 v[92:95], v[92:93], off offset:128
	s_branch .LBB0_437
.LBB0_440:
	s_waitcnt vmcnt(6)
	v_add_u32_e32 v70, s0, v174
	v_mul_hi_i32 v64, v70, s11
	v_lshrrev_b32_e32 v65, 31, v64
	v_ashrrev_i32_e32 v64, 13, v64
	v_add_u32_e32 v71, v64, v65
	v_mad_i32_i24 v67, v71, s16, v70
	v_cmp_gt_i32_e32 vcc, s17, v67
	v_cmp_lt_i32_e64 s[0:1], s18, v67
	v_mov_b64_e32 v[64:65], s[40:41]
	s_and_saveexec_b64 s[12:13], s[0:1]
	s_xor_b64 s[0:1], exec, s[12:13]
	v_lshlrev_b32_e32 v64, 14, v71
	v_add3_u32 v66, v64, v67, s19
	v_mov_b64_e32 v[64:65], s[36:37]
	s_or_saveexec_b64 s[0:1], s[0:1]
	v_mov_b64_e32 v[68:69], s[92:93]
	s_xor_b64 exec, exec, s[0:1]
	v_lshl_add_u32 v66, v71, 8, v67
	v_mov_b64_e32 v[68:69], s[68:69]
	s_or_b64 exec, exec, s[0:1]
	v_ashrrev_i32_e32 v67, 31, v66
	v_lshlrev_b64 v[66:67], 12, v[66:67]
	s_waitcnt vmcnt(3)
	v_lshl_add_u64 v[74:75], v[64:65], 0, v[66:67]
	v_mul_i32_i24_e32 v64, 0x1800, v71
	v_or_b32_e32 v72, s8, v176
	v_cndmask_b32_e32 v64, v64, v184, vcc
	v_ashrrev_i32_e32 v73, 31, v72
	v_ashrrev_i32_e32 v65, 31, v64
	v_lshl_add_u64 v[66:67], v[68:69], 0, v[66:67]
	v_lshl_add_u64 v[68:69], v[64:65], 2, s[6:7]
	v_lshlrev_b64 v[64:65], 2, v[72:73]
	s_waitcnt vmcnt(2)
	v_lshl_add_u64 v[76:77], v[74:75], 0, v[64:65]
	v_lshl_add_u64 v[78:79], v[68:69], 0, v[64:65]
	v_lshl_add_u64 v[80:81], v[66:67], 0, v[64:65]
	global_load_dwordx4 v[66:69], v[76:77], off
	global_load_dwordx4 v[72:75], v[78:79], off
	s_waitcnt vmcnt(0)
	v_pk_fma_f32 v[60:61], v[60:61], v[72:73], v[66:67]
	v_pk_fma_f32 v[62:63], v[62:63], v[74:75], v[68:69]
	global_store_dwordx4 v[80:81], v[60:63], off
	global_load_dwordx4 v[60:63], v[76:77], off offset:64
	global_load_dwordx4 v[66:69], v[78:79], off offset:64
	s_waitcnt vmcnt(0)
	v_pk_fma_f32 v[56:57], v[56:57], v[66:67], v[60:61]
	v_pk_fma_f32 v[58:59], v[58:59], v[68:69], v[62:63]
	global_store_dwordx4 v[80:81], v[56:59], off offset:64
	global_load_dwordx4 v[56:59], v[76:77], off offset:128
	global_load_dwordx4 v[60:63], v[78:79], off offset:128
	s_waitcnt vmcnt(0)
	v_pk_fma_f32 v[52:53], v[52:53], v[60:61], v[56:57]
	v_pk_fma_f32 v[54:55], v[54:55], v[62:63], v[58:59]
	global_store_dwordx4 v[80:81], v[52:55], off offset:128
	global_load_dwordx4 v[52:55], v[76:77], off offset:192
	global_load_dwordx4 v[56:59], v[78:79], off offset:192
	s_waitcnt vmcnt(0)
;   __device__ __forceinline__ void operator()(const f32x4 (&acc)[4][4], int row0w, int col0w, int l15, int quad) const {
;     ...
;     for (int i = 0; i < 4; ++i) {
;       const int row = row0w + i * 16 + l15;
;       const int b = row / TPB, kidx = row - b * TPB;
;       const bool isc = kidx < 256;
;       const size_t off = isc ? (size_t)(b * 256 + kidx) * DM : (size_t)(b * 16384 + kidx - 256) * DM;
;       const float* src = (isc ? ctx_src : lat_src) + off;
;       float* dst = (isc ? ctx_dst : lat_dst) + off;
;       const float* g = gate + (isc ? 2 : b) * 6144;
; #pragma unroll
;       for (int j = 0; j < 4; ++j) {
;         const int n = col0w + j * 16 + quad * 4;
;         const float4 xo = *(const float4*)(src + n);
;         const float4 g4 = *(const float4*)(g + n);
;         float4 o;
;         o.x = xo.x + g4.x * acc[i][j][0];
;         o.y = xo.y + g4.y * acc[i][j][1];
;         o.z = xo.z + g4.z * acc[i][j][2];
;         o.w = xo.w + g4.w * acc[i][j][3];
;         *(float4*)(dst + n) = o;
;       }
	v_pk_fma_f32 v[48:49], v[48:49], v[56:57], v[52:53]
	v_pk_fma_f32 v[50:51], v[50:51], v[58:59], v[54:55]
	global_store_dwordx4 v[80:81], v[48:51], off offset:192
	s_nop 1
	v_or_b32_e32 v48, 16, v70
	v_mul_hi_i32 v49, v48, s11
	v_lshrrev_b32_e32 v50, 31, v49
	v_ashrrev_i32_e32 v49, 13, v49
	v_add_u32_e32 v54, v49, v50
	v_mad_i32_i24 v51, v54, s16, v48
	v_cmp_gt_i32_e32 vcc, s17, v51
	v_cmp_lt_i32_e64 s[0:1], s18, v51
	v_mov_b64_e32 v[48:49], s[40:41]
	s_and_saveexec_b64 s[8:9], s[0:1]
	s_xor_b64 s[0:1], exec, s[8:9]
	v_lshlrev_b32_e32 v48, 14, v54
	v_add3_u32 v50, v48, v51, s19
	v_mov_b64_e32 v[48:49], s[36:37]
	s_or_saveexec_b64 s[0:1], s[0:1]
	v_mov_b64_e32 v[52:53], s[92:93]
	s_xor_b64 exec, exec, s[0:1]
	v_lshl_add_u32 v50, v54, 8, v51
	v_mov_b64_e32 v[52:53], s[68:69]
	s_or_b64 exec, exec, s[0:1]
	v_ashrrev_i32_e32 v51, 31, v50
	v_mul_i32_i24_e32 v54, 0x1800, v54
	v_lshlrev_b64 v[50:51], 12, v[50:51]
	v_cndmask_b32_e32 v54, v54, v184, vcc
	v_lshl_add_u64 v[48:49], v[48:49], 0, v[50:51]
	v_ashrrev_i32_e32 v55, 31, v54
	v_lshl_add_u64 v[50:51], v[52:53], 0, v[50:51]
	v_lshl_add_u64 v[52:53], v[54:55], 2, s[6:7]
	v_lshl_add_u64 v[56:57], v[48:49], 0, v[64:65]
	v_lshl_add_u64 v[58:59], v[52:53], 0, v[64:65]
	v_lshl_add_u64 v[60:61], v[50:51], 0, v[64:65]
	global_load_dwordx4 v[48:51], v[56:57], off
	global_load_dwordx4 v[52:55], v[58:59], off
	s_waitcnt vmcnt(0)
	v_pk_fma_f32 v[44:45], v[44:45], v[52:53], v[48:49]
	v_pk_fma_f32 v[46:47], v[46:47], v[54:55], v[50:51]
	global_store_dwordx4 v[60:61], v[44:47], off
	global_load_dwordx4 v[44:47], v[56:57], off offset:64
	global_load_dwordx4 v[48:51], v[58:59], off offset:64
	s_waitcnt vmcnt(0)
	v_pk_fma_f32 v[40:41], v[40:41], v[48:49], v[44:45]
	v_pk_fma_f32 v[42:43], v[42:43], v[50:51], v[46:47]
	global_store_dwordx4 v[60:61], v[40:43], off offset:64
	global_load_dwordx4 v[40:43], v[56:57], off offset:128
	global_load_dwordx4 v[44:47], v[58:59], off offset:128
	s_waitcnt vmcnt(0)
	v_pk_fma_f32 v[36:37], v[36:37], v[44:45], v[40:41]
	v_pk_fma_f32 v[38:39], v[38:39], v[46:47], v[42:43]
	global_store_dwordx4 v[60:61], v[36:39], off offset:128
	global_load_dwordx4 v[36:39], v[56:57], off offset:192
	global_load_dwordx4 v[40:43], v[58:59], off offset:192
	s_waitcnt vmcnt(0)
	v_pk_fma_f32 v[32:33], v[32:33], v[40:41], v[36:37]
	v_pk_fma_f32 v[34:35], v[34:35], v[42:43], v[38:39]
	global_store_dwordx4 v[60:61], v[32:35], off offset:192
	s_nop 1
	v_or_b32_e32 v32, 32, v70
	v_mul_hi_i32 v33, v32, s11
	v_lshrrev_b32_e32 v34, 31, v33
	v_ashrrev_i32_e32 v33, 13, v33
	v_add_u32_e32 v38, v33, v34
	v_mad_i32_i24 v35, v38, s16, v32
	v_cmp_gt_i32_e32 vcc, s17, v35
	v_cmp_lt_i32_e64 s[0:1], s18, v35
	v_mov_b64_e32 v[32:33], s[40:41]
	s_and_saveexec_b64 s[8:9], s[0:1]
	s_xor_b64 s[0:1], exec, s[8:9]
	v_lshlrev_b32_e32 v32, 14, v38
	v_add3_u32 v34, v32, v35, s19
	v_mov_b64_e32 v[32:33], s[36:37]
	s_or_saveexec_b64 s[0:1], s[0:1]
	v_mov_b64_e32 v[36:37], s[92:93]
	s_xor_b64 exec, exec, s[0:1]
	v_lshl_add_u32 v34, v38, 8, v35
	v_mov_b64_e32 v[36:37], s[68:69]
	s_or_b64 exec, exec, s[0:1]
	v_ashrrev_i32_e32 v35, 31, v34
	v_mul_i32_i24_e32 v38, 0x1800, v38
	v_lshlrev_b64 v[34:35], 12, v[34:35]
	v_cndmask_b32_e32 v38, v38, v184, vcc
	v_lshl_add_u64 v[32:33], v[32:33], 0, v[34:35]
	v_ashrrev_i32_e32 v39, 31, v38
	v_lshl_add_u64 v[34:35], v[36:37], 0, v[34:35]
	v_lshl_add_u64 v[36:37], v[38:39], 2, s[6:7]
	v_lshl_add_u64 v[40:41], v[32:33], 0, v[64:65]
	v_lshl_add_u64 v[42:43], v[36:37], 0, v[64:65]
	v_lshl_add_u64 v[44:45], v[34:35], 0, v[64:65]
	global_load_dwordx4 v[32:35], v[40:41], off
	global_load_dwordx4 v[36:39], v[42:43], off
	s_waitcnt vmcnt(0)
	v_pk_fma_f32 v[28:29], v[28:29], v[36:37], v[32:33]
	v_pk_fma_f32 v[30:31], v[30:31], v[38:39], v[34:35]
	global_store_dwordx4 v[44:45], v[28:31], off
	global_load_dwordx4 v[28:31], v[40:41], off offset:64
	global_load_dwordx4 v[32:35], v[42:43], off offset:64
	s_waitcnt vmcnt(0)
	v_pk_fma_f32 v[24:25], v[24:25], v[32:33], v[28:29]
	v_pk_fma_f32 v[26:27], v[26:27], v[34:35], v[30:31]
	global_store_dwordx4 v[44:45], v[24:27], off offset:64
	global_load_dwordx4 v[24:27], v[40:41], off offset:128
	global_load_dwordx4 v[28:31], v[42:43], off offset:128
	s_waitcnt vmcnt(0)
	v_pk_fma_f32 v[20:21], v[20:21], v[28:29], v[24:25]
	v_pk_fma_f32 v[22:23], v[22:23], v[30:31], v[26:27]
	global_store_dwordx4 v[44:45], v[20:23], off offset:128
	global_load_dwordx4 v[20:23], v[40:41], off offset:192
	global_load_dwordx4 v[24:27], v[42:43], off offset:192
	s_waitcnt vmcnt(0)
	v_pk_fma_f32 v[16:17], v[16:17], v[24:25], v[20:21]
	v_pk_fma_f32 v[18:19], v[18:19], v[26:27], v[22:23]
	global_store_dwordx4 v[44:45], v[16:19], off offset:192
	s_nop 1
	v_or_b32_e32 v16, 48, v70
	v_mul_hi_i32 v17, v16, s11
	v_lshrrev_b32_e32 v18, 31, v17
	v_ashrrev_i32_e32 v17, 13, v17
	v_add_u32_e32 v19, v17, v18
	v_mad_i32_i24 v22, v19, s16, v16
	v_cmp_gt_i32_e32 vcc, s17, v22
	v_cmp_lt_i32_e64 s[0:1], s18, v22
	v_mov_b64_e32 v[16:17], s[40:41]
	s_and_saveexec_b64 s[8:9], s[0:1]
	s_xor_b64 s[0:1], exec, s[8:9]
	v_lshlrev_b32_e32 v16, 14, v19
	v_add3_u32 v18, v16, v22, s19
	v_mov_b64_e32 v[16:17], s[36:37]
	s_or_saveexec_b64 s[0:1], s[0:1]
	v_mov_b64_e32 v[20:21], s[92:93]
	s_xor_b64 exec, exec, s[0:1]
	s_cbranch_execz .LBB0_435
	v_lshl_add_u32 v18, v19, 8, v22
	v_mov_b64_e32 v[20:21], s[68:69]
	s_branch .LBB0_435

; __device__ __forceinline__ void phase_norm(const float* lat_src, const float* ctx_src, const float* gain, const float* modl,
;                                            int sh_off, int sc_off, bf16_t* A, bool lat_only) {
;     ...
;   for (int idx0 = (blockIdx.x * 4 + wave) * 2; idx0 < total; idx0 += gridDim.x * 8) {
;     float4 xv[2][4];
;     const float* md[2];
;     int rowi[2];
; #pragma unroll
;     for (int u = 0; u < 2; ++u) {
;       const int idx = idx0 + u;
;       const int row = lat_only ? ((idx >> 14) * TPB + 256 + (idx & 16383)) : idx;
;       const int b = row / TPB, kidx = row - b * TPB;
;       const bool isc = kidx < 256;
;       const float* src = isc ? ctx_src + (size_t)(b * 256 + kidx) * DM : lat_src + (size_t)(b * 16384 + kidx - 256) * DM;
;       md[u] = modl + (isc ? 2 : b) * 6144;
;       rowi[u] = row;
; #pragma unroll
;       for (int i = 0; i < 4; ++i) xv[u][i] = *(const float4*)(src + i * 256 + lane * 4);
;     }
; #pragma unroll
;     for (int u = 0; u < 2; ++u) {
;       float ss = 0.f;
; #pragma unroll
;       for (int i = 0; i < 4; ++i) ss += xv[u][i].x * xv[u][i].x + xv[u][i].y * xv[u][i].y + xv[u][i].z * xv[u][i].z + xv[u][i].w * xv[u][i].w;
;       ss = wave_sum(ss);
;       const float rstd = rsqrtf(ss * (1.0f / 1024.0f) + 1e-6f);
; #pragma unroll
;       for (int i = 0; i < 4; ++i) {
;         const int c = i * 256 + lane * 4;
;         const float4 g = *(const float4*)(gain + c);
;         const float4 sh = *(const float4*)(md[u] + sh_off + c);
;         const float4 sc = *(const float4*)(md[u] + sc_off + c);
;         uint2 w;
;         w.x = pack2(xv[u][i].x * rstd * g.x * (1.f + sc.x) + sh.x, xv[u][i].y * rstd * g.y * (1.f + sc.y) + sh.y);
;         w.y = pack2(xv[u][i].z * rstd * g.z * (1.f + sc.z) + sh.z, xv[u][i].w * rstd * g.w * (1.f + sc.w) + sh.w);
;         *(uint2*)(A + (size_t)rowi[u] * DM + c) = w;
;       }
;     }
;   }
.LBB0_510:
	s_or_b64 exec, exec, s[2:3]
	v_lshl_add_u64 v[8:9], v[8:9], 0, v[32:33]
	global_load_dwordx4 v[28:31], v[8:9], off
	global_load_dwordx4 v[20:23], v[8:9], off offset:1024
	global_load_dwordx4 v[16:19], v[8:9], off offset:2048
	global_load_dwordx4 v[8:11], v[8:9], off offset:3072
	v_lshl_add_u64 v[52:53], v[52:53], 2, s[14:15]
	s_waitcnt vmcnt(7)
	v_mov_b32_e32 v66, v25
	s_waitcnt vmcnt(6)
	v_mov_b32_e32 v67, v13
	s_waitcnt vmcnt(5)
	v_mov_b32_e32 v74, v5
	s_waitcnt vmcnt(4)
	v_mov_b32_e32 v75, v1
	v_mov_b32_e32 v64, v24
	v_mov_b32_e32 v65, v12
	v_mov_b32_e32 v70, v4
	v_mov_b32_e32 v71, v0
	v_pk_mul_f32 v[66:67], v[66:67], v[66:67]
	v_pk_mul_f32 v[74:75], v[74:75], v[74:75]
	v_lshl_add_u64 v[80:81], v[52:53], 0, s[8:9]
	v_mov_b32_e32 v68, v26
	v_mov_b32_e32 v69, v14
	v_mov_b32_e32 v76, v6
	v_mov_b32_e32 v77, v2
	v_lshl_add_u64 v[52:53], v[52:53], 0, s[12:13]
	v_pk_fma_f32 v[64:65], v[64:65], v[64:65], v[66:67]
	v_pk_fma_f32 v[66:67], v[70:71], v[70:71], v[74:75]
	v_lshl_add_u64 v[70:71], v[80:81], 0, v[32:33]
	global_load_dwordx4 v[60:63], v[34:35], off
	v_lshl_add_u64 v[74:75], v[52:53], 0, v[32:33]
	v_pk_fma_f32 v[82:83], v[68:69], v[68:69], v[64:65]
	v_pk_fma_f32 v[76:77], v[76:77], v[76:77], v[66:67]
	global_load_dwordx4 v[64:67], v[70:71], off
	global_load_dwordx4 v[68:71], v[74:75], off
	v_mov_b32_e32 v72, v27
	v_mov_b32_e32 v73, v15
	v_pk_fma_f32 v[72:73], v[72:73], v[72:73], v[82:83]
	v_mov_b32_e32 v78, v7
	v_mov_b32_e32 v79, v3
	v_pk_fma_f32 v[74:75], v[78:79], v[78:79], v[76:77]
	v_mov_b32_e32 v77, v72
	v_mov_b32_e32 v79, v74
	s_mov_b32 s2, 0x3a800000
	v_ashrrev_i32_e32 v47, 31, v46
	v_mov_b32_e32 v39, v33
	v_lshl_add_u64 v[50:51], v[50:51], 2, s[14:15]
	v_ashrrev_i32_e32 v49, 31, v48
	s_waitcnt vmcnt(6)
	v_mov_b32_e32 v88, v29
	s_waitcnt vmcnt(5)
	v_mov_b32_e32 v89, v21
	v_mov_b32_e32 v86, v28
	v_mov_b32_e32 v87, v20
	s_waitcnt vmcnt(4)
	v_mov_b32_e32 v96, v17
	s_waitcnt vmcnt(3)
	v_mov_b32_e32 v97, v9
	v_pk_mul_f32 v[88:89], v[88:89], v[88:89]
	v_mov_b32_e32 v82, v30
	v_mov_b32_e32 v83, v22
	v_mov_b32_e32 v94, v16
	v_mov_b32_e32 v95, v8
	v_pk_mul_f32 v[96:97], v[96:97], v[96:97]
	v_pk_fma_f32 v[86:87], v[86:87], v[86:87], v[88:89]
	v_mov_b32_e32 v84, v31
	v_mov_b32_e32 v85, v23
	v_mov_b32_e32 v90, v18
	v_mov_b32_e32 v91, v10
	v_pk_fma_f32 v[88:89], v[94:95], v[94:95], v[96:97]
	v_pk_fma_f32 v[82:83], v[82:83], v[82:83], v[86:87]
	v_mov_b32_e32 v92, v19
	v_mov_b32_e32 v93, v11
	v_pk_fma_f32 v[86:87], v[90:91], v[90:91], v[88:89]
	v_pk_fma_f32 v[82:83], v[84:85], v[84:85], v[82:83]
	v_pk_fma_f32 v[84:85], v[92:93], v[92:93], v[86:87]
	v_mov_b32_e32 v76, v82
	v_mov_b32_e32 v72, v83
	v_mov_b32_e32 v78, v84
	v_pk_add_f32 v[72:73], v[76:77], v[72:73]
	v_mov_b32_e32 v74, v85
	v_pk_add_f32 v[72:73], v[72:73], v[78:79]
	s_waitcnt vmcnt(0)
	v_pk_add_f32 v[68:69], v[68:69], 1.0 op_sel_hi:[1,0]
	v_pk_add_f32 v[72:73], v[72:73], v[74:75]
	ds_bpermute_b32 v75, v45, v73
	ds_bpermute_b32 v74, v45, v72
	v_pk_add_f32 v[70:71], v[70:71], 1.0 op_sel_hi:[1,0]
	v_lshlrev_b64 v[76:77], 11, v[46:47]
	v_lshl_add_u64 v[76:77], v[36:37], 0, v[76:77]
	v_add_u32_e32 v46, s10, v46
	s_waitcnt lgkmcnt(0)
	v_pk_add_f32 v[72:73], v[72:73], v[74:75]
	ds_bpermute_b32 v75, v54, v73
	ds_bpermute_b32 v74, v54, v72
	s_waitcnt lgkmcnt(0)
	v_pk_add_f32 v[72:73], v[72:73], v[74:75]
	ds_bpermute_b32 v75, v55, v73
	ds_bpermute_b32 v74, v55, v72
	s_waitcnt lgkmcnt(0)
	v_pk_add_f32 v[72:73], v[72:73], v[74:75]
	ds_bpermute_b32 v75, v56, v73
	ds_bpermute_b32 v74, v56, v72
	s_waitcnt lgkmcnt(0)
	v_pk_add_f32 v[72:73], v[72:73], v[74:75]
	ds_bpermute_b32 v75, v57, v73
	ds_bpermute_b32 v74, v57, v72
	s_waitcnt lgkmcnt(0)
	v_pk_add_f32 v[72:73], v[72:73], v[74:75]
	ds_bpermute_b32 v75, v58, v73
	ds_bpermute_b32 v74, v58, v72
	s_waitcnt lgkmcnt(0)
	v_pk_add_f32 v[72:73], v[72:73], v[74:75]
	s_nop 0
	v_pk_fma_f32 v[72:73], v[72:73], s[2:3], v[44:45] op_sel_hi:[1,0,0]
	v_lshl_add_u64 v[74:75], v[52:53], 0, v[38:39]
	v_mul_f32_e32 v41, 0x4b800000, v73
	v_cmp_gt_f32_e32 vcc, s18, v73
	s_mov_b32 s2, 0x81ff
	s_nop 0
	v_cndmask_b32_e32 v41, v73, v41, vcc
	v_rsq_f32_e32 v41, v41
	s_nop 0
	v_mul_f32_e32 v43, 0x45800000, v41
	v_cndmask_b32_e32 v78, v41, v43, vcc
	v_pk_mul_f32 v[24:25], v[24:25], v[78:79] op_sel_hi:[1,0]
	v_pk_mul_f32 v[26:27], v[26:27], v[78:79] op_sel_hi:[1,0]
	v_pk_mul_f32 v[24:25], v[60:61], v[24:25]
	v_pk_mul_f32 v[26:27], v[62:63], v[26:27]
	v_pk_fma_f32 v[24:25], v[68:69], v[24:25], v[64:65]
	v_pk_fma_f32 v[26:27], v[26:27], v[70:71], v[66:67]
	v_cvt_pk_bf16_f32 v24, v24, v25
	v_cvt_pk_bf16_f32 v25, v26, v27
	global_store_dwordx2 v[76:77], v[24:25], off
	global_load_dwordx4 v[24:27], v[34:35], off offset:1024
	global_load_dwordx4 v[60:63], v[74:75], off
	v_lshl_add_u64 v[64:65], v[80:81], 0, v[38:39]
	global_load_dwordx4 v[64:67], v[64:65], off
	v_pk_mul_f32 v[12:13], v[12:13], v[78:79] op_sel_hi:[1,0]
	v_pk_mul_f32 v[14:15], v[14:15], v[78:79] op_sel_hi:[1,0]
	v_mov_b32_e32 v41, v33
	v_lshl_add_u64 v[68:69], v[52:53], 0, v[40:41]
	v_pk_mul_f32 v[4:5], v[4:5], v[78:79] op_sel_hi:[1,0]
	v_pk_mul_f32 v[6:7], v[6:7], v[78:79] op_sel_hi:[1,0]
	v_mov_b32_e32 v43, v33
	v_lshl_add_u64 v[52:53], v[52:53], 0, v[42:43]
	v_pk_mul_f32 v[0:1], v[0:1], v[78:79] op_sel_hi:[1,0]
	v_pk_mul_f32 v[2:3], v[2:3], v[78:79] op_sel_hi:[1,0]
	v_cmp_gt_f32_e32 vcc, s18, v72
	s_waitcnt vmcnt(2)
	v_pk_mul_f32 v[12:13], v[12:13], v[24:25]
	s_waitcnt vmcnt(1)
	v_pk_add_f32 v[24:25], v[60:61], 1.0 op_sel_hi:[1,0]
	v_pk_mul_f32 v[14:15], v[14:15], v[26:27]
	v_pk_add_f32 v[26:27], v[62:63], 1.0 op_sel_hi:[1,0]
	s_waitcnt vmcnt(0)
; __device__ __forceinline__ void phase_norm(const float* lat_src, const float* ctx_src, const float* gain, const float* modl,
;                                            int sh_off, int sc_off, bf16_t* A, bool lat_only) {
;     ...
; #pragma unroll
;     for (int u = 0; u < 2; ++u) {
;       float ss = 0.f;
; #pragma unroll
;       for (int i = 0; i < 4; ++i) ss += xv[u][i].x * xv[u][i].x + xv[u][i].y * xv[u][i].y + xv[u][i].z * xv[u][i].z + xv[u][i].w * xv[u][i].w;
;       ss = wave_sum(ss);
;       const float rstd = rsqrtf(ss * (1.0f / 1024.0f) + 1e-6f);
; #pragma unroll
;       for (int i = 0; i < 4; ++i) {
;         const int c = i * 256 + lane * 4;
;         const float4 g = *(const float4*)(gain + c);
;         const float4 sh = *(const float4*)(md[u] + sh_off + c);
;         const float4 sc = *(const float4*)(md[u] + sc_off + c);
;         uint2 w;
;         w.x = pack2(xv[u][i].x * rstd * g.x * (1.f + sc.x) + sh.x, xv[u][i].y * rstd * g.y * (1.f + sc.y) + sh.y);
;         w.y = pack2(xv[u][i].z * rstd * g.z * (1.f + sc.z) + sh.z, xv[u][i].w * rstd * g.w * (1.f + sc.w) + sh.w);
;         *(uint2*)(A + (size_t)rowi[u] * DM + c) = w;
;       }
;     }
	v_pk_fma_f32 v[12:13], v[12:13], v[24:25], v[64:65]
	v_pk_fma_f32 v[14:15], v[14:15], v[26:27], v[66:67]
	v_cvt_pk_bf16_f32 v12, v12, v13
	v_cvt_pk_bf16_f32 v13, v14, v15
	global_store_dwordx2 v[76:77], v[12:13], off offset:512
	global_load_dwordx4 v[12:15], v[34:35], off offset:2048
	global_load_dwordx4 v[24:27], v[68:69], off
	v_lshl_add_u64 v[60:61], v[80:81], 0, v[40:41]
	global_load_dwordx4 v[60:63], v[60:61], off
	s_waitcnt vmcnt(2)
	v_pk_mul_f32 v[4:5], v[4:5], v[12:13]
	s_waitcnt vmcnt(1)
	v_pk_add_f32 v[12:13], v[24:25], 1.0 op_sel_hi:[1,0]
	v_pk_mul_f32 v[6:7], v[6:7], v[14:15]
	v_pk_add_f32 v[14:15], v[26:27], 1.0 op_sel_hi:[1,0]
	s_waitcnt vmcnt(0)
	v_pk_fma_f32 v[4:5], v[4:5], v[12:13], v[60:61]
	v_pk_fma_f32 v[6:7], v[6:7], v[14:15], v[62:63]
	v_cvt_pk_bf16_f32 v4, v4, v5
	v_cvt_pk_bf16_f32 v5, v6, v7
	global_store_dwordx2 v[76:77], v[4:5], off offset:1024
	global_load_dwordx4 v[4:7], v[34:35], off offset:3072
	global_load_dwordx4 v[12:15], v[52:53], off
	v_lshl_add_u64 v[24:25], v[80:81], 0, v[42:43]
	global_load_dwordx4 v[24:27], v[24:25], off
	v_lshl_add_u64 v[52:53], v[50:51], 0, s[12:13]
	v_lshl_add_u64 v[60:61], v[52:53], 0, v[32:33]
	s_waitcnt vmcnt(2)
	v_pk_mul_f32 v[0:1], v[0:1], v[4:5]
	s_waitcnt vmcnt(1)
	v_pk_add_f32 v[4:5], v[12:13], 1.0 op_sel_hi:[1,0]
	v_pk_mul_f32 v[2:3], v[2:3], v[6:7]
	v_pk_add_f32 v[6:7], v[14:15], 1.0 op_sel_hi:[1,0]
	s_waitcnt vmcnt(0)
	v_pk_fma_f32 v[0:1], v[0:1], v[4:5], v[24:25]
	v_pk_fma_f32 v[2:3], v[2:3], v[6:7], v[26:27]
	v_cvt_pk_bf16_f32 v0, v0, v1
	v_cvt_pk_bf16_f32 v1, v2, v3
	global_store_dwordx2 v[76:77], v[0:1], off offset:1536
	v_lshl_add_u64 v[24:25], v[50:51], 0, s[8:9]
	global_load_dwordx4 v[0:3], v[34:35], off
	global_load_dwordx4 v[4:7], v[60:61], off
	v_lshl_add_u64 v[12:13], v[24:25], 0, v[32:33]
	global_load_dwordx4 v[12:15], v[12:13], off
	v_mul_f32_e32 v26, 0x4b800000, v72
	v_cndmask_b32_e32 v26, v72, v26, vcc
	v_rsq_f32_e32 v47, v26
	v_lshlrev_b64 v[26:27], 11, v[48:49]
	v_lshl_add_u64 v[26:27], v[36:37], 0, v[26:27]
	v_lshl_add_u64 v[48:49], v[52:53], 0, v[38:39]
	v_mul_f32_e32 v50, 0x45800000, v47
	v_cndmask_b32_e32 v50, v47, v50, vcc
	v_pk_mul_f32 v[28:29], v[28:29], v[50:51] op_sel_hi:[1,0]
	v_pk_mul_f32 v[30:31], v[30:31], v[50:51] op_sel_hi:[1,0]
	v_pk_mul_f32 v[20:21], v[20:21], v[50:51] op_sel_hi:[1,0]
	v_pk_mul_f32 v[22:23], v[22:23], v[50:51] op_sel_hi:[1,0]
	v_pk_mul_f32 v[16:17], v[16:17], v[50:51] op_sel_hi:[1,0]
	v_pk_mul_f32 v[18:19], v[18:19], v[50:51] op_sel_hi:[1,0]
	v_pk_mul_f32 v[8:9], v[8:9], v[50:51] op_sel_hi:[1,0]
	v_pk_mul_f32 v[10:11], v[10:11], v[50:51] op_sel_hi:[1,0]
	v_cmp_lt_i32_e32 vcc, s2, v46
	s_or_b64 s[6:7], vcc, s[6:7]
	s_waitcnt vmcnt(2)
	v_pk_mul_f32 v[0:1], v[0:1], v[28:29]
	s_waitcnt vmcnt(1)
	v_pk_add_f32 v[4:5], v[4:5], 1.0 op_sel_hi:[1,0]
	v_pk_mul_f32 v[2:3], v[2:3], v[30:31]
	v_pk_add_f32 v[6:7], v[6:7], 1.0 op_sel_hi:[1,0]
	s_waitcnt vmcnt(0)
	v_pk_fma_f32 v[0:1], v[4:5], v[0:1], v[12:13]
	v_pk_fma_f32 v[2:3], v[2:3], v[6:7], v[14:15]
	v_cvt_pk_bf16_f32 v0, v0, v1
	v_cvt_pk_bf16_f32 v1, v2, v3
	global_store_dwordx2 v[26:27], v[0:1], off
	global_load_dwordx4 v[0:3], v[34:35], off offset:1024
	global_load_dwordx4 v[4:7], v[48:49], off
	v_lshl_add_u64 v[12:13], v[24:25], 0, v[38:39]
	global_load_dwordx4 v[12:15], v[12:13], off
	v_lshl_add_u64 v[28:29], v[52:53], 0, v[40:41]
	s_waitcnt vmcnt(2)
	v_pk_mul_f32 v[0:1], v[20:21], v[0:1]
	s_waitcnt vmcnt(1)
	v_pk_add_f32 v[4:5], v[4:5], 1.0 op_sel_hi:[1,0]
	v_pk_mul_f32 v[2:3], v[22:23], v[2:3]
	v_pk_add_f32 v[6:7], v[6:7], 1.0 op_sel_hi:[1,0]
	s_waitcnt vmcnt(0)
	v_pk_fma_f32 v[0:1], v[0:1], v[4:5], v[12:13]
	v_pk_fma_f32 v[2:3], v[2:3], v[6:7], v[14:15]
	v_cvt_pk_bf16_f32 v0, v0, v1
	v_cvt_pk_bf16_f32 v1, v2, v3
	global_store_dwordx2 v[26:27], v[0:1], off offset:512
	global_load_dwordx4 v[0:3], v[34:35], off offset:2048
	global_load_dwordx4 v[4:7], v[28:29], off
	v_lshl_add_u64 v[12:13], v[24:25], 0, v[40:41]
	global_load_dwordx4 v[12:15], v[12:13], off
	v_lshl_add_u64 v[20:21], v[52:53], 0, v[42:43]
	s_waitcnt vmcnt(2)
	v_pk_mul_f32 v[0:1], v[16:17], v[0:1]
	s_waitcnt vmcnt(1)
	v_pk_add_f32 v[4:5], v[4:5], 1.0 op_sel_hi:[1,0]
	v_pk_mul_f32 v[2:3], v[18:19], v[2:3]
	v_pk_add_f32 v[6:7], v[6:7], 1.0 op_sel_hi:[1,0]
	s_waitcnt vmcnt(0)
	v_pk_fma_f32 v[0:1], v[0:1], v[4:5], v[12:13]
	v_pk_fma_f32 v[2:3], v[2:3], v[6:7], v[14:15]
	v_cvt_pk_bf16_f32 v0, v0, v1
	v_cvt_pk_bf16_f32 v1, v2, v3
	global_store_dwordx2 v[26:27], v[0:1], off offset:1024
	global_load_dwordx4 v[0:3], v[34:35], off offset:3072
	global_load_dwordx4 v[4:7], v[20:21], off
	v_lshl_add_u64 v[12:13], v[24:25], 0, v[42:43]
	global_load_dwordx4 v[12:15], v[12:13], off
	s_waitcnt vmcnt(2)
	v_pk_mul_f32 v[0:1], v[8:9], v[0:1]
	s_waitcnt vmcnt(1)
	v_pk_add_f32 v[4:5], v[4:5], 1.0 op_sel_hi:[1,0]
	v_pk_mul_f32 v[2:3], v[10:11], v[2:3]
	v_pk_add_f32 v[6:7], v[6:7], 1.0 op_sel_hi:[1,0]
	s_waitcnt vmcnt(0)
	v_pk_fma_f32 v[0:1], v[0:1], v[4:5], v[12:13]
	v_pk_fma_f32 v[2:3], v[2:3], v[6:7], v[14:15]
	v_cvt_pk_bf16_f32 v0, v0, v1
	v_cvt_pk_bf16_f32 v1, v2, v3
	global_store_dwordx2 v[26:27], v[0:1], off offset:1536
	s_andn2_b64 exec, exec, s[6:7]
	s_cbranch_execz .LBB0_519
; __device__ __forceinline__ void phase_norm(const float* lat_src, const float* ctx_src, const float* gain, const float* modl,
;                                            int sh_off, int sc_off, bf16_t* A, bool lat_only) {
;     ...
;   for (int idx0 = (blockIdx.x * 4 + wave) * 2; idx0 < total; idx0 += gridDim.x * 8) {
;     float4 xv[2][4];
;     const float* md[2];
;     int rowi[2];
; #pragma unroll
;     for (int u = 0; u < 2; ++u) {
;       const int idx = idx0 + u;
;       const int row = lat_only ? ((idx >> 14) * TPB + 256 + (idx & 16383)) : idx;
;       const int b = row / TPB, kidx = row - b * TPB;
;       const bool isc = kidx < 256;
;       const float* src = isc ? ctx_src + (size_t)(b * 256 + kidx) * DM : lat_src + (size_t)(b * 16384 + kidx - 256) * DM;
;       md[u] = modl + (isc ? 2 : b) * 6144;
;       rowi[u] = row;
; #pragma unroll
;       for (int i = 0; i < 4; ++i) xv[u][i] = *(const float4*)(src + i * 256 + lane * 4);
.LBB0_511:
	v_mul_hi_i32 v0, v46, s11
	v_lshrrev_b32_e32 v1, 31, v0
	v_ashrrev_i32_e32 v0, 13, v0
	v_add_u32_e32 v2, v0, v1
	v_mad_i32_i24 v0, v2, s16, v46
	v_mul_i32_i24_e32 v3, 0xffffbf00, v2
	v_cmp_lt_i32_e32 vcc, s17, v0
	s_and_saveexec_b64 s[2:3], vcc
	s_xor_b64 s[2:3], exec, s[2:3]
	v_lshl_add_u32 v0, v2, 14, v3
	s_movk_i32 s19, 0xff00
	v_add3_u32 v0, v46, v0, s19
	v_ashrrev_i32_e32 v1, 31, v0
	v_lshlrev_b64 v[0:1], 12, v[0:1]
	v_mul_i32_i24_e32 v52, 0x1800, v2
	v_lshl_add_u64 v[0:1], s[92:93], 0, v[0:1]
	v_ashrrev_i32_e32 v53, 31, v52
	s_andn2_saveexec_b64 s[2:3], s[2:3]
	v_lshlrev_b32_e32 v0, 8, v2
	v_add3_u32 v0, v3, v0, v46
	v_ashrrev_i32_e32 v1, 31, v0
	v_lshlrev_b64 v[0:1], 12, v[0:1]
	v_lshl_add_u64 v[0:1], s[68:69], 0, v[0:1]
	v_mov_b64_e32 v[52:53], 0x3000
	s_or_b64 exec, exec, s[2:3]
	v_lshl_add_u64 v[0:1], v[0:1], 0, v[32:33]
	global_load_dwordx4 v[24:27], v[0:1], off
	global_load_dwordx4 v[12:15], v[0:1], off offset:1024
	global_load_dwordx4 v[4:7], v[0:1], off offset:2048
	global_load_dwordx4 v[0:3], v[0:1], off offset:3072
	v_add_u32_e32 v48, 1, v46
	v_mul_hi_i32 v8, v48, s11
	v_lshrrev_b32_e32 v9, 31, v8
	v_ashrrev_i32_e32 v8, 13, v8
	v_add_u32_e32 v10, v8, v9
	v_mad_i32_i24 v8, v10, s16, v48
	v_mul_i32_i24_e32 v11, 0xffffbf00, v10
	v_cmp_lt_i32_e32 vcc, s17, v8
	s_and_saveexec_b64 s[2:3], vcc
	s_xor_b64 s[2:3], exec, s[2:3]
	v_lshl_add_u32 v8, v10, 14, v11
	s_movk_i32 s19, 0xff01
	v_add3_u32 v8, v46, v8, s19
	v_ashrrev_i32_e32 v9, 31, v8
	v_lshlrev_b64 v[8:9], 12, v[8:9]
	v_mul_i32_i24_e32 v50, 0x1800, v10
	v_lshl_add_u64 v[8:9], s[92:93], 0, v[8:9]
	v_ashrrev_i32_e32 v51, 31, v50
	s_andn2_saveexec_b64 s[2:3], s[2:3]
	s_cbranch_execz .LBB0_510
	v_lshl_add_u32 v8, v10, 8, v11
	v_add3_u32 v8, v46, v8, 1
	v_ashrrev_i32_e32 v9, 31, v8
	v_lshlrev_b64 v[8:9], 12, v[8:9]
	v_lshl_add_u64 v[8:9], s[68:69], 0, v[8:9]
	v_mov_b64_e32 v[50:51], 0x3000
	s_branch .LBB0_510

; template <bool DEEP, class Epi>
; __device__ __forceinline__ void gemm_phase(const bf16_t* __restrict__ A, int lda, const bf16_t* __restrict__ Wt,
;                                            int K, int ntn, bool lat_only, const Epi& epi, char* smem) {
;     ...
;     for (int kt = 0; kt < nk; ++kt) {
;       __syncthreads();
;       GEMM_STORE(ra0, ra1, ra2, ra3, rb0, rb1, rb2, rb3, 0)
;       __syncthreads();
;       {
;         bf16x8 af0[4], bf0[4], af1[4], bf1[4];
;         __builtin_amdgcn_s_setprio(1);
; #pragma unroll
;         for (int i = 0; i < 4; ++i) af0[i] = *(const bf16x8*)(sA + (wm * 64 + i * 16 + l15) * LSTR + quad * 8);
; #pragma unroll
;         for (int j = 0; j < 4; ++j) bf0[j] = *(const bf16x8*)(sB + (wn * 64 + j * 16 + l15) * LSTR + quad * 8);
; #pragma unroll
;         for (int i = 0; i < 4; ++i) af1[i] = *(const bf16x8*)(sA + (wm * 64 + i * 16 + l15) * LSTR + 32 + quad * 8);
; #pragma unroll
;         for (int j = 0; j < 4; ++j) bf1[j] = *(const bf16x8*)(sB + (wn * 64 + j * 16 + l15) * LSTR + 32 + quad * 8);
;         __builtin_amdgcn_sched_barrier(0);
;         if (kt + 1 < nk) GEMM_LOAD(ra0, ra1, ra2, ra3, rb0, rb1, rb2, rb3, (kt + 1) * 64)
;         __builtin_amdgcn_sched_barrier(0);
.LBB0_576:
	s_waitcnt vmcnt(63) expcnt(7) lgkmcnt(15)
	s_barrier
	s_waitcnt vmcnt(7)
	ds_write_b128 v176, v[56:59]
	s_waitcnt vmcnt(6)
	ds_write_b128 v176, v[60:63] offset:5120
	s_waitcnt vmcnt(5)
	ds_write_b128 v176, v[68:71] offset:10240
	s_waitcnt vmcnt(4)
	ds_write_b128 v176, v[76:79] offset:15360
	s_waitcnt vmcnt(3)
	ds_write_b128 v176, v[80:83] offset:20480
	s_waitcnt vmcnt(2)
	ds_write_b128 v176, v[84:87] offset:25600
	s_waitcnt vmcnt(1)
	ds_write_b128 v176, v[88:91] offset:30720
	s_waitcnt vmcnt(0)
	ds_write_b128 v176, v[92:95] offset:35840
	v_add_u32_e32 v96, v180, v182
	s_waitcnt lgkmcnt(0)
	s_barrier
	s_setprio 1
	ds_read_b128 v[156:159], v96
	ds_read_b128 v[152:155], v96 offset:2560
	ds_read_b128 v[132:135], v96 offset:5120
	ds_read_b128 v[124:127], v96 offset:7680
	ds_read_b128 v[136:139], v183 offset:20480
	ds_read_b128 v[140:143], v183 offset:23040
	ds_read_b128 v[144:147], v183 offset:25600
	ds_read_b128 v[148:151], v183 offset:28160
	ds_read_b128 v[128:131], v184 offset:64
	ds_read_b128 v[120:123], v184 offset:2624
	ds_read_b128 v[100:103], v184 offset:5184
	ds_read_b128 v[96:99], v184 offset:7744
	ds_read_b128 v[104:107], v185 offset:20544
	ds_read_b128 v[108:111], v185 offset:23104
	ds_read_b128 v[112:115], v185 offset:25664
	ds_read_b128 v[116:119], v185 offset:28224
	s_cmpk_eq_i32 s8, 0x780
	s_cbranch_scc1 .LBB0_575
	v_lshl_add_u64 v[68:69], v[172:173], 0, s[8:9]
	v_add_co_u32_e32 v56, vcc, 0x1d00000, v68
	v_lshl_add_u64 v[88:89], v[174:175], 0, s[8:9]
	s_nop 0
	v_addc_co_u32_e32 v57, vcc, 0, v69, vcc
	v_add_co_u32_e32 v60, vcc, 0x1d10000, v68
	s_nop 1
	v_addc_co_u32_e32 v61, vcc, 0, v69, vcc
	v_add_co_u32_e32 v70, vcc, 0x1d20000, v68
	global_load_dwordx4 v[56:59], v[56:57], off offset:128
	global_load_dwordx4 v[60:63], v[60:61], off offset:128
	v_addc_co_u32_e32 v71, vcc, 0, v69, vcc
	v_add_co_u32_e32 v76, vcc, 0x1d30000, v68
	s_nop 1
	v_addc_co_u32_e32 v77, vcc, 0, v69, vcc
	v_add_co_u32_e32 v80, vcc, 0x880000, v88
	global_load_dwordx4 v[68:71], v[70:71], off offset:128
	global_load_dwordx4 v[76:79], v[76:77], off offset:128
	v_addc_co_u32_e32 v81, vcc, 0, v89, vcc
	v_add_co_u32_e32 v84, vcc, 0x890000, v88
	s_nop 1
	v_addc_co_u32_e32 v85, vcc, 0, v89, vcc
	v_add_co_u32_e32 v90, vcc, 0x8a0000, v88
	global_load_dwordx4 v[80:83], v[80:81], off offset:128
	global_load_dwordx4 v[84:87], v[84:85], off offset:128
	v_addc_co_u32_e32 v91, vcc, 0, v89, vcc
	v_add_co_u32_e32 v92, vcc, 0x8b0000, v88
	s_nop 1
	v_addc_co_u32_e32 v93, vcc, 0, v89, vcc
	global_load_dwordx4 v[88:91], v[90:91], off offset:128
	global_load_dwordx4 v[92:95], v[92:93], off offset:128
	s_branch .LBB0_575

;   __device__ __forceinline__ void operator()(const f32x4 (&acc)[4][4], int row0w, int col0w, int l15, int quad) const {
;     ...
;     for (int i = 0; i < 4; ++i) {
;       const int row = row0w + i * 16 + l15;
;       const int b = row / TPB, kidx = row - b * TPB;
;       const bool isc = kidx < 256;
;       const size_t off = isc ? (size_t)(b * 256 + kidx) * DM : (size_t)(b * 16384 + kidx - 256) * DM;
;       const float* src = (isc ? ctx_src : lat_src) + off;
;       float* dst = (isc ? ctx_dst : lat_dst) + off;
;       const float* g = gate + (isc ? 2 : b) * 6144;
; #pragma unroll
;       for (int j = 0; j < 4; ++j) {
;         const int n = col0w + j * 16 + quad * 4;
;         const float4 xo = *(const float4*)(src + n);
;         const float4 g4 = *(const float4*)(g + n);
;         float4 o;
;         o.x = xo.x + g4.x * acc[i][j][0];
;         o.y = xo.y + g4.y * acc[i][j][1];
;         o.z = xo.z + g4.z * acc[i][j][2];
;         o.w = xo.w + g4.w * acc[i][j][3];
;         *(float4*)(dst + n) = o;
;       }
.LBB0_632:
	s_or_b64 exec, exec, s[0:1]
	v_mul_i32_i24_e32 v17, 0x1800, v20
	v_cndmask_b32_e32 v20, v17, v185, vcc
	v_ashrrev_i32_e32 v17, 31, v16
	v_ashrrev_i32_e32 v21, 31, v20
	v_lshlrev_b64 v[16:17], 12, v[16:17]
	v_lshl_add_u64 v[16:17], v[18:19], 0, v[16:17]
	v_lshl_add_u64 v[18:19], v[20:21], 2, s[4:5]
	v_lshl_add_u64 v[30:31], v[18:19], 0, v[64:65]
	v_lshl_add_u64 v[28:29], v[16:17], 0, v[64:65]
	global_load_dwordx4 v[16:19], v[30:31], off
	global_load_dwordx4 v[20:23], v[28:29], off
	global_load_dwordx4 v[24:27], v[28:29], off offset:64
	s_add_i32 s12, s12, s90
	s_add_i32 s2, s2, s90
	s_cmp_ge_i32 s12, s84
	s_waitcnt vmcnt(1)
	v_pk_fma_f32 v[12:13], v[12:13], v[16:17], v[20:21]
	v_pk_fma_f32 v[14:15], v[14:15], v[18:19], v[22:23]
	global_store_dwordx4 v[28:29], v[12:15], off
	global_load_dwordx4 v[12:15], v[30:31], off offset:64
	s_waitcnt vmcnt(0)
	v_pk_fma_f32 v[8:9], v[8:9], v[12:13], v[24:25]
	v_pk_fma_f32 v[10:11], v[10:11], v[14:15], v[26:27]
	global_store_dwordx4 v[28:29], v[8:11], off offset:64
	global_load_dwordx4 v[8:11], v[30:31], off offset:128
	global_load_dwordx4 v[12:15], v[28:29], off offset:128
	global_load_dwordx4 v[16:19], v[28:29], off offset:192
	s_waitcnt vmcnt(1)
	v_pk_fma_f32 v[4:5], v[4:5], v[8:9], v[12:13]
	v_pk_fma_f32 v[6:7], v[6:7], v[10:11], v[14:15]
	global_store_dwordx4 v[28:29], v[4:7], off offset:128
	global_load_dwordx4 v[4:7], v[30:31], off offset:192
	s_waitcnt vmcnt(0)
	v_pk_fma_f32 v[0:1], v[0:1], v[4:5], v[16:17]
	v_pk_fma_f32 v[2:3], v[2:3], v[6:7], v[18:19]
	global_store_dwordx4 v[28:29], v[0:3], off offset:192
	s_cbranch_scc1 .LBB0_653

; template <bool DEEP, class Epi>
; __device__ __forceinline__ void gemm_phase(const bf16_t* __restrict__ A, int lda, const bf16_t* __restrict__ Wt,
;                                            int K, int ntn, bool lat_only, const Epi& epi, char* smem) {
;     ...
;     for (int kt = 0; kt < nk; ++kt) {
;       __syncthreads();
;       GEMM_STORE(ra0, ra1, ra2, ra3, rb0, rb1, rb2, rb3, 0)
;       __syncthreads();
;       {
;         bf16x8 af0[4], bf0[4], af1[4], bf1[4];
;         __builtin_amdgcn_s_setprio(1);
; #pragma unroll
;         for (int i = 0; i < 4; ++i) af0[i] = *(const bf16x8*)(sA + (wm * 64 + i * 16 + l15) * LSTR + quad * 8);
; #pragma unroll
;         for (int j = 0; j < 4; ++j) bf0[j] = *(const bf16x8*)(sB + (wn * 64 + j * 16 + l15) * LSTR + quad * 8);
; #pragma unroll
;         for (int i = 0; i < 4; ++i) af1[i] = *(const bf16x8*)(sA + (wm * 64 + i * 16 + l15) * LSTR + 32 + quad * 8);
; #pragma unroll
;         for (int j = 0; j < 4; ++j) bf1[j] = *(const bf16x8*)(sB + (wn * 64 + j * 16 + l15) * LSTR + 32 + quad * 8);
;         __builtin_amdgcn_sched_barrier(0);
;         if (kt + 1 < nk) GEMM_LOAD(ra0, ra1, ra2, ra3, rb0, rb1, rb2, rb3, (kt + 1) * 64)
;         __builtin_amdgcn_sched_barrier(0);
.LBB0_635:
	s_waitcnt vmcnt(63) expcnt(7) lgkmcnt(15)
	s_barrier
	s_waitcnt vmcnt(0)
	ds_write_b128 v161, v[64:67]
	ds_write_b128 v161, v[68:71] offset:5120
	ds_write_b128 v161, v[80:83] offset:10240
	ds_write_b128 v161, v[88:91] offset:15360
	ds_write_b128 v161, v[72:75] offset:20480
	ds_write_b128 v161, v[76:79] offset:25600
	ds_write_b128 v161, v[84:87] offset:30720
	ds_write_b128 v161, v[92:95] offset:35840
	v_add_u32_e32 v96, v175, v178
	s_waitcnt lgkmcnt(0)
	s_barrier
	s_setprio 1
	ds_read_b128 v[156:159], v96
	ds_read_b128 v[152:155], v96 offset:2560
	ds_read_b128 v[132:135], v96 offset:5120
	ds_read_b128 v[124:127], v96 offset:7680
	ds_read_b128 v[136:139], v182 offset:20480
	ds_read_b128 v[140:143], v182 offset:23040
	ds_read_b128 v[144:147], v182 offset:25600
	ds_read_b128 v[148:151], v182 offset:28160
	ds_read_b128 v[128:131], v183 offset:64
	ds_read_b128 v[120:123], v183 offset:2624
	ds_read_b128 v[100:103], v183 offset:5184
	ds_read_b128 v[96:99], v183 offset:7744
	ds_read_b128 v[104:107], v184 offset:20544
	ds_read_b128 v[108:111], v184 offset:23104
	ds_read_b128 v[112:115], v184 offset:25664
	ds_read_b128 v[116:119], v184 offset:28224
	s_cmp_gt_u32 s15, 42
	s_cbranch_scc1 .LBB0_634
	v_lshl_add_u64 v[72:73], v[170:171], 0, s[0:1]
	v_add_co_u32_e32 v64, vcc, 0x5e00000, v72
	v_lshl_add_u64 v[84:85], v[172:173], 0, s[0:1]
	s_nop 0
	v_addc_co_u32_e32 v65, vcc, 0, v73, vcc
	v_add_co_u32_e32 v68, vcc, 0x5e2c000, v72
	s_nop 1
	v_addc_co_u32_e32 v69, vcc, 0, v73, vcc
	v_add_co_u32_e32 v74, vcc, 0x5e58000, v72
	global_load_dwordx4 v[64:67], v[64:65], off offset:128
	global_load_dwordx4 v[68:71], v[68:69], off offset:128
	v_addc_co_u32_e32 v75, vcc, 0, v73, vcc
	v_add_co_u32_e32 v72, vcc, 0x5e84000, v72
	s_nop 1
	v_addc_co_u32_e32 v73, vcc, 0, v73, vcc
	global_load_dwordx4 v[80:83], v[74:75], off offset:128
	global_load_dwordx4 v[88:91], v[72:73], off offset:128
	v_add_co_u32_e32 v72, vcc, 0x1380000, v84
	s_nop 1
	v_addc_co_u32_e32 v73, vcc, 0, v85, vcc
	v_add_co_u32_e32 v76, vcc, 0x13ac000, v84
	s_nop 1
	v_addc_co_u32_e32 v77, vcc, 0, v85, vcc
	v_add_co_u32_e32 v86, vcc, 0x13d8000, v84
	global_load_dwordx4 v[72:75], v[72:73], off offset:128
	global_load_dwordx4 v[76:79], v[76:77], off offset:128
	v_addc_co_u32_e32 v87, vcc, 0, v85, vcc
	v_add_co_u32_e32 v92, vcc, 0x1404000, v84
	s_nop 1
	v_addc_co_u32_e32 v93, vcc, 0, v85, vcc
	global_load_dwordx4 v[84:87], v[86:87], off offset:128
	global_load_dwordx4 v[92:95], v[92:93], off offset:128
	s_branch .LBB0_634
;   __device__ __forceinline__ void operator()(const f32x4 (&acc)[4][4], int row0w, int col0w, int l15, int quad) const {
;     ...
;     for (int i = 0; i < 4; ++i) {
;       const int row = row0w + i * 16 + l15;
;       const int b = row / TPB, kidx = row - b * TPB;
;       const bool isc = kidx < 256;
;       const size_t off = isc ? (size_t)(b * 256 + kidx) * DM : (size_t)(b * 16384 + kidx - 256) * DM;
;       const float* src = (isc ? ctx_src : lat_src) + off;
;       float* dst = (isc ? ctx_dst : lat_dst) + off;
;       const float* g = gate + (isc ? 2 : b) * 6144;
; #pragma unroll
;       for (int j = 0; j < 4; ++j) {
;         const int n = col0w + j * 16 + quad * 4;
;         const float4 xo = *(const float4*)(src + n);
;         const float4 g4 = *(const float4*)(g + n);
;         float4 o;
;         o.x = xo.x + g4.x * acc[i][j][0];
;         o.y = xo.y + g4.y * acc[i][j][1];
;         o.z = xo.z + g4.z * acc[i][j][2];
;         o.w = xo.w + g4.w * acc[i][j][3];
;         *(float4*)(dst + n) = o;
;       }
.LBB0_637:
	s_waitcnt vmcnt(6)
	v_add_u32_e32 v68, s14, v174
	v_mul_hi_i32 v64, v68, s7
	v_lshrrev_b32_e32 v65, 31, v64
	v_ashrrev_i32_e32 v64, 13, v64
	v_add_u32_e32 v69, v64, v65
	v_mad_i32_i24 v65, v69, s8, v68
	v_cmp_gt_i32_e32 vcc, s9, v65
	v_cmp_lt_i32_e64 s[0:1], s10, v65
	s_and_saveexec_b64 s[14:15], s[0:1]
	s_xor_b64 s[0:1], exec, s[14:15]
	v_lshlrev_b32_e32 v64, 14, v69
	v_add3_u32 v64, v64, v65, s11
	s_or_saveexec_b64 s[0:1], s[0:1]
	v_mov_b64_e32 v[66:67], s[92:93]
	s_xor_b64 exec, exec, s[0:1]
	v_lshl_add_u32 v64, v69, 8, v65
	v_mov_b64_e32 v[66:67], s[68:69]
	s_or_b64 exec, exec, s[0:1]
	v_ashrrev_i32_e32 v65, 31, v64
	v_lshlrev_b64 v[64:65], 12, v[64:65]
	v_lshl_add_u64 v[66:67], v[66:67], 0, v[64:65]
	v_mul_i32_i24_e32 v64, 0x1800, v69
	v_or_b32_e32 v70, s13, v176
	v_cndmask_b32_e32 v64, v64, v185, vcc
	v_ashrrev_i32_e32 v71, 31, v70
	v_ashrrev_i32_e32 v65, 31, v64
	s_waitcnt vmcnt(3)
	v_lshl_add_u64 v[72:73], v[64:65], 2, s[4:5]
	v_lshlrev_b64 v[64:65], 2, v[70:71]
	v_lshl_add_u64 v[82:83], v[72:73], 0, v[64:65]
	v_lshl_add_u64 v[66:67], v[66:67], 0, v[64:65]
	global_load_dwordx4 v[70:73], v[82:83], off
	global_load_dwordx4 v[74:77], v[66:67], off
	global_load_dwordx4 v[78:81], v[66:67], off offset:64
	s_waitcnt vmcnt(1)
	v_pk_fma_f32 v[60:61], v[60:61], v[70:71], v[74:75]
	v_pk_fma_f32 v[62:63], v[62:63], v[72:73], v[76:77]
	global_store_dwordx4 v[66:67], v[60:63], off
	global_load_dwordx4 v[60:63], v[82:83], off offset:64
	s_waitcnt vmcnt(0)
	v_pk_fma_f32 v[56:57], v[56:57], v[60:61], v[78:79]
	v_pk_fma_f32 v[58:59], v[58:59], v[62:63], v[80:81]
	global_store_dwordx4 v[66:67], v[56:59], off offset:64
	global_load_dwordx4 v[56:59], v[82:83], off offset:128
	global_load_dwordx4 v[60:63], v[66:67], off offset:128
	global_load_dwordx4 v[70:73], v[66:67], off offset:192
	s_waitcnt vmcnt(1)
	v_pk_fma_f32 v[52:53], v[52:53], v[56:57], v[60:61]
	v_pk_fma_f32 v[54:55], v[54:55], v[58:59], v[62:63]
	global_store_dwordx4 v[66:67], v[52:55], off offset:128
	global_load_dwordx4 v[54:57], v[82:83], off offset:192
	s_waitcnt vmcnt(0)
	v_pk_fma_f32 v[48:49], v[48:49], v[54:55], v[70:71]
	v_or_b32_e32 v53, 16, v68
	v_mul_hi_i32 v52, v53, s7
	v_lshrrev_b32_e32 v58, 31, v52
	v_ashrrev_i32_e32 v52, 13, v52
	v_add_u32_e32 v52, v52, v58
	v_mad_i32_i24 v53, v52, s8, v53
	v_cmp_gt_i32_e32 vcc, s9, v53
	v_pk_fma_f32 v[50:51], v[50:51], v[56:57], v[72:73]
	v_cmp_lt_i32_e64 s[0:1], s10, v53
	global_store_dwordx4 v[66:67], v[48:51], off offset:192
	s_and_saveexec_b64 s[14:15], s[0:1]
	s_xor_b64 s[0:1], exec, s[14:15]
	v_lshlrev_b32_e32 v48, 14, v52
	v_add3_u32 v48, v48, v53, s11
	s_or_saveexec_b64 s[0:1], s[0:1]
	v_mov_b64_e32 v[50:51], s[92:93]
	s_xor_b64 exec, exec, s[0:1]
	v_lshl_add_u32 v48, v52, 8, v53
	v_mov_b64_e32 v[50:51], s[68:69]
	s_or_b64 exec, exec, s[0:1]
	v_ashrrev_i32_e32 v49, 31, v48
	v_lshlrev_b64 v[48:49], 12, v[48:49]
	v_lshl_add_u64 v[48:49], v[50:51], 0, v[48:49]
	v_mul_i32_i24_e32 v50, 0x1800, v52
	v_cndmask_b32_e32 v50, v50, v185, vcc
	v_ashrrev_i32_e32 v51, 31, v50
	v_lshl_add_u64 v[50:51], v[50:51], 2, s[4:5]
	v_lshl_add_u64 v[62:63], v[50:51], 0, v[64:65]
	v_lshl_add_u64 v[60:61], v[48:49], 0, v[64:65]
	global_load_dwordx4 v[48:51], v[62:63], off
	global_load_dwordx4 v[52:55], v[60:61], off
	global_load_dwordx4 v[56:59], v[60:61], off offset:64
	s_waitcnt vmcnt(1)
	v_pk_fma_f32 v[44:45], v[44:45], v[48:49], v[52:53]
	v_pk_fma_f32 v[46:47], v[46:47], v[50:51], v[54:55]
	global_store_dwordx4 v[60:61], v[44:47], off
	global_load_dwordx4 v[44:47], v[62:63], off offset:64
	s_waitcnt vmcnt(0)
	v_pk_fma_f32 v[40:41], v[40:41], v[44:45], v[56:57]
	v_pk_fma_f32 v[42:43], v[42:43], v[46:47], v[58:59]
	global_store_dwordx4 v[60:61], v[40:43], off offset:64
	global_load_dwordx4 v[40:43], v[62:63], off offset:128
	global_load_dwordx4 v[44:47], v[60:61], off offset:128
	global_load_dwordx4 v[48:51], v[60:61], off offset:192
	s_waitcnt vmcnt(1)
	v_pk_fma_f32 v[36:37], v[36:37], v[40:41], v[44:45]
	v_pk_fma_f32 v[38:39], v[38:39], v[42:43], v[46:47]
	global_store_dwordx4 v[60:61], v[36:39], off offset:128
	global_load_dwordx4 v[38:41], v[62:63], off offset:192
	s_waitcnt vmcnt(0)
	v_pk_fma_f32 v[32:33], v[32:33], v[38:39], v[48:49]
	v_or_b32_e32 v37, 32, v68
	v_mul_hi_i32 v36, v37, s7
	v_lshrrev_b32_e32 v42, 31, v36
	v_ashrrev_i32_e32 v36, 13, v36
	v_add_u32_e32 v36, v36, v42
	v_mad_i32_i24 v37, v36, s8, v37
	v_cmp_gt_i32_e32 vcc, s9, v37
	v_pk_fma_f32 v[34:35], v[34:35], v[40:41], v[50:51]
	v_cmp_lt_i32_e64 s[0:1], s10, v37
	global_store_dwordx4 v[60:61], v[32:35], off offset:192
	s_and_saveexec_b64 s[14:15], s[0:1]
	s_xor_b64 s[0:1], exec, s[14:15]
	v_lshlrev_b32_e32 v32, 14, v36
	v_add3_u32 v32, v32, v37, s11
	s_or_saveexec_b64 s[0:1], s[0:1]
	v_mov_b64_e32 v[34:35], s[92:93]
	s_xor_b64 exec, exec, s[0:1]
	v_lshl_add_u32 v32, v36, 8, v37
	v_mov_b64_e32 v[34:35], s[68:69]
	s_or_b64 exec, exec, s[0:1]
	v_ashrrev_i32_e32 v33, 31, v32
	v_lshlrev_b64 v[32:33], 12, v[32:33]
	v_lshl_add_u64 v[32:33], v[34:35], 0, v[32:33]
	v_mul_i32_i24_e32 v34, 0x1800, v36
	v_cndmask_b32_e32 v34, v34, v185, vcc
	v_ashrrev_i32_e32 v35, 31, v34
	v_lshl_add_u64 v[34:35], v[34:35], 2, s[4:5]
	v_lshl_add_u64 v[46:47], v[34:35], 0, v[64:65]
	v_lshl_add_u64 v[44:45], v[32:33], 0, v[64:65]
	global_load_dwordx4 v[32:35], v[46:47], off
	global_load_dwordx4 v[36:39], v[44:45], off
	global_load_dwordx4 v[40:43], v[44:45], off offset:64
	s_waitcnt vmcnt(1)
	v_pk_fma_f32 v[28:29], v[28:29], v[32:33], v[36:37]
	v_pk_fma_f32 v[30:31], v[30:31], v[34:35], v[38:39]
	global_store_dwordx4 v[44:45], v[28:31], off
	global_load_dwordx4 v[28:31], v[46:47], off offset:64
	s_waitcnt vmcnt(0)
	v_pk_fma_f32 v[24:25], v[24:25], v[28:29], v[40:41]
	v_pk_fma_f32 v[26:27], v[26:27], v[30:31], v[42:43]
	global_store_dwordx4 v[44:45], v[24:27], off offset:64
	global_load_dwordx4 v[24:27], v[46:47], off offset:128
	global_load_dwordx4 v[28:31], v[44:45], off offset:128
	global_load_dwordx4 v[32:35], v[44:45], off offset:192
	s_waitcnt vmcnt(1)
	v_pk_fma_f32 v[20:21], v[20:21], v[24:25], v[28:29]
	v_pk_fma_f32 v[22:23], v[22:23], v[26:27], v[30:31]
	global_store_dwordx4 v[44:45], v[20:23], off offset:128
	global_load_dwordx4 v[22:25], v[46:47], off offset:192
	s_waitcnt vmcnt(0)
	v_pk_fma_f32 v[16:17], v[16:17], v[22:23], v[32:33]
	v_or_b32_e32 v21, 48, v68
	v_mul_hi_i32 v20, v21, s7
	v_lshrrev_b32_e32 v26, 31, v20
	v_ashrrev_i32_e32 v20, 13, v20
	v_add_u32_e32 v20, v20, v26
	v_mad_i32_i24 v21, v20, s8, v21
	v_cmp_gt_i32_e32 vcc, s9, v21
	v_pk_fma_f32 v[18:19], v[18:19], v[24:25], v[34:35]
	v_cmp_lt_i32_e64 s[0:1], s10, v21
	global_store_dwordx4 v[44:45], v[16:19], off offset:192
	s_and_saveexec_b64 s[14:15], s[0:1]
	s_xor_b64 s[0:1], exec, s[14:15]
	v_lshlrev_b32_e32 v16, 14, v20
	v_add3_u32 v16, v16, v21, s11
	s_or_saveexec_b64 s[0:1], s[0:1]
	v_mov_b64_e32 v[18:19], s[92:93]
	s_xor_b64 exec, exec, s[0:1]
	s_cbranch_execz .LBB0_632
	v_lshl_add_u32 v16, v20, 8, v21
	v_mov_b64_e32 v[18:19], s[68:69]
	s_branch .LBB0_632

; __device__ __forceinline__ void conv_tile(const float* __restrict__ W, int K, int N, int Npad, bf16_t* __restrict__ dst, int mode,
;                           int kt, int nt, char* smem) {
;   float* T = (float*)smem;
;   const int tid = threadIdx.x;
;   const int k0 = kt * 64, n0 = nt * 64;
;   __syncthreads();
;   {
;     const int r = tid >> 4, c4 = (tid & 15) * 4;
; #pragma unroll
;     for (int i = 0; i < 4; ++i) {
;       const int k = r + 16 * i, n = n0 + c4;
;       float4 v = make_float4(0.f, 0.f, 0.f, 0.f);
;       if (n < N) v = *(const float4*)(W + (size_t)(k0 + k) * N + n);
;       T[k * 65 + c4 + 0] = v.x;
;       T[k * 65 + c4 + 1] = v.y;
;       T[k * 65 + c4 + 2] = v.z;
;       T[k * 65 + c4 + 3] = v.w;
;     }
;   }
; __device__ __forceinline__ void phase_conv(const Params& P, int layer, char* smem, int part, int rank, int nrank) {
;     ...
;   for (int t = t_lo + rank; t < total; t += nrank) {
;     if (t < t_in) {
;       conv_tile(w_in, 1024, n_in, np_in, (bf16_t*)(ws + OFF_WIN), 0, t / nt_in, t % nt_in, smem);
.LBB0_708:
	s_mul_hi_i32 s0, s9, 0x4ec4ec4f
	s_lshr_b32 s1, s0, 31
	s_ashr_i32 s0, s0, 4
	s_add_i32 s1, s0, s1
	s_lshl_b32 s0, s1, 6
	s_mulk_i32 s1, 0xf300
	s_add_i32 s1, s1, s4
	v_add_u32_e32 v18, s1, v20
	v_cmp_gt_i32_e32 vcc, s6, v18
	v_mov_b32_e32 v0, 0
	v_mov_b32_e32 v1, 0
	v_mov_b32_e32 v2, 0
	v_mov_b32_e32 v3, 0
	v_mov_b32_e32 v4, 0
	v_mov_b32_e32 v5, 0
	v_mov_b32_e32 v6, 0
	v_mov_b32_e32 v7, 0
	v_mov_b32_e32 v8, 0
	v_mov_b32_e32 v9, 0
	v_mov_b32_e32 v10, 0
	v_mov_b32_e32 v11, 0
	v_mov_b32_e32 v12, 0
	v_mov_b32_e32 v13, 0
	v_mov_b32_e32 v14, 0
	v_mov_b32_e32 v15, 0
	s_barrier
	s_and_saveexec_b64 s[2:3], vcc
	s_cbranch_execz .LBB0_710
	v_readlane_b32 s72, v211, 38
	v_ashrrev_i32_e32 v19, 31, v18
	v_readlane_b32 s80, v211, 46
	v_readlane_b32 s81, v211, 47
	v_or_b32_e32 v0, s0, v179
	v_add_u32_e32 v2, s0, v171
	v_lshl_add_u64 v[8:9], v[18:19], 2, s[80:81]
	v_add_u32_e32 v10, s0, v21
	v_add_u32_e32 v12, s0, v22
	v_mad_i64_i32 v[0:1], s[10:11], v0, s7, v[8:9]
	v_mad_i64_i32 v[4:5], s[10:11], v2, s7, v[8:9]
	v_mad_i64_i32 v[10:11], s[10:11], v10, s7, v[8:9]
	v_mad_i64_i32 v[12:13], s[10:11], v12, s7, v[8:9]
	global_load_dwordx4 v[0:3], v[0:1], off
	global_load_dwordx4 v[4:7], v[4:5], off
	global_load_dwordx4 v[8:11], v[10:11], off
	global_load_dwordx4 v[12:15], v[12:13], off
	v_readlane_b32 s73, v211, 39
	v_readlane_b32 s74, v211, 40
	v_readlane_b32 s75, v211, 41
	v_readlane_b32 s76, v211, 42
	v_readlane_b32 s77, v211, 43
	v_readlane_b32 s78, v211, 44
	v_readlane_b32 s79, v211, 45
	v_readlane_b32 s82, v211, 48
	v_readlane_b32 s83, v211, 49
	v_readlane_b32 s84, v211, 50
	v_readlane_b32 s85, v211, 51
	v_readlane_b32 s86, v211, 52
	v_readlane_b32 s87, v211, 53

; __device__ __forceinline__ void phase_norm(const float* lat_src, const float* ctx_src, const float* gain, const float* modl,
;                                            int sh_off, int sc_off, bf16_t* A, bool lat_only) {
;     ...
;   for (int idx0 = (blockIdx.x * 4 + wave) * 2; idx0 < total; idx0 += gridDim.x * 8) {
;     float4 xv[2][4];
;     const float* md[2];
;     int rowi[2];
; #pragma unroll
;     for (int u = 0; u < 2; ++u) {
;       const int idx = idx0 + u;
;       const int row = lat_only ? ((idx >> 14) * TPB + 256 + (idx & 16383)) : idx;
;       const int b = row / TPB, kidx = row - b * TPB;
;       const bool isc = kidx < 256;
;       const float* src = isc ? ctx_src + (size_t)(b * 256 + kidx) * DM : lat_src + (size_t)(b * 16384 + kidx - 256) * DM;
;       md[u] = modl + (isc ? 2 : b) * 6144;
;       rowi[u] = row;
; #pragma unroll
;       for (int i = 0; i < 4; ++i) xv[u][i] = *(const float4*)(src + i * 256 + lane * 4);
;     }
; #pragma unroll
;     for (int u = 0; u < 2; ++u) {
;       float ss = 0.f;
; #pragma unroll
;       for (int i = 0; i < 4; ++i) ss += xv[u][i].x * xv[u][i].x + xv[u][i].y * xv[u][i].y + xv[u][i].z * xv[u][i].z + xv[u][i].w * xv[u][i].w;
;       ss = wave_sum(ss);
;       const float rstd = rsqrtf(ss * (1.0f / 1024.0f) + 1e-6f);
; #pragma unroll
;       for (int i = 0; i < 4; ++i) {
;         const int c = i * 256 + lane * 4;
;         const float4 g = *(const float4*)(gain + c);
;         const float4 sh = *(const float4*)(md[u] + sh_off + c);
;         const float4 sc = *(const float4*)(md[u] + sc_off + c);
;         uint2 w;
;         w.x = pack2(xv[u][i].x * rstd * g.x * (1.f + sc.x) + sh.x, xv[u][i].y * rstd * g.y * (1.f + sc.y) + sh.y);
;         w.y = pack2(xv[u][i].z * rstd * g.z * (1.f + sc.z) + sh.z, xv[u][i].w * rstd * g.w * (1.f + sc.w) + sh.w);
;         *(uint2*)(A + (size_t)rowi[u] * DM + c) = w;
;       }
;     }
;   }
.LBB0_782:
	s_or_b64 exec, exec, s[2:3]
	v_lshl_add_u64 v[8:9], v[8:9], 0, v[32:33]
	global_load_dwordx4 v[28:31], v[8:9], off
	global_load_dwordx4 v[20:23], v[8:9], off offset:1024
	global_load_dwordx4 v[16:19], v[8:9], off offset:2048
	global_load_dwordx4 v[8:11], v[8:9], off offset:3072
	v_lshl_add_u64 v[58:59], v[58:59], 2, s[40:41]
	s_waitcnt vmcnt(7)
	v_mov_b32_e32 v72, v25
	s_waitcnt vmcnt(6)
	v_mov_b32_e32 v73, v13
	s_waitcnt vmcnt(5)
	v_mov_b32_e32 v80, v5
	s_waitcnt vmcnt(4)
	v_mov_b32_e32 v81, v1
	v_mov_b32_e32 v70, v24
	v_mov_b32_e32 v71, v12
	v_mov_b32_e32 v76, v4
	v_mov_b32_e32 v77, v0
	v_pk_mul_f32 v[72:73], v[72:73], v[72:73]
	v_pk_mul_f32 v[80:81], v[80:81], v[80:81]
	v_lshl_add_u64 v[86:87], v[58:59], 0, s[4:5]
	v_mov_b32_e32 v74, v26
	v_mov_b32_e32 v75, v14
	v_mov_b32_e32 v82, v6
	v_mov_b32_e32 v83, v2
	v_lshl_add_u64 v[58:59], v[58:59], 0, v[32:33]
	v_pk_fma_f32 v[70:71], v[70:71], v[70:71], v[72:73]
	v_pk_fma_f32 v[72:73], v[76:77], v[76:77], v[80:81]
	v_lshl_add_u64 v[76:77], v[86:87], 0, v[32:33]
	global_load_dwordx4 v[66:69], v[34:35], off
	v_pk_fma_f32 v[80:81], v[74:75], v[74:75], v[70:71]
	v_pk_fma_f32 v[82:83], v[82:83], v[82:83], v[72:73]
	global_load_dwordx4 v[70:73], v[58:59], off
	global_load_dwordx4 v[74:77], v[76:77], off
	v_mov_b32_e32 v78, v27
	v_mov_b32_e32 v79, v15
	v_mov_b32_e32 v84, v7
	v_mov_b32_e32 v85, v3
	v_pk_fma_f32 v[78:79], v[78:79], v[78:79], v[80:81]
	v_pk_fma_f32 v[80:81], v[84:85], v[84:85], v[82:83]
	v_mov_b32_e32 v83, v78
	v_mov_b32_e32 v85, v80
	v_ashrrev_i32_e32 v53, 31, v52
	v_mov_b32_e32 v45, v33
	v_lshl_add_u64 v[56:57], v[56:57], 2, s[40:41]
	v_ashrrev_i32_e32 v55, 31, v54
	s_waitcnt vmcnt(6)
	v_mov_b32_e32 v94, v29
	s_waitcnt vmcnt(5)
	v_mov_b32_e32 v95, v21
	v_mov_b32_e32 v92, v28
	v_mov_b32_e32 v93, v20
	s_waitcnt vmcnt(4)
	v_mov_b32_e32 v102, v17
	s_waitcnt vmcnt(3)
	v_mov_b32_e32 v103, v9
	v_pk_mul_f32 v[94:95], v[94:95], v[94:95]
	v_mov_b32_e32 v88, v30
	v_mov_b32_e32 v89, v22
	v_mov_b32_e32 v100, v16
	v_mov_b32_e32 v101, v8
	v_pk_mul_f32 v[102:103], v[102:103], v[102:103]
	v_pk_fma_f32 v[92:93], v[92:93], v[92:93], v[94:95]
	v_mov_b32_e32 v90, v31
	v_mov_b32_e32 v91, v23
	v_mov_b32_e32 v96, v18
	v_mov_b32_e32 v97, v10
	v_pk_fma_f32 v[94:95], v[100:101], v[100:101], v[102:103]
	v_pk_fma_f32 v[88:89], v[88:89], v[88:89], v[92:93]
	v_mov_b32_e32 v98, v19
	v_mov_b32_e32 v99, v11
	v_pk_fma_f32 v[92:93], v[96:97], v[96:97], v[94:95]
	v_pk_fma_f32 v[88:89], v[90:91], v[90:91], v[88:89]
	v_pk_fma_f32 v[90:91], v[98:99], v[98:99], v[92:93]
	v_mov_b32_e32 v82, v88
	v_mov_b32_e32 v78, v89
	v_mov_b32_e32 v84, v90
	v_pk_add_f32 v[78:79], v[82:83], v[78:79]
	v_mov_b32_e32 v80, v91
	v_pk_add_f32 v[78:79], v[78:79], v[84:85]
	s_waitcnt vmcnt(0)
	v_pk_add_f32 v[74:75], v[74:75], 1.0 op_sel_hi:[1,0]
	v_pk_add_f32 v[78:79], v[78:79], v[80:81]
	ds_bpermute_b32 v81, v51, v79
	ds_bpermute_b32 v80, v51, v78
	v_pk_add_f32 v[76:77], v[76:77], 1.0 op_sel_hi:[1,0]
	v_lshlrev_b64 v[82:83], 11, v[52:53]
	v_lshl_add_u64 v[82:83], v[42:43], 0, v[82:83]
	v_add_u32_e32 v52, s9, v52
	s_waitcnt lgkmcnt(0)
	v_pk_add_f32 v[78:79], v[78:79], v[80:81]
	ds_bpermute_b32 v81, v60, v79
	ds_bpermute_b32 v80, v60, v78
	s_waitcnt lgkmcnt(0)
	v_pk_add_f32 v[78:79], v[78:79], v[80:81]
	ds_bpermute_b32 v81, v61, v79
	ds_bpermute_b32 v80, v61, v78
	s_waitcnt lgkmcnt(0)
	v_pk_add_f32 v[78:79], v[78:79], v[80:81]
	ds_bpermute_b32 v81, v62, v79
	ds_bpermute_b32 v80, v62, v78
	s_waitcnt lgkmcnt(0)
	v_pk_add_f32 v[78:79], v[78:79], v[80:81]
	ds_bpermute_b32 v81, v63, v79
	ds_bpermute_b32 v80, v63, v78
	s_waitcnt lgkmcnt(0)
	v_pk_add_f32 v[78:79], v[78:79], v[80:81]
	ds_bpermute_b32 v81, v64, v79
	ds_bpermute_b32 v80, v64, v78
	s_waitcnt lgkmcnt(0)
	v_pk_add_f32 v[78:79], v[78:79], v[80:81]
	s_nop 0
	v_pk_fma_f32 v[78:79], v[78:79], s[8:9], v[50:51] op_sel_hi:[1,0,0]
	v_lshl_add_u64 v[80:81], v[86:87], 0, v[44:45]
	v_mul_f32_e32 v47, 0x4b800000, v79
	v_cmp_gt_f32_e32 vcc, s15, v79
	s_nop 1
	v_cndmask_b32_e32 v47, v79, v47, vcc
	v_rsq_f32_e32 v47, v47
	s_nop 0
	v_mul_f32_e32 v49, 0x45800000, v47
	v_cndmask_b32_e32 v84, v47, v49, vcc
	v_pk_mul_f32 v[24:25], v[24:25], v[84:85] op_sel_hi:[1,0]
	v_pk_mul_f32 v[26:27], v[26:27], v[84:85] op_sel_hi:[1,0]
	v_pk_mul_f32 v[24:25], v[66:67], v[24:25]
	v_pk_mul_f32 v[26:27], v[68:69], v[26:27]
	v_pk_fma_f32 v[24:25], v[74:75], v[24:25], v[70:71]
	v_pk_fma_f32 v[26:27], v[26:27], v[76:77], v[72:73]
	v_cvt_pk_bf16_f32 v24, v24, v25
	v_cvt_pk_bf16_f32 v25, v26, v27
	global_store_dwordx2 v[82:83], v[24:25], off
	global_load_dwordx4 v[24:27], v[36:37], off
	global_load_dwordx4 v[66:69], v[80:81], off
	global_load_dwordx4 v[70:73], v[58:59], off offset:1024
	v_pk_mul_f32 v[12:13], v[12:13], v[84:85] op_sel_hi:[1,0]
	v_pk_mul_f32 v[14:15], v[14:15], v[84:85] op_sel_hi:[1,0]
	v_mov_b32_e32 v47, v33
	v_lshl_add_u64 v[74:75], v[86:87], 0, v[46:47]
	v_pk_mul_f32 v[4:5], v[4:5], v[84:85] op_sel_hi:[1,0]
	v_pk_mul_f32 v[6:7], v[6:7], v[84:85] op_sel_hi:[1,0]
	v_mov_b32_e32 v49, v33
	v_pk_mul_f32 v[0:1], v[0:1], v[84:85] op_sel_hi:[1,0]
	v_pk_mul_f32 v[2:3], v[2:3], v[84:85] op_sel_hi:[1,0]
	v_cmp_gt_f32_e32 vcc, s15, v78
	s_waitcnt vmcnt(2)
	v_pk_mul_f32 v[12:13], v[12:13], v[24:25]
	s_waitcnt vmcnt(1)
	v_pk_add_f32 v[24:25], v[66:67], 1.0 op_sel_hi:[1,0]
	v_pk_mul_f32 v[14:15], v[14:15], v[26:27]
	v_pk_add_f32 v[26:27], v[68:69], 1.0 op_sel_hi:[1,0]
	s_waitcnt vmcnt(0)
	v_pk_fma_f32 v[12:13], v[12:13], v[24:25], v[70:71]
	v_pk_fma_f32 v[14:15], v[14:15], v[26:27], v[72:73]
	v_cvt_pk_bf16_f32 v12, v12, v13
	v_cvt_pk_bf16_f32 v13, v14, v15
	global_store_dwordx2 v[82:83], v[12:13], off offset:512
	global_load_dwordx4 v[12:15], v[38:39], off
	global_load_dwordx4 v[24:27], v[74:75], off
	global_load_dwordx4 v[66:69], v[58:59], off offset:2048
	v_lshl_add_u64 v[70:71], v[86:87], 0, v[48:49]
	s_waitcnt vmcnt(2)
; __device__ __forceinline__ void phase_norm(const float* lat_src, const float* ctx_src, const float* gain, const float* modl,
;                                            int sh_off, int sc_off, bf16_t* A, bool lat_only) {
;     ...
;   for (int idx0 = (blockIdx.x * 4 + wave) * 2; idx0 < total; idx0 += gridDim.x * 8) {
;     float4 xv[2][4];
;     const float* md[2];
;     int rowi[2];
; #pragma unroll
;     for (int u = 0; u < 2; ++u) {
;       const int idx = idx0 + u;
;       const int row = lat_only ? ((idx >> 14) * TPB + 256 + (idx & 16383)) : idx;
;       const int b = row / TPB, kidx = row - b * TPB;
;       const bool isc = kidx < 256;
;       const float* src = isc ? ctx_src + (size_t)(b * 256 + kidx) * DM : lat_src + (size_t)(b * 16384 + kidx - 256) * DM;
;       md[u] = modl + (isc ? 2 : b) * 6144;
;       rowi[u] = row;
; #pragma unroll
;       for (int i = 0; i < 4; ++i) xv[u][i] = *(const float4*)(src + i * 256 + lane * 4);
;     ...
; #pragma unroll
;     for (int u = 0; u < 2; ++u) {
;       float ss = 0.f;
; #pragma unroll
;       for (int i = 0; i < 4; ++i) ss += xv[u][i].x * xv[u][i].x + xv[u][i].y * xv[u][i].y + xv[u][i].z * xv[u][i].z + xv[u][i].w * xv[u][i].w;
;       ss = wave_sum(ss);
;       const float rstd = rsqrtf(ss * (1.0f / 1024.0f) + 1e-6f);
; #pragma unroll
;       for (int i = 0; i < 4; ++i) {
;         const int c = i * 256 + lane * 4;
;         const float4 g = *(const float4*)(gain + c);
;         const float4 sh = *(const float4*)(md[u] + sh_off + c);
;         const float4 sc = *(const float4*)(md[u] + sc_off + c);
;         uint2 w;
;         w.x = pack2(xv[u][i].x * rstd * g.x * (1.f + sc.x) + sh.x, xv[u][i].y * rstd * g.y * (1.f + sc.y) + sh.y);
;         w.y = pack2(xv[u][i].z * rstd * g.z * (1.f + sc.z) + sh.z, xv[u][i].w * rstd * g.w * (1.f + sc.w) + sh.w);
;         *(uint2*)(A + (size_t)rowi[u] * DM + c) = w;
;       }
;     }
	v_pk_mul_f32 v[4:5], v[4:5], v[12:13]
	s_waitcnt vmcnt(1)
	v_pk_add_f32 v[12:13], v[24:25], 1.0 op_sel_hi:[1,0]
	v_pk_mul_f32 v[6:7], v[6:7], v[14:15]
	v_pk_add_f32 v[14:15], v[26:27], 1.0 op_sel_hi:[1,0]
	s_waitcnt vmcnt(0)
	v_pk_fma_f32 v[4:5], v[4:5], v[12:13], v[66:67]
	v_pk_fma_f32 v[6:7], v[6:7], v[14:15], v[68:69]
	v_cvt_pk_bf16_f32 v4, v4, v5
	v_cvt_pk_bf16_f32 v5, v6, v7
	global_store_dwordx2 v[82:83], v[4:5], off offset:1024
	global_load_dwordx4 v[4:7], v[40:41], off
	global_load_dwordx4 v[12:15], v[70:71], off
	global_load_dwordx4 v[24:27], v[58:59], off offset:3072
	v_lshl_add_u64 v[58:59], v[56:57], 0, s[4:5]
	v_lshl_add_u64 v[66:67], v[58:59], 0, v[32:33]
	s_waitcnt vmcnt(2)
	v_pk_mul_f32 v[0:1], v[0:1], v[4:5]
	s_waitcnt vmcnt(1)
	v_pk_add_f32 v[4:5], v[12:13], 1.0 op_sel_hi:[1,0]
	v_pk_mul_f32 v[2:3], v[2:3], v[6:7]
	v_pk_add_f32 v[6:7], v[14:15], 1.0 op_sel_hi:[1,0]
	s_waitcnt vmcnt(0)
	v_pk_fma_f32 v[0:1], v[0:1], v[4:5], v[24:25]
	v_pk_fma_f32 v[2:3], v[2:3], v[6:7], v[26:27]
	v_cvt_pk_bf16_f32 v0, v0, v1
	v_cvt_pk_bf16_f32 v1, v2, v3
	global_store_dwordx2 v[82:83], v[0:1], off offset:1536
	global_load_dwordx4 v[0:3], v[34:35], off
	global_load_dwordx4 v[4:7], v[66:67], off
	v_lshl_add_u64 v[24:25], v[56:57], 0, v[32:33]
	global_load_dwordx4 v[12:15], v[24:25], off
	v_mul_f32_e32 v26, 0x4b800000, v78
	v_cndmask_b32_e32 v26, v78, v26, vcc
	v_rsq_f32_e32 v53, v26
	v_lshlrev_b64 v[26:27], 11, v[54:55]
	v_lshl_add_u64 v[54:55], v[58:59], 0, v[44:45]
	v_lshl_add_u64 v[26:27], v[42:43], 0, v[26:27]
	v_mul_f32_e32 v45, 0x45800000, v53
	v_cndmask_b32_e32 v56, v53, v45, vcc
	v_pk_mul_f32 v[28:29], v[28:29], v[56:57] op_sel_hi:[1,0]
	v_pk_mul_f32 v[30:31], v[30:31], v[56:57] op_sel_hi:[1,0]
	v_pk_mul_f32 v[20:21], v[20:21], v[56:57] op_sel_hi:[1,0]
	v_pk_mul_f32 v[22:23], v[22:23], v[56:57] op_sel_hi:[1,0]
	v_pk_mul_f32 v[16:17], v[16:17], v[56:57] op_sel_hi:[1,0]
	v_pk_mul_f32 v[18:19], v[18:19], v[56:57] op_sel_hi:[1,0]
	v_pk_mul_f32 v[8:9], v[8:9], v[56:57] op_sel_hi:[1,0]
	v_pk_mul_f32 v[10:11], v[10:11], v[56:57] op_sel_hi:[1,0]
	v_cmp_lt_i32_e32 vcc, s16, v52
	s_or_b64 s[6:7], vcc, s[6:7]
	s_waitcnt vmcnt(2)
	v_pk_mul_f32 v[0:1], v[0:1], v[28:29]
	s_waitcnt vmcnt(1)
	v_pk_add_f32 v[4:5], v[4:5], 1.0 op_sel_hi:[1,0]
	v_pk_mul_f32 v[2:3], v[2:3], v[30:31]
	v_pk_add_f32 v[6:7], v[6:7], 1.0 op_sel_hi:[1,0]
	s_waitcnt vmcnt(0)
	v_pk_fma_f32 v[0:1], v[4:5], v[0:1], v[12:13]
	v_pk_fma_f32 v[2:3], v[2:3], v[6:7], v[14:15]
	v_cvt_pk_bf16_f32 v0, v0, v1
	v_cvt_pk_bf16_f32 v1, v2, v3
	global_store_dwordx2 v[26:27], v[0:1], off
	global_load_dwordx4 v[0:3], v[36:37], off
	global_load_dwordx4 v[4:7], v[54:55], off
	global_load_dwordx4 v[12:15], v[24:25], off offset:1024
	v_lshl_add_u64 v[28:29], v[58:59], 0, v[46:47]
	s_waitcnt vmcnt(2)
	v_pk_mul_f32 v[0:1], v[20:21], v[0:1]
	s_waitcnt vmcnt(1)
	v_pk_add_f32 v[4:5], v[4:5], 1.0 op_sel_hi:[1,0]
	v_pk_mul_f32 v[2:3], v[22:23], v[2:3]
	v_pk_add_f32 v[6:7], v[6:7], 1.0 op_sel_hi:[1,0]
	s_waitcnt vmcnt(0)
	v_pk_fma_f32 v[0:1], v[0:1], v[4:5], v[12:13]
	v_pk_fma_f32 v[2:3], v[2:3], v[6:7], v[14:15]
	v_cvt_pk_bf16_f32 v0, v0, v1
	v_cvt_pk_bf16_f32 v1, v2, v3
	global_store_dwordx2 v[26:27], v[0:1], off offset:512
	global_load_dwordx4 v[0:3], v[38:39], off
	global_load_dwordx4 v[4:7], v[28:29], off
	global_load_dwordx4 v[12:15], v[24:25], off offset:2048
	v_lshl_add_u64 v[20:21], v[58:59], 0, v[48:49]
	s_waitcnt vmcnt(2)
	v_pk_mul_f32 v[0:1], v[16:17], v[0:1]
	s_waitcnt vmcnt(1)
	v_pk_add_f32 v[4:5], v[4:5], 1.0 op_sel_hi:[1,0]
	v_pk_mul_f32 v[2:3], v[18:19], v[2:3]
	v_pk_add_f32 v[6:7], v[6:7], 1.0 op_sel_hi:[1,0]
	s_waitcnt vmcnt(0)
	v_pk_fma_f32 v[0:1], v[0:1], v[4:5], v[12:13]
	v_pk_fma_f32 v[2:3], v[2:3], v[6:7], v[14:15]
	v_cvt_pk_bf16_f32 v0, v0, v1
	v_cvt_pk_bf16_f32 v1, v2, v3
	global_store_dwordx2 v[26:27], v[0:1], off offset:1024
	global_load_dwordx4 v[0:3], v[40:41], off
	global_load_dwordx4 v[4:7], v[20:21], off
	global_load_dwordx4 v[12:15], v[24:25], off offset:3072
	s_waitcnt vmcnt(2)
	v_pk_mul_f32 v[0:1], v[8:9], v[0:1]
	s_waitcnt vmcnt(1)
	v_pk_add_f32 v[4:5], v[4:5], 1.0 op_sel_hi:[1,0]
	v_pk_mul_f32 v[2:3], v[10:11], v[2:3]
	v_pk_add_f32 v[6:7], v[6:7], 1.0 op_sel_hi:[1,0]
	s_waitcnt vmcnt(0)
	v_pk_fma_f32 v[0:1], v[0:1], v[4:5], v[12:13]
	v_pk_fma_f32 v[2:3], v[2:3], v[6:7], v[14:15]
	v_cvt_pk_bf16_f32 v0, v0, v1
	v_cvt_pk_bf16_f32 v1, v2, v3
	global_store_dwordx2 v[26:27], v[0:1], off offset:1536
	s_andn2_b64 exec, exec, s[6:7]
	s_cbranch_execz .LBB0_791
.LBB0_783:
	v_mul_hi_i32 v0, v52, s10
	v_lshrrev_b32_e32 v1, 31, v0
	v_ashrrev_i32_e32 v0, 13, v0
	v_add_u32_e32 v2, v0, v1
	v_mad_i32_i24 v0, v2, s11, v52
	v_mul_i32_i24_e32 v3, 0xffffbf00, v2
	v_cmp_lt_i32_e32 vcc, s12, v0
	s_and_saveexec_b64 s[2:3], vcc
	s_xor_b64 s[2:3], exec, s[2:3]
	v_lshl_add_u32 v0, v2, 14, v3
	v_add3_u32 v0, v52, v0, s13
	v_ashrrev_i32_e32 v1, 31, v0
	v_lshlrev_b64 v[0:1], 12, v[0:1]
	v_mul_i32_i24_e32 v58, 0x1800, v2
	v_lshl_add_u64 v[0:1], s[92:93], 0, v[0:1]
	v_ashrrev_i32_e32 v59, 31, v58
	s_andn2_saveexec_b64 s[2:3], s[2:3]
	v_lshlrev_b32_e32 v0, 8, v2
	v_add3_u32 v0, v3, v0, v52
	v_ashrrev_i32_e32 v1, 31, v0
	v_lshlrev_b64 v[0:1], 12, v[0:1]
	v_lshl_add_u64 v[0:1], s[68:69], 0, v[0:1]
	v_mov_b64_e32 v[58:59], 0x3000
	s_or_b64 exec, exec, s[2:3]
	v_lshl_add_u64 v[0:1], v[0:1], 0, v[32:33]
	global_load_dwordx4 v[24:27], v[0:1], off
	global_load_dwordx4 v[12:15], v[0:1], off offset:1024
	global_load_dwordx4 v[4:7], v[0:1], off offset:2048
	global_load_dwordx4 v[0:3], v[0:1], off offset:3072
	v_add_u32_e32 v54, 1, v52
	v_mul_hi_i32 v8, v54, s10
	v_lshrrev_b32_e32 v9, 31, v8
	v_ashrrev_i32_e32 v8, 13, v8
	v_add_u32_e32 v10, v8, v9
	v_mad_i32_i24 v8, v10, s11, v54
	v_mul_i32_i24_e32 v11, 0xffffbf00, v10
	v_cmp_lt_i32_e32 vcc, s12, v8
	s_and_saveexec_b64 s[2:3], vcc
	s_xor_b64 s[2:3], exec, s[2:3]
	v_lshl_add_u32 v8, v10, 14, v11
	v_add3_u32 v8, v52, v8, s14
	v_ashrrev_i32_e32 v9, 31, v8
	v_lshlrev_b64 v[8:9], 12, v[8:9]
	v_mul_i32_i24_e32 v56, 0x1800, v10
	v_lshl_add_u64 v[8:9], s[92:93], 0, v[8:9]
	v_ashrrev_i32_e32 v57, 31, v56
	s_andn2_saveexec_b64 s[2:3], s[2:3]
	s_cbranch_execz .LBB0_782
	v_lshl_add_u32 v8, v10, 8, v11
	v_add3_u32 v8, v52, v8, 1
	v_ashrrev_i32_e32 v9, 31, v8
	v_lshlrev_b64 v[8:9], 12, v[8:9]
	v_lshl_add_u64 v[8:9], s[68:69], 0, v[8:9]
	v_mov_b64_e32 v[56:57], 0x3000
	s_branch .LBB0_782

; template <bool DEEP, class Epi>
; __device__ __forceinline__ void gemm_phase(const bf16_t* __restrict__ A, int lda, const bf16_t* __restrict__ Wt,
;                                            int K, int ntn, bool lat_only, const Epi& epi, char* smem) {
;     ...
;     for (int kt = 0; kt < nk; ++kt) {
;       __syncthreads();
;       GEMM_STORE(ra0, ra1, ra2, ra3, rb0, rb1, rb2, rb3, 0)
;       __syncthreads();
;       {
;         bf16x8 af0[4], bf0[4], af1[4], bf1[4];
;         __builtin_amdgcn_s_setprio(1);
; #pragma unroll
;         for (int i = 0; i < 4; ++i) af0[i] = *(const bf16x8*)(sA + (wm * 64 + i * 16 + l15) * LSTR + quad * 8);
; #pragma unroll
;         for (int j = 0; j < 4; ++j) bf0[j] = *(const bf16x8*)(sB + (wn * 64 + j * 16 + l15) * LSTR + quad * 8);
; #pragma unroll
;         for (int i = 0; i < 4; ++i) af1[i] = *(const bf16x8*)(sA + (wm * 64 + i * 16 + l15) * LSTR + 32 + quad * 8);
; #pragma unroll
;         for (int j = 0; j < 4; ++j) bf1[j] = *(const bf16x8*)(sB + (wn * 64 + j * 16 + l15) * LSTR + 32 + quad * 8);
;         __builtin_amdgcn_sched_barrier(0);
;         if (kt + 1 < nk) GEMM_LOAD(ra0, ra1, ra2, ra3, rb0, rb1, rb2, rb3, (kt + 1) * 64)
;         __builtin_amdgcn_sched_barrier(0);
.LBB0_848:
	s_waitcnt vmcnt(63) expcnt(7) lgkmcnt(15)
	s_barrier
	s_waitcnt vmcnt(7)
	ds_write_b128 v173, v[64:67]
	s_waitcnt vmcnt(6)
	ds_write_b128 v173, v[68:71] offset:5120
	s_waitcnt vmcnt(5)
	ds_write_b128 v173, v[72:75] offset:10240
	s_waitcnt vmcnt(4)
	ds_write_b128 v173, v[76:79] offset:15360
	s_waitcnt vmcnt(3)
	ds_write_b128 v173, v[80:83] offset:20480
	s_waitcnt vmcnt(2)
	ds_write_b128 v173, v[84:87] offset:25600
	s_waitcnt vmcnt(1)
	ds_write_b128 v173, v[88:91] offset:30720
	s_waitcnt vmcnt(0)
	ds_write_b128 v173, v[92:95] offset:35840
	v_add_u32_e32 v96, v183, v187
	s_waitcnt lgkmcnt(0)
	s_barrier
	s_setprio 1
	ds_read_b128 v[156:159], v96
	ds_read_b128 v[152:155], v96 offset:2560
	ds_read_b128 v[132:135], v96 offset:5120
	ds_read_b128 v[124:127], v96 offset:7680
	ds_read_b128 v[136:139], v189 offset:20480
	ds_read_b128 v[140:143], v189 offset:23040
	ds_read_b128 v[144:147], v189 offset:25600
	ds_read_b128 v[148:151], v189 offset:28160
	ds_read_b128 v[128:131], v191 offset:64
	ds_read_b128 v[120:123], v191 offset:2624
	ds_read_b128 v[100:103], v191 offset:5184
	ds_read_b128 v[96:99], v191 offset:7744
	ds_read_b128 v[104:107], v193 offset:20544
	ds_read_b128 v[108:111], v193 offset:23104
	ds_read_b128 v[112:115], v193 offset:25664
	ds_read_b128 v[116:119], v193 offset:28224
	s_cmpk_eq_i32 s6, 0x780
	s_cbranch_scc1 .LBB0_847
	v_lshl_add_u64 v[72:73], v[204:205], 0, s[6:7]
	v_add_co_u32_e32 v64, vcc, 0x1d00000, v72
	v_lshl_add_u64 v[88:89], v[206:207], 0, s[6:7]
	s_nop 0
	v_addc_co_u32_e32 v65, vcc, 0, v73, vcc
	v_add_co_u32_e32 v68, vcc, 0x1d10000, v72
	s_nop 1
	v_addc_co_u32_e32 v69, vcc, 0, v73, vcc
	v_add_co_u32_e32 v74, vcc, 0x1d20000, v72
	global_load_dwordx4 v[64:67], v[64:65], off offset:128
	global_load_dwordx4 v[68:71], v[68:69], off offset:128
	v_addc_co_u32_e32 v75, vcc, 0, v73, vcc
	v_add_co_u32_e32 v76, vcc, 0x1d30000, v72
	s_nop 1
	v_addc_co_u32_e32 v77, vcc, 0, v73, vcc
	v_add_co_u32_e32 v84, vcc, 0x10000, v88
	global_load_dwordx4 v[72:75], v[74:75], off offset:128
	global_load_dwordx4 v[76:79], v[76:77], off offset:128
	v_addc_co_u32_e32 v85, vcc, 0, v89, vcc
	v_add_co_u32_e32 v90, vcc, 0x20000, v88
	global_load_dwordx4 v[80:83], v[88:89], off offset:128
	global_load_dwordx4 v[84:87], v[84:85], off offset:128
	v_addc_co_u32_e32 v91, vcc, 0, v89, vcc
	v_add_co_u32_e32 v92, vcc, 0x30000, v88
	s_nop 1
	v_addc_co_u32_e32 v93, vcc, 0, v89, vcc
	global_load_dwordx4 v[88:91], v[90:91], off offset:128
	global_load_dwordx4 v[92:95], v[92:93], off offset:128
	s_branch .LBB0_847

; template <int NMAP, int NDT, int MODE, bool FIXED> ...
;     ...
;   for (int n = 0; n < ntiles; ++n) {
;     const int kidx0 = (MODE == 0) ? n * 64 : (n < 4 ? n * 64 : seg_lo + (n - 4) * 64);
;     __syncthreads();
;     *(uint4*)(sK + (lr) * LSTR + lch) = rk00;
;     *(uint4*)(sK + (lr + 32) * LSTR + lch) = rk01;
;     if (NMAP > 1) {
;       *(uint4*)(sK + (64 + lr) * LSTR + lch) = rk10;
;       *(uint4*)(sK + (64 + lr + 32) * LSTR + lch) = rk11;
;     }
;     *(uint4*)(sVt + (lr) * LSTR + lch) = rv0;
;     *(uint4*)(sVt + (lr + 32) * LSTR + lch) = rv1;
;     if (NVL > 2) {
;       *(uint4*)(sVt + (lr + 64) * LSTR + lch) = rv2;
;       *(uint4*)(sVt + (lr + 96) * LSTR + lch) = rv3;
;     }
;     __syncthreads();
;     const int knext = (MODE == 0) ? (n + 1) * 64 : ((n + 1) < 4 ? (n + 1) * 64 : seg_lo + (n + 1 - 4) * 64);
;     if (n + 1 < ntiles) {
;       ATTN_LOAD_K(knext)
;     }
;     bf16x8 pf[NMAP][2];
; #pragma unroll
;     for (int c = 0; c < NMAP; ++c) {
;       f32x4 s[4];
; #pragma unroll
;       for (int kt = 0; kt < 4; ++kt) {
;         const float ini = FIXED ? negM : 0.f;
;         s[kt] = (f32x4){ini, ini, ini, ini};
;         const int krow = 32 * (kt >> 1) + (l15 >> 2) * 8 + (kt & 1) * 4 + (l15 & 3);
; #pragma unroll
;         for (int ks = 0; ks < 2; ++ks) {
;           const bf16x8 kf = *(const bf16x8*)(sK + (c * 64 + krow) * LSTR + ks * 32 + quad * 8);
;           s[kt] = __builtin_amdgcn_mfma_f32_16x16x32_bf16(kf, qf[c][ks], s[kt], 0, 0, 0);
;         }
;       }
;     ...
;       if (MODE == 2 && n >= 4) {
;         const int ri = na_r0 + (n - 4) - na_i + 7;
;         const int qc = wave * 16 + l15;
;         const int cs = min(max(qc - 8, 0), 48);
; #pragma unroll
;         for (int kt = 0; kt < 4; ++kt)
; #pragma unroll
;           for (int e = 0; e < 4; ++e) {
;             const int kc = 32 * (kt >> 1) + quad * 8 + (kt & 1) * 4 + e;
;             if (kc >= cs && kc < cs + 16) s[kt][e] += s_rpb[ri * 31 + kc - qc + 15];
;             else s[kt][e] = -1e30f;
;           }
.LBB0_989:
	s_waitcnt vmcnt(63) expcnt(7) lgkmcnt(15)
	s_barrier
	s_waitcnt vmcnt(3)
	ds_write_b128 v69, v[24:27]
	s_waitcnt vmcnt(2)
	ds_write_b128 v70, v[28:31]
	s_waitcnt vmcnt(1)
	ds_write_b128 v69, v[32:35] offset:10240
	s_waitcnt vmcnt(0)
	ds_write_b128 v70, v[36:39] offset:10240
	s_waitcnt lgkmcnt(0)
	s_barrier
	ds_read_b128 v[24:27], v71
	ds_read_b128 v[28:31], v71 offset:64
	ds_read_b128 v[32:35], v71 offset:640
	s_waitcnt lgkmcnt(2)
	v_mfma_f32_16x16x32_bf16 v[24:27], v[24:27], v[20:23], 0
	s_add_i32 s2, s84, s85
	s_cmp_lt_u32 s9, 3
	s_cselect_b32 s82, s85, s2
	s_waitcnt lgkmcnt(1)
	v_mfma_f32_16x16x32_bf16 v[44:47], v[28:31], v[16:19], v[24:27]
	s_nop 2
	ds_read_b128 v[24:27], v71 offset:704
	ds_read_b128 v[28:31], v71 offset:5120
	ds_read_b128 v[36:39], v71 offset:5184
	s_ashr_i32 s83, s82, 31
	s_waitcnt lgkmcnt(3)
	v_mfma_f32_16x16x32_bf16 v[32:35], v[32:35], v[20:23], 0
	s_lshl_b64 s[2:3], s[82:83], 10
	s_add_u32 s2, s74, s2
	s_addc_u32 s3, s75, s3
	s_waitcnt lgkmcnt(2)
	v_mfma_f32_16x16x32_bf16 v[40:43], v[24:27], v[16:19], v[32:35]
	ds_read_b128 v[24:27], v71 offset:5760
	s_cmp_lt_u32 s9, 4
	s_waitcnt lgkmcnt(2)
	v_mfma_f32_16x16x32_bf16 v[28:31], v[28:31], v[20:23], 0
	ds_read_b128 v[32:35], v71 offset:5824
	s_waitcnt lgkmcnt(2)
	v_mfma_f32_16x16x32_bf16 v[36:39], v[36:39], v[16:19], v[28:31]
	s_waitcnt lgkmcnt(1)
	v_mfma_f32_16x16x32_bf16 v[76:79], v[24:27], v[20:23], 0
	s_nop 2
	v_lshl_add_u64 v[28:29], s[2:3], 0, v[54:55]
	v_lshl_add_u64 v[30:31], s[2:3], 0, v[48:49]
	global_load_dwordx4 v[24:27], v[30:31], off
	global_load_dwordx4 v[28:31], v[28:29], off
	s_waitcnt lgkmcnt(0)
	v_mfma_f32_16x16x32_bf16 v[32:35], v[32:35], v[16:19], v[76:79]
	s_cbranch_scc1 .LBB0_1023
	v_mov_b32_e32 v75, 0xf149f2ca
	s_nop 0
	v_mov_b32_e32 v76, 0xf149f2ca
	s_and_saveexec_b64 s[2:3], s[72:73]
	s_cbranch_execz .LBB0_992
	ds_read_b32 v76, v72
	s_waitcnt lgkmcnt(0)
	v_add_f32_e32 v76, v44, v76

; __device__ __forceinline__ float fexp2(float x) { return __builtin_amdgcn_exp2f(x); }
; template <int NMAP, int NDT, int MODE, bool FIXED> ...
;     ...
;       } else {
;         float mx = s[0][0];
; #pragma unroll
;         for (int kt = 0; kt < 4; ++kt)
; #pragma unroll
;           for (int e = 0; e < 4; ++e) mx = fmaxf(mx, s[kt][e]);
;         mx = fmaxf(mx, __shfl_xor(mx, 16));
;         mx = fmaxf(mx, __shfl_xor(mx, 32));
;         const float mnew = fmaxf(m[c], mx);
;         const float alpha = fexp2(m[c] - mnew);
;         m[c] = mnew;
;         float ls = 0.f;
; #pragma unroll
;         for (int kt = 0; kt < 4; ++kt)
; #pragma unroll
;           for (int e = 0; e < 4; ++e) {
;             s[kt][e] = fexp2(s[kt][e] - mnew);
;             ls += s[kt][e];
;           }
;         l[c] = l[c] * alpha + ls;
;         if (__ballot(alpha != 1.0f) != 0ull) {
; #pragma unroll
;           for (int dt = 0; dt < NDT; ++dt) o[c][dt] *= alpha;
;         }
;       }
;       __builtin_amdgcn_sched_barrier(0);
; #pragma unroll
;       for (int ks2 = 0; ks2 < 2; ++ks2) {
;         union { uint32_t u[4]; bf16x8 v; } pk;
;         pk.u[0] = pack2(s[2 * ks2][0], s[2 * ks2][1]);
;         pk.u[1] = pack2(s[2 * ks2][2], s[2 * ks2][3]);
;         pk.u[2] = pack2(s[2 * ks2 + 1][0], s[2 * ks2 + 1][1]);
;         pk.u[3] = pack2(s[2 * ks2 + 1][2], s[2 * ks2 + 1][3]);
;         pf[c][ks2] = pk.v;
;       }
;     }
;     if (n + 1 < ntiles) {
;       ATTN_LOAD_V(knext)
;     }
; #pragma unroll
;     for (int ks2 = 0; ks2 < 2; ++ks2) {
;       __builtin_amdgcn_sched_barrier(0);
; #pragma unroll
;       for (int dt = 0; dt < NDT; ++dt) {
;         const bf16x8 vf = *(const bf16x8*)(sVt + (dt * 16 + l15) * LSTR + 32 * ks2 + quad * 8);
; #pragma unroll
;         for (int c = 0; c < NMAP; ++c) o[c][dt] = __builtin_amdgcn_mfma_f32_16x16x32_bf16(vf, pf[c][ks2], o[c][dt], 0, 0, 0);
;       }
;     }
.LBB0_1026:
	v_sub_f32_e32 v33, v76, v41
	v_exp_f32_e32 v42, v33
	v_sub_f32_e32 v33, v75, v41
	v_exp_f32_e32 v43, v33
	v_sub_f32_e32 v33, v78, v41
	v_exp_f32_e32 v44, v33
	v_sub_f32_e32 v33, v77, v41
	v_exp_f32_e32 v45, v33
	v_sub_f32_e32 v34, v80, v41
	v_add_f32_e32 v33, 0, v42
	v_exp_f32_e32 v46, v34
	v_sub_f32_e32 v34, v79, v41
	v_add_f32_e32 v33, v43, v33
	v_exp_f32_e32 v47, v34
	v_sub_f32_e32 v34, v82, v41
	v_add_f32_e32 v33, v44, v33
	v_exp_f32_e32 v74, v34
	v_sub_f32_e32 v34, v81, v41
	v_add_f32_e32 v33, v45, v33
	v_exp_f32_e32 v75, v34
	v_sub_f32_e32 v34, v84, v41
	v_add_f32_e32 v33, v46, v33
	v_exp_f32_e32 v76, v34
	v_sub_f32_e32 v34, v83, v41
	v_add_f32_e32 v33, v47, v33
	v_exp_f32_e32 v77, v34
	v_sub_f32_e32 v34, v86, v41
	v_add_f32_e32 v33, v74, v33
	v_exp_f32_e32 v78, v34
	v_sub_f32_e32 v34, v85, v41
	v_add_f32_e32 v33, v75, v33
	v_exp_f32_e32 v79, v34
	v_sub_f32_e32 v34, v88, v41
	v_add_f32_e32 v33, v76, v33
	v_exp_f32_e32 v80, v34
	v_sub_f32_e32 v34, v87, v41
	v_add_f32_e32 v33, v77, v33
	v_exp_f32_e32 v81, v34
	v_sub_f32_e32 v34, v90, v41
	v_add_f32_e32 v33, v78, v33
	v_exp_f32_e32 v82, v34
	v_sub_f32_e32 v34, v89, v41
	v_add_f32_e32 v33, v79, v33
	v_exp_f32_e32 v83, v34
	v_add_f32_e32 v33, v80, v33
	v_add_f32_e32 v33, v81, v33
	v_add_f32_e32 v33, v82, v33
	v_add_f32_e32 v40, v83, v33
	v_fmac_f32_e32 v40, v73, v32
	s_add_i32 s9, s9, 1
	s_lshl_b64 s[2:3], s[82:83], 1
	s_add_u32 s2, s80, s2
	s_addc_u32 s3, s81, s3
	v_lshl_add_u64 v[36:37], s[2:3], 0, v[58:59]
	v_lshl_add_u64 v[32:33], s[2:3], 0, v[56:57]
	global_load_dwordx4 v[32:35], v[32:33], off
	global_load_dwordx4 v[36:39], v[36:37], off
	v_cvt_pk_bf16_f32 v42, v42, v43
	v_cvt_pk_bf16_f32 v43, v44, v45
	v_cvt_pk_bf16_f32 v44, v46, v47
	v_cvt_pk_bf16_f32 v45, v74, v75
	v_cvt_pk_bf16_f32 v74, v76, v77
	v_cvt_pk_bf16_f32 v75, v78, v79
	v_cvt_pk_bf16_f32 v76, v80, v81
	v_cvt_pk_bf16_f32 v77, v82, v83
	ds_read_b128 v[78:81], v67 offset:10240
	s_waitcnt lgkmcnt(0)
	v_mfma_f32_16x16x32_bf16 v[12:15], v[78:81], v[42:45], v[12:15]
	ds_read_b128 v[78:81], v67 offset:12800
	s_waitcnt lgkmcnt(0)
	v_mfma_f32_16x16x32_bf16 v[8:11], v[78:81], v[42:45], v[8:11]
	ds_read_b128 v[78:81], v67 offset:15360
	s_waitcnt lgkmcnt(0)
	v_mfma_f32_16x16x32_bf16 v[4:7], v[78:81], v[42:45], v[4:7]
	ds_read_b128 v[78:81], v67 offset:17920
	s_waitcnt lgkmcnt(0)
	v_mfma_f32_16x16x32_bf16 v[0:3], v[78:81], v[42:45], v[0:3]
	ds_read_b128 v[42:45], v67 offset:10304
	s_add_i32 s85, s85, 64
	v_add_u32_e32 v72, 0x7c, v72
	s_cmp_eq_u32 s9, 11
	s_waitcnt lgkmcnt(0)
	v_mfma_f32_16x16x32_bf16 v[12:15], v[42:45], v[74:77], v[12:15]
	ds_read_b128 v[42:45], v67 offset:12864
	s_waitcnt lgkmcnt(0)
	v_mfma_f32_16x16x32_bf16 v[8:11], v[42:45], v[74:77], v[8:11]
	ds_read_b128 v[42:45], v67 offset:15424
	s_waitcnt lgkmcnt(0)
	v_mfma_f32_16x16x32_bf16 v[4:7], v[42:45], v[74:77], v[4:7]
	ds_read_b128 v[42:45], v67 offset:17984
	s_waitcnt lgkmcnt(0)
	v_mfma_f32_16x16x32_bf16 v[0:3], v[42:45], v[74:77], v[0:3]
	s_cbranch_scc1 .LBB0_1028
	v_mov_b32_e32 v74, v41
	v_mov_b32_e32 v73, v40
	s_branch .LBB0_989

; __device__ __forceinline__ void phase_prep(const Params& P, char* smem) {
;     ...
;     for (int nt = 0; nt < 8; ++nt) {
;       const int n0 = wave * 128 + nt * 16;
;       bf16x8 wf[7];
; #pragma unroll
;       for (int kb = 0; kb < 7; ++kb) wf[kb] = *(const bf16x8*)(WL + (size_t)(n0 + l15) * 224 + kb * 32 + quad * 8);
;       const int c4 = n0 + quad * 4;
;       const float4 w00 = *(const float4*)(P.d_w0 + c4), w01 = *(const float4*)(P.d_w0 + 512 + c4);
;       const float4 a00 = *(const float4*)(P.d_a0 + c4), a01 = *(const float4*)(P.d_a0 + 512 + c4);
; #pragma unroll
;       for (int mt = 0; mt < PREP_T / 16; ++mt) {
;         bf16x8 af[7];
; #pragma unroll
;         for (int kb = 0; kb < 7; ++kb) af[kb] = *(const bf16x8*)(sL + (mt * 16 + l15) * SLS + kb * 32 + quad * 8);
;         const f32x4 zero = (f32x4){0.f, 0.f, 0.f, 0.f};
;         f32x4 aw0 = __builtin_amdgcn_mfma_f32_16x16x32_bf16(wf[0], af[0], zero, 0, 0, 0);
;         f32x4 aw1 = __builtin_amdgcn_mfma_f32_16x16x32_bf16(wf[1], af[1], zero, 0, 0, 0);
;         f32x4 aa0 = __builtin_amdgcn_mfma_f32_16x16x32_bf16(wf[2], af[2], zero, 0, 0, 0);
;         f32x4 aa1 = __builtin_amdgcn_mfma_f32_16x16x32_bf16(wf[3], af[3], zero, 0, 0, 0);
;         f32x4 ag = __builtin_amdgcn_mfma_f32_16x16x32_bf16(wf[4], af[4], zero, 0, 0, 0);
;         ag = __builtin_amdgcn_mfma_f32_16x16x32_bf16(wf[5], af[5], ag, 0, 0, 0);
;         ag = __builtin_amdgcn_mfma_f32_16x16x32_bf16(wf[6], af[6], ag, 0, 0, 0);
;         const size_t row = (size_t)(row0 + mt * 16 + l15);
;         float dp0[4], dp1[4], az0[4], az1[4];
; #pragma unroll
;         for (int e = 0; e < 4; ++e) {
;           const float wb0 = e == 0 ? w00.x : (e == 1 ? w00.y : (e == 2 ? w00.z : w00.w));
;           const float wb1 = e == 0 ? w01.x : (e == 1 ? w01.y : (e == 2 ? w01.z : w01.w));
;           const float ab0 = e == 0 ? a00.x : (e == 1 ? a00.y : (e == 2 ? a00.z : a00.w));
;           const float ab1 = e == 0 ? a01.x : (e == 1 ? a01.y : (e == 2 ? a01.z : a01.w));
; #pragma unroll
;           for (int z = 0; z < 2; ++z) {
;             const float wv = z == 0 ? wb0 + aw0[e] : wb1 + aw1[e];
;             const float ee = 0.60653066f * sigmoidf_(wv);
;             const float dpv = 1.0f - __expf(-ee);
;             const float av = sigmoidf_(z == 0 ? ab0 + aa0[e] : ab1 + aa1[e]);
.LBB0_1190:
	v_lshl_add_u64 v[56:57], s[94:95], 0, v[144:145]
	v_add_co_u32_e32 v64, vcc, 0x1b40000, v56
	v_lshl_add_u64 v[72:73], v[122:123], 0, s[0:1]
	s_nop 0
	v_addc_co_u32_e32 v65, vcc, 0, v57, vcc
	global_load_dwordx4 v[84:87], v[64:65], off
	global_load_dwordx4 v[88:91], v[64:65], off offset:64
	global_load_dwordx4 v[92:95], v[64:65], off offset:128
	global_load_dwordx4 v[96:99], v[64:65], off offset:192
	global_load_dwordx4 v[56:59], v[64:65], off offset:256
	global_load_dwordx4 v[60:63], v[64:65], off offset:320
	global_load_dwordx4 v[64:67], v[64:65], off offset:384
	global_load_dwordx4 v[68:71], v[72:73], off
	global_load_dwordx4 v[72:75], v[72:73], off offset:2048
	v_lshl_add_u64 v[80:81], v[126:127], 0, s[0:1]
	global_load_dwordx4 v[76:79], v[80:81], off
	global_load_dwordx4 v[80:83], v[80:81], off offset:2048
	s_add_u32 s0, s0, 64
	s_addc_u32 s1, s1, 0
	s_mov_b64 s[2:3], 0x1c00
	v_lshl_add_u64 v[144:145], v[144:145], 0, s[2:3]
	s_cmpk_eq_i32 s0, 0x200
	s_waitcnt vmcnt(10) lgkmcnt(13)
	v_mfma_f32_16x16x32_bf16 v[100:103], v[84:87], v[0:3], 0
	s_waitcnt vmcnt(3)
	s_nop 6
	v_add_f32_e32 v100, v68, v100
	s_waitcnt lgkmcnt(12)
	v_mfma_f32_16x16x32_bf16 v[146:149], v[88:91], v[4:7], 0
	v_add_f32_e32 v101, v69, v101
	v_mul_f32_e32 v100, 0xbfb8aa3b, v100
	v_mul_f32_e32 v101, 0xbfb8aa3b, v101
	v_exp_f32_e32 v100, v100
	v_exp_f32_e32 v101, v101
	s_waitcnt vmcnt(2)
	s_nop 1
	v_add_f32_e32 v133, v72, v146
	v_mul_f32_e32 v133, 0xbfb8aa3b, v133
	v_exp_f32_e32 v133, v133
	v_add_f32_e32 v100, 1.0, v100
	v_add_f32_e32 v101, 1.0, v101
	v_rcp_f32_e32 v100, v100
	v_rcp_f32_e32 v101, v101
	v_add_f32_e32 v133, 1.0, v133
	v_rcp_f32_e32 v133, v133
	s_waitcnt lgkmcnt(10)
	v_mfma_f32_16x16x32_bf16 v[172:175], v[96:99], v[12:15], 0
	v_mul_f32_e32 v100, 0xbf1b4598, v100
	v_mul_f32_e32 v101, 0xbf1b4598, v101
	v_mul_f32_e32 v100, 0x3fb8aa3b, v100
	v_mfma_f32_16x16x32_bf16 v[166:169], v[92:95], v[8:11], 0
	v_mul_f32_e32 v101, 0x3fb8aa3b, v101
	v_exp_f32_e32 v100, v100
	v_exp_f32_e32 v101, v101
	v_mul_f32_e32 v133, 0xbf1b4598, v133
	s_waitcnt vmcnt(0)
	v_add_f32_e32 v135, v80, v172
	v_mul_f32_e32 v133, 0x3fb8aa3b, v133
	v_exp_f32_e32 v146, v133
	v_mul_f32_e32 v133, 0xbfb8aa3b, v135
	v_add_f32_e32 v135, v77, v167
	v_pk_add_f32 v[150:151], v[100:101], 1.0 op_sel_hi:[1,0] neg_lo:[1,0] neg_hi:[1,0]
	v_mul_f32_e32 v100, 0xbfb8aa3b, v135
	v_exp_f32_e32 v100, v100
	v_add_f32_e32 v147, v73, v147
	s_waitcnt lgkmcnt(6)
	v_mfma_f32_16x16x32_bf16 v[84:87], v[84:87], v[28:31], 0
	v_add_f32_e32 v157, v81, v173
	v_add_f32_e32 v100, 1.0, v100
	v_rcp_f32_e32 v135, v100
	v_mul_f32_e32 v100, 0xbfb8aa3b, v147
	v_exp_f32_e32 v100, v100
	v_add_f32_e32 v101, v74, v148
	v_mul_f32_e32 v101, 0xbfb8aa3b, v101
	v_exp_f32_e32 v101, v101
	v_add_f32_e32 v100, 1.0, v100
	v_rcp_f32_e32 v100, v100
	s_waitcnt lgkmcnt(5)
	v_mfma_f32_16x16x32_bf16 v[88:91], v[88:91], v[32:35], 0
	v_add_f32_e32 v68, v68, v84
	v_add_f32_e32 v69, v69, v85
	v_mul_f32_e32 v100, 0xbf1b4598, v100
	v_mul_f32_e32 v100, 0x3fb8aa3b, v100
	v_exp_f32_e32 v147, v100
	v_mul_f32_e32 v100, 0xbfb8aa3b, v157
	v_exp_f32_e32 v100, v100
	s_waitcnt lgkmcnt(4)
	v_mfma_f32_16x16x32_bf16 v[92:95], v[92:95], v[36:39], 0
	v_mul_f32_e32 v68, 0xbfb8aa3b, v68
	v_mul_f32_e32 v69, 0xbfb8aa3b, v69
	v_exp_f32_e32 v68, v68
	v_exp_f32_e32 v69, v69
	v_add_f32_e32 v100, 1.0, v100
	v_rcp_f32_e32 v157, v100
	v_add_f32_e32 v100, v70, v102
	v_add_f32_e32 v102, v78, v168
	v_add_f32_e32 v101, 1.0, v101
	v_add_f32_e32 v88, v72, v88
	v_add_f32_e32 v131, v76, v166
	v_mul_f32_e32 v102, 0xbfb8aa3b, v102
	v_rcp_f32_e32 v101, v101
	v_add_f32_e32 v72, v76, v92
	v_mul_f32_e32 v76, 0xbfb8aa3b, v88
	v_exp_f32_e32 v102, v102
	v_add_f32_e32 v68, 1.0, v68
	v_exp_f32_e32 v76, v76
	v_add_f32_e32 v69, 1.0, v69
	v_rcp_f32_e32 v68, v68
	v_rcp_f32_e32 v69, v69
	v_mul_f32_e32 v101, 0xbf1b4598, v101
	v_add_f32_e32 v148, v82, v174
	v_add_f32_e32 v102, 1.0, v102
	v_mul_f32_e32 v101, 0x3fb8aa3b, v101
	v_add_f32_e32 v76, 1.0, v76
	v_rcp_f32_e32 v158, v102
	v_exp_f32_e32 v102, v101
	v_mul_f32_e32 v101, 0xbfb8aa3b, v148
	v_mul_f32_e32 v68, 0xbf1b4598, v68
	v_rcp_f32_e32 v76, v76
	v_mul_f32_e32 v69, 0xbf1b4598, v69
	v_exp_f32_e32 v101, v101
	s_waitcnt lgkmcnt(3)
	v_mfma_f32_16x16x32_bf16 v[96:99], v[96:99], v[40:43], 0
	v_mul_f32_e32 v68, 0x3fb8aa3b, v68
	v_mul_f32_e32 v69, 0x3fb8aa3b, v69
	v_exp_f32_e32 v68, v68
	v_exp_f32_e32 v69, v69
	v_mul_f32_e32 v76, 0xbf1b4598, v76
	v_add_f32_e32 v101, 1.0, v101
	s_nop 1
	v_add_f32_e32 v84, v80, v96
	v_mul_f32_e32 v76, 0x3fb8aa3b, v76
	v_add_f32_e32 v88, v73, v89
	v_add_f32_e32 v73, v77, v93
	v_rcp_f32_e32 v159, v101
	v_add_f32_e32 v101, v71, v103
	v_exp_f32_e32 v80, v76
	v_mul_f32_e32 v76, 0xbfb8aa3b, v84
	v_pk_add_f32 v[84:85], v[68:69], 1.0 op_sel_hi:[1,0] neg_lo:[1,0] neg_hi:[1,0]
	v_mul_f32_e32 v68, 0xbfb8aa3b, v73
	v_mul_f32_e32 v100, 0xbfb8aa3b, v100
	v_mul_f32_e32 v101, 0xbfb8aa3b, v101
	v_exp_f32_e32 v68, v68
	v_exp_f32_e32 v100, v100
	v_exp_f32_e32 v101, v101
	v_add_f32_e32 v103, v79, v169
	v_add_f32_e32 v68, 1.0, v68
	v_add_f32_e32 v100, 1.0, v100
	v_add_f32_e32 v101, 1.0, v101
	v_rcp_f32_e32 v73, v68
	v_mul_f32_e32 v68, 0xbfb8aa3b, v88
	v_rcp_f32_e32 v100, v100
	v_rcp_f32_e32 v101, v101
	v_exp_f32_e32 v68, v68
	v_add_f32_e32 v89, v81, v97
	v_mul_f32_e32 v100, 0xbf1b4598, v100
	v_mul_f32_e32 v101, 0xbf1b4598, v101
	v_add_f32_e32 v68, 1.0, v68
	v_mul_f32_e32 v100, 0x3fb8aa3b, v100
	v_mul_f32_e32 v101, 0x3fb8aa3b, v101
	v_rcp_f32_e32 v68, v68
	v_exp_f32_e32 v100, v100
	v_exp_f32_e32 v101, v101
	v_add_f32_e32 v70, v70, v86
	v_mul_f32_e32 v68, 0xbf1b4598, v68
	v_mul_f32_e32 v68, 0x3fb8aa3b, v68
; __device__ __forceinline__ void phase_prep(const Params& P, char* smem) {
;     ...
;         f32x4 aw0 = __builtin_amdgcn_mfma_f32_16x16x32_bf16(wf[0], af[0], zero, 0, 0, 0);
;         f32x4 aw1 = __builtin_amdgcn_mfma_f32_16x16x32_bf16(wf[1], af[1], zero, 0, 0, 0);
;         f32x4 aa0 = __builtin_amdgcn_mfma_f32_16x16x32_bf16(wf[2], af[2], zero, 0, 0, 0);
;         f32x4 aa1 = __builtin_amdgcn_mfma_f32_16x16x32_bf16(wf[3], af[3], zero, 0, 0, 0);
;         f32x4 ag = __builtin_amdgcn_mfma_f32_16x16x32_bf16(wf[4], af[4], zero, 0, 0, 0);
;         ag = __builtin_amdgcn_mfma_f32_16x16x32_bf16(wf[5], af[5], ag, 0, 0, 0);
;         ag = __builtin_amdgcn_mfma_f32_16x16x32_bf16(wf[6], af[6], ag, 0, 0, 0);
;         const size_t row = (size_t)(row0 + mt * 16 + l15);
;         float dp0[4], dp1[4], az0[4], az1[4];
; #pragma unroll
;         for (int e = 0; e < 4; ++e) {
;           const float wb0 = e == 0 ? w00.x : (e == 1 ? w00.y : (e == 2 ? w00.z : w00.w));
;           const float wb1 = e == 0 ? w01.x : (e == 1 ? w01.y : (e == 2 ? w01.z : w01.w));
;           const float ab0 = e == 0 ? a00.x : (e == 1 ? a00.y : (e == 2 ? a00.z : a00.w));
;           const float ab1 = e == 0 ? a01.x : (e == 1 ? a01.y : (e == 2 ? a01.z : a01.w));
; #pragma unroll
;           for (int z = 0; z < 2; ++z) {
;             const float wv = z == 0 ? wb0 + aw0[e] : wb1 + aw1[e];
;             const float ee = 0.60653066f * sigmoidf_(wv);
;             const float dpv = 1.0f - __expf(-ee);
;             const float av = sigmoidf_(z == 0 ? ab0 + aa0[e] : ab1 + aa1[e]);
;             if (z == 0) { dp0[e] = dpv; az0[e] = av; } else { dp1[e] = dpv; az1[e] = av; }
;           }
;         }
;         uint2 w;
;         w.x = pack2(dp0[0], dp0[1]); w.y = pack2(dp0[2], dp0[3]);
;         *(uint2*)(DP + row * 512 + c4) = w;
;         w.x = pack2(dp1[0], dp1[1]); w.y = pack2(dp1[2], dp1[3]);
;         *(uint2*)(DP + (SZ512 / 2) + row * 512 + c4) = w;
;         w.x = pack2(az0[0], az0[1]); w.y = pack2(az0[2], az0[3]);
;         *(uint2*)(AZ + row * 512 + c4) = w;
;         w.x = pack2(az1[0], az1[1]); w.y = pack2(az1[2], az1[3]);
;         *(uint2*)(AZ + (SZ512 / 2) + row * 512 + c4) = w;
;         w.x = pack2(ag[0], ag[1]); w.y = pack2(ag[2], ag[3]);
;         *(uint2*)(Acat + row * DM + 512 + c4) = w;
;       }
;     ...
;     __syncthreads();
;     {
;       const int c8 = (tid & 63) * 8, tk = tid >> 6;
	v_pk_add_f32 v[168:169], v[100:101], 1.0 op_sel_hi:[1,0] neg_lo:[1,0] neg_hi:[1,0]
	v_mul_f32_e32 v100, 0xbfb8aa3b, v103
	v_exp_f32_e32 v100, v100
	v_exp_f32_e32 v81, v68
	v_add_f32_e32 v71, v71, v87
	v_mul_f32_e32 v70, 0xbfb8aa3b, v70
	v_mul_f32_e32 v71, 0xbfb8aa3b, v71
	v_exp_f32_e32 v70, v70
	v_exp_f32_e32 v71, v71
	v_add_f32_e32 v148, v75, v149
	v_add_f32_e32 v100, 1.0, v100
	v_pk_add_f32 v[68:69], v[80:81], 1.0 op_sel_hi:[1,0] neg_lo:[1,0] neg_hi:[1,0]
	v_add_f32_e32 v80, v74, v90
	v_rcp_f32_e32 v166, v100
	v_mul_f32_e32 v100, 0xbfb8aa3b, v148
	v_add_f32_e32 v74, v78, v94
	v_mul_f32_e32 v78, 0xbfb8aa3b, v80
	v_exp_f32_e32 v100, v100
	v_exp_f32_e32 v78, v78
	v_add_f32_e32 v70, 1.0, v70
	v_add_f32_e32 v71, 1.0, v71
	v_rcp_f32_e32 v70, v70
	v_rcp_f32_e32 v71, v71
	v_add_f32_e32 v100, 1.0, v100
	v_add_f32_e32 v78, 1.0, v78
	v_rcp_f32_e32 v100, v100
	v_rcp_f32_e32 v78, v78
	v_mul_f32_e32 v70, 0xbf1b4598, v70
	v_mul_f32_e32 v71, 0xbf1b4598, v71
	v_mul_f32_e32 v70, 0x3fb8aa3b, v70
	v_mul_f32_e32 v71, 0x3fb8aa3b, v71
	v_exp_f32_e32 v70, v70
	v_exp_f32_e32 v71, v71
	v_mul_f32_e32 v100, 0xbf1b4598, v100
	v_mul_f32_e32 v78, 0xbf1b4598, v78
	v_add_f32_e32 v167, v83, v175
	v_mul_f32_e32 v100, 0x3fb8aa3b, v100
	v_add_f32_e32 v81, v82, v98
	v_mul_f32_e32 v78, 0x3fb8aa3b, v78
	v_exp_f32_e32 v103, v100
	v_mul_f32_e32 v100, 0xbfb8aa3b, v167
	v_exp_f32_e32 v80, v78
	v_mul_f32_e32 v78, 0xbfb8aa3b, v81
	v_add_f32_e32 v81, v75, v91
	v_add_f32_e32 v75, v79, v95
	v_exp_f32_e32 v100, v100
	v_add_f32_e32 v86, v83, v99
	v_pk_add_f32 v[82:83], v[70:71], 1.0 op_sel_hi:[1,0] neg_lo:[1,0] neg_hi:[1,0]
	v_mul_f32_e32 v70, 0xbfb8aa3b, v75
	v_exp_f32_e32 v70, v70
	v_add_f32_e32 v100, 1.0, v100
	v_mul_f32_e32 v131, 0xbfb8aa3b, v131
	v_pk_add_f32 v[148:149], v[102:103], 1.0 op_sel_hi:[1,0] neg_lo:[1,0] neg_hi:[1,0]
	v_rcp_f32_e32 v167, v100
	v_mfma_f32_16x16x32_bf16 v[100:103], v[56:59], v[16:19], 0
	v_add_f32_e32 v70, 1.0, v70
	v_exp_f32_e32 v131, v131
	v_rcp_f32_e32 v75, v70
	v_mul_f32_e32 v70, 0xbfb8aa3b, v81
	v_exp_f32_e32 v70, v70
	v_mfma_f32_16x16x32_bf16 v[100:103], v[60:63], v[20:23], v[100:103]
	v_cvt_pk_bf16_f32 v150, v150, v151
	v_cvt_pk_bf16_f32 v151, v168, v169
	v_lshl_add_u64 v[168:169], s[94:95], 0, v[136:137]
	v_add_f32_e32 v131, 1.0, v131
	v_add_co_u32_e32 v172, vcc, s19, v168
	v_rcp_f32_e32 v131, v131
	v_pk_add_f32 v[146:147], v[146:147], 1.0 op_sel_hi:[1,0] neg_lo:[1,0] neg_hi:[1,0]
	v_addc_co_u32_e32 v173, vcc, 0, v169, vcc
	v_add_f32_e32 v70, 1.0, v70
	v_exp_f32_e32 v133, v133
	v_cvt_pk_bf16_f32 v146, v146, v147
	v_cvt_pk_bf16_f32 v147, v148, v149
	v_add_co_u32_e32 v148, vcc, s22, v168
	v_rcp_f32_e32 v70, v70
	s_waitcnt lgkmcnt(2)
	v_mfma_f32_16x16x32_bf16 v[56:59], v[56:59], v[44:47], 0
	v_addc_co_u32_e32 v149, vcc, 0, v169, vcc
	global_store_dwordx2 v[148:149], v[146:147], off
	v_mfma_f32_16x16x32_bf16 v[100:103], v[64:67], v[24:27], v[100:103]
	v_add_co_u32_e32 v148, vcc, s23, v168
	v_cvt_pk_bf16_f32 v146, v131, v135
	v_cvt_pk_bf16_f32 v147, v158, v166
	v_addc_co_u32_e32 v149, vcc, 0, v169, vcc
	v_add_f32_e32 v133, 1.0, v133
	global_store_dwordx2 v[148:149], v[146:147], off
	v_add_co_u32_e32 v148, vcc, s24, v168
	v_mul_f32_e32 v70, 0xbf1b4598, v70
	s_waitcnt lgkmcnt(1)
	v_mfma_f32_16x16x32_bf16 v[56:59], v[60:63], v[48:51], v[56:59]
	v_rcp_f32_e32 v133, v133
	v_addc_co_u32_e32 v149, vcc, 0, v169, vcc
	v_cvt_pk_bf16_f32 v100, v100, v101
	v_cvt_pk_bf16_f32 v101, v102, v103
	v_lshl_add_u64 v[102:103], s[94:95], 0, v[140:141]
	v_mul_f32_e32 v70, 0x3fb8aa3b, v70
	v_add_co_u32_e32 v102, vcc, s25, v102
	v_mul_f32_e32 v72, 0xbfb8aa3b, v72
	v_mul_f32_e32 v74, 0xbfb8aa3b, v74
	v_exp_f32_e32 v81, v70
	v_addc_co_u32_e32 v103, vcc, 0, v103, vcc
	v_exp_f32_e32 v72, v72
	v_mul_f32_e32 v77, 0xbfb8aa3b, v89
	v_exp_f32_e32 v74, v74
	v_mul_f32_e32 v79, 0xbfb8aa3b, v86
	v_lshl_add_u64 v[62:63], s[94:95], 0, v[138:139]
	v_exp_f32_e32 v76, v76
	v_exp_f32_e32 v77, v77
	v_exp_f32_e32 v78, v78
	v_exp_f32_e32 v79, v79
	s_waitcnt lgkmcnt(0)
	v_mfma_f32_16x16x32_bf16 v[56:59], v[64:67], v[52:55], v[56:59]
	v_add_co_u32_e32 v64, vcc, s19, v62
	v_cvt_pk_bf16_f32 v146, v133, v157
	v_cvt_pk_bf16_f32 v147, v159, v167
	v_cvt_pk_bf16_f32 v60, v84, v85
	v_cvt_pk_bf16_f32 v61, v82, v83
	v_addc_co_u32_e32 v65, vcc, 0, v63, vcc
	global_store_dwordx2 v[172:173], v[150:151], off
	global_store_dwordx2 v[148:149], v[146:147], off
	global_store_dwordx2 v[102:103], v[100:101], off offset:1024
	v_pk_add_f32 v[70:71], v[80:81], 1.0 op_sel_hi:[1,0] neg_lo:[1,0] neg_hi:[1,0]
	global_store_dwordx2 v[64:65], v[60:61], off
	v_add_co_u32_e32 v64, vcc, s22, v62
	v_add_f32_e32 v72, 1.0, v72
	v_add_f32_e32 v74, 1.0, v74
	v_cvt_pk_bf16_f32 v60, v68, v69
	v_cvt_pk_bf16_f32 v61, v70, v71
	v_addc_co_u32_e32 v65, vcc, 0, v63, vcc
	v_rcp_f32_e32 v72, v72
	v_add_f32_e32 v76, 1.0, v76
	v_add_f32_e32 v77, 1.0, v77
	v_rcp_f32_e32 v74, v74
	v_add_f32_e32 v78, 1.0, v78
	v_add_f32_e32 v79, 1.0, v79
	global_store_dwordx2 v[64:65], v[60:61], off
	v_add_co_u32_e32 v64, vcc, s23, v62
	v_rcp_f32_e32 v76, v76
	v_rcp_f32_e32 v77, v77
	v_rcp_f32_e32 v78, v78
	v_rcp_f32_e32 v79, v79
	v_addc_co_u32_e32 v65, vcc, 0, v63, vcc
	v_add_co_u32_e32 v62, vcc, s24, v62
	v_cvt_pk_bf16_f32 v56, v56, v57
	s_nop 0
	v_addc_co_u32_e32 v63, vcc, 0, v63, vcc
	v_cvt_pk_bf16_f32 v57, v58, v59
	v_lshl_add_u64 v[58:59], s[94:95], 0, v[142:143]
	v_cvt_pk_bf16_f32 v60, v72, v73
	v_cvt_pk_bf16_f32 v61, v74, v75
	v_add_co_u32_e32 v58, vcc, s25, v58
	global_store_dwordx2 v[64:65], v[60:61], off
	v_cvt_pk_bf16_f32 v60, v76, v77
	v_cvt_pk_bf16_f32 v61, v78, v79
	v_addc_co_u32_e32 v59, vcc, 0, v59, vcc
	v_lshl_add_u64 v[136:137], v[136:137], 0, 32
	v_lshl_add_u64 v[138:139], v[138:139], 0, 32
	v_lshl_add_u64 v[140:141], v[140:141], 0, 32
	v_lshl_add_u64 v[142:143], v[142:143], 0, 32
	global_store_dwordx2 v[62:63], v[60:61], off
	global_store_dwordx2 v[58:59], v[56:57], off offset:1024
	s_cbranch_scc0 .LBB0_1190
	s_barrier
	global_load_dwordx4 v[0:3], v[114:115], off offset:16
	global_load_dwordx4 v[4:7], v[114:115], off
	global_load_dwordx4 v[8:11], v[114:115], off offset:2064
	global_load_dwordx4 v[12:15], v[114:115], off offset:2048
	global_load_dwordx4 v[16:19], v[116:117], off offset:16
	global_load_dwordx4 v[20:23], v[116:117], off
	global_load_dwordx4 v[24:27], v[118:119], off offset:16
	global_load_dwordx4 v[28:31], v[118:119], off
	v_ashrrev_i32_e32 v135, 31, v134
	v_lshlrev_b64 v[32:33], 10, v[134:135]
	v_lshl_add_u64 v[68:69], s[94:95], 0, v[32:33]
	v_mov_b64_e32 v[32:33], s[94:95]
	v_mad_i64_i32 v[70:71], s[0:1], v134, s26, v[32:33]
	s_mov_b32 s30, 8
	v_mov_b32_e32 v72, v154
	s_branch .LBB0_1193

; __device__ __forceinline__ void conv_tile(const float* __restrict__ W, int K, int N, int Npad, bf16_t* __restrict__ dst, int mode,
;                           int kt, int nt, char* smem) {
;   float* T = (float*)smem;
;   const int tid = threadIdx.x;
;   const int k0 = kt * 64, n0 = nt * 64;
;   __syncthreads();
;   {
;     const int r = tid >> 4, c4 = (tid & 15) * 4;
; #pragma unroll
;     for (int i = 0; i < 4; ++i) {
;       const int k = r + 16 * i, n = n0 + c4;
;       float4 v = make_float4(0.f, 0.f, 0.f, 0.f);
;       if (n < N) v = *(const float4*)(W + (size_t)(k0 + k) * N + n);
;       T[k * 65 + c4 + 0] = v.x;
;       T[k * 65 + c4 + 1] = v.y;
;       T[k * 65 + c4 + 2] = v.z;
;       T[k * 65 + c4 + 3] = v.w;
;     }
;   }
;   __syncthreads();
;   {
;     const int n = tid >> 2, ks = (tid & 3) * 16;
;     const int gn = n0 + n;
;     if (gn < Npad) {
;       const int drow = mode == 0 ? gn : ((gn >> 5) * 64 + (gn & 31) + (mode == 2 ? 32 : 0));
;       uint32_t w[8];
; #pragma unroll
;       for (int q = 0; q < 8; ++q) w[q] = pack2(T[(ks + 2 * q) * 65 + n], T[(ks + 2 * q + 1) * 65 + n]);
;       uint4* d = (uint4*)(dst + (size_t)drow * K + k0 + ks);
;       d[0] = make_uint4(w[0], w[1], w[2], w[3]);
;       d[1] = make_uint4(w[4], w[5], w[6], w[7]);
;     }
;   }
; __device__ __forceinline__ void phase_conv(const Params& P, int layer, char* smem, int part, int rank, int nrank) {
;     ...
;     } else {
;       const int q = t - t_in - 256 - 1408;
;       conv_tile(P.w_down + (size_t)layer * DFF * 1024, DFF, 1024, 1024, (bf16_t*)(ws + OFF_WDN), 0, q >> 4, q & 15, smem);
.LBB0_1273:
	s_cmpk_gt_i32 s16, 0x33f
	s_cbranch_scc0 .LBB0_1280
	s_cmpk_gt_u32 s16, 0x43f
	s_cbranch_scc0 .LBB0_1281
	s_cmpk_gt_u32 s16, 0x6ff
	s_cbranch_scc0 .LBB0_1282
	s_cmpk_gt_u32 s16, 0x9bf
	s_cbranch_scc0 .LBB0_1283
	s_add_i32 s2, s20, 0x7ffff300
	s_and_b32 s2, s2, 0x7fffffc0
	s_add_i32 s8, s2, 0xffffe600
	s_and_b32 s2, s18, 0x3c0
	v_or_b32_e32 v0, s2, v24
	v_lshlrev_b32_e32 v16, 2, v0
	v_or_b32_e32 v0, s8, v179
	v_add_u32_e32 v2, s8, v171
	v_ashrrev_i32_e32 v1, 31, v0
	v_ashrrev_i32_e32 v3, 31, v2
	v_lshl_add_u64 v[12:13], s[0:1], 0, v[16:17]
	v_lshlrev_b64 v[0:1], 12, v[0:1]
	v_lshlrev_b64 v[2:3], 12, v[2:3]
	v_lshl_add_u64 v[0:1], v[12:13], 0, v[0:1]
	v_lshl_add_u64 v[4:5], v[12:13], 0, v[2:3]
	s_barrier
	global_load_dwordx4 v[0:3], v[0:1], off
	global_load_dwordx4 v[4:7], v[4:5], off
	v_add_u32_e32 v8, s8, v25
	v_ashrrev_i32_e32 v9, 31, v8
	v_lshlrev_b64 v[8:9], 12, v[8:9]
	v_add_u32_e32 v14, s8, v26
	v_lshl_add_u64 v[8:9], v[12:13], 0, v[8:9]
	v_ashrrev_i32_e32 v15, 31, v14
	global_load_dwordx4 v[8:11], v[8:9], off
	v_lshlrev_b64 v[14:15], 12, v[14:15]
	v_lshl_add_u64 v[12:13], v[12:13], 0, v[14:15]
	global_load_dwordx4 v[12:15], v[12:13], off
	v_add_u32_e32 v16, s2, v27
	s_mov_b64 s[14:15], 0
	v_cmp_gt_u32_e32 vcc, s22, v16
	s_mov_b64 s[12:13], 0
	s_waitcnt vmcnt(3)
	ds_write2_b32 v32, v0, v1 offset1:1
	ds_write2_b32 v32, v2, v3 offset0:2 offset1:3
	s_waitcnt vmcnt(2)
	ds_write2_b32 v33, v4, v5 offset1:1
	ds_write2_b32 v34, v6, v7 offset1:1
	s_waitcnt vmcnt(1)
	ds_write2_b32 v35, v8, v9 offset1:1
	ds_write2_b32 v36, v10, v11 offset1:1
	s_waitcnt vmcnt(0)
	ds_write2_b32 v37, v12, v13 offset1:1
	ds_write2_b32 v38, v14, v15 offset1:1
	s_waitcnt lgkmcnt(0)
	s_barrier
	s_and_saveexec_b64 s[2:3], vcc
	s_xor_b64 s[10:11], exec, s[2:3]
	s_cbranch_execz .LBB0_1279
	ds_read2_b32 v[6:7], v28 offset1:130
	ds_read2_b32 v[0:1], v29 offset0:65 offset1:195
	ds_read2_b32 v[10:11], v39 offset0:4 offset1:134
	ds_read2_b32 v[2:3], v40 offset0:69 offset1:199
	ds_read2_b32 v[14:15], v41 offset0:8 offset1:138
	ds_read2_b32 v[8:9], v42 offset0:73 offset1:203
	s_waitcnt lgkmcnt(5)
	v_mov_b32_e32 v4, v6
	s_waitcnt lgkmcnt(4)
	v_mov_b32_e32 v5, v0
	v_mov_b32_e32 v0, v7
	s_waitcnt lgkmcnt(3)
	v_mov_b32_e32 v6, v10
	s_waitcnt lgkmcnt(2)
	v_mov_b32_e32 v7, v2
	v_mov_b32_e32 v2, v11
	ds_read2_b32 v[20:21], v43 offset0:12 offset1:142
	ds_read2_b32 v[10:11], v44 offset0:77 offset1:207
	v_mul_u32_u24_e32 v16, 0xb00, v16
	v_lshlrev_b32_e32 v16, 1, v16
	s_mov_b64 s[12:13], exec
	s_waitcnt lgkmcnt(3)
	v_mov_b32_e32 v12, v14
	s_waitcnt lgkmcnt(2)
	v_mov_b32_e32 v13, v8
	v_mov_b32_e32 v8, v15
	s_waitcnt lgkmcnt(1)
	v_mov_b32_e32 v14, v20
	s_waitcnt lgkmcnt(0)
	v_mov_b32_e32 v15, v10
	v_mov_b32_e32 v10, v21
	v_lshl_add_u64 v[20:21], s[96:97], 0, v[16:17]

; __device__ __forceinline__ void conv_tile(const float* __restrict__ W, int K, int N, int Npad, bf16_t* __restrict__ dst, int mode,
;                           int kt, int nt, char* smem) {
;   float* T = (float*)smem;
;   const int tid = threadIdx.x;
;   const int k0 = kt * 64, n0 = nt * 64;
;   __syncthreads();
;   {
;     const int r = tid >> 4, c4 = (tid & 15) * 4;
; #pragma unroll
;     for (int i = 0; i < 4; ++i) {
;       const int k = r + 16 * i, n = n0 + c4;
;       float4 v = make_float4(0.f, 0.f, 0.f, 0.f);
;       if (n < N) v = *(const float4*)(W + (size_t)(k0 + k) * N + n);
;       T[k * 65 + c4 + 0] = v.x;
;       T[k * 65 + c4 + 1] = v.y;
;       T[k * 65 + c4 + 2] = v.z;
;       T[k * 65 + c4 + 3] = v.w;
;     }
;   }
;   __syncthreads();
;   {
;     const int n = tid >> 2, ks = (tid & 3) * 16;
;     const int gn = n0 + n;
;     if (gn < Npad) {
;       const int drow = mode == 0 ? gn : ((gn >> 5) * 64 + (gn & 31) + (mode == 2 ? 32 : 0));
;       uint32_t w[8];
; #pragma unroll
;       for (int q = 0; q < 8; ++q) w[q] = pack2(T[(ks + 2 * q) * 65 + n], T[(ks + 2 * q + 1) * 65 + n]);
;       uint4* d = (uint4*)(dst + (size_t)drow * K + k0 + ks);
;       d[0] = make_uint4(w[0], w[1], w[2], w[3]);
;       d[1] = make_uint4(w[4], w[5], w[6], w[7]);
;     }
;   }
; __device__ __forceinline__ void phase_conv(const Params& P, int layer, char* smem, int part, int rank, int nrank) {
;     ...
;     } else if (t < t_in + 256 + 1408) {
;       const int q = t - t_in - 256 - 704;
;       conv_tile(P.w_up + (size_t)layer * 1024 * DFF, 1024, DFF, DFF, (bf16_t*)(ws + OFF_WGU), 2, q / 44, q % 44, smem);
.LBB0_1284:
	s_add_i32 s2, s16, 0xf900
	s_and_b32 s3, s2, 0xffff
	s_mul_i32 s3, s3, 0xba2f
	s_lshr_b32 s3, s3, 21
	s_mul_i32 s8, s3, 44
	s_sub_i32 s2, s2, s8
	s_lshl_b32 s2, s2, 6
	s_and_b32 s2, s2, 0xffc0
	s_lshl_b32 s8, s3, 6
	v_or_b32_e32 v0, s2, v24
	v_lshlrev_b32_e32 v16, 2, v0
	v_or_b32_e32 v0, s8, v179
	v_lshl_add_u64 v[12:13], s[4:5], 0, v[16:17]
	v_mul_u32_u24_e32 v16, 0x2c00, v0
	v_add_u32_e32 v2, s8, v171
	v_lshl_add_u64 v[0:1], v[12:13], 0, v[16:17]
	v_mul_u32_u24_e32 v16, 0x2c00, v2
	v_lshl_add_u64 v[4:5], v[12:13], 0, v[16:17]
	s_barrier
	global_load_dwordx4 v[0:3], v[0:1], off
	global_load_dwordx4 v[4:7], v[4:5], off
	v_add_u32_e32 v8, s8, v25
	v_mul_u32_u24_e32 v16, 0x2c00, v8
	v_lshl_add_u64 v[8:9], v[12:13], 0, v[16:17]
	v_add_u32_e32 v10, s8, v26
	v_mul_u32_u24_e32 v16, 0x2c00, v10
	global_load_dwordx4 v[8:11], v[8:9], off
	v_lshl_add_u64 v[12:13], v[12:13], 0, v[16:17]
	global_load_dwordx4 v[12:15], v[12:13], off
	v_add_u32_e32 v16, s2, v27
	v_cmp_gt_u32_e32 vcc, s23, v16
	s_waitcnt vmcnt(3)
	ds_write2_b32 v32, v0, v1 offset1:1
	ds_write2_b32 v32, v2, v3 offset0:2 offset1:3
	s_waitcnt vmcnt(2)
	ds_write2_b32 v33, v4, v5 offset1:1
	ds_write2_b32 v34, v6, v7 offset1:1
	s_waitcnt vmcnt(1)
	ds_write2_b32 v35, v8, v9 offset1:1
	ds_write2_b32 v36, v10, v11 offset1:1
	s_waitcnt vmcnt(0)
	ds_write2_b32 v37, v12, v13 offset1:1
	ds_write2_b32 v38, v14, v15 offset1:1
	s_waitcnt lgkmcnt(0)
	s_barrier
	s_and_saveexec_b64 s[2:3], vcc
	s_xor_b64 s[10:11], exec, s[2:3]
	s_cbranch_execz .LBB0_1286
	v_lshlrev_b32_e32 v2, 1, v16
	ds_read2_b32 v[6:7], v28 offset1:130
	ds_read2_b32 v[0:1], v29 offset0:65 offset1:195
	v_and_or_b32 v16, v2, s24, v31
	ds_read2_b32 v[10:11], v39 offset0:4 offset1:134
	ds_read2_b32 v[2:3], v40 offset0:69 offset1:199
	ds_read2_b32 v[14:15], v41 offset0:8 offset1:138
	ds_read2_b32 v[8:9], v42 offset0:73 offset1:203
	s_waitcnt lgkmcnt(5)
	v_mov_b32_e32 v4, v6
	s_waitcnt lgkmcnt(4)
	v_mov_b32_e32 v5, v0
	v_mov_b32_e32 v0, v7
	s_waitcnt lgkmcnt(3)
	v_mov_b32_e32 v6, v10
	s_waitcnt lgkmcnt(2)
	v_mov_b32_e32 v7, v2
	v_mov_b32_e32 v2, v11
	ds_read2_b32 v[20:21], v43 offset0:12 offset1:142
	ds_read2_b32 v[10:11], v44 offset0:77 offset1:207
	v_readlane_b32 s2, v211, 36
	v_lshlrev_b32_e32 v16, 11, v16
	v_readlane_b32 s3, v211, 37
	s_waitcnt lgkmcnt(3)
	v_mov_b32_e32 v12, v14
	s_waitcnt lgkmcnt(2)
	v_mov_b32_e32 v13, v8
	v_mov_b32_e32 v8, v15
	s_waitcnt lgkmcnt(1)
	v_mov_b32_e32 v14, v20
	s_waitcnt lgkmcnt(0)
	v_mov_b32_e32 v15, v10
	v_mov_b32_e32 v10, v21
	v_lshl_add_u64 v[20:21], s[2:3], 0, v[16:17]
	s_or_b64 s[12:13], s[12:13], exec

; __device__ __forceinline__ void conv_tile(const float* __restrict__ W, int K, int N, int Npad, bf16_t* __restrict__ dst, int mode,
;                           int kt, int nt, char* smem) {
;   float* T = (float*)smem;
;   const int tid = threadIdx.x;
;   const int k0 = kt * 64, n0 = nt * 64;
;   __syncthreads();
;   {
;     const int r = tid >> 4, c4 = (tid & 15) * 4;
; #pragma unroll
;     for (int i = 0; i < 4; ++i) {
;       const int k = r + 16 * i, n = n0 + c4;
;       float4 v = make_float4(0.f, 0.f, 0.f, 0.f);
;       if (n < N) v = *(const float4*)(W + (size_t)(k0 + k) * N + n);
;       T[k * 65 + c4 + 0] = v.x;
;       T[k * 65 + c4 + 1] = v.y;
;       T[k * 65 + c4 + 2] = v.z;
;       T[k * 65 + c4 + 3] = v.w;
;     }
;   }
;   __syncthreads();
;   {
;     const int n = tid >> 2, ks = (tid & 3) * 16;
;     const int gn = n0 + n;
;     if (gn < Npad) {
;       const int drow = mode == 0 ? gn : ((gn >> 5) * 64 + (gn & 31) + (mode == 2 ? 32 : 0));
;       uint32_t w[8];
; #pragma unroll
;       for (int q = 0; q < 8; ++q) w[q] = pack2(T[(ks + 2 * q) * 65 + n], T[(ks + 2 * q + 1) * 65 + n]);
;       uint4* d = (uint4*)(dst + (size_t)drow * K + k0 + ks);
;       d[0] = make_uint4(w[0], w[1], w[2], w[3]);
;       d[1] = make_uint4(w[4], w[5], w[6], w[7]);
;     }
;   }
; __device__ __forceinline__ void phase_conv(const Params& P, int layer, char* smem, int part, int rank, int nrank) {
;     ...
;     } else if (t < t_in + 256 + 704) {
;       const int q = t - t_in - 256;
;       conv_tile(P.w_gate + (size_t)layer * 1024 * DFF, 1024, DFF, DFF, (bf16_t*)(ws + OFF_WGU), 1, q / 44, q % 44, smem);
.LBB0_1288:
	s_add_i32 s2, s16, 0xfbc0
	s_and_b32 s3, s2, 0xffff
	s_mul_i32 s3, s3, 0xba2f
	s_lshr_b32 s3, s3, 21
	s_mul_i32 s8, s3, 44
	s_sub_i32 s2, s2, s8
	s_lshl_b32 s2, s2, 6
	s_and_b32 s2, s2, 0xffc0
	s_lshl_b32 s8, s3, 6
	v_or_b32_e32 v0, s2, v24
	v_lshlrev_b32_e32 v16, 2, v0
	v_or_b32_e32 v0, s8, v179
	v_lshl_add_u64 v[12:13], s[6:7], 0, v[16:17]
	v_mul_u32_u24_e32 v16, 0x2c00, v0
	v_add_u32_e32 v2, s8, v171
	v_lshl_add_u64 v[0:1], v[12:13], 0, v[16:17]
	v_mul_u32_u24_e32 v16, 0x2c00, v2
	v_lshl_add_u64 v[4:5], v[12:13], 0, v[16:17]
	s_barrier
	global_load_dwordx4 v[0:3], v[0:1], off
	global_load_dwordx4 v[4:7], v[4:5], off
	v_add_u32_e32 v8, s8, v25
	v_mul_u32_u24_e32 v16, 0x2c00, v8
	v_lshl_add_u64 v[8:9], v[12:13], 0, v[16:17]
	v_add_u32_e32 v10, s8, v26
	v_mul_u32_u24_e32 v16, 0x2c00, v10
	global_load_dwordx4 v[8:11], v[8:9], off
	v_lshl_add_u64 v[12:13], v[12:13], 0, v[16:17]
	global_load_dwordx4 v[12:15], v[12:13], off
	v_add_u32_e32 v16, s2, v27
	v_cmp_gt_u32_e32 vcc, s23, v16
	s_waitcnt vmcnt(3)
	ds_write2_b32 v32, v0, v1 offset1:1
	ds_write2_b32 v32, v2, v3 offset0:2 offset1:3
	s_waitcnt vmcnt(2)
	ds_write2_b32 v33, v4, v5 offset1:1
	ds_write2_b32 v34, v6, v7 offset1:1
	s_waitcnt vmcnt(1)
	ds_write2_b32 v35, v8, v9 offset1:1
	ds_write2_b32 v36, v10, v11 offset1:1
	s_waitcnt vmcnt(0)
	ds_write2_b32 v37, v12, v13 offset1:1
	ds_write2_b32 v38, v14, v15 offset1:1
	s_waitcnt lgkmcnt(0)
	s_barrier
	s_and_saveexec_b64 s[2:3], vcc
	s_xor_b64 s[10:11], exec, s[2:3]
	s_cbranch_execz .LBB0_1290
	v_lshlrev_b32_e32 v2, 1, v16
	ds_read2_b32 v[6:7], v28 offset1:130
	ds_read2_b32 v[0:1], v29 offset0:65 offset1:195
	v_and_or_b32 v16, v2, s24, v30
	ds_read2_b32 v[10:11], v39 offset0:4 offset1:134
	ds_read2_b32 v[2:3], v40 offset0:69 offset1:199
	ds_read2_b32 v[14:15], v41 offset0:8 offset1:138
	ds_read2_b32 v[8:9], v42 offset0:73 offset1:203
	s_waitcnt lgkmcnt(5)
	v_mov_b32_e32 v4, v6
	s_waitcnt lgkmcnt(4)
	v_mov_b32_e32 v5, v0
	v_mov_b32_e32 v0, v7
	s_waitcnt lgkmcnt(3)
	v_mov_b32_e32 v6, v10
	s_waitcnt lgkmcnt(2)
	v_mov_b32_e32 v7, v2
	v_mov_b32_e32 v2, v11
	ds_read2_b32 v[20:21], v43 offset0:12 offset1:142
	ds_read2_b32 v[10:11], v44 offset0:77 offset1:207
	v_readlane_b32 s2, v211, 36
	v_lshlrev_b32_e32 v16, 11, v16
	v_readlane_b32 s3, v211, 37
	s_waitcnt lgkmcnt(3)
	v_mov_b32_e32 v12, v14
	s_waitcnt lgkmcnt(2)
	v_mov_b32_e32 v13, v8
	v_mov_b32_e32 v8, v15
	s_waitcnt lgkmcnt(1)
	v_mov_b32_e32 v14, v20
	s_waitcnt lgkmcnt(0)
	v_mov_b32_e32 v15, v10
	v_mov_b32_e32 v10, v21
	v_lshl_add_u64 v[20:21], s[2:3], 0, v[16:17]
	s_or_b64 s[12:13], s[12:13], exec

; __device__ __forceinline__ void conv_tile(const float* __restrict__ W, int K, int N, int Npad, bf16_t* __restrict__ dst, int mode,
;                           int kt, int nt, char* smem) {
;   float* T = (float*)smem;
;   const int tid = threadIdx.x;
;   const int k0 = kt * 64, n0 = nt * 64;
;   __syncthreads();
;   {
;     const int r = tid >> 4, c4 = (tid & 15) * 4;
; #pragma unroll
;     for (int i = 0; i < 4; ++i) {
;       const int k = r + 16 * i, n = n0 + c4;
;       float4 v = make_float4(0.f, 0.f, 0.f, 0.f);
;       if (n < N) v = *(const float4*)(W + (size_t)(k0 + k) * N + n);
;       T[k * 65 + c4 + 0] = v.x;
;       T[k * 65 + c4 + 1] = v.y;
;       T[k * 65 + c4 + 2] = v.z;
;       T[k * 65 + c4 + 3] = v.w;
;     }
;   }
;   __syncthreads();
;   {
;     const int n = tid >> 2, ks = (tid & 3) * 16;
;     const int gn = n0 + n;
;     if (gn < Npad) {
;       const int drow = mode == 0 ? gn : ((gn >> 5) * 64 + (gn & 31) + (mode == 2 ? 32 : 0));
;       uint32_t w[8];
; #pragma unroll
;       for (int q = 0; q < 8; ++q) w[q] = pack2(T[(ks + 2 * q) * 65 + n], T[(ks + 2 * q + 1) * 65 + n]);
;       uint4* d = (uint4*)(dst + (size_t)drow * K + k0 + ks);
;       d[0] = make_uint4(w[0], w[1], w[2], w[3]);
;       d[1] = make_uint4(w[4], w[5], w[6], w[7]);
;     }
;   }
; __device__ __forceinline__ void phase_conv(const Params& P, int layer, char* smem, int part, int rank, int nrank) {
;     ...
;     } else if (t < t_in + 256) {
;       const int q = t - t_in;
;       conv_tile(w_out, 1024, 1024, 1024, (bf16_t*)(ws + OFF_WOUT), 0, q >> 4, q & 15, smem);
.LBB0_1292:
	s_and_b32 s2, s20, 0x1fc0
	s_add_i32 s8, s2, 0xfffff300
	s_and_b32 s2, s18, 0x3c0
	v_or_b32_e32 v0, s2, v24
	v_readlane_b32 s72, v211, 38
	v_lshlrev_b32_e32 v16, 2, v0
	v_readlane_b32 s82, v211, 48
	v_readlane_b32 s83, v211, 49
	s_barrier
	s_nop 0
	v_lshl_add_u64 v[12:13], s[82:83], 0, v[16:17]
	v_or_b32_e32 v16, s8, v179
	v_lshlrev_b64 v[0:1], 12, v[16:17]
	v_add_u32_e32 v16, s8, v171
	v_lshlrev_b64 v[2:3], 12, v[16:17]
	v_lshl_add_u64 v[0:1], v[12:13], 0, v[0:1]
	v_lshl_add_u64 v[4:5], v[12:13], 0, v[2:3]
	global_load_dwordx4 v[0:3], v[0:1], off
	global_load_dwordx4 v[4:7], v[4:5], off
	v_add_u32_e32 v16, s8, v25
	v_lshlrev_b64 v[8:9], 12, v[16:17]
	v_lshl_add_u64 v[8:9], v[12:13], 0, v[8:9]
	v_add_u32_e32 v16, s8, v26
	global_load_dwordx4 v[8:11], v[8:9], off
	v_lshlrev_b64 v[14:15], 12, v[16:17]
	v_lshl_add_u64 v[12:13], v[12:13], 0, v[14:15]
	global_load_dwordx4 v[12:15], v[12:13], off
	v_add_u32_e32 v16, s2, v27
	v_cmp_gt_u32_e32 vcc, s22, v16
	v_readlane_b32 s73, v211, 39
	v_readlane_b32 s74, v211, 40
	v_readlane_b32 s75, v211, 41
	v_readlane_b32 s76, v211, 42
	v_readlane_b32 s77, v211, 43
	v_readlane_b32 s78, v211, 44
	v_readlane_b32 s79, v211, 45
	v_readlane_b32 s80, v211, 46
	v_readlane_b32 s81, v211, 47
	v_readlane_b32 s84, v211, 50
	v_readlane_b32 s85, v211, 51
	v_readlane_b32 s86, v211, 52
	v_readlane_b32 s87, v211, 53
	s_waitcnt vmcnt(3)
	ds_write2_b32 v32, v0, v1 offset1:1
	ds_write2_b32 v32, v2, v3 offset0:2 offset1:3
	s_waitcnt vmcnt(2)
	ds_write2_b32 v33, v4, v5 offset1:1
	ds_write2_b32 v34, v6, v7 offset1:1
	s_waitcnt vmcnt(1)
	ds_write2_b32 v35, v8, v9 offset1:1
	ds_write2_b32 v36, v10, v11 offset1:1
	s_waitcnt vmcnt(0)
	ds_write2_b32 v37, v12, v13 offset1:1
	ds_write2_b32 v38, v14, v15 offset1:1
	s_waitcnt lgkmcnt(0)
	s_barrier
	s_and_saveexec_b64 s[2:3], vcc
	s_xor_b64 s[10:11], exec, s[2:3]
	s_cbranch_execz .LBB0_1294
	ds_read2_b32 v[6:7], v28 offset1:130
	ds_read2_b32 v[0:1], v29 offset0:65 offset1:195
	ds_read2_b32 v[10:11], v39 offset0:4 offset1:134
	ds_read2_b32 v[2:3], v40 offset0:69 offset1:199
	ds_read2_b32 v[14:15], v41 offset0:8 offset1:138
	ds_read2_b32 v[8:9], v42 offset0:73 offset1:203
	s_waitcnt lgkmcnt(5)
	v_mov_b32_e32 v4, v6
	s_waitcnt lgkmcnt(4)
	v_mov_b32_e32 v5, v0
	v_mov_b32_e32 v0, v7
	s_waitcnt lgkmcnt(3)
	v_mov_b32_e32 v6, v10
	s_waitcnt lgkmcnt(2)
	v_mov_b32_e32 v7, v2
	v_mov_b32_e32 v2, v11
	ds_read2_b32 v[20:21], v43 offset0:12 offset1:142
	ds_read2_b32 v[10:11], v44 offset0:77 offset1:207
	v_readlane_b32 s2, v211, 34
	v_lshlrev_b32_e32 v16, 11, v16
	v_readlane_b32 s3, v211, 35
	s_waitcnt lgkmcnt(3)
	v_mov_b32_e32 v12, v14
	s_waitcnt lgkmcnt(2)
	v_mov_b32_e32 v13, v8
	v_mov_b32_e32 v8, v15
	s_waitcnt lgkmcnt(1)
	v_mov_b32_e32 v14, v20
	s_waitcnt lgkmcnt(0)
	v_mov_b32_e32 v15, v10
	v_mov_b32_e32 v10, v21
	v_lshl_add_u64 v[20:21], s[2:3], 0, v[16:17]
	s_or_b64 s[12:13], s[12:13], exec

; __device__ __forceinline__ void conv_tile(const float* __restrict__ W, int K, int N, int Npad, bf16_t* __restrict__ dst, int mode,
;                           int kt, int nt, char* smem) {
;     ...
;   const int k0 = kt * 64, n0 = nt * 64;
;   __syncthreads();
;   {
;     const int r = tid >> 4, c4 = (tid & 15) * 4;
; #pragma unroll
;     for (int i = 0; i < 4; ++i) {
;       const int k = r + 16 * i, n = n0 + c4;
;       float4 v = make_float4(0.f, 0.f, 0.f, 0.f);
;       if (n < N) v = *(const float4*)(W + (size_t)(k0 + k) * N + n);
;       T[k * 65 + c4 + 0] = v.x;
;       T[k * 65 + c4 + 1] = v.y;
;       T[k * 65 + c4 + 2] = v.z;
;       T[k * 65 + c4 + 3] = v.w;
;     }
;   }
; __device__ __forceinline__ void phase_conv(const Params& P, int layer, char* smem, int part, int rank, int nrank) {
;     ...
;   for (int t = t_lo + rank; t < total; t += nrank) {
;     if (t < t_in) {
;       conv_tile(w_in, 1024, n_in, np_in, (bf16_t*)(ws + OFF_WIN), 0, t / nt_in, t % nt_in, smem);
.LBB0_1296:
	s_mul_hi_i32 s2, s16, 0x4ec4ec4f
	s_lshr_b32 s3, s2, 31
	s_ashr_i32 s2, s2, 4
	s_add_i32 s2, s2, s3
	s_mul_i32 s9, s2, 0xfffff300
	s_add_i32 s9, s9, s18
	v_add_u32_e32 v20, s9, v24
	s_lshl_b32 s8, s2, 6
	v_cmp_gt_i32_e32 vcc, s25, v20
	v_mov_b32_e32 v0, 0
	v_mov_b32_e32 v1, 0
	v_mov_b32_e32 v2, 0
	v_mov_b32_e32 v3, 0
	v_mov_b32_e32 v4, 0
	v_mov_b32_e32 v5, 0
	v_mov_b32_e32 v6, 0
	v_mov_b32_e32 v7, 0
	v_mov_b32_e32 v8, 0
	v_mov_b32_e32 v9, 0
	v_mov_b32_e32 v10, 0
	v_mov_b32_e32 v11, 0
	v_mov_b32_e32 v12, 0
	v_mov_b32_e32 v13, 0
	v_mov_b32_e32 v14, 0
	v_mov_b32_e32 v15, 0
	s_barrier
	s_and_saveexec_b64 s[2:3], vcc
	s_cbranch_execz .LBB0_1298
	v_readlane_b32 s72, v211, 38
	v_ashrrev_i32_e32 v21, 31, v20
	v_readlane_b32 s80, v211, 46
	v_readlane_b32 s81, v211, 47
	v_or_b32_e32 v0, s8, v179
	v_add_u32_e32 v2, s8, v171
	v_lshl_add_u64 v[8:9], v[20:21], 2, s[80:81]
	v_add_u32_e32 v10, s8, v25
	v_add_u32_e32 v12, s8, v26
	v_mad_i64_i32 v[0:1], s[10:11], v0, s26, v[8:9]
	v_mad_i64_i32 v[4:5], s[10:11], v2, s26, v[8:9]
	v_mad_i64_i32 v[10:11], s[10:11], v10, s26, v[8:9]
	v_mad_i64_i32 v[12:13], s[10:11], v12, s26, v[8:9]
	global_load_dwordx4 v[0:3], v[0:1], off
	global_load_dwordx4 v[4:7], v[4:5], off
	global_load_dwordx4 v[8:11], v[10:11], off
	global_load_dwordx4 v[12:15], v[12:13], off
	v_readlane_b32 s73, v211, 39
	v_readlane_b32 s74, v211, 40
	v_readlane_b32 s75, v211, 41
	v_readlane_b32 s76, v211, 42
	v_readlane_b32 s77, v211, 43
	v_readlane_b32 s78, v211, 44
	v_readlane_b32 s79, v211, 45
	v_readlane_b32 s82, v211, 48
	v_readlane_b32 s83, v211, 49
	v_readlane_b32 s84, v211, 50
	v_readlane_b32 s85, v211, 51
	v_readlane_b32 s86, v211, 52
	v_readlane_b32 s87, v211, 53

; __device__ __forceinline__ void phase_rwkv_out(const Params& P) {
;     ...
;   const int lane = threadIdx.x & 63, wave = threadIdx.x >> 6;
;   const int c8 = lane * 8;
;   float lw[8], lb[8], kav[8], rkv[8];
; #pragma unroll
;   for (int q = 0; q < 8; ++q) { lw[q] = P.d_ln_w[c8 + q]; lb[q] = P.d_ln_b[c8 + q]; kav[q] = P.d_k_a[c8 + q]; rkv[q] = P.d_r_k[c8 + q]; }
; #pragma unroll 2
;   for (int idx = blockIdx.x * 4 + wave; idx < 32768; idx += gridDim.x * 4) {
;     const size_t row = (size_t)((idx >> 14) * TPB + 256 + (idx & 16383));
;     const size_t off = row * 512 + c8;
;     const uint4 u_y0 = *(const uint4*)(YZ + off), u_y1 = *(const uint4*)(YZ + (SZ512 / 2) + off);
;     const uint4 u_r = *(const uint4*)(XR + off), u_k = *(const uint4*)(XK + off), u_v = *(const uint4*)(XV + off);
;     const uint4 u_a0 = *(const uint4*)(AZ + off), u_a1 = *(const uint4*)(AZ + (SZ512 / 2) + off);
;     const uint4 u_g = *(const uint4*)(Acat + row * DM + 512 + c8);
;     float y0[8], y1[8], rr[8], kk_[8], vv[8], a0[8], a1[8], gg[8];
;     unpack8(u_y0, y0); unpack8(u_y1, y1); unpack8(u_r, rr); unpack8(u_k, kk_); unpack8(u_v, vv);
;     unpack8(u_a0, a0); unpack8(u_a1, a1); unpack8(u_g, gg);
.LBB0_1361:
	s_or_b64 exec, exec, s[0:1]
	v_readlane_b32 s0, v209, 0
	s_waitcnt lgkmcnt(0)
	s_barrier
	v_lshl_add_u32 v34, s0, 2, v165
	s_mov_b32 s0, 0x8000
	v_cmp_gt_i32_e32 vcc, s0, v34
	s_and_saveexec_b64 s[0:1], vcc
	s_cbranch_execz .LBB0_1364
	v_and_b32_e32 v32, 0x1f8, v164
	v_readlane_b32 s4, v211, 0
	s_waitcnt vmcnt(2)
	v_lshlrev_b32_e32 v28, 2, v32
	v_readlane_b32 s8, v211, 4
	v_readlane_b32 s9, v211, 5
	v_readlane_b32 s5, v211, 1
	v_readlane_b32 s6, v211, 2
	v_readlane_b32 s7, v211, 3
	v_readlane_b32 s10, v211, 6
	v_readlane_b32 s11, v211, 7
	global_load_dwordx4 v[0:3], v28, s[8:9] offset:16
	s_nop 3
	global_load_dwordx4 v[4:7], v28, s[10:11] offset:16
	global_load_dwordx4 v[8:11], v28, s[8:9]
	global_load_dwordx4 v[12:15], v28, s[10:11]
	global_load_dwordx4 v[16:19], v28, s[4:5] offset:16
	global_load_dwordx4 v[20:23], v28, s[6:7] offset:16
	global_load_dwordx4 v[24:27], v28, s[4:5]
	global_load_dwordx4 v[28:31], v28, s[6:7]
	v_readlane_b32 s4, v211, 9
	s_add_u32 s2, s94, 0x1bf70000
	v_readlane_b32 s5, v211, 10
	v_mov_b32_e32 v33, 0
	s_addc_u32 s3, s95, 0
	s_lshl_b32 s6, s4, 2
	s_mov_b64 s[4:5], 0
	s_movk_i32 s7, 0x100
	v_lshlrev_b32_e32 v32, 1, v32
	s_mov_b32 s8, 0x1d00000
	v_mov_b32_e32 v35, 0x3a27c5ac
	s_mov_b32 s9, 0x800000
	s_movk_i32 s10, 0x7fff
.LBB0_1363:
	v_ashrrev_i32_e32 v36, 14, v34
	v_and_b32_e32 v37, 0x3fff, v34
	v_mul_i32_i24_e32 v36, 0x4100, v36
	v_add3_u32 v36, v37, v36, s7
	v_ashrrev_i32_e32 v37, 31, v36
	v_lshlrev_b64 v[38:39], 10, v[36:37]
	v_lshlrev_b64 v[36:37], 11, v[36:37]
	v_or_b32_e32 v38, v38, v32
	v_lshl_add_u64 v[36:37], s[94:95], 0, v[36:37]
	v_lshl_add_u64 v[40:41], s[42:43], 0, v[38:39]
	v_lshl_add_u64 v[42:43], s[66:67], 0, v[38:39]
	v_lshl_add_u64 v[44:45], s[48:49], 0, v[38:39]
	v_lshl_add_u64 v[48:49], s[58:59], 0, v[38:39]
	v_lshl_add_u64 v[52:53], s[62:63], 0, v[38:39]
	v_lshl_add_u64 v[56:57], s[52:53], 0, v[38:39]
	v_lshl_add_u64 v[60:61], s[2:3], 0, v[38:39]
	v_lshl_add_u64 v[64:65], v[36:37], 0, v[32:33]
	global_load_dwordx4 v[36:39], v[40:41], off
	global_load_dwordx4 v[40:43], v[42:43], off
	global_load_dwordx4 v[44:47], v[44:45], off
	global_load_dwordx4 v[48:51], v[48:49], off
	global_load_dwordx4 v[52:55], v[52:53], off
	global_load_dwordx4 v[56:59], v[56:57], off
	global_load_dwordx4 v[60:63], v[60:61], off
	v_add_u32_e32 v34, s6, v34
	v_cmp_lt_i32_e32 vcc, s10, v34
	s_or_b64 s[4:5], vcc, s[4:5]
	v_add_co_u32_e32 v68, vcc, s8, v64
	s_waitcnt vmcnt(6)
	v_lshlrev_b32_e32 v70, 16, v36
	v_addc_co_u32_e32 v69, vcc, 0, v65, vcc
	global_load_dwordx4 v[64:67], v[68:69], off offset:1024
	v_and_b32_e32 v71, 0xffff0000, v36
	v_lshlrev_b32_e32 v36, 16, v37
	s_waitcnt vmcnt(1)
	v_lshlrev_b32_e32 v94, 16, v60
	v_and_b32_e32 v95, 0xffff0000, v60
	v_and_b32_e32 v37, 0xffff0000, v37
	v_lshlrev_b32_e32 v72, 16, v38
	v_and_b32_e32 v73, 0xffff0000, v38
	v_lshlrev_b32_e32 v38, 16, v39
	v_and_b32_e32 v39, 0xffff0000, v39
	v_lshlrev_b32_e32 v74, 16, v40
	v_and_b32_e32 v75, 0xffff0000, v40
	v_lshlrev_b32_e32 v40, 16, v41
	v_and_b32_e32 v41, 0xffff0000, v41
	v_lshlrev_b32_e32 v76, 16, v42
	v_and_b32_e32 v77, 0xffff0000, v42
	v_lshlrev_b32_e32 v42, 16, v43
	v_and_b32_e32 v43, 0xffff0000, v43
	v_lshlrev_b32_e32 v90, 16, v56
	v_and_b32_e32 v91, 0xffff0000, v56
	v_lshlrev_b32_e32 v60, 16, v61
	v_and_b32_e32 v61, 0xffff0000, v61
	v_lshlrev_b32_e32 v96, 16, v62
	v_and_b32_e32 v97, 0xffff0000, v62
	v_lshlrev_b32_e32 v62, 16, v63
	v_and_b32_e32 v63, 0xffff0000, v63
	v_pk_add_f32 v[94:95], v[94:95], -1.0 op_sel_hi:[1,0]
	v_lshlrev_b32_e32 v82, 16, v48
	v_and_b32_e32 v83, 0xffff0000, v48
	v_lshlrev_b32_e32 v56, 16, v57
	v_and_b32_e32 v57, 0xffff0000, v57
	v_lshlrev_b32_e32 v92, 16, v58
	v_and_b32_e32 v93, 0xffff0000, v58
	v_lshlrev_b32_e32 v58, 16, v59
	v_and_b32_e32 v59, 0xffff0000, v59
	v_pk_add_f32 v[90:91], v[90:91], -1.0 op_sel_hi:[1,0]
	v_pk_add_f32 v[60:61], v[60:61], -1.0 op_sel_hi:[1,0]
	v_pk_add_f32 v[96:97], v[96:97], -1.0 op_sel_hi:[1,0]
	v_pk_add_f32 v[62:63], v[62:63], -1.0 op_sel_hi:[1,0]
	v_pk_add_f32 v[38:39], v[38:39], v[42:43]
	v_pk_add_f32 v[42:43], v[72:73], v[76:77]
	v_pk_add_f32 v[36:37], v[36:37], v[40:41]
	v_pk_add_f32 v[40:41], v[70:71], v[74:75]
	v_pk_fma_f32 v[72:73], v[24:25], v[94:95], 1.0 op_sel_hi:[1,1,0]
	v_lshlrev_b32_e32 v48, 16, v49
	v_and_b32_e32 v49, 0xffff0000, v49
	v_lshlrev_b32_e32 v84, 16, v50
	v_and_b32_e32 v85, 0xffff0000, v50
	v_lshlrev_b32_e32 v50, 16, v51
	v_and_b32_e32 v51, 0xffff0000, v51
	v_pk_add_f32 v[56:57], v[56:57], -1.0 op_sel_hi:[1,0]
	v_pk_add_f32 v[92:93], v[92:93], -1.0 op_sel_hi:[1,0]
	v_pk_add_f32 v[58:59], v[58:59], -1.0 op_sel_hi:[1,0]
	v_pk_fma_f32 v[70:71], v[24:25], v[90:91], 1.0 op_sel_hi:[1,1,0]
	v_pk_fma_f32 v[60:61], v[26:27], v[60:61], 1.0 op_sel_hi:[1,1,0]
	v_pk_fma_f32 v[76:77], v[16:17], v[96:97], 1.0 op_sel_hi:[1,1,0]
	v_pk_fma_f32 v[62:63], v[18:19], v[62:63], 1.0 op_sel_hi:[1,1,0]
	v_add_f32_e32 v90, 0, v40
	v_pk_mul_f32 v[72:73], v[72:73], v[82:83]
	v_lshlrev_b32_e32 v78, 16, v44
	v_and_b32_e32 v79, 0xffff0000, v44
; __device__ __forceinline__ void phase_rwkv_out(const Params& P) {
;     ...
;     float y[8], sy = 0.f, sd = 0.f;
; #pragma unroll
;     for (int q = 0; q < 8; ++q) {
;       y[q] = y0[q] + y1[q];
;       sy += y[q];
;       const float kd = kk_[q] * (1.f + (a0[q] - 1.f) * kav[q]) + kk_[q] * (1.f + (a1[q] - 1.f) * kav[q]);
;       sd += rr[q] * kd * rkv[q];
;     }
;     const float mean = red8(sy) * (1.0f / 64.0f);
;     const float sdot = red8(sd);
;     float sv = 0.f;
; #pragma unroll
;     for (int q = 0; q < 8; ++q) { y[q] -= mean; sv += y[q] * y[q]; }
;     const float rstd = rsqrtf(red8(sv) * (1.0f / 64.0f) + 64e-5f);
;     float o[8];
; #pragma unroll
;     for (int q = 0; q < 8; ++q) o[q] = (y[q] * rstd * lw[q] + lb[q] + sdot * vv[q]) * gg[q];
;     *(uint4*)(Acat + row * DM + 512 + c8) = make_uint4(pack2(o[0], o[1]), pack2(o[2], o[3]), pack2(o[4], o[5]), pack2(o[6], o[7]));
	v_pk_fma_f32 v[56:57], v[26:27], v[56:57], 1.0 op_sel_hi:[1,1,0]
	v_pk_fma_f32 v[74:75], v[16:17], v[92:93], 1.0 op_sel_hi:[1,1,0]
	v_pk_fma_f32 v[58:59], v[18:19], v[58:59], 1.0 op_sel_hi:[1,1,0]
	v_pk_mul_f32 v[60:61], v[60:61], v[48:49]
	v_pk_mul_f32 v[76:77], v[76:77], v[84:85]
	v_pk_mul_f32 v[62:63], v[62:63], v[50:51]
	v_add_f32_e32 v90, v41, v90
	v_pk_fma_f32 v[70:71], v[70:71], v[82:83], v[72:73]
	v_lshlrev_b32_e32 v44, 16, v45
	v_and_b32_e32 v45, 0xffff0000, v45
	v_lshlrev_b32_e32 v80, 16, v46
	v_and_b32_e32 v81, 0xffff0000, v46
	v_lshlrev_b32_e32 v46, 16, v47
	v_and_b32_e32 v47, 0xffff0000, v47
	v_pk_fma_f32 v[48:49], v[56:57], v[48:49], v[60:61]
	v_pk_fma_f32 v[56:57], v[74:75], v[84:85], v[76:77]
	v_pk_fma_f32 v[50:51], v[58:59], v[50:51], v[62:63]
	v_add_f32_e32 v60, v36, v90
	v_pk_mul_f32 v[58:59], v[70:71], v[78:79]
	v_pk_mul_f32 v[44:45], v[48:49], v[44:45]
	v_pk_mul_f32 v[48:49], v[56:57], v[80:81]
	v_pk_mul_f32 v[46:47], v[50:51], v[46:47]
	v_add_f32_e32 v56, v37, v60
	v_pk_mul_f32 v[50:51], v[28:29], v[58:59]
	v_add_f32_e32 v56, v42, v56
	v_add_f32_e32 v50, 0, v50
	v_pk_mul_f32 v[44:45], v[30:31], v[44:45]
	v_add_f32_e32 v56, v43, v56
	v_add_f32_e32 v50, v51, v50
	v_add_f32_e32 v51, v38, v56
	v_add_f32_e32 v44, v44, v50
	v_pk_mul_f32 v[48:49], v[20:21], v[48:49]
	v_add_f32_e32 v50, v39, v51
	v_add_f32_e32 v44, v45, v44
	v_add_f32_e32 v44, v48, v44
	v_add_f32_dpp v45, v50, v50 quad_perm:[1,0,3,2] row_mask:0xf bank_mask:0xf bound_ctrl:1
	v_pk_mul_f32 v[46:47], v[22:23], v[46:47]
	v_add_f32_e32 v44, v49, v44
	v_add_f32_dpp v45, v45, v45 quad_perm:[2,3,0,1] row_mask:0xf bank_mask:0xf bound_ctrl:1
	v_add_f32_e32 v46, v46, v44
	v_lshlrev_b32_e32 v86, 16, v52
	v_add_f32_dpp v45, v45, v45 row_half_mirror row_mask:0xf bank_mask:0xf bound_ctrl:1
	v_mul_f32_e32 v44, 0x3c800000, v45
	v_add_f32_e32 v45, v47, v46
	v_pk_add_f32 v[40:41], v[40:41], v[44:45] op_sel_hi:[1,0] neg_lo:[0,1] neg_hi:[0,1]
	v_pk_add_f32 v[36:37], v[36:37], v[44:45] op_sel_hi:[1,0] neg_lo:[0,1] neg_hi:[0,1]
	v_pk_add_f32 v[42:43], v[42:43], v[44:45] op_sel_hi:[1,0] neg_lo:[0,1] neg_hi:[0,1]
	v_pk_add_f32 v[38:39], v[38:39], v[44:45] op_sel_hi:[1,0] neg_lo:[0,1] neg_hi:[0,1]
	v_add_f32_dpp v56, v45, v45 quad_perm:[1,0,3,2] row_mask:0xf bank_mask:0xf bound_ctrl:1
	v_pk_mul_f32 v[44:45], v[40:41], v[40:41]
	v_pk_mul_f32 v[46:47], v[36:37], v[36:37]
	v_add_f32_e32 v45, v44, v45
	v_add_f32_e32 v45, v46, v45
	v_pk_mul_f32 v[48:49], v[42:43], v[42:43]
	v_add_f32_e32 v45, v47, v45
	v_add_f32_e32 v45, v48, v45
	v_pk_mul_f32 v[50:51], v[38:39], v[38:39]
	v_add_f32_e32 v45, v49, v45
	v_add_f32_e32 v45, v50, v45
	v_add_f32_e32 v45, v51, v45
	v_add_f32_dpp v56, v56, v56 quad_perm:[2,3,0,1] row_mask:0xf bank_mask:0xf bound_ctrl:1
	v_and_b32_e32 v87, 0xffff0000, v52
	v_add_f32_dpp v45, v45, v45 quad_perm:[1,0,3,2] row_mask:0xf bank_mask:0xf bound_ctrl:1
	v_lshlrev_b32_e32 v52, 16, v53
	v_and_b32_e32 v53, 0xffff0000, v53
	v_add_f32_dpp v45, v45, v45 quad_perm:[2,3,0,1] row_mask:0xf bank_mask:0xf bound_ctrl:1
	v_lshlrev_b32_e32 v88, 16, v54
	v_and_b32_e32 v89, 0xffff0000, v54
	v_add_f32_dpp v45, v45, v45 row_half_mirror row_mask:0xf bank_mask:0xf bound_ctrl:1
	v_fmamk_f32 v45, v45, 0x3c800000, v35
	v_mul_f32_e32 v46, 0x4b800000, v45
	v_cmp_gt_f32_e32 vcc, s9, v45
	v_lshlrev_b32_e32 v54, 16, v55
	v_and_b32_e32 v55, 0xffff0000, v55
	v_cndmask_b32_e32 v45, v45, v46, vcc
	v_rsq_f32_e32 v45, v45
	v_add_f32_dpp v44, v56, v56 row_half_mirror row_mask:0xf bank_mask:0xf bound_ctrl:1
	s_waitcnt vmcnt(0)
	v_lshlrev_b32_e32 v98, 16, v64
	v_and_b32_e32 v99, 0xffff0000, v64
	v_mul_f32_e32 v46, 0x45800000, v45
	v_cndmask_b32_e32 v46, v45, v46, vcc
	v_pk_mul_f32 v[40:41], v[40:41], v[46:47] op_sel_hi:[1,0]
	v_pk_mul_f32 v[36:37], v[36:37], v[46:47] op_sel_hi:[1,0]
	v_pk_mul_f32 v[42:43], v[42:43], v[46:47] op_sel_hi:[1,0]
	v_pk_mul_f32 v[38:39], v[38:39], v[46:47] op_sel_hi:[1,0]
	v_pk_fma_f32 v[40:41], v[8:9], v[40:41], v[12:13]
	v_pk_fma_f32 v[36:37], v[10:11], v[36:37], v[14:15]
	v_pk_fma_f32 v[42:43], v[0:1], v[42:43], v[4:5]
	v_pk_fma_f32 v[38:39], v[2:3], v[38:39], v[6:7]
	v_lshlrev_b32_e32 v64, 16, v65
	v_and_b32_e32 v65, 0xffff0000, v65
	v_lshlrev_b32_e32 v100, 16, v66
	v_and_b32_e32 v101, 0xffff0000, v66
	v_lshlrev_b32_e32 v66, 16, v67
	v_and_b32_e32 v67, 0xffff0000, v67
	v_pk_fma_f32 v[40:41], v[44:45], v[86:87], v[40:41] op_sel_hi:[0,1,1]
	v_pk_fma_f32 v[36:37], v[44:45], v[52:53], v[36:37] op_sel_hi:[0,1,1]
	v_pk_fma_f32 v[42:43], v[44:45], v[88:89], v[42:43] op_sel_hi:[0,1,1]
	v_pk_fma_f32 v[38:39], v[44:45], v[54:55], v[38:39] op_sel_hi:[0,1,1]
	v_pk_mul_f32 v[40:41], v[40:41], v[98:99]
	v_pk_mul_f32 v[44:45], v[36:37], v[64:65]
	v_pk_mul_f32 v[42:43], v[42:43], v[100:101]
	v_pk_mul_f32 v[46:47], v[38:39], v[66:67]
	v_cvt_pk_bf16_f32 v36, v40, v41
	v_cvt_pk_bf16_f32 v37, v44, v45
	v_cvt_pk_bf16_f32 v38, v42, v43
	v_cvt_pk_bf16_f32 v39, v46, v47
	global_store_dwordx4 v[68:69], v[36:39], off offset:1024
	s_andn2_b64 exec, exec, s[4:5]
	s_cbranch_execnz .LBB0_1363

;   __device__ __forceinline__ void operator()(const f32x4 (&acc)[4][4], int row0w, int col0w, int l15, int quad) const {
;     ...
;       const size_t off = isc ? (size_t)(b * 256 + kidx) * DM : (size_t)(b * 16384 + kidx - 256) * DM;
;       const float* src = (isc ? ctx_src : lat_src) + off;
;       float* dst = (isc ? ctx_dst : lat_dst) + off;
;       const float* g = gate + (isc ? 2 : b) * 6144;
; #pragma unroll
;       for (int j = 0; j < 4; ++j) {
;         const int n = col0w + j * 16 + quad * 4;
;         const float4 xo = *(const float4*)(src + n);
;         const float4 g4 = *(const float4*)(g + n);
;         float4 o;
;         o.x = xo.x + g4.x * acc[i][j][0];
;         o.y = xo.y + g4.y * acc[i][j][1];
;         o.z = xo.z + g4.z * acc[i][j][2];
;         o.w = xo.w + g4.w * acc[i][j][3];
;         *(float4*)(dst + n) = o;
;       }
.LBB0_1418:
	s_or_b64 exec, exec, s[0:1]
	v_mul_i32_i24_e32 v17, 0x1800, v20
	v_cndmask_b32_e32 v20, v17, v180, vcc
	v_ashrrev_i32_e32 v17, 31, v16
	v_ashrrev_i32_e32 v21, 31, v20
	v_lshlrev_b64 v[16:17], 12, v[16:17]
	v_lshl_add_u64 v[16:17], v[18:19], 0, v[16:17]
	v_lshl_add_u64 v[18:19], v[20:21], 2, s[4:5]
	v_lshl_add_u64 v[30:31], v[18:19], 0, v[64:65]
	v_lshl_add_u64 v[28:29], v[16:17], 0, v[64:65]
	global_load_dwordx4 v[16:19], v[30:31], off
	global_load_dwordx4 v[20:23], v[28:29], off
	global_load_dwordx4 v[24:27], v[28:29], off offset:64
	s_add_i32 s19, s19, s90
	s_add_i32 s11, s11, s90
	s_cmp_ge_i32 s19, s56
	s_waitcnt vmcnt(1)
	v_pk_fma_f32 v[12:13], v[12:13], v[16:17], v[20:21]
	v_pk_fma_f32 v[14:15], v[14:15], v[18:19], v[22:23]
	global_store_dwordx4 v[28:29], v[12:15], off
	global_load_dwordx4 v[12:15], v[30:31], off offset:64
	s_waitcnt vmcnt(0)
	v_pk_fma_f32 v[8:9], v[8:9], v[12:13], v[24:25]
	v_pk_fma_f32 v[10:11], v[10:11], v[14:15], v[26:27]
	global_store_dwordx4 v[28:29], v[8:11], off offset:64
	global_load_dwordx4 v[8:11], v[30:31], off offset:128
	global_load_dwordx4 v[12:15], v[28:29], off offset:128
	global_load_dwordx4 v[16:19], v[28:29], off offset:192
	s_waitcnt vmcnt(1)
	v_pk_fma_f32 v[4:5], v[4:5], v[8:9], v[12:13]
	v_pk_fma_f32 v[6:7], v[6:7], v[10:11], v[14:15]
	global_store_dwordx4 v[28:29], v[4:7], off offset:128
	global_load_dwordx4 v[4:7], v[30:31], off offset:192
	s_waitcnt vmcnt(0)
	v_pk_fma_f32 v[0:1], v[0:1], v[4:5], v[16:17]
	v_pk_fma_f32 v[2:3], v[2:3], v[6:7], v[18:19]
	global_store_dwordx4 v[28:29], v[0:3], off offset:192
	s_cbranch_scc1 .LBB0_1439

; template <bool DEEP, class Epi>
; __device__ __forceinline__ void gemm_phase(const bf16_t* __restrict__ A, int lda, const bf16_t* __restrict__ Wt,
;                                            int K, int ntn, bool lat_only, const Epi& epi, char* smem) {
;     ...
;     for (int kt = 0; kt < nk; ++kt) {
;       __syncthreads();
;       GEMM_STORE(ra0, ra1, ra2, ra3, rb0, rb1, rb2, rb3, 0)
;       __syncthreads();
;       {
;         bf16x8 af0[4], bf0[4], af1[4], bf1[4];
;         __builtin_amdgcn_s_setprio(1);
; #pragma unroll
;         for (int i = 0; i < 4; ++i) af0[i] = *(const bf16x8*)(sA + (wm * 64 + i * 16 + l15) * LSTR + quad * 8);
; #pragma unroll
;         for (int j = 0; j < 4; ++j) bf0[j] = *(const bf16x8*)(sB + (wn * 64 + j * 16 + l15) * LSTR + quad * 8);
; #pragma unroll
;         for (int i = 0; i < 4; ++i) af1[i] = *(const bf16x8*)(sA + (wm * 64 + i * 16 + l15) * LSTR + 32 + quad * 8);
; #pragma unroll
;         for (int j = 0; j < 4; ++j) bf1[j] = *(const bf16x8*)(sB + (wn * 64 + j * 16 + l15) * LSTR + 32 + quad * 8);
;         __builtin_amdgcn_sched_barrier(0);
;         if (kt + 1 < nk) GEMM_LOAD(ra0, ra1, ra2, ra3, rb0, rb1, rb2, rb3, (kt + 1) * 64)
;         __builtin_amdgcn_sched_barrier(0);
.LBB0_1421:
	s_barrier
	s_waitcnt vmcnt(0)
	ds_write_b128 v161, v[64:67]
	ds_write_b128 v161, v[68:71] offset:5120
	ds_write_b128 v161, v[76:79] offset:10240
	ds_write_b128 v161, v[84:87] offset:15360
	ds_write_b128 v161, v[72:75] offset:20480
	ds_write_b128 v161, v[80:83] offset:25600
	ds_write_b128 v161, v[88:91] offset:30720
	ds_write_b128 v161, v[92:95] offset:35840
	v_add_u32_e32 v96, v173, v175
	s_waitcnt lgkmcnt(0)
	s_barrier
	s_setprio 1
	ds_read_b128 v[156:159], v96
	ds_read_b128 v[152:155], v96 offset:2560
	ds_read_b128 v[132:135], v96 offset:5120
	ds_read_b128 v[124:127], v96 offset:7680
	ds_read_b128 v[136:139], v176 offset:20480
	ds_read_b128 v[140:143], v176 offset:23040
	ds_read_b128 v[144:147], v176 offset:25600
	ds_read_b128 v[148:151], v176 offset:28160
	ds_read_b128 v[128:131], v178 offset:64
	ds_read_b128 v[120:123], v178 offset:2624
	ds_read_b128 v[100:103], v178 offset:5184
	ds_read_b128 v[96:99], v178 offset:7744
	ds_read_b128 v[104:107], v179 offset:20544
	ds_read_b128 v[108:111], v179 offset:23104
	ds_read_b128 v[112:115], v179 offset:25664
	ds_read_b128 v[116:119], v179 offset:28224
	s_cmp_gt_u32 s1, 14
	s_cbranch_scc1 .LBB0_1420
	v_lshl_add_u64 v[72:73], v[168:169], 0, s[8:9]
	v_add_co_u32_e32 v64, vcc, 0x1d00000, v72
	v_lshl_add_u64 v[88:89], v[170:171], 0, s[8:9]
	s_nop 0
	v_addc_co_u32_e32 v65, vcc, 0, v73, vcc
	v_add_co_u32_e32 v68, vcc, 0x1d10000, v72
	s_nop 1
	v_addc_co_u32_e32 v69, vcc, 0, v73, vcc
	v_add_co_u32_e32 v74, vcc, 0x1d20000, v72
	global_load_dwordx4 v[64:67], v[64:65], off offset:128
	global_load_dwordx4 v[68:71], v[68:69], off offset:128
	v_addc_co_u32_e32 v75, vcc, 0, v73, vcc
	v_add_co_u32_e32 v72, vcc, 0x1d30000, v72
	s_nop 1
	v_addc_co_u32_e32 v73, vcc, 0, v73, vcc
	global_load_dwordx4 v[76:79], v[74:75], off offset:128
	global_load_dwordx4 v[84:87], v[72:73], off offset:128
	v_add_co_u32_e32 v72, vcc, 0x680000, v88
	s_nop 1
	v_addc_co_u32_e32 v73, vcc, 0, v89, vcc
	v_add_co_u32_e32 v80, vcc, 0x690000, v88
	s_nop 1
	v_addc_co_u32_e32 v81, vcc, 0, v89, vcc
	v_add_co_u32_e32 v90, vcc, 0x6a0000, v88
	global_load_dwordx4 v[72:75], v[72:73], off offset:128
	global_load_dwordx4 v[80:83], v[80:81], off offset:128
	v_addc_co_u32_e32 v91, vcc, 0, v89, vcc
	v_add_co_u32_e32 v92, vcc, 0x6b0000, v88
	s_nop 1
	v_addc_co_u32_e32 v93, vcc, 0, v89, vcc
	global_load_dwordx4 v[88:91], v[90:91], off offset:128
	global_load_dwordx4 v[92:95], v[92:93], off offset:128
	s_branch .LBB0_1420
;   __device__ __forceinline__ void operator()(const f32x4 (&acc)[4][4], int row0w, int col0w, int l15, int quad) const {
;     ...
;     for (int i = 0; i < 4; ++i) {
;       const int row = row0w + i * 16 + l15;
;       const int b = row / TPB, kidx = row - b * TPB;
;       const bool isc = kidx < 256;
;       const size_t off = isc ? (size_t)(b * 256 + kidx) * DM : (size_t)(b * 16384 + kidx - 256) * DM;
;       const float* src = (isc ? ctx_src : lat_src) + off;
;       float* dst = (isc ? ctx_dst : lat_dst) + off;
;       const float* g = gate + (isc ? 2 : b) * 6144;
; #pragma unroll
;       for (int j = 0; j < 4; ++j) {
;         const int n = col0w + j * 16 + quad * 4;
;         const float4 xo = *(const float4*)(src + n);
;         const float4 g4 = *(const float4*)(g + n);
;         float4 o;
;         o.x = xo.x + g4.x * acc[i][j][0];
;         o.y = xo.y + g4.y * acc[i][j][1];
;         o.z = xo.z + g4.z * acc[i][j][2];
;         o.w = xo.w + g4.w * acc[i][j][3];
;         *(float4*)(dst + n) = o;
;       }
.LBB0_1423:
	s_waitcnt vmcnt(6)
	v_add_u32_e32 v68, s0, v172
	v_mul_hi_i32 v64, v68, s15
	v_lshrrev_b32_e32 v65, 31, v64
	v_ashrrev_i32_e32 v64, 13, v64
	v_add_u32_e32 v69, v64, v65
	v_mad_i32_i24 v65, v69, s16, v68
	v_cmp_gt_i32_e32 vcc, s10, v65
	v_cmp_lt_i32_e64 s[0:1], s17, v65
	s_and_saveexec_b64 s[8:9], s[0:1]
	s_xor_b64 s[0:1], exec, s[8:9]
	v_lshlrev_b32_e32 v64, 14, v69
	v_add3_u32 v64, v64, v65, s18
	s_or_saveexec_b64 s[0:1], s[0:1]
	v_mov_b64_e32 v[66:67], s[92:93]
	s_xor_b64 exec, exec, s[0:1]
	v_lshl_add_u32 v64, v69, 8, v65
	v_mov_b64_e32 v[66:67], s[68:69]
	s_or_b64 exec, exec, s[0:1]
	v_ashrrev_i32_e32 v65, 31, v64
	v_lshlrev_b64 v[64:65], 12, v[64:65]
	v_lshl_add_u64 v[66:67], v[66:67], 0, v[64:65]
	v_mul_i32_i24_e32 v64, 0x1800, v69
	v_or_b32_e32 v70, s6, v174
	v_cndmask_b32_e32 v64, v64, v180, vcc
	v_ashrrev_i32_e32 v71, 31, v70
	v_ashrrev_i32_e32 v65, 31, v64
	s_waitcnt vmcnt(3)
	v_lshl_add_u64 v[72:73], v[64:65], 2, s[4:5]
	v_lshlrev_b64 v[64:65], 2, v[70:71]
	s_waitcnt vmcnt(2)
	v_lshl_add_u64 v[82:83], v[72:73], 0, v[64:65]
	v_lshl_add_u64 v[66:67], v[66:67], 0, v[64:65]
	global_load_dwordx4 v[70:73], v[82:83], off
	global_load_dwordx4 v[74:77], v[66:67], off
	global_load_dwordx4 v[78:81], v[66:67], off offset:64
	s_waitcnt vmcnt(1)
	v_pk_fma_f32 v[60:61], v[60:61], v[70:71], v[74:75]
	v_pk_fma_f32 v[62:63], v[62:63], v[72:73], v[76:77]
	global_store_dwordx4 v[66:67], v[60:63], off
	global_load_dwordx4 v[60:63], v[82:83], off offset:64
	s_waitcnt vmcnt(0)
	v_pk_fma_f32 v[56:57], v[56:57], v[60:61], v[78:79]
	v_pk_fma_f32 v[58:59], v[58:59], v[62:63], v[80:81]
	global_store_dwordx4 v[66:67], v[56:59], off offset:64
	global_load_dwordx4 v[56:59], v[82:83], off offset:128
	global_load_dwordx4 v[60:63], v[66:67], off offset:128
	global_load_dwordx4 v[70:73], v[66:67], off offset:192
	s_waitcnt vmcnt(1)
	v_pk_fma_f32 v[52:53], v[52:53], v[56:57], v[60:61]
	v_pk_fma_f32 v[54:55], v[54:55], v[58:59], v[62:63]
	global_store_dwordx4 v[66:67], v[52:55], off offset:128
	global_load_dwordx4 v[54:57], v[82:83], off offset:192
	s_waitcnt vmcnt(0)
	v_pk_fma_f32 v[48:49], v[48:49], v[54:55], v[70:71]
	v_or_b32_e32 v53, 16, v68
	v_mul_hi_i32 v52, v53, s15
	v_lshrrev_b32_e32 v58, 31, v52
	v_ashrrev_i32_e32 v52, 13, v52
	v_add_u32_e32 v52, v52, v58
	v_mad_i32_i24 v53, v52, s16, v53
	v_cmp_gt_i32_e32 vcc, s10, v53
	v_pk_fma_f32 v[50:51], v[50:51], v[56:57], v[72:73]
	v_cmp_lt_i32_e64 s[0:1], s17, v53
	global_store_dwordx4 v[66:67], v[48:51], off offset:192
	s_and_saveexec_b64 s[6:7], s[0:1]
	s_xor_b64 s[0:1], exec, s[6:7]
	v_lshlrev_b32_e32 v48, 14, v52
	v_add3_u32 v48, v48, v53, s18
	s_or_saveexec_b64 s[0:1], s[0:1]
	v_mov_b64_e32 v[50:51], s[92:93]
	s_xor_b64 exec, exec, s[0:1]
	v_lshl_add_u32 v48, v52, 8, v53
	v_mov_b64_e32 v[50:51], s[68:69]
	s_or_b64 exec, exec, s[0:1]
	v_ashrrev_i32_e32 v49, 31, v48
	v_lshlrev_b64 v[48:49], 12, v[48:49]
	v_lshl_add_u64 v[48:49], v[50:51], 0, v[48:49]
	v_mul_i32_i24_e32 v50, 0x1800, v52
	v_cndmask_b32_e32 v50, v50, v180, vcc
	v_ashrrev_i32_e32 v51, 31, v50
	v_lshl_add_u64 v[50:51], v[50:51], 2, s[4:5]
	v_lshl_add_u64 v[62:63], v[50:51], 0, v[64:65]
	v_lshl_add_u64 v[60:61], v[48:49], 0, v[64:65]
	global_load_dwordx4 v[48:51], v[62:63], off
	global_load_dwordx4 v[52:55], v[60:61], off
	global_load_dwordx4 v[56:59], v[60:61], off offset:64
	s_waitcnt vmcnt(1)
	v_pk_fma_f32 v[44:45], v[44:45], v[48:49], v[52:53]
	v_pk_fma_f32 v[46:47], v[46:47], v[50:51], v[54:55]
	global_store_dwordx4 v[60:61], v[44:47], off
	global_load_dwordx4 v[44:47], v[62:63], off offset:64
	s_waitcnt vmcnt(0)
	v_pk_fma_f32 v[40:41], v[40:41], v[44:45], v[56:57]
	v_pk_fma_f32 v[42:43], v[42:43], v[46:47], v[58:59]
	global_store_dwordx4 v[60:61], v[40:43], off offset:64
	global_load_dwordx4 v[40:43], v[62:63], off offset:128
	global_load_dwordx4 v[44:47], v[60:61], off offset:128
	global_load_dwordx4 v[48:51], v[60:61], off offset:192
	s_waitcnt vmcnt(1)
	v_pk_fma_f32 v[36:37], v[36:37], v[40:41], v[44:45]
	v_pk_fma_f32 v[38:39], v[38:39], v[42:43], v[46:47]
	global_store_dwordx4 v[60:61], v[36:39], off offset:128
	global_load_dwordx4 v[38:41], v[62:63], off offset:192
	s_waitcnt vmcnt(0)
	v_pk_fma_f32 v[32:33], v[32:33], v[38:39], v[48:49]
	v_or_b32_e32 v37, 32, v68
	v_mul_hi_i32 v36, v37, s15
	v_lshrrev_b32_e32 v42, 31, v36
	v_ashrrev_i32_e32 v36, 13, v36
	v_add_u32_e32 v36, v36, v42
	v_mad_i32_i24 v37, v36, s16, v37
	v_cmp_gt_i32_e32 vcc, s10, v37
	v_pk_fma_f32 v[34:35], v[34:35], v[40:41], v[50:51]
	v_cmp_lt_i32_e64 s[0:1], s17, v37
	global_store_dwordx4 v[60:61], v[32:35], off offset:192
	s_and_saveexec_b64 s[6:7], s[0:1]
	s_xor_b64 s[0:1], exec, s[6:7]
	v_lshlrev_b32_e32 v32, 14, v36
	v_add3_u32 v32, v32, v37, s18
	s_or_saveexec_b64 s[0:1], s[0:1]
	v_mov_b64_e32 v[34:35], s[92:93]
	s_xor_b64 exec, exec, s[0:1]
	v_lshl_add_u32 v32, v36, 8, v37
	v_mov_b64_e32 v[34:35], s[68:69]
	s_or_b64 exec, exec, s[0:1]
	v_ashrrev_i32_e32 v33, 31, v32
	v_lshlrev_b64 v[32:33], 12, v[32:33]
	v_lshl_add_u64 v[32:33], v[34:35], 0, v[32:33]
	v_mul_i32_i24_e32 v34, 0x1800, v36
	v_cndmask_b32_e32 v34, v34, v180, vcc
	v_ashrrev_i32_e32 v35, 31, v34
	v_lshl_add_u64 v[34:35], v[34:35], 2, s[4:5]
	v_lshl_add_u64 v[46:47], v[34:35], 0, v[64:65]
	v_lshl_add_u64 v[44:45], v[32:33], 0, v[64:65]
	global_load_dwordx4 v[32:35], v[46:47], off
	global_load_dwordx4 v[36:39], v[44:45], off
	global_load_dwordx4 v[40:43], v[44:45], off offset:64
	s_waitcnt vmcnt(1)
	v_pk_fma_f32 v[28:29], v[28:29], v[32:33], v[36:37]
	v_pk_fma_f32 v[30:31], v[30:31], v[34:35], v[38:39]
	global_store_dwordx4 v[44:45], v[28:31], off
	global_load_dwordx4 v[28:31], v[46:47], off offset:64
	s_waitcnt vmcnt(0)
	v_pk_fma_f32 v[24:25], v[24:25], v[28:29], v[40:41]
	v_pk_fma_f32 v[26:27], v[26:27], v[30:31], v[42:43]
	global_store_dwordx4 v[44:45], v[24:27], off offset:64
	global_load_dwordx4 v[24:27], v[46:47], off offset:128
	global_load_dwordx4 v[28:31], v[44:45], off offset:128
	global_load_dwordx4 v[32:35], v[44:45], off offset:192
	s_waitcnt vmcnt(1)
	v_pk_fma_f32 v[20:21], v[20:21], v[24:25], v[28:29]
	v_pk_fma_f32 v[22:23], v[22:23], v[26:27], v[30:31]
	global_store_dwordx4 v[44:45], v[20:23], off offset:128
	global_load_dwordx4 v[22:25], v[46:47], off offset:192
	s_waitcnt vmcnt(0)
	v_pk_fma_f32 v[16:17], v[16:17], v[22:23], v[32:33]
	v_or_b32_e32 v21, 48, v68
	v_mul_hi_i32 v20, v21, s15
	v_lshrrev_b32_e32 v26, 31, v20
	v_ashrrev_i32_e32 v20, 13, v20
	v_add_u32_e32 v20, v20, v26
	v_mad_i32_i24 v21, v20, s16, v21
	v_cmp_gt_i32_e32 vcc, s10, v21
	v_pk_fma_f32 v[18:19], v[18:19], v[24:25], v[34:35]
	v_cmp_lt_i32_e64 s[0:1], s17, v21
	global_store_dwordx4 v[44:45], v[16:19], off offset:192
	s_and_saveexec_b64 s[6:7], s[0:1]
	s_xor_b64 s[0:1], exec, s[6:7]
	v_lshlrev_b32_e32 v16, 14, v20
	v_add3_u32 v16, v16, v21, s18
	s_or_saveexec_b64 s[0:1], s[0:1]
	v_mov_b64_e32 v[18:19], s[92:93]
	s_xor_b64 exec, exec, s[0:1]
	s_cbranch_execz .LBB0_1418
	v_lshl_add_u32 v16, v20, 8, v21
	v_mov_b64_e32 v[18:19], s[68:69]
	s_branch .LBB0_1418

; __device__ __forceinline__ void phase_norm(const float* lat_src, const float* ctx_src, const float* gain, const float* modl,
;                                            int sh_off, int sc_off, bf16_t* A, bool lat_only) {
;     ...
;       for (int i = 0; i < 4; ++i) xv[u][i] = *(const float4*)(src + i * 256 + lane * 4);
;     }
; #pragma unroll
;     for (int u = 0; u < 2; ++u) {
;       float ss = 0.f;
; #pragma unroll
;       for (int i = 0; i < 4; ++i) ss += xv[u][i].x * xv[u][i].x + xv[u][i].y * xv[u][i].y + xv[u][i].z * xv[u][i].z + xv[u][i].w * xv[u][i].w;
;       ss = wave_sum(ss);
;       const float rstd = rsqrtf(ss * (1.0f / 1024.0f) + 1e-6f);
; #pragma unroll
;       for (int i = 0; i < 4; ++i) {
;         const int c = i * 256 + lane * 4;
;         const float4 g = *(const float4*)(gain + c);
;         const float4 sh = *(const float4*)(md[u] + sh_off + c);
;         const float4 sc = *(const float4*)(md[u] + sc_off + c);
;         uint2 w;
;         w.x = pack2(xv[u][i].x * rstd * g.x * (1.f + sc.x) + sh.x, xv[u][i].y * rstd * g.y * (1.f + sc.y) + sh.y);
;         w.y = pack2(xv[u][i].z * rstd * g.z * (1.f + sc.z) + sh.z, xv[u][i].w * rstd * g.w * (1.f + sc.w) + sh.w);
;         *(uint2*)(A + (size_t)rowi[u] * DM + c) = w;
;       }
.LBB0_1493:
	s_or_b64 exec, exec, s[10:11]
	v_lshl_add_u64 v[8:9], v[8:9], 0, v[32:33]
	global_load_dwordx4 v[28:31], v[8:9], off
	global_load_dwordx4 v[20:23], v[8:9], off offset:1024
	global_load_dwordx4 v[16:19], v[8:9], off offset:2048
	global_load_dwordx4 v[8:11], v[8:9], off offset:3072
	v_lshl_add_u64 v[58:59], v[58:59], 2, s[40:41]
	s_waitcnt vmcnt(7)
	v_mov_b32_e32 v72, v25
	s_waitcnt vmcnt(6)
	v_mov_b32_e32 v73, v13
	s_waitcnt vmcnt(5)
	v_mov_b32_e32 v80, v5
	s_waitcnt vmcnt(4)
	v_mov_b32_e32 v81, v1
	v_mov_b32_e32 v70, v24
	v_mov_b32_e32 v71, v12
	v_mov_b32_e32 v76, v4
	v_mov_b32_e32 v77, v0
	v_pk_mul_f32 v[72:73], v[72:73], v[72:73]
	v_pk_mul_f32 v[80:81], v[80:81], v[80:81]
	v_lshl_add_u64 v[86:87], v[58:59], 0, s[6:7]
	v_lshl_add_u64 v[88:89], v[58:59], 0, s[8:9]
	v_mov_b32_e32 v74, v26
	v_mov_b32_e32 v75, v14
	v_mov_b32_e32 v82, v6
	v_mov_b32_e32 v83, v2
	v_pk_fma_f32 v[58:59], v[70:71], v[70:71], v[72:73]
	v_pk_fma_f32 v[70:71], v[76:77], v[76:77], v[80:81]
	v_lshl_add_u64 v[72:73], v[86:87], 0, v[32:33]
	v_lshl_add_u64 v[76:77], v[88:89], 0, v[32:33]
	global_load_dwordx4 v[66:69], v[34:35], off
	v_pk_fma_f32 v[58:59], v[74:75], v[74:75], v[58:59]
	v_pk_fma_f32 v[80:81], v[82:83], v[82:83], v[70:71]
	global_load_dwordx4 v[70:73], v[72:73], off
	global_load_dwordx4 v[74:77], v[76:77], off
	v_mov_b32_e32 v78, v27
	v_mov_b32_e32 v79, v15
	v_mov_b32_e32 v84, v7
	v_mov_b32_e32 v85, v3
	v_pk_fma_f32 v[58:59], v[78:79], v[78:79], v[58:59]
	v_pk_fma_f32 v[78:79], v[84:85], v[84:85], v[80:81]
	v_mov_b32_e32 v81, v58
	v_mov_b32_e32 v83, v78
	v_ashrrev_i32_e32 v57, 31, v56
	v_lshlrev_b64 v[56:57], 11, v[56:57]
	v_mov_b32_e32 v45, v33
	v_lshl_add_u64 v[54:55], v[54:55], 2, s[40:41]
	v_ashrrev_i32_e32 v53, 31, v52
	v_add_u32_e32 v163, s13, v163
	s_waitcnt vmcnt(6)
	v_mov_b32_e32 v94, v29
	s_waitcnt vmcnt(5)
	v_mov_b32_e32 v95, v21
	v_mov_b32_e32 v92, v28
	v_mov_b32_e32 v93, v20
	s_waitcnt vmcnt(4)
	v_mov_b32_e32 v102, v17
	s_waitcnt vmcnt(3)
	v_mov_b32_e32 v103, v9
	v_pk_mul_f32 v[94:95], v[94:95], v[94:95]
	v_mov_b32_e32 v84, v30
	v_mov_b32_e32 v85, v22
	v_mov_b32_e32 v100, v16
	v_mov_b32_e32 v101, v8
	v_pk_mul_f32 v[102:103], v[102:103], v[102:103]
	v_pk_fma_f32 v[92:93], v[92:93], v[92:93], v[94:95]
	v_mov_b32_e32 v90, v31
	v_mov_b32_e32 v91, v23
	v_mov_b32_e32 v96, v18
	v_mov_b32_e32 v97, v10
	v_pk_fma_f32 v[94:95], v[100:101], v[100:101], v[102:103]
	v_pk_fma_f32 v[84:85], v[84:85], v[84:85], v[92:93]
	v_mov_b32_e32 v98, v19
	v_mov_b32_e32 v99, v11
	v_pk_fma_f32 v[92:93], v[96:97], v[96:97], v[94:95]
	v_pk_fma_f32 v[84:85], v[90:91], v[90:91], v[84:85]
	v_pk_fma_f32 v[90:91], v[98:99], v[98:99], v[92:93]
	v_mov_b32_e32 v80, v84
	v_mov_b32_e32 v58, v85
	v_mov_b32_e32 v82, v90
	v_pk_add_f32 v[58:59], v[80:81], v[58:59]
	v_mov_b32_e32 v78, v91
	v_pk_add_f32 v[58:59], v[58:59], v[82:83]
	v_lshl_add_u64 v[80:81], v[42:43], 0, v[56:57]
	v_pk_add_f32 v[58:59], v[58:59], v[78:79]
	ds_bpermute_b32 v79, v51, v59
	ds_bpermute_b32 v78, v51, v58
	s_waitcnt lgkmcnt(0)
	v_pk_add_f32 v[58:59], v[58:59], v[78:79]
	ds_bpermute_b32 v79, v60, v59
	ds_bpermute_b32 v78, v60, v58
	s_waitcnt lgkmcnt(0)
	v_pk_add_f32 v[58:59], v[58:59], v[78:79]
	ds_bpermute_b32 v79, v61, v59
	ds_bpermute_b32 v78, v61, v58
	s_waitcnt lgkmcnt(0)
	v_pk_add_f32 v[58:59], v[58:59], v[78:79]
	ds_bpermute_b32 v79, v62, v59
	ds_bpermute_b32 v78, v62, v58
	s_waitcnt lgkmcnt(0)
	v_pk_add_f32 v[58:59], v[58:59], v[78:79]
	ds_bpermute_b32 v79, v63, v59
	ds_bpermute_b32 v78, v63, v58
	s_waitcnt lgkmcnt(0)
	v_pk_add_f32 v[58:59], v[58:59], v[78:79]
	ds_bpermute_b32 v79, v64, v59
	ds_bpermute_b32 v78, v64, v58
	s_waitcnt lgkmcnt(0)
	v_pk_add_f32 v[56:57], v[58:59], v[78:79]
	s_nop 0
	v_pk_fma_f32 v[78:79], v[56:57], s[12:13], v[50:51] op_sel_hi:[1,0,0]
	s_waitcnt vmcnt(0)
	v_pk_add_f32 v[58:59], v[74:75], 1.0 op_sel_hi:[1,0]
	v_mul_f32_e32 v47, 0x4b800000, v79
	v_cmp_gt_f32_e32 vcc, s19, v79
	v_pk_add_f32 v[74:75], v[76:77], 1.0 op_sel_hi:[1,0]
	v_lshl_add_u64 v[56:57], v[88:89], 0, v[44:45]
	v_cndmask_b32_e32 v47, v79, v47, vcc
	v_rsq_f32_e32 v47, v47
	s_nop 0
	v_mul_f32_e32 v49, 0x45800000, v47
	v_cndmask_b32_e32 v76, v47, v49, vcc
	v_pk_mul_f32 v[24:25], v[24:25], v[76:77] op_sel_hi:[1,0]
	v_pk_mul_f32 v[26:27], v[26:27], v[76:77] op_sel_hi:[1,0]
	v_pk_mul_f32 v[24:25], v[66:67], v[24:25]
	v_pk_mul_f32 v[26:27], v[68:69], v[26:27]
	v_pk_fma_f32 v[24:25], v[58:59], v[24:25], v[70:71]
	v_pk_fma_f32 v[26:27], v[26:27], v[74:75], v[72:73]
	v_cvt_pk_bf16_f32 v24, v24, v25
	v_cvt_pk_bf16_f32 v25, v26, v27
	global_store_dwordx2 v[80:81], v[24:25], off
	global_load_dwordx4 v[24:27], v[36:37], off
	global_load_dwordx4 v[56:59], v[56:57], off
	v_lshl_add_u64 v[66:67], v[86:87], 0, v[44:45]
	global_load_dwordx4 v[66:69], v[66:67], off
	v_pk_mul_f32 v[12:13], v[12:13], v[76:77] op_sel_hi:[1,0]
	v_pk_mul_f32 v[14:15], v[14:15], v[76:77] op_sel_hi:[1,0]
	v_mov_b32_e32 v47, v33
	v_lshl_add_u64 v[70:71], v[88:89], 0, v[46:47]
	v_pk_mul_f32 v[4:5], v[4:5], v[76:77] op_sel_hi:[1,0]
	v_pk_mul_f32 v[6:7], v[6:7], v[76:77] op_sel_hi:[1,0]
	v_mov_b32_e32 v49, v33
	v_pk_mul_f32 v[0:1], v[0:1], v[76:77] op_sel_hi:[1,0]
	v_pk_mul_f32 v[2:3], v[2:3], v[76:77] op_sel_hi:[1,0]
	v_cmp_gt_f32_e32 vcc, s19, v78
	s_waitcnt vmcnt(2)
	v_pk_mul_f32 v[12:13], v[12:13], v[24:25]
	s_waitcnt vmcnt(1)
	v_pk_add_f32 v[24:25], v[56:57], 1.0 op_sel_hi:[1,0]
	v_pk_mul_f32 v[14:15], v[14:15], v[26:27]
	v_pk_add_f32 v[26:27], v[58:59], 1.0 op_sel_hi:[1,0]
	s_waitcnt vmcnt(0)
; __device__ __forceinline__ void phase_norm(const float* lat_src, const float* ctx_src, const float* gain, const float* modl,
;                                            int sh_off, int sc_off, bf16_t* A, bool lat_only) {
;     ...
;       for (int i = 0; i < 4; ++i) {
;         const int c = i * 256 + lane * 4;
;         const float4 g = *(const float4*)(gain + c);
;         const float4 sh = *(const float4*)(md[u] + sh_off + c);
;         const float4 sc = *(const float4*)(md[u] + sc_off + c);
;         uint2 w;
;         w.x = pack2(xv[u][i].x * rstd * g.x * (1.f + sc.x) + sh.x, xv[u][i].y * rstd * g.y * (1.f + sc.y) + sh.y);
;         w.y = pack2(xv[u][i].z * rstd * g.z * (1.f + sc.z) + sh.z, xv[u][i].w * rstd * g.w * (1.f + sc.w) + sh.w);
;         *(uint2*)(A + (size_t)rowi[u] * DM + c) = w;
;       }
	v_pk_fma_f32 v[12:13], v[12:13], v[24:25], v[66:67]
	v_pk_fma_f32 v[14:15], v[14:15], v[26:27], v[68:69]
	v_cvt_pk_bf16_f32 v12, v12, v13
	v_cvt_pk_bf16_f32 v13, v14, v15
	global_store_dwordx2 v[80:81], v[12:13], off offset:512
	global_load_dwordx4 v[12:15], v[38:39], off
	global_load_dwordx4 v[24:27], v[70:71], off
	v_lshl_add_u64 v[56:57], v[86:87], 0, v[46:47]
	global_load_dwordx4 v[56:59], v[56:57], off
	v_lshl_add_u64 v[66:67], v[88:89], 0, v[48:49]
	s_waitcnt vmcnt(2)
	v_pk_mul_f32 v[4:5], v[4:5], v[12:13]
	s_waitcnt vmcnt(1)
	v_pk_add_f32 v[12:13], v[24:25], 1.0 op_sel_hi:[1,0]
	v_pk_mul_f32 v[6:7], v[6:7], v[14:15]
	v_pk_add_f32 v[14:15], v[26:27], 1.0 op_sel_hi:[1,0]
	s_waitcnt vmcnt(0)
	v_pk_fma_f32 v[4:5], v[4:5], v[12:13], v[56:57]
	v_pk_fma_f32 v[6:7], v[6:7], v[14:15], v[58:59]
	v_cvt_pk_bf16_f32 v4, v4, v5
	v_cvt_pk_bf16_f32 v5, v6, v7
	global_store_dwordx2 v[80:81], v[4:5], off offset:1024
	global_load_dwordx4 v[4:7], v[40:41], off
	global_load_dwordx4 v[12:15], v[66:67], off
	v_lshl_add_u64 v[24:25], v[86:87], 0, v[48:49]
	global_load_dwordx4 v[24:27], v[24:25], off
	v_lshl_add_u64 v[56:57], v[54:55], 0, s[8:9]
	v_lshl_add_u64 v[58:59], v[56:57], 0, v[32:33]
	s_waitcnt vmcnt(2)
	v_pk_mul_f32 v[0:1], v[0:1], v[4:5]
	s_waitcnt vmcnt(1)
	v_pk_add_f32 v[4:5], v[12:13], 1.0 op_sel_hi:[1,0]
	v_pk_mul_f32 v[2:3], v[2:3], v[6:7]
	v_pk_add_f32 v[6:7], v[14:15], 1.0 op_sel_hi:[1,0]
	s_waitcnt vmcnt(0)
	v_pk_fma_f32 v[0:1], v[0:1], v[4:5], v[24:25]
	v_pk_fma_f32 v[2:3], v[2:3], v[6:7], v[26:27]
	v_cvt_pk_bf16_f32 v0, v0, v1
	v_cvt_pk_bf16_f32 v1, v2, v3
	global_store_dwordx2 v[80:81], v[0:1], off offset:1536
	v_lshl_add_u64 v[24:25], v[54:55], 0, s[6:7]
	global_load_dwordx4 v[0:3], v[34:35], off
	global_load_dwordx4 v[4:7], v[58:59], off
	v_lshl_add_u64 v[12:13], v[24:25], 0, v[32:33]
	global_load_dwordx4 v[12:15], v[12:13], off
	v_mul_f32_e32 v26, 0x4b800000, v78
	v_cndmask_b32_e32 v26, v78, v26, vcc
	v_rsq_f32_e32 v54, v26
	v_lshlrev_b64 v[26:27], 11, v[52:53]
	v_lshl_add_u64 v[26:27], v[42:43], 0, v[26:27]
	v_lshl_add_u64 v[52:53], v[56:57], 0, v[44:45]
	v_mul_f32_e32 v55, 0x45800000, v54
	v_cndmask_b32_e32 v54, v54, v55, vcc
	v_pk_mul_f32 v[28:29], v[28:29], v[54:55] op_sel_hi:[1,0]
	v_pk_mul_f32 v[30:31], v[30:31], v[54:55] op_sel_hi:[1,0]
	v_pk_mul_f32 v[20:21], v[20:21], v[54:55] op_sel_hi:[1,0]
	v_pk_mul_f32 v[22:23], v[22:23], v[54:55] op_sel_hi:[1,0]
	v_pk_mul_f32 v[16:17], v[16:17], v[54:55] op_sel_hi:[1,0]
	v_pk_mul_f32 v[18:19], v[18:19], v[54:55] op_sel_hi:[1,0]
	v_pk_mul_f32 v[8:9], v[8:9], v[54:55] op_sel_hi:[1,0]
	v_pk_mul_f32 v[10:11], v[10:11], v[54:55] op_sel_hi:[1,0]
	v_cmp_lt_i32_e32 vcc, s20, v163
	s_or_b64 s[4:5], vcc, s[4:5]
	s_waitcnt vmcnt(2)
	v_pk_mul_f32 v[0:1], v[0:1], v[28:29]
	s_waitcnt vmcnt(1)
	v_pk_add_f32 v[4:5], v[4:5], 1.0 op_sel_hi:[1,0]
	v_pk_mul_f32 v[2:3], v[2:3], v[30:31]
	v_pk_add_f32 v[6:7], v[6:7], 1.0 op_sel_hi:[1,0]
	s_waitcnt vmcnt(0)
	v_pk_fma_f32 v[0:1], v[4:5], v[0:1], v[12:13]
	v_pk_fma_f32 v[2:3], v[2:3], v[6:7], v[14:15]
	v_cvt_pk_bf16_f32 v0, v0, v1
	v_cvt_pk_bf16_f32 v1, v2, v3
	global_store_dwordx2 v[26:27], v[0:1], off
	global_load_dwordx4 v[0:3], v[36:37], off
	global_load_dwordx4 v[4:7], v[52:53], off
	v_lshl_add_u64 v[12:13], v[24:25], 0, v[44:45]
	global_load_dwordx4 v[12:15], v[12:13], off
	v_lshl_add_u64 v[28:29], v[56:57], 0, v[46:47]
	s_waitcnt vmcnt(2)
	v_pk_mul_f32 v[0:1], v[20:21], v[0:1]
	s_waitcnt vmcnt(1)
	v_pk_add_f32 v[4:5], v[4:5], 1.0 op_sel_hi:[1,0]
	v_pk_mul_f32 v[2:3], v[22:23], v[2:3]
	v_pk_add_f32 v[6:7], v[6:7], 1.0 op_sel_hi:[1,0]
	s_waitcnt vmcnt(0)
	v_pk_fma_f32 v[0:1], v[0:1], v[4:5], v[12:13]
	v_pk_fma_f32 v[2:3], v[2:3], v[6:7], v[14:15]
	v_cvt_pk_bf16_f32 v0, v0, v1
	v_cvt_pk_bf16_f32 v1, v2, v3
	global_store_dwordx2 v[26:27], v[0:1], off offset:512
	global_load_dwordx4 v[0:3], v[38:39], off
	global_load_dwordx4 v[4:7], v[28:29], off
	v_lshl_add_u64 v[12:13], v[24:25], 0, v[46:47]
	global_load_dwordx4 v[12:15], v[12:13], off
	v_lshl_add_u64 v[20:21], v[56:57], 0, v[48:49]
	s_waitcnt vmcnt(2)
	v_pk_mul_f32 v[0:1], v[16:17], v[0:1]
	s_waitcnt vmcnt(1)
	v_pk_add_f32 v[4:5], v[4:5], 1.0 op_sel_hi:[1,0]
	v_pk_mul_f32 v[2:3], v[18:19], v[2:3]
	v_pk_add_f32 v[6:7], v[6:7], 1.0 op_sel_hi:[1,0]
	s_waitcnt vmcnt(0)
	v_pk_fma_f32 v[0:1], v[0:1], v[4:5], v[12:13]
	v_pk_fma_f32 v[2:3], v[2:3], v[6:7], v[14:15]
	v_cvt_pk_bf16_f32 v0, v0, v1
	v_cvt_pk_bf16_f32 v1, v2, v3
	global_store_dwordx2 v[26:27], v[0:1], off offset:1024
	global_load_dwordx4 v[0:3], v[40:41], off
	global_load_dwordx4 v[4:7], v[20:21], off
	v_lshl_add_u64 v[12:13], v[24:25], 0, v[48:49]
	global_load_dwordx4 v[12:15], v[12:13], off
	s_waitcnt vmcnt(2)
	v_pk_mul_f32 v[0:1], v[8:9], v[0:1]
	s_waitcnt vmcnt(1)
	v_pk_add_f32 v[4:5], v[4:5], 1.0 op_sel_hi:[1,0]
	v_pk_mul_f32 v[2:3], v[10:11], v[2:3]
	v_pk_add_f32 v[6:7], v[6:7], 1.0 op_sel_hi:[1,0]
	s_waitcnt vmcnt(0)
	v_pk_fma_f32 v[0:1], v[0:1], v[4:5], v[12:13]
	v_pk_fma_f32 v[2:3], v[2:3], v[6:7], v[14:15]
	v_cvt_pk_bf16_f32 v0, v0, v1
	v_cvt_pk_bf16_f32 v1, v2, v3
	global_store_dwordx2 v[26:27], v[0:1], off offset:1536
	s_andn2_b64 exec, exec, s[4:5]
	s_cbranch_execz .LBB0_1502
; __device__ __forceinline__ void phase_norm(const float* lat_src, const float* ctx_src, const float* gain, const float* modl,
;                                            int sh_off, int sc_off, bf16_t* A, bool lat_only) {
;     ...
;     for (int u = 0; u < 2; ++u) {
;       const int idx = idx0 + u;
;       const int row = lat_only ? ((idx >> 14) * TPB + 256 + (idx & 16383)) : idx;
;       const int b = row / TPB, kidx = row - b * TPB;
;       const bool isc = kidx < 256;
;       const float* src = isc ? ctx_src + (size_t)(b * 256 + kidx) * DM : lat_src + (size_t)(b * 16384 + kidx - 256) * DM;
;       md[u] = modl + (isc ? 2 : b) * 6144;
;       rowi[u] = row;
; #pragma unroll
;       for (int i = 0; i < 4; ++i) xv[u][i] = *(const float4*)(src + i * 256 + lane * 4);
.LBB0_1494:
	v_ashrrev_i32_e32 v0, 14, v163
	s_waitcnt vmcnt(11)
	v_mad_i32_i24 v8, v0, s14, v65
	v_and_b32_e32 v9, 0x3ffe, v163
	v_add_u32_e32 v56, v8, v9
	v_mul_hi_i32 v0, v56, s15
	v_lshrrev_b32_e32 v1, 31, v0
	v_ashrrev_i32_e32 v0, 13, v0
	v_add_u32_e32 v2, v0, v1
	v_mad_i32_i24 v3, v2, s16, v56
	v_cmp_lt_i32_e32 vcc, s17, v3
	s_and_saveexec_b64 s[10:11], vcc
	s_xor_b64 s[10:11], exec, s[10:11]
	v_lshlrev_b32_e32 v0, 14, v2
	v_add3_u32 v0, v0, v3, s18
	v_ashrrev_i32_e32 v1, 31, v0
	v_lshlrev_b64 v[0:1], 12, v[0:1]
	v_mul_i32_i24_e32 v58, 0x1800, v2
	v_lshl_add_u64 v[0:1], s[92:93], 0, v[0:1]
	v_ashrrev_i32_e32 v59, 31, v58
	s_andn2_saveexec_b64 s[10:11], s[10:11]
	v_lshl_add_u32 v0, v2, 8, v3
	v_ashrrev_i32_e32 v1, 31, v0
	v_lshlrev_b64 v[0:1], 12, v[0:1]
	v_lshl_add_u64 v[0:1], s[68:69], 0, v[0:1]
	v_mov_b64_e32 v[58:59], 0x3000
	s_or_b64 exec, exec, s[10:11]
	v_lshl_add_u64 v[0:1], v[0:1], 0, v[32:33]
	global_load_dwordx4 v[24:27], v[0:1], off
	global_load_dwordx4 v[12:15], v[0:1], off offset:1024
	global_load_dwordx4 v[4:7], v[0:1], off offset:2048
	global_load_dwordx4 v[0:3], v[0:1], off offset:3072
	v_add3_u32 v52, v8, v9, 1
	v_mul_hi_i32 v8, v52, s15
	v_lshrrev_b32_e32 v9, 31, v8
	v_ashrrev_i32_e32 v8, 13, v8
	s_waitcnt vmcnt(14)
	v_add_u32_e32 v10, v8, v9
	v_mad_i32_i24 v11, v10, s16, v52
	v_cmp_lt_i32_e32 vcc, s17, v11
	s_and_saveexec_b64 s[10:11], vcc
	s_xor_b64 s[10:11], exec, s[10:11]
	v_lshlrev_b32_e32 v8, 14, v10
	v_add3_u32 v8, v8, v11, s18
	v_ashrrev_i32_e32 v9, 31, v8
	v_lshlrev_b64 v[8:9], 12, v[8:9]
	v_mul_i32_i24_e32 v54, 0x1800, v10
	v_lshl_add_u64 v[8:9], s[92:93], 0, v[8:9]
	v_ashrrev_i32_e32 v55, 31, v54
	s_andn2_saveexec_b64 s[10:11], s[10:11]
	s_cbranch_execz .LBB0_1493
	v_lshl_add_u32 v8, v10, 8, v11
	v_ashrrev_i32_e32 v9, 31, v8
	v_lshlrev_b64 v[8:9], 12, v[8:9]
	v_lshl_add_u64 v[8:9], s[68:69], 0, v[8:9]
	v_mov_b64_e32 v[54:55], 0x3000
	s_branch .LBB0_1493

; template <bool DEEP, class Epi>
; __device__ __forceinline__ void gemm_phase(const bf16_t* __restrict__ A, int lda, const bf16_t* __restrict__ Wt,
;                                            int K, int ntn, bool lat_only, const Epi& epi, char* smem) {
;     ...
;     for (int kt = 0; kt < nk; ++kt) {
;       __syncthreads();
;       GEMM_STORE(ra0, ra1, ra2, ra3, rb0, rb1, rb2, rb3, 0)
;       __syncthreads();
;       {
;         bf16x8 af0[4], bf0[4], af1[4], bf1[4];
;         __builtin_amdgcn_s_setprio(1);
; #pragma unroll
;         for (int i = 0; i < 4; ++i) af0[i] = *(const bf16x8*)(sA + (wm * 64 + i * 16 + l15) * LSTR + quad * 8);
; #pragma unroll
;         for (int j = 0; j < 4; ++j) bf0[j] = *(const bf16x8*)(sB + (wn * 64 + j * 16 + l15) * LSTR + quad * 8);
; #pragma unroll
;         for (int i = 0; i < 4; ++i) af1[i] = *(const bf16x8*)(sA + (wm * 64 + i * 16 + l15) * LSTR + 32 + quad * 8);
; #pragma unroll
;         for (int j = 0; j < 4; ++j) bf1[j] = *(const bf16x8*)(sB + (wn * 64 + j * 16 + l15) * LSTR + 32 + quad * 8);
;         __builtin_amdgcn_sched_barrier(0);
;         if (kt + 1 < nk) GEMM_LOAD(ra0, ra1, ra2, ra3, rb0, rb1, rb2, rb3, (kt + 1) * 64)
;         __builtin_amdgcn_sched_barrier(0);
.LBB0_1559:
	s_barrier
	s_waitcnt vmcnt(7)
	ds_write_b128 v172, v[56:59]
	s_waitcnt vmcnt(6)
	ds_write_b128 v172, v[60:63] offset:5120
	s_waitcnt vmcnt(5)
	ds_write_b128 v172, v[64:67] offset:10240
	s_waitcnt vmcnt(4)
	ds_write_b128 v172, v[72:75] offset:15360
	s_waitcnt vmcnt(3)
	ds_write_b128 v172, v[80:83] offset:20480
	s_waitcnt vmcnt(2)
	ds_write_b128 v172, v[84:87] offset:25600
	s_waitcnt vmcnt(1)
	ds_write_b128 v172, v[88:91] offset:30720
	s_waitcnt vmcnt(0)
	ds_write_b128 v172, v[92:95] offset:35840
	v_add_u32_e32 v96, v174, v175
	s_waitcnt lgkmcnt(0)
	s_barrier
	s_setprio 1
	ds_read_b128 v[156:159], v96
	ds_read_b128 v[152:155], v96 offset:2560
	ds_read_b128 v[132:135], v96 offset:5120
	ds_read_b128 v[124:127], v96 offset:7680
	ds_read_b128 v[136:139], v176 offset:20480
	ds_read_b128 v[140:143], v176 offset:23040
	ds_read_b128 v[144:147], v176 offset:25600
	ds_read_b128 v[148:151], v176 offset:28160
	ds_read_b128 v[128:131], v177 offset:64
	ds_read_b128 v[120:123], v177 offset:2624
	ds_read_b128 v[100:103], v177 offset:5184
	ds_read_b128 v[96:99], v177 offset:7744
	ds_read_b128 v[104:107], v178 offset:20544
	ds_read_b128 v[108:111], v178 offset:23104
	ds_read_b128 v[112:115], v178 offset:25664
	ds_read_b128 v[116:119], v178 offset:28224
	s_cmpk_eq_i32 s6, 0x780
	s_cbranch_scc1 .LBB0_1558
	v_lshl_add_u64 v[64:65], v[168:169], 0, s[6:7]
	v_add_co_u32_e32 v56, vcc, 0x1d00000, v64
	v_lshl_add_u64 v[88:89], v[170:171], 0, s[6:7]
	s_nop 0
	v_addc_co_u32_e32 v57, vcc, 0, v65, vcc
	v_add_co_u32_e32 v60, vcc, 0x1d10000, v64
	s_nop 1
	v_addc_co_u32_e32 v61, vcc, 0, v65, vcc
	v_add_co_u32_e32 v66, vcc, 0x1d20000, v64
	global_load_dwordx4 v[56:59], v[56:57], off offset:128
	global_load_dwordx4 v[60:63], v[60:61], off offset:128
	v_addc_co_u32_e32 v67, vcc, 0, v65, vcc
	v_add_co_u32_e32 v72, vcc, 0x1d30000, v64
	s_nop 1
	v_addc_co_u32_e32 v73, vcc, 0, v65, vcc
	v_add_co_u32_e32 v80, vcc, 0x880000, v88
	global_load_dwordx4 v[64:67], v[66:67], off offset:128
	global_load_dwordx4 v[72:75], v[72:73], off offset:128
	v_addc_co_u32_e32 v81, vcc, 0, v89, vcc
	v_add_co_u32_e32 v84, vcc, 0x890000, v88
	s_nop 1
	v_addc_co_u32_e32 v85, vcc, 0, v89, vcc
	v_add_co_u32_e32 v90, vcc, 0x8a0000, v88
	global_load_dwordx4 v[80:83], v[80:81], off offset:128
	global_load_dwordx4 v[84:87], v[84:85], off offset:128
	v_addc_co_u32_e32 v91, vcc, 0, v89, vcc
	v_add_co_u32_e32 v92, vcc, 0x8b0000, v88
	s_nop 1
	v_addc_co_u32_e32 v93, vcc, 0, v89, vcc
	global_load_dwordx4 v[88:91], v[90:91], off offset:128
	global_load_dwordx4 v[92:95], v[92:93], off offset:128
	s_branch .LBB0_1558

;   __device__ __forceinline__ void operator()(const f32x4 (&acc)[4][4], int row0w, int col0w, int l15, int quad) const {
;     ...
;       const size_t off = isc ? (size_t)(b * 256 + kidx) * DM : (size_t)(b * 16384 + kidx - 256) * DM;
;       const float* src = (isc ? ctx_src : lat_src) + off;
;       float* dst = (isc ? ctx_dst : lat_dst) + off;
;       const float* g = gate + (isc ? 2 : b) * 6144;
; #pragma unroll
;       for (int j = 0; j < 4; ++j) {
;         const int n = col0w + j * 16 + quad * 4;
;         const float4 xo = *(const float4*)(src + n);
;         const float4 g4 = *(const float4*)(g + n);
;         float4 o;
;         o.x = xo.x + g4.x * acc[i][j][0];
;         o.y = xo.y + g4.y * acc[i][j][1];
;         o.z = xo.z + g4.z * acc[i][j][2];
;         o.w = xo.w + g4.w * acc[i][j][3];
;         *(float4*)(dst + n) = o;
;       }
.LBB0_1615:
	s_or_b64 exec, exec, s[0:1]
	v_mul_i32_i24_e32 v17, 0x1800, v20
	v_cndmask_b32_e32 v20, v17, v177, vcc
	v_ashrrev_i32_e32 v17, 31, v16
	v_ashrrev_i32_e32 v21, 31, v20
	v_lshlrev_b64 v[16:17], 12, v[16:17]
	v_lshl_add_u64 v[16:17], v[18:19], 0, v[16:17]
	v_lshl_add_u64 v[18:19], v[20:21], 2, s[2:3]
	v_lshl_add_u64 v[30:31], v[18:19], 0, v[64:65]
	v_lshl_add_u64 v[28:29], v[16:17], 0, v[64:65]
	global_load_dwordx4 v[16:19], v[30:31], off
	global_load_dwordx4 v[20:23], v[28:29], off
	global_load_dwordx4 v[24:27], v[28:29], off offset:64
	s_add_i32 s91, s91, s90
	s_add_i32 s4, s4, s90
	s_cmp_ge_i32 s91, s56
	s_waitcnt vmcnt(1)
	v_pk_fma_f32 v[12:13], v[12:13], v[16:17], v[20:21]
	v_pk_fma_f32 v[14:15], v[14:15], v[18:19], v[22:23]
	global_store_dwordx4 v[28:29], v[12:15], off
	global_load_dwordx4 v[12:15], v[30:31], off offset:64
	s_waitcnt vmcnt(0)
	v_pk_fma_f32 v[8:9], v[8:9], v[12:13], v[24:25]
	v_pk_fma_f32 v[10:11], v[10:11], v[14:15], v[26:27]
	global_store_dwordx4 v[28:29], v[8:11], off offset:64
	global_load_dwordx4 v[8:11], v[30:31], off offset:128
	global_load_dwordx4 v[12:15], v[28:29], off offset:128
	global_load_dwordx4 v[16:19], v[28:29], off offset:192
	s_waitcnt vmcnt(1)
	v_pk_fma_f32 v[4:5], v[4:5], v[8:9], v[12:13]
	v_pk_fma_f32 v[6:7], v[6:7], v[10:11], v[14:15]
	global_store_dwordx4 v[28:29], v[4:7], off offset:128
	global_load_dwordx4 v[4:7], v[30:31], off offset:192
	s_waitcnt vmcnt(0)
	v_pk_fma_f32 v[0:1], v[0:1], v[4:5], v[16:17]
	v_pk_fma_f32 v[2:3], v[2:3], v[6:7], v[18:19]
	global_store_dwordx4 v[28:29], v[0:3], off offset:192
	s_cbranch_scc1 .LBB0_1636

; template <bool DEEP, class Epi>
; __device__ __forceinline__ void gemm_phase(const bf16_t* __restrict__ A, int lda, const bf16_t* __restrict__ Wt,
;                                            int K, int ntn, bool lat_only, const Epi& epi, char* smem) {
;     ...
;     for (int kt = 0; kt < nk; ++kt) {
;       __syncthreads();
;       GEMM_STORE(ra0, ra1, ra2, ra3, rb0, rb1, rb2, rb3, 0)
;       __syncthreads();
;       {
;         bf16x8 af0[4], bf0[4], af1[4], bf1[4];
;         __builtin_amdgcn_s_setprio(1);
; #pragma unroll
;         for (int i = 0; i < 4; ++i) af0[i] = *(const bf16x8*)(sA + (wm * 64 + i * 16 + l15) * LSTR + quad * 8);
; #pragma unroll
;         for (int j = 0; j < 4; ++j) bf0[j] = *(const bf16x8*)(sB + (wn * 64 + j * 16 + l15) * LSTR + quad * 8);
; #pragma unroll
;         for (int i = 0; i < 4; ++i) af1[i] = *(const bf16x8*)(sA + (wm * 64 + i * 16 + l15) * LSTR + 32 + quad * 8);
; #pragma unroll
;         for (int j = 0; j < 4; ++j) bf1[j] = *(const bf16x8*)(sB + (wn * 64 + j * 16 + l15) * LSTR + 32 + quad * 8);
;         __builtin_amdgcn_sched_barrier(0);
;         if (kt + 1 < nk) GEMM_LOAD(ra0, ra1, ra2, ra3, rb0, rb1, rb2, rb3, (kt + 1) * 64)
;         __builtin_amdgcn_sched_barrier(0);
.LBB0_1618:
	s_barrier
	s_waitcnt vmcnt(0)
	ds_write_b128 v168, v[64:67]
	ds_write_b128 v168, v[72:75] offset:5120
	ds_write_b128 v168, v[80:83] offset:10240
	ds_write_b128 v168, v[88:91] offset:15360
	ds_write_b128 v168, v[68:71] offset:20480
	ds_write_b128 v168, v[76:79] offset:25600
	ds_write_b128 v168, v[84:87] offset:30720
	ds_write_b128 v168, v[92:95] offset:35840
	v_add_u32_e32 v96, v170, v172
	s_waitcnt lgkmcnt(0)
	s_barrier
	s_setprio 1
	ds_read_b128 v[156:159], v96
	ds_read_b128 v[152:155], v96 offset:2560
	ds_read_b128 v[132:135], v96 offset:5120
	ds_read_b128 v[124:127], v96 offset:7680
	ds_read_b128 v[136:139], v174 offset:20480
	ds_read_b128 v[140:143], v174 offset:23040
	ds_read_b128 v[144:147], v174 offset:25600
	ds_read_b128 v[148:151], v174 offset:28160
	ds_read_b128 v[128:131], v175 offset:64
	ds_read_b128 v[120:123], v175 offset:2624
	ds_read_b128 v[100:103], v175 offset:5184
	ds_read_b128 v[96:99], v175 offset:7744
	ds_read_b128 v[104:107], v176 offset:20544
	ds_read_b128 v[108:111], v176 offset:23104
	ds_read_b128 v[112:115], v176 offset:25664
	ds_read_b128 v[116:119], v176 offset:28224
	s_cmp_gt_u32 s15, 42
	s_cbranch_scc1 .LBB0_1617
	v_lshl_add_u64 v[68:69], v[164:165], 0, s[0:1]
	v_add_co_u32_e32 v64, vcc, 0x5e00000, v68
	v_lshl_add_u64 v[84:85], v[166:167], 0, s[0:1]
	s_nop 0
	v_addc_co_u32_e32 v65, vcc, 0, v69, vcc
	v_add_co_u32_e32 v70, vcc, 0x5e2c000, v68
	s_nop 1
	v_addc_co_u32_e32 v71, vcc, 0, v69, vcc
	global_load_dwordx4 v[64:67], v[64:65], off offset:128
	global_load_dwordx4 v[72:75], v[70:71], off offset:128
	v_add_co_u32_e32 v70, vcc, 0x5e58000, v68
	s_nop 1
	v_addc_co_u32_e32 v71, vcc, 0, v69, vcc
	v_add_co_u32_e32 v68, vcc, 0x5e84000, v68
	s_nop 1
	v_addc_co_u32_e32 v69, vcc, 0, v69, vcc
	global_load_dwordx4 v[80:83], v[70:71], off offset:128
	global_load_dwordx4 v[88:91], v[68:69], off offset:128
	v_add_co_u32_e32 v68, vcc, 0x1380000, v84
	s_nop 1
	v_addc_co_u32_e32 v69, vcc, 0, v85, vcc
	v_add_co_u32_e32 v76, vcc, 0x13ac000, v84
	s_nop 1
	v_addc_co_u32_e32 v77, vcc, 0, v85, vcc
	v_add_co_u32_e32 v86, vcc, 0x13d8000, v84
	global_load_dwordx4 v[68:71], v[68:69], off offset:128
	global_load_dwordx4 v[76:79], v[76:77], off offset:128
	v_addc_co_u32_e32 v87, vcc, 0, v85, vcc
	v_add_co_u32_e32 v92, vcc, 0x1404000, v84
	s_nop 1
	v_addc_co_u32_e32 v93, vcc, 0, v85, vcc
	global_load_dwordx4 v[84:87], v[86:87], off offset:128
	global_load_dwordx4 v[92:95], v[92:93], off offset:128
	s_branch .LBB0_1617
;   __device__ __forceinline__ void operator()(const f32x4 (&acc)[4][4], int row0w, int col0w, int l15, int quad) const {
;     ...
;     for (int i = 0; i < 4; ++i) {
;       const int row = row0w + i * 16 + l15;
;       const int b = row / TPB, kidx = row - b * TPB;
;       const bool isc = kidx < 256;
;       const size_t off = isc ? (size_t)(b * 256 + kidx) * DM : (size_t)(b * 16384 + kidx - 256) * DM;
;       const float* src = (isc ? ctx_src : lat_src) + off;
;       float* dst = (isc ? ctx_dst : lat_dst) + off;
;       const float* g = gate + (isc ? 2 : b) * 6144;
; #pragma unroll
;       for (int j = 0; j < 4; ++j) {
;         const int n = col0w + j * 16 + quad * 4;
;         const float4 xo = *(const float4*)(src + n);
;         const float4 g4 = *(const float4*)(g + n);
;         float4 o;
;         o.x = xo.x + g4.x * acc[i][j][0];
;         o.y = xo.y + g4.y * acc[i][j][1];
;         o.z = xo.z + g4.z * acc[i][j][2];
;         o.w = xo.w + g4.w * acc[i][j][3];
;         *(float4*)(dst + n) = o;
;       }
.LBB0_1620:
	s_waitcnt vmcnt(3)
	v_add_u32_e32 v68, s14, v169
	v_mul_hi_i32 v64, v68, s9
	v_lshrrev_b32_e32 v65, 31, v64
	v_ashrrev_i32_e32 v64, 13, v64
	v_add_u32_e32 v69, v64, v65
	v_mad_i32_i24 v65, v69, s10, v68
	v_cmp_gt_i32_e32 vcc, s5, v65
	v_cmp_lt_i32_e64 s[0:1], s11, v65
	s_and_saveexec_b64 s[14:15], s[0:1]
	s_xor_b64 s[0:1], exec, s[14:15]
	v_lshlrev_b32_e32 v64, 14, v69
	v_add3_u32 v64, v64, v65, s12
	s_or_saveexec_b64 s[0:1], s[0:1]
	v_mov_b64_e32 v[66:67], s[92:93]
	s_xor_b64 exec, exec, s[0:1]
	v_lshl_add_u32 v64, v69, 8, v65
	v_mov_b64_e32 v[66:67], s[68:69]
	s_or_b64 exec, exec, s[0:1]
	v_ashrrev_i32_e32 v65, 31, v64
	v_lshlrev_b64 v[64:65], 12, v[64:65]
	v_lshl_add_u64 v[66:67], v[66:67], 0, v[64:65]
	v_mul_i32_i24_e32 v64, 0x1800, v69
	v_or_b32_e32 v70, s13, v171
	v_cndmask_b32_e32 v64, v64, v177, vcc
	v_ashrrev_i32_e32 v71, 31, v70
	v_ashrrev_i32_e32 v65, 31, v64
	v_lshl_add_u64 v[72:73], v[64:65], 2, s[2:3]
	v_lshlrev_b64 v[64:65], 2, v[70:71]
	v_lshl_add_u64 v[82:83], v[72:73], 0, v[64:65]
	v_lshl_add_u64 v[66:67], v[66:67], 0, v[64:65]
	global_load_dwordx4 v[70:73], v[82:83], off
	global_load_dwordx4 v[74:77], v[66:67], off
	global_load_dwordx4 v[78:81], v[66:67], off offset:64
	s_waitcnt vmcnt(1)
	v_pk_fma_f32 v[60:61], v[60:61], v[70:71], v[74:75]
	v_pk_fma_f32 v[62:63], v[62:63], v[72:73], v[76:77]
	global_store_dwordx4 v[66:67], v[60:63], off
	global_load_dwordx4 v[60:63], v[82:83], off offset:64
	s_waitcnt vmcnt(0)
	v_pk_fma_f32 v[56:57], v[56:57], v[60:61], v[78:79]
	v_pk_fma_f32 v[58:59], v[58:59], v[62:63], v[80:81]
	global_store_dwordx4 v[66:67], v[56:59], off offset:64
	global_load_dwordx4 v[56:59], v[82:83], off offset:128
	global_load_dwordx4 v[60:63], v[66:67], off offset:128
	global_load_dwordx4 v[70:73], v[66:67], off offset:192
	s_waitcnt vmcnt(1)
	v_pk_fma_f32 v[52:53], v[52:53], v[56:57], v[60:61]
	v_pk_fma_f32 v[54:55], v[54:55], v[58:59], v[62:63]
	global_store_dwordx4 v[66:67], v[52:55], off offset:128
	global_load_dwordx4 v[54:57], v[82:83], off offset:192
	s_waitcnt vmcnt(0)
	v_pk_fma_f32 v[48:49], v[48:49], v[54:55], v[70:71]
	v_or_b32_e32 v53, 16, v68
	v_mul_hi_i32 v52, v53, s9
	v_lshrrev_b32_e32 v58, 31, v52
	v_ashrrev_i32_e32 v52, 13, v52
	v_add_u32_e32 v52, v52, v58
	v_mad_i32_i24 v53, v52, s10, v53
	v_cmp_gt_i32_e32 vcc, s5, v53
	v_pk_fma_f32 v[50:51], v[50:51], v[56:57], v[72:73]
	v_cmp_lt_i32_e64 s[0:1], s11, v53
	global_store_dwordx4 v[66:67], v[48:51], off offset:192
	s_and_saveexec_b64 s[14:15], s[0:1]
	s_xor_b64 s[0:1], exec, s[14:15]
	v_lshlrev_b32_e32 v48, 14, v52
	v_add3_u32 v48, v48, v53, s12
	s_or_saveexec_b64 s[0:1], s[0:1]
	v_mov_b64_e32 v[50:51], s[92:93]
	s_xor_b64 exec, exec, s[0:1]
	v_lshl_add_u32 v48, v52, 8, v53
	v_mov_b64_e32 v[50:51], s[68:69]
	s_or_b64 exec, exec, s[0:1]
	v_ashrrev_i32_e32 v49, 31, v48
	v_lshlrev_b64 v[48:49], 12, v[48:49]
	v_lshl_add_u64 v[48:49], v[50:51], 0, v[48:49]
	v_mul_i32_i24_e32 v50, 0x1800, v52
	v_cndmask_b32_e32 v50, v50, v177, vcc
	v_ashrrev_i32_e32 v51, 31, v50
	v_lshl_add_u64 v[50:51], v[50:51], 2, s[2:3]
	v_lshl_add_u64 v[62:63], v[50:51], 0, v[64:65]
	v_lshl_add_u64 v[60:61], v[48:49], 0, v[64:65]
	global_load_dwordx4 v[48:51], v[62:63], off
	global_load_dwordx4 v[52:55], v[60:61], off
	global_load_dwordx4 v[56:59], v[60:61], off offset:64
	s_waitcnt vmcnt(1)
	v_pk_fma_f32 v[44:45], v[44:45], v[48:49], v[52:53]
	v_pk_fma_f32 v[46:47], v[46:47], v[50:51], v[54:55]
	global_store_dwordx4 v[60:61], v[44:47], off
	global_load_dwordx4 v[44:47], v[62:63], off offset:64
	s_waitcnt vmcnt(0)
	v_pk_fma_f32 v[40:41], v[40:41], v[44:45], v[56:57]
	v_pk_fma_f32 v[42:43], v[42:43], v[46:47], v[58:59]
	global_store_dwordx4 v[60:61], v[40:43], off offset:64
	global_load_dwordx4 v[40:43], v[62:63], off offset:128
	global_load_dwordx4 v[44:47], v[60:61], off offset:128
	global_load_dwordx4 v[48:51], v[60:61], off offset:192
	s_waitcnt vmcnt(1)
	v_pk_fma_f32 v[36:37], v[36:37], v[40:41], v[44:45]
	v_pk_fma_f32 v[38:39], v[38:39], v[42:43], v[46:47]
	global_store_dwordx4 v[60:61], v[36:39], off offset:128
	global_load_dwordx4 v[38:41], v[62:63], off offset:192
	s_waitcnt vmcnt(0)
	v_pk_fma_f32 v[32:33], v[32:33], v[38:39], v[48:49]
	v_or_b32_e32 v37, 32, v68
	v_mul_hi_i32 v36, v37, s9
	v_lshrrev_b32_e32 v42, 31, v36
	v_ashrrev_i32_e32 v36, 13, v36
	v_add_u32_e32 v36, v36, v42
	v_mad_i32_i24 v37, v36, s10, v37
	v_cmp_gt_i32_e32 vcc, s5, v37
	v_pk_fma_f32 v[34:35], v[34:35], v[40:41], v[50:51]
	v_cmp_lt_i32_e64 s[0:1], s11, v37
	global_store_dwordx4 v[60:61], v[32:35], off offset:192
	s_and_saveexec_b64 s[14:15], s[0:1]
	s_xor_b64 s[0:1], exec, s[14:15]
	v_lshlrev_b32_e32 v32, 14, v36
	v_add3_u32 v32, v32, v37, s12
	s_or_saveexec_b64 s[0:1], s[0:1]
	v_mov_b64_e32 v[34:35], s[92:93]
	s_xor_b64 exec, exec, s[0:1]
	v_lshl_add_u32 v32, v36, 8, v37
	v_mov_b64_e32 v[34:35], s[68:69]
	s_or_b64 exec, exec, s[0:1]
	v_ashrrev_i32_e32 v33, 31, v32
	v_lshlrev_b64 v[32:33], 12, v[32:33]
	v_lshl_add_u64 v[32:33], v[34:35], 0, v[32:33]
	v_mul_i32_i24_e32 v34, 0x1800, v36
	v_cndmask_b32_e32 v34, v34, v177, vcc
	v_ashrrev_i32_e32 v35, 31, v34
	v_lshl_add_u64 v[34:35], v[34:35], 2, s[2:3]
	v_lshl_add_u64 v[46:47], v[34:35], 0, v[64:65]
	v_lshl_add_u64 v[44:45], v[32:33], 0, v[64:65]
	global_load_dwordx4 v[32:35], v[46:47], off
	global_load_dwordx4 v[36:39], v[44:45], off
	global_load_dwordx4 v[40:43], v[44:45], off offset:64
	s_waitcnt vmcnt(1)
	v_pk_fma_f32 v[28:29], v[28:29], v[32:33], v[36:37]
	v_pk_fma_f32 v[30:31], v[30:31], v[34:35], v[38:39]
	global_store_dwordx4 v[44:45], v[28:31], off
	global_load_dwordx4 v[28:31], v[46:47], off offset:64
	s_waitcnt vmcnt(0)
	v_pk_fma_f32 v[24:25], v[24:25], v[28:29], v[40:41]
	v_pk_fma_f32 v[26:27], v[26:27], v[30:31], v[42:43]
	global_store_dwordx4 v[44:45], v[24:27], off offset:64
	global_load_dwordx4 v[24:27], v[46:47], off offset:128
	global_load_dwordx4 v[28:31], v[44:45], off offset:128
	global_load_dwordx4 v[32:35], v[44:45], off offset:192
	s_waitcnt vmcnt(1)
	v_pk_fma_f32 v[20:21], v[20:21], v[24:25], v[28:29]
	v_pk_fma_f32 v[22:23], v[22:23], v[26:27], v[30:31]
	global_store_dwordx4 v[44:45], v[20:23], off offset:128
	global_load_dwordx4 v[22:25], v[46:47], off offset:192
	s_waitcnt vmcnt(0)
	v_pk_fma_f32 v[16:17], v[16:17], v[22:23], v[32:33]
	v_or_b32_e32 v21, 48, v68
	v_mul_hi_i32 v20, v21, s9
	v_lshrrev_b32_e32 v26, 31, v20
	v_ashrrev_i32_e32 v20, 13, v20
	v_add_u32_e32 v20, v20, v26
	v_mad_i32_i24 v21, v20, s10, v21
	v_cmp_gt_i32_e32 vcc, s5, v21
	v_pk_fma_f32 v[18:19], v[18:19], v[24:25], v[34:35]
	v_cmp_lt_i32_e64 s[0:1], s11, v21
	global_store_dwordx4 v[44:45], v[16:19], off offset:192
	s_and_saveexec_b64 s[14:15], s[0:1]
	s_xor_b64 s[0:1], exec, s[14:15]
	v_lshlrev_b32_e32 v16, 14, v20
	v_add3_u32 v16, v16, v21, s12
	s_or_saveexec_b64 s[0:1], s[0:1]
	v_mov_b64_e32 v[18:19], s[92:93]
	s_xor_b64 exec, exec, s[0:1]
	s_cbranch_execz .LBB0_1615
	v_lshl_add_u32 v16, v20, 8, v21
	v_mov_b64_e32 v[18:19], s[68:69]
	s_branch .LBB0_1615
